# loop-edge edit: GEMM k-loop fragment-address arithmetic moved ahead of the stage barrier so LDS reads issue right after the release (all 10 rolled loops)
# speedup vs baseline: 1.0692x; 1.0009x over previous
; template <bool SWAP, class Epi, bool THIN = false> ...
;     ...
;     for (int st = 0; st < ns; ++st) {
;       asm volatile("s_waitcnt vmcnt(0)" ::: "memory");
;       __builtin_amdgcn_s_barrier();
;       asm volatile("" ::: "memory");
;       if (st + 1 < ns) {
;         char* nb = smem + ((st + 1) & 1) * 65536;
;         const int ko = (st + 1) * 64;
; #pragma unroll
;         for (int i = 0; i < 4; ++i) { GLDS16(A + (size_t)(ap[i] + ko), nb + tid * 16 + i * 8192); GLDS16(Bt + (size_t)(bp[i] + ko), nb + 32768 + tid * 16 + i * 8192); }
;       }
;       const char* sa = smem + (st & 1) * 65536 + (wr * 64 + fr) * 128;
;       const char* sb = smem + (st & 1) * 65536 + 32768 + (wc * 128 + fr) * 128;
;       if constexpr (THIN) {
;         if (wc == 0) {
; #pragma unroll
;           for (int ks = 0; ks < 2; ++ks) {
;             bf16x8 af[4], bf[2];
; #pragma unroll
;             for (int m = 0; m < 4; ++m) af[m] = *(const bf16x8*)(sa + m * 2048 + (((ks * 4 + fq) ^ swz) << 4));
; #pragma unroll
;             for (int n = 0; n < 2; ++n) bf[n] = *(const bf16x8*)(sb + n * 2048 + (((ks * 4 + fq) ^ swz) << 4));
; #pragma unroll
;             for (int m = 0; m < 4; ++m)
; #pragma unroll
;               for (int n = 0; n < 2; ++n)
;                 acc[m][n] = SWAP ? __builtin_amdgcn_mfma_f32_16x16x32_bf16(bf[n], af[m], acc[m][n], 0, 0, 0)
;                                  : __builtin_amdgcn_mfma_f32_16x16x32_bf16(af[m], bf[n], acc[m][n], 0, 0, 0);
;           }
;         }
;       } else {
;       bf16x8 afA[4], afB[4], bfb[2][2];
; #pragma unroll
;       for (int m = 0; m < 4; ++m) afA[m] = *(const bf16x8*)(sa + m * 2048 + ((fq ^ swz) << 4));
; #pragma unroll
;       for (int n = 0; n < 2; ++n) bfb[0][n] = *(const bf16x8*)(sb + n * 2048 + ((fq ^ swz) << 4));
; #pragma unroll
;       for (int gq = 0; gq < 8; ++gq) {
;         const int ks = gq >> 2, nh = gq & 3;
;         if (gq < 7) {
;           const int ks2 = (gq + 1) >> 2, nh2 = (gq + 1) & 3;
; #pragma unroll
;           for (int n = 0; n < 2; ++n) bfb[(gq + 1) & 1][n] = *(const bf16x8*)(sb + (nh2 * 2 + n) * 2048 + (((ks2 * 4 + fq) ^ swz) << 4));
;         }
;         if (gq == 3) {
; #pragma unroll
;           for (int m = 0; m < 4; ++m) afB[m] = *(const bf16x8*)(sa + m * 2048 + (((4 + fq) ^ swz) << 4));
;         }
;         __builtin_amdgcn_sched_barrier(0);
; #pragma unroll
.LBB0_339:
	s_add_i32 s8, s7, 0x10000
	s_and_b32 s9, s8, 0x10000
	v_add_u32_e32 v171, s9, v144
	s_nop 0
	v_readfirstlane_b32 s9, v171
	s_and_b32 s7, s7, 0x10000
	v_add_u32_e32 v130, s7, v145
	v_add_u32_e32 v140, v130, v147
	s_waitcnt vmcnt(0)
	s_barrier
	ds_read_b128 v[172:175], v140
	ds_read_b128 v[176:179], v140 offset:2048
	ds_read_b128 v[180:183], v140 offset:4096
	ds_read_b128 v[184:187], v140 offset:6144
	v_or_b32_e32 v140, s7, v146
	v_add_u32_e32 v141, v140, v147
	ds_read_b128 v[188:191], v141 offset:32768
	ds_read_b128 v[192:195], v141 offset:34816
	ds_read_b128 v[196:199], v141 offset:36864
	ds_read_b128 v[200:203], v141 offset:38912
	v_add_u32_e32 v130, v130, v148
	s_waitcnt lgkmcnt(3)
	v_mfma_f32_16x16x32_bf16 v[126:129], v[188:191], v[172:175], v[126:129]
	s_mov_b32 m0, s9
	v_mfma_f32_16x16x32_bf16 v[110:113], v[188:191], v[176:179], v[110:113]
	global_load_lds_dwordx4 v139, s[36:37]
	v_add_u32_e32 v139, 0x80, v139
	v_mfma_f32_16x16x32_bf16 v[82:85], v[188:191], v[180:183], v[82:85]
	v_mfma_f32_16x16x32_bf16 v[50:53], v[188:191], v[184:187], v[50:53]
	ds_read_b128 v[188:191], v141 offset:40960
	ds_read_b128 v[204:207], v141 offset:43008
	s_waitcnt lgkmcnt(4)
	v_mfma_f32_16x16x32_bf16 v[122:125], v[192:195], v[172:175], v[122:125]
	s_add_u32 m0, s9, 0x8000
	v_mfma_f32_16x16x32_bf16 v[106:109], v[192:195], v[176:179], v[106:109]
	global_load_lds_dwordx4 v138, s[22:23]
	v_add_u32_e32 v138, 0x80, v138
	v_mfma_f32_16x16x32_bf16 v[78:81], v[192:195], v[180:183], v[78:81]
	v_mfma_f32_16x16x32_bf16 v[42:45], v[192:195], v[184:187], v[42:45]
	s_waitcnt lgkmcnt(3)
	v_mfma_f32_16x16x32_bf16 v[118:121], v[196:199], v[172:175], v[118:121]
	s_add_u32 m0, s9, 0x2000
	v_mfma_f32_16x16x32_bf16 v[94:97], v[196:199], v[176:179], v[94:97]
	global_load_lds_dwordx4 v137, s[36:37]
	v_add_u32_e32 v137, 0x80, v137
	v_mfma_f32_16x16x32_bf16 v[58:61], v[196:199], v[180:183], v[58:61]
	v_mfma_f32_16x16x32_bf16 v[26:29], v[196:199], v[184:187], v[26:29]
	ds_read_b128 v[192:195], v141 offset:45056
	ds_read_b128 v[196:199], v141 offset:47104
	s_waitcnt lgkmcnt(4)
	v_mfma_f32_16x16x32_bf16 v[114:117], v[200:203], v[172:175], v[114:117]
	s_add_u32 m0, s9, 0xa000
	v_mfma_f32_16x16x32_bf16 v[86:89], v[200:203], v[176:179], v[86:89]
	global_load_lds_dwordx4 v136, s[22:23]
	v_add_u32_e32 v136, 0x80, v136
	v_mfma_f32_16x16x32_bf16 v[54:57], v[200:203], v[180:183], v[54:57]
	v_mfma_f32_16x16x32_bf16 v[22:25], v[200:203], v[184:187], v[22:25]
	v_add_u32_e32 v140, v140, v148
	s_waitcnt lgkmcnt(3)
	v_mfma_f32_16x16x32_bf16 v[102:105], v[188:191], v[172:175], v[102:105]
	ds_read_b128 v[200:203], v140 offset:32768
	ds_read_b128 v[208:211], v140 offset:34816
	s_add_u32 m0, s9, 0x4000
	v_mfma_f32_16x16x32_bf16 v[74:77], v[188:191], v[176:179], v[74:77]
	global_load_lds_dwordx4 v135, s[36:37]
	v_add_u32_e32 v135, 0x80, v135
	v_mfma_f32_16x16x32_bf16 v[46:49], v[188:191], v[180:183], v[46:49]
	v_mfma_f32_16x16x32_bf16 v[10:13], v[188:191], v[184:187], v[10:13]
	ds_read_b128 v[188:191], v130
	ds_read_b128 v[212:215], v130 offset:2048
	ds_read_b128 v[216:219], v130 offset:4096
	ds_read_b128 v[220:223], v130 offset:6144
	s_waitcnt lgkmcnt(8)
	v_mfma_f32_16x16x32_bf16 v[98:101], v[204:207], v[172:175], v[98:101]
	s_add_u32 m0, s9, 0xc000
	v_mfma_f32_16x16x32_bf16 v[66:69], v[204:207], v[176:179], v[66:69]
	global_load_lds_dwordx4 v134, s[22:23]
	v_add_u32_e32 v134, 0x80, v134
	v_mfma_f32_16x16x32_bf16 v[30:33], v[204:207], v[180:183], v[30:33]
	v_mfma_f32_16x16x32_bf16 v[6:9], v[204:207], v[184:187], v[6:9]
	s_waitcnt lgkmcnt(7)
	v_mfma_f32_16x16x32_bf16 v[70:73], v[192:195], v[172:175], v[70:73]
	s_add_u32 m0, s9, 0x6000
	s_waitcnt lgkmcnt(6)
	v_mfma_f32_16x16x32_bf16 v[62:65], v[196:199], v[172:175], v[62:65]
	global_load_lds_dwordx4 v133, s[36:37]
	v_add_u32_e32 v133, 0x80, v133
	v_mfma_f32_16x16x32_bf16 v[38:41], v[192:195], v[176:179], v[38:41]
	v_mfma_f32_16x16x32_bf16 v[34:37], v[196:199], v[176:179], v[34:37]
	ds_read_b128 v[172:175], v140 offset:36864
	ds_read_b128 v[176:179], v140 offset:38912
	v_mfma_f32_16x16x32_bf16 v[18:21], v[192:195], v[180:183], v[18:21]
	s_add_u32 m0, s9, 0xe000
	v_mfma_f32_16x16x32_bf16 v[14:17], v[196:199], v[180:183], v[14:17]
	global_load_lds_dwordx4 v132, s[22:23]
	v_add_u32_e32 v132, 0x80, v132
	v_mfma_f32_16x16x32_bf16 v[2:5], v[192:195], v[184:187], v[2:5]
	v_mfma_f32_16x16x32_bf16 v[90:93], v[196:199], v[184:187], v[90:93]
	ds_read_b128 v[180:183], v140 offset:40960
	ds_read_b128 v[184:187], v140 offset:43008
	s_waitcnt lgkmcnt(7)
	v_mfma_f32_16x16x32_bf16 v[126:129], v[200:203], v[188:191], v[126:129]
	v_mfma_f32_16x16x32_bf16 v[122:125], v[208:211], v[188:191], v[122:125]
	s_waitcnt lgkmcnt(6)
	v_mfma_f32_16x16x32_bf16 v[110:113], v[200:203], v[212:215], v[110:113]
	v_mfma_f32_16x16x32_bf16 v[106:109], v[208:211], v[212:215], v[106:109]
	s_waitcnt lgkmcnt(5)
	v_mfma_f32_16x16x32_bf16 v[82:85], v[200:203], v[216:219], v[82:85]
	v_mfma_f32_16x16x32_bf16 v[78:81], v[208:211], v[216:219], v[78:81]
	s_waitcnt lgkmcnt(4)
	v_mfma_f32_16x16x32_bf16 v[50:53], v[200:203], v[220:223], v[50:53]
	v_mfma_f32_16x16x32_bf16 v[42:45], v[208:211], v[220:223], v[42:45]
	s_waitcnt lgkmcnt(3)
	v_mfma_f32_16x16x32_bf16 v[118:121], v[172:175], v[188:191], v[118:121]
	v_mfma_f32_16x16x32_bf16 v[94:97], v[172:175], v[212:215], v[94:97]
	v_mfma_f32_16x16x32_bf16 v[58:61], v[172:175], v[216:219], v[58:61]
	v_mfma_f32_16x16x32_bf16 v[26:29], v[172:175], v[220:223], v[26:29]
	ds_read_b128 v[172:175], v140 offset:45056
	ds_read_b128 v[192:195], v140 offset:47104
	s_waitcnt lgkmcnt(4)
; template <bool SWAP, class Epi, bool THIN = false> ...
;     ...
;     for (int st = 0; st < ns; ++st) {
;       asm volatile("s_waitcnt vmcnt(0)" ::: "memory");
;       __builtin_amdgcn_s_barrier();
;       asm volatile("" ::: "memory");
;       if (st + 1 < ns) {
;         char* nb = smem + ((st + 1) & 1) * 65536;
;         const int ko = (st + 1) * 64;
; #pragma unroll
;         for (int i = 0; i < 4; ++i) { GLDS16(A + (size_t)(ap[i] + ko), nb + tid * 16 + i * 8192); GLDS16(Bt + (size_t)(bp[i] + ko), nb + 32768 + tid * 16 + i * 8192); }
;       }
;       const char* sa = smem + (st & 1) * 65536 + (wr * 64 + fr) * 128;
;       const char* sb = smem + (st & 1) * 65536 + 32768 + (wc * 128 + fr) * 128;
;       if constexpr (THIN) {
;         if (wc == 0) {
; #pragma unroll
;           for (int ks = 0; ks < 2; ++ks) {
;             bf16x8 af[4], bf[2];
; #pragma unroll
;             for (int m = 0; m < 4; ++m) af[m] = *(const bf16x8*)(sa + m * 2048 + (((ks * 4 + fq) ^ swz) << 4));
; #pragma unroll
;             for (int n = 0; n < 2; ++n) bf[n] = *(const bf16x8*)(sb + n * 2048 + (((ks * 4 + fq) ^ swz) << 4));
; #pragma unroll
;             for (int m = 0; m < 4; ++m)
; #pragma unroll
;               for (int n = 0; n < 2; ++n)
;                 acc[m][n] = SWAP ? __builtin_amdgcn_mfma_f32_16x16x32_bf16(bf[n], af[m], acc[m][n], 0, 0, 0)
;                                  : __builtin_amdgcn_mfma_f32_16x16x32_bf16(af[m], bf[n], acc[m][n], 0, 0, 0);
;           }
;         }
;       } else {
;       bf16x8 afA[4], afB[4], bfb[2][2];
; #pragma unroll
;       for (int m = 0; m < 4; ++m) afA[m] = *(const bf16x8*)(sa + m * 2048 + ((fq ^ swz) << 4));
; #pragma unroll
;       for (int n = 0; n < 2; ++n) bfb[0][n] = *(const bf16x8*)(sb + n * 2048 + ((fq ^ swz) << 4));
; #pragma unroll
;       for (int gq = 0; gq < 8; ++gq) {
;         const int ks = gq >> 2, nh = gq & 3;
;         if (gq < 7) {
;           const int ks2 = (gq + 1) >> 2, nh2 = (gq + 1) & 3;
; #pragma unroll
;           for (int n = 0; n < 2; ++n) bfb[(gq + 1) & 1][n] = *(const bf16x8*)(sb + (nh2 * 2 + n) * 2048 + (((ks2 * 4 + fq) ^ swz) << 4));
;         }
;         if (gq == 3) {
; #pragma unroll
;           for (int m = 0; m < 4; ++m) afB[m] = *(const bf16x8*)(sa + m * 2048 + (((4 + fq) ^ swz) << 4));
;         }
;         __builtin_amdgcn_sched_barrier(0);
; #pragma unroll
	v_mfma_f32_16x16x32_bf16 v[114:117], v[176:179], v[188:191], v[114:117]
	v_mfma_f32_16x16x32_bf16 v[86:89], v[176:179], v[212:215], v[86:89]
	v_mfma_f32_16x16x32_bf16 v[54:57], v[176:179], v[216:219], v[54:57]
	v_mfma_f32_16x16x32_bf16 v[22:25], v[176:179], v[220:223], v[22:25]
	s_waitcnt lgkmcnt(3)
	v_mfma_f32_16x16x32_bf16 v[102:105], v[180:183], v[188:191], v[102:105]
	s_waitcnt lgkmcnt(2)
	v_mfma_f32_16x16x32_bf16 v[98:101], v[184:187], v[188:191], v[98:101]
	v_mfma_f32_16x16x32_bf16 v[74:77], v[180:183], v[212:215], v[74:77]
	v_mfma_f32_16x16x32_bf16 v[66:69], v[184:187], v[212:215], v[66:69]
	v_mfma_f32_16x16x32_bf16 v[46:49], v[180:183], v[216:219], v[46:49]
	v_mfma_f32_16x16x32_bf16 v[30:33], v[184:187], v[216:219], v[30:33]
	v_mfma_f32_16x16x32_bf16 v[10:13], v[180:183], v[220:223], v[10:13]
	v_mfma_f32_16x16x32_bf16 v[6:9], v[184:187], v[220:223], v[6:9]
	s_waitcnt lgkmcnt(1)
	v_mfma_f32_16x16x32_bf16 v[70:73], v[172:175], v[188:191], v[70:73]
	s_add_i32 s6, s6, 64
	s_cmpk_eq_i32 s6, 0x3c0
	s_mov_b32 s7, s8
	s_waitcnt lgkmcnt(0)
	v_mfma_f32_16x16x32_bf16 v[62:65], v[192:195], v[188:191], v[62:65]
	v_mfma_f32_16x16x32_bf16 v[38:41], v[172:175], v[212:215], v[38:41]
	v_mfma_f32_16x16x32_bf16 v[34:37], v[192:195], v[212:215], v[34:37]
	v_mfma_f32_16x16x32_bf16 v[18:21], v[172:175], v[216:219], v[18:21]
	v_mfma_f32_16x16x32_bf16 v[14:17], v[192:195], v[216:219], v[14:17]
	v_mfma_f32_16x16x32_bf16 v[2:5], v[172:175], v[220:223], v[2:5]
	v_mfma_f32_16x16x32_bf16 v[90:93], v[192:195], v[220:223], v[90:93]
	s_cbranch_scc0 .LBB0_339
	s_waitcnt vmcnt(0)
	s_barrier
	v_add_u32_e32 v130, v159, v147
	ds_read_b128 v[132:135], v130
	ds_read_b128 v[136:139], v130 offset:2048
	ds_read_b128 v[172:175], v130 offset:4096
	ds_read_b128 v[176:179], v130 offset:6144
	v_add_u32_e32 v130, v160, v147
	ds_read_b128 v[180:183], v130
	ds_read_b128 v[184:187], v130 offset:2048
	ds_read_b128 v[188:191], v130 offset:4096
	ds_read_b128 v[192:195], v130 offset:6144
	s_waitcnt lgkmcnt(0)
	v_mfma_f32_16x16x32_bf16 v[126:129], v[180:183], v[132:135], v[126:129]
	v_mfma_f32_16x16x32_bf16 v[110:113], v[180:183], v[136:139], v[110:113]
	v_mfma_f32_16x16x32_bf16 v[82:85], v[180:183], v[172:175], v[82:85]
	v_mfma_f32_16x16x32_bf16 v[50:53], v[180:183], v[176:179], v[50:53]
	ds_read_b128 v[180:183], v130 offset:8192
	ds_read_b128 v[196:199], v130 offset:10240
	v_mfma_f32_16x16x32_bf16 v[122:125], v[184:187], v[132:135], v[122:125]
	v_mfma_f32_16x16x32_bf16 v[106:109], v[184:187], v[136:139], v[106:109]
	v_mfma_f32_16x16x32_bf16 v[78:81], v[184:187], v[172:175], v[78:81]
	v_mfma_f32_16x16x32_bf16 v[42:45], v[184:187], v[176:179], v[42:45]
	v_mfma_f32_16x16x32_bf16 v[118:121], v[188:191], v[132:135], v[118:121]
	v_mfma_f32_16x16x32_bf16 v[184:187], v[188:191], v[136:139], v[94:97]
	v_mfma_f32_16x16x32_bf16 v[204:207], v[188:191], v[172:175], v[58:61]
	v_mfma_f32_16x16x32_bf16 v[208:211], v[192:195], v[172:175], v[54:57]
	v_mfma_f32_16x16x32_bf16 v[188:191], v[188:191], v[176:179], v[26:29]
	s_nop 2
	ds_read_b128 v[26:29], v130 offset:12288
	ds_read_b128 v[54:57], v130 offset:14336
	v_mfma_f32_16x16x32_bf16 v[114:117], v[192:195], v[132:135], v[114:117]
	v_mfma_f32_16x16x32_bf16 v[200:203], v[192:195], v[136:139], v[86:89]
	v_mfma_f32_16x16x32_bf16 v[192:195], v[192:195], v[176:179], v[22:25]
	v_add_u32_e32 v130, v160, v148
	s_waitcnt lgkmcnt(0)
	v_mfma_f32_16x16x32_bf16 v[212:215], v[196:199], v[172:175], v[30:33]
	ds_read_b128 v[22:25], v130
	ds_read_b128 v[86:89], v130 offset:2048
	s_nop 0
	v_add_u32_e32 v30, v159, v148
	v_mfma_f32_16x16x32_bf16 v[102:105], v[180:183], v[132:135], v[102:105]
	v_mfma_f32_16x16x32_bf16 v[74:77], v[180:183], v[136:139], v[74:77]
	v_mfma_f32_16x16x32_bf16 v[46:49], v[180:183], v[172:175], v[46:49]
	v_mfma_f32_16x16x32_bf16 v[10:13], v[180:183], v[176:179], v[10:13]
	ds_read_b128 v[180:183], v30
	ds_read_b128 v[216:219], v30 offset:2048
	ds_read_b128 v[220:223], v30 offset:4096
	ds_read_b128 v[224:227], v30 offset:6144
	v_mfma_f32_16x16x32_bf16 v[98:101], v[196:199], v[132:135], v[98:101]
	v_mfma_f32_16x16x32_bf16 v[66:69], v[196:199], v[136:139], v[66:69]
	v_mfma_f32_16x16x32_bf16 v[6:9], v[196:199], v[176:179], v[6:9]
	v_mfma_f32_16x16x32_bf16 v[196:199], v[26:29], v[172:175], v[18:21]
	v_mfma_f32_16x16x32_bf16 v[172:175], v[54:57], v[172:175], v[14:17]
	s_nop 2
	ds_read_b128 v[14:17], v130 offset:4096
	ds_read_b128 v[18:21], v130 offset:6144
	v_mfma_f32_16x16x32_bf16 v[70:73], v[26:29], v[132:135], v[70:73]
	v_mfma_f32_16x16x32_bf16 v[132:135], v[54:57], v[132:135], v[62:65]
	v_mfma_f32_16x16x32_bf16 v[38:41], v[26:29], v[136:139], v[38:41]
	v_mfma_f32_16x16x32_bf16 v[34:37], v[54:57], v[136:139], v[34:37]
	v_mfma_f32_16x16x32_bf16 v[2:5], v[26:29], v[176:179], v[2:5]
	v_mfma_f32_16x16x32_bf16 v[176:179], v[54:57], v[176:179], v[90:93]
	ds_read_b128 v[136:139], v130 offset:8192
	ds_read_b128 v[228:231], v130 offset:10240
	s_waitcnt lgkmcnt(0)
	v_mfma_f32_16x16x32_bf16 v[126:129], v[22:25], v[180:183], v[126:129]
	v_mfma_f32_16x16x32_bf16 v[122:125], v[86:89], v[180:183], v[122:125]
	v_mfma_f32_16x16x32_bf16 v[94:97], v[22:25], v[216:219], v[110:113]
	v_mfma_f32_16x16x32_bf16 v[90:93], v[86:89], v[216:219], v[106:109]
	v_mfma_f32_16x16x32_bf16 v[62:65], v[22:25], v[220:223], v[82:85]
	v_mfma_f32_16x16x32_bf16 v[58:61], v[86:89], v[220:223], v[78:81]
	v_mfma_f32_16x16x32_bf16 v[30:33], v[22:25], v[224:227], v[50:53]
	v_mfma_f32_16x16x32_bf16 v[26:29], v[86:89], v[224:227], v[42:45]
	v_mfma_f32_16x16x32_bf16 v[86:89], v[14:17], v[216:219], v[184:187]
	v_mfma_f32_16x16x32_bf16 v[22:25], v[14:17], v[224:227], v[188:191]
	s_nop 1
	ds_read_b128 v[184:187], v130 offset:12288
	ds_read_b128 v[188:191], v130 offset:14336
	v_mfma_f32_16x16x32_bf16 v[118:121], v[14:17], v[180:183], v[118:121]
	v_mfma_f32_16x16x32_bf16 v[114:117], v[18:21], v[180:183], v[114:117]
	v_mfma_f32_16x16x32_bf16 v[82:85], v[18:21], v[216:219], v[200:203]
	v_mfma_f32_16x16x32_bf16 v[54:57], v[14:17], v[220:223], v[204:207]
	v_mfma_f32_16x16x32_bf16 v[50:53], v[18:21], v[220:223], v[208:211]
	v_mfma_f32_16x16x32_bf16 v[18:21], v[18:21], v[224:227], v[192:195]
	v_mfma_f32_16x16x32_bf16 v[110:113], v[136:139], v[180:183], v[102:105]
	v_mfma_f32_16x16x32_bf16 v[106:109], v[228:231], v[180:183], v[98:101]
	v_mfma_f32_16x16x32_bf16 v[78:81], v[136:139], v[216:219], v[74:77]
	v_mfma_f32_16x16x32_bf16 v[74:77], v[228:231], v[216:219], v[66:69]
	v_mfma_f32_16x16x32_bf16 v[46:49], v[136:139], v[220:223], v[46:49]
	v_mfma_f32_16x16x32_bf16 v[42:45], v[228:231], v[220:223], v[212:215]
	v_mfma_f32_16x16x32_bf16 v[14:17], v[136:139], v[224:227], v[10:13]
	v_mfma_f32_16x16x32_bf16 v[6:9], v[228:231], v[224:227], v[6:9]
	s_nop 1
	v_mov_b32_e32 v10, v1
	s_waitcnt vmcnt(0) lgkmcnt(0)
	s_barrier
; __device__ __forceinline__ int get_tid512() { int t = threadIdx.x; asm volatile("" : "+v"(t)); return t; }
; __device__ __forceinline__ unsigned pack2(float a, float b) { unsigned r; asm("v_cvt_pk_bf16_f32 %0, %1, %2" : "=v"(r) : "v"(a), "v"(b)); return r; }
;   __device__ __forceinline__ float c4(int g, int rig, int col, f32x4 v) const {
;     ...
;     uint2 u; u.x = pack2(v[0], v[1]); u.y = pack2(v[2], v[3]);
;     *(uint2*)(out + row * ld + col) = u;
;     return v[0] * v[0] + v[1] * v[1] + v[2] * v[2] + v[3] * v[3];
;   }
;   __device__ __forceinline__ void rowsum(int g, int rig, int slot, float ss) const {
;     if (slot < nslots) part[(size_t)slot * ((size_t)8 * ostride) + (size_t)g * ostride + rig] = ss;
;   }
; template <bool SWAP, class Epi, bool THIN = false> ...
;     ...
;     const int te = get_tid512();
;     const int fr_e = te & 15, fq_e = (te & 63) >> 4, wr_e = te >> 7, wc_e = (te >> 6) & 1;
;     const int sub = 2 * mt + (wr_e >> 1);
;     const int g = sub / tpg, ti = sub - g * tpg;
;     const int rig0 = ti * step - halo;
;     const int rw = (wr_e & 1) * 64;
;     if constexpr (Epi::KIND == 0) {
; #pragma unroll
;       for (int m = 0; m < 4; ++m) {
;         const int rig = rig0 + rw + m * 16 + fr_e;
;         if constexpr (Epi::ROWSUM) {
;           float ss = 0.f;
; #pragma unroll
;           for (int n = 0; n < 8; ++n) {
;             const int col = nt * 256 + wc_e * 128 + n * 16 + fq_e * 4;
;             if (col < N) ss += epi.c4(g, rig, col, acc[m][n]);
;           }
;           ss += __shfl_xor(ss, 16); ss += __shfl_xor(ss, 32);
;           if (fq_e == 0) epi.rowsum(g, rig, nt * 2 + wc_e, ss);
;         } else {
	v_mfma_f32_16x16x32_bf16 v[98:101], v[188:191], v[180:183], v[132:135]
	v_ashrrev_i32_e32 v11, 8, v10
	v_add_u32_e32 v11, s5, v11
	v_ashrrev_i32_e32 v12, 31, v11
	v_lshrrev_b32_e32 v12, 28, v12
	v_add_u32_e32 v12, v11, v12
	v_ashrrev_i32_e32 v138, 4, v12
	v_and_b32_e32 v132, 15, v10
	v_bfe_u32 v130, v10, 4, 2
	v_bfe_u32 v171, v10, 6, 1
	v_lshlrev_b32_e32 v12, 11, v138
	v_lshlrev_b32_e32 v11, 7, v11
	v_lshrrev_b32_e32 v10, 1, v10
	v_sub_u32_e32 v133, v11, v12
	v_and_b32_e32 v135, 64, v10
	v_lshlrev_b32_e32 v134, 7, v171
	v_mfma_f32_16x16x32_bf16 v[10:13], v[184:187], v[224:227], v[2:5]
	v_ashrrev_i32_e32 v139, 31, v138
	v_or3_b32 v132, v133, v135, v132
	v_ashrrev_i32_e32 v133, 31, v132
	v_lshlrev_b32_e32 v2, 2, v130
	v_mfma_f32_16x16x32_bf16 v[102:105], v[184:187], v[180:183], v[70:73]
	v_or3_b32 v134, v134, v2, s4
	v_lshlrev_b64 v[136:137], 21, v[138:139]
	v_cmp_gt_i32_e32 vcc, s29, v134
	v_mfma_f32_16x16x32_bf16 v[70:73], v[184:187], v[216:219], v[38:41]
	v_lshlrev_b64 v[140:141], 10, v[132:133]
	v_ashrrev_i32_e32 v135, 31, v134
	v_lshl_add_u64 v[136:137], s[38:39], 0, v[136:137]
	v_mfma_f32_16x16x32_bf16 v[66:69], v[188:191], v[216:219], v[34:37]
	v_mfma_f32_16x16x32_bf16 v[38:41], v[184:187], v[220:223], v[196:199]
	v_mfma_f32_16x16x32_bf16 v[34:37], v[188:191], v[220:223], v[172:175]
	v_mfma_f32_16x16x32_bf16 v[2:5], v[188:191], v[224:227], v[176:179]
	s_nop 1
	v_bfe_u32 v246, v1, 4, 1
	v_mul_u32_u24_e32 v246, 24, v246
	v_mov_b32_e32 v247, 0
	v_xor_b32_e32 v254, 16, v170
	v_lshlrev_b32_e32 v254, 2, v254
	v_xor_b32_e32 v255, 32, v170
	v_lshlrev_b32_e32 v255, 2, v255
	v_lshl_or_b32 v252, s20, 1, v171
	v_ashrrev_i32_e32 v253, 31, v252
	v_cmp_eq_u32_e64 s[18:19], 0, v130
	v_cmp_gt_i32_e64 s[20:21], 4, v252
	s_and_b64 s[18:19], s[18:19], s[20:21]
	v_lshlrev_b64 v[252:253], 16, v[252:253]
	v_lshl_add_u64 v[252:253], s[24:25], 0, v[252:253]
	v_lshlrev_b64 v[248:249], 13, v[138:139]
	v_lshl_add_u64 v[252:253], v[252:253], 0, v[248:249]
	v_lshl_add_u64 v[252:253], v[132:133], 2, v[252:253]
	v_lshl_add_u64 v[248:249], v[136:137], 0, v[140:141]
	v_lshl_add_u64 v[248:249], v[134:135], 1, v[248:249]
	v_lshl_add_u64 v[248:249], v[248:249], 0, v[246:247]
	v_cvt_pk_bf16_f32 v232, v126, v127
	v_cvt_pk_bf16_f32 v233, v128, v129
	v_mul_f32_e32 v240, v126, v126
	v_mul_f32_e32 v241, v127, v127
	v_mul_f32_e32 v242, v128, v128
	v_mul_f32_e32 v243, v129, v129
	v_add_f32_e32 v245, v240, v241
	v_add_f32_e32 v245, v242, v245
	v_add_f32_e32 v244, v243, v245
	v_cvt_pk_bf16_f32 v234, v122, v123
	v_cvt_pk_bf16_f32 v235, v124, v125
	v_mul_f32_e32 v240, v122, v122
	v_mul_f32_e32 v241, v123, v123
	v_mul_f32_e32 v242, v124, v124
	v_mul_f32_e32 v243, v125, v125
	v_add_f32_e32 v245, v240, v241
	v_add_f32_e32 v245, v242, v245
	v_add_f32_e32 v245, v243, v245
	v_add_f32_e32 v244, v245, v244
	s_nop 1
	v_permlane16_swap_b32 v232, v234
	v_permlane16_swap_b32 v233, v235
	global_store_dwordx4 v[248:249], v[232:235], off
	v_cvt_pk_bf16_f32 v236, v118, v119
	v_cvt_pk_bf16_f32 v237, v120, v121
	v_mul_f32_e32 v240, v118, v118
	v_mul_f32_e32 v241, v119, v119
	v_mul_f32_e32 v242, v120, v120
	v_mul_f32_e32 v243, v121, v121
	v_add_f32_e32 v245, v240, v241
	v_add_f32_e32 v245, v242, v245
	v_add_f32_e32 v245, v243, v245
	v_add_f32_e32 v244, v245, v244
	v_cvt_pk_bf16_f32 v238, v114, v115
	v_cvt_pk_bf16_f32 v239, v116, v117
	v_mul_f32_e32 v240, v114, v114
	v_mul_f32_e32 v241, v115, v115
	v_mul_f32_e32 v242, v116, v116
	v_mul_f32_e32 v243, v117, v117
	v_add_f32_e32 v245, v240, v241
	v_add_f32_e32 v245, v242, v245
	v_add_f32_e32 v245, v243, v245
	v_add_f32_e32 v244, v245, v244
	s_nop 1
	v_permlane16_swap_b32 v236, v238
	v_permlane16_swap_b32 v237, v239
	global_store_dwordx4 v[248:249], v[236:239], off offset:64
	v_cvt_pk_bf16_f32 v232, v110, v111
	v_cvt_pk_bf16_f32 v233, v112, v113
	v_mul_f32_e32 v240, v110, v110
	v_mul_f32_e32 v241, v111, v111
	v_mul_f32_e32 v242, v112, v112
	v_mul_f32_e32 v243, v113, v113
	v_add_f32_e32 v245, v240, v241
	v_add_f32_e32 v245, v242, v245
	v_add_f32_e32 v245, v243, v245
	v_add_f32_e32 v244, v245, v244
	v_cvt_pk_bf16_f32 v234, v106, v107
	v_cvt_pk_bf16_f32 v235, v108, v109
	v_mul_f32_e32 v240, v106, v106
	v_mul_f32_e32 v241, v107, v107
	v_mul_f32_e32 v242, v108, v108
	v_mul_f32_e32 v243, v109, v109
	v_add_f32_e32 v245, v240, v241
	v_add_f32_e32 v245, v242, v245
	v_add_f32_e32 v245, v243, v245
	v_add_f32_e32 v244, v245, v244
	s_nop 1
	v_permlane16_swap_b32 v232, v234
	v_permlane16_swap_b32 v233, v235
	global_store_dwordx4 v[248:249], v[232:235], off offset:128
	v_cvt_pk_bf16_f32 v236, v102, v103
	v_cvt_pk_bf16_f32 v237, v104, v105
	v_mul_f32_e32 v240, v102, v102
	v_mul_f32_e32 v241, v103, v103
	v_mul_f32_e32 v242, v104, v104
	v_mul_f32_e32 v243, v105, v105
	v_add_f32_e32 v245, v240, v241
	v_add_f32_e32 v245, v242, v245
	v_add_f32_e32 v245, v243, v245
	v_add_f32_e32 v244, v245, v244
	v_cvt_pk_bf16_f32 v238, v98, v99
	v_cvt_pk_bf16_f32 v239, v100, v101
	v_mul_f32_e32 v240, v98, v98
	v_mul_f32_e32 v241, v99, v99
	v_mul_f32_e32 v242, v100, v100
	v_mul_f32_e32 v243, v101, v101
	v_add_f32_e32 v245, v240, v241
	v_add_f32_e32 v245, v242, v245
	v_add_f32_e32 v245, v243, v245
	v_add_f32_e32 v244, v245, v244
	s_nop 1
	v_permlane16_swap_b32 v236, v238
	v_permlane16_swap_b32 v237, v239
	global_store_dwordx4 v[248:249], v[236:239], off offset:192
	ds_bpermute_b32 v251, v254, v244
	s_waitcnt lgkmcnt(0)
	v_add_f32_e32 v245, v244, v251
	ds_bpermute_b32 v251, v255, v245
	s_waitcnt lgkmcnt(0)
; __device__ __forceinline__ unsigned pack2(float a, float b) { unsigned r; asm("v_cvt_pk_bf16_f32 %0, %1, %2" : "=v"(r) : "v"(a), "v"(b)); return r; }
;   __device__ __forceinline__ float c4(int g, int rig, int col, f32x4 v) const {
;     ...
;     uint2 u; u.x = pack2(v[0], v[1]); u.y = pack2(v[2], v[3]);
;     *(uint2*)(out + row * ld + col) = u;
;     return v[0] * v[0] + v[1] * v[1] + v[2] * v[2] + v[3] * v[3];
;   }
;   __device__ __forceinline__ void rowsum(int g, int rig, int slot, float ss) const {
;     if (slot < nslots) part[(size_t)slot * ((size_t)8 * ostride) + (size_t)g * ostride + rig] = ss;
; template <bool SWAP, class Epi, bool THIN = false> ...
;     ...
;       for (int m = 0; m < 4; ++m) {
;         const int rig = rig0 + rw + m * 16 + fr_e;
;         if constexpr (Epi::ROWSUM) {
;           float ss = 0.f;
; #pragma unroll
;           for (int n = 0; n < 8; ++n) {
;             const int col = nt * 256 + wc_e * 128 + n * 16 + fq_e * 4;
;             if (col < N) ss += epi.c4(g, rig, col, acc[m][n]);
;           }
;           ss += __shfl_xor(ss, 16); ss += __shfl_xor(ss, 32);
;           if (fq_e == 0) epi.rowsum(g, rig, nt * 2 + wc_e, ss);
	v_add_f32_e32 v245, v245, v251
	s_and_saveexec_b64 s[20:21], s[18:19]
	global_store_dword v[252:253], v245, off
	s_or_b64 exec, exec, s[20:21]
	v_or_b32_e32 v248, 16, v132
	v_ashrrev_i32_e32 v249, 31, v248
	v_lshlrev_b64 v[248:249], 10, v[248:249]
	v_lshl_add_u64 v[248:249], v[136:137], 0, v[248:249]
	v_lshl_add_u64 v[248:249], v[134:135], 1, v[248:249]
	v_lshl_add_u64 v[248:249], v[248:249], 0, v[246:247]
	v_cvt_pk_bf16_f32 v232, v94, v95
	v_cvt_pk_bf16_f32 v233, v96, v97
	v_mul_f32_e32 v240, v94, v94
	v_mul_f32_e32 v241, v95, v95
	v_mul_f32_e32 v242, v96, v96
	v_mul_f32_e32 v243, v97, v97
	v_add_f32_e32 v245, v240, v241
	v_add_f32_e32 v245, v242, v245
	v_add_f32_e32 v244, v243, v245
	v_cvt_pk_bf16_f32 v234, v90, v91
	v_cvt_pk_bf16_f32 v235, v92, v93
	v_mul_f32_e32 v240, v90, v90
	v_mul_f32_e32 v241, v91, v91
	v_mul_f32_e32 v242, v92, v92
	v_mul_f32_e32 v243, v93, v93
	v_add_f32_e32 v245, v240, v241
	v_add_f32_e32 v245, v242, v245
	v_add_f32_e32 v245, v243, v245
	v_add_f32_e32 v244, v245, v244
	s_nop 1
	v_permlane16_swap_b32 v232, v234
	v_permlane16_swap_b32 v233, v235
	global_store_dwordx4 v[248:249], v[232:235], off
	v_cvt_pk_bf16_f32 v236, v86, v87
	v_cvt_pk_bf16_f32 v237, v88, v89
	v_mul_f32_e32 v240, v86, v86
	v_mul_f32_e32 v241, v87, v87
	v_mul_f32_e32 v242, v88, v88
	v_mul_f32_e32 v243, v89, v89
	v_add_f32_e32 v245, v240, v241
	v_add_f32_e32 v245, v242, v245
	v_add_f32_e32 v245, v243, v245
	v_add_f32_e32 v244, v245, v244
	v_cvt_pk_bf16_f32 v238, v82, v83
	v_cvt_pk_bf16_f32 v239, v84, v85
	v_mul_f32_e32 v240, v82, v82
	v_mul_f32_e32 v241, v83, v83
	v_mul_f32_e32 v242, v84, v84
	v_mul_f32_e32 v243, v85, v85
	v_add_f32_e32 v245, v240, v241
	v_add_f32_e32 v245, v242, v245
	v_add_f32_e32 v245, v243, v245
	v_add_f32_e32 v244, v245, v244
	s_nop 1
	v_permlane16_swap_b32 v236, v238
	v_permlane16_swap_b32 v237, v239
	global_store_dwordx4 v[248:249], v[236:239], off offset:64
	v_cvt_pk_bf16_f32 v232, v78, v79
	v_cvt_pk_bf16_f32 v233, v80, v81
	v_mul_f32_e32 v240, v78, v78
	v_mul_f32_e32 v241, v79, v79
	v_mul_f32_e32 v242, v80, v80
	v_mul_f32_e32 v243, v81, v81
	v_add_f32_e32 v245, v240, v241
	v_add_f32_e32 v245, v242, v245
	v_add_f32_e32 v245, v243, v245
	v_add_f32_e32 v244, v245, v244
	v_cvt_pk_bf16_f32 v234, v74, v75
	v_cvt_pk_bf16_f32 v235, v76, v77
	v_mul_f32_e32 v240, v74, v74
	v_mul_f32_e32 v241, v75, v75
	v_mul_f32_e32 v242, v76, v76
	v_mul_f32_e32 v243, v77, v77
	v_add_f32_e32 v245, v240, v241
	v_add_f32_e32 v245, v242, v245
	v_add_f32_e32 v245, v243, v245
	v_add_f32_e32 v244, v245, v244
	s_nop 1
	v_permlane16_swap_b32 v232, v234
	v_permlane16_swap_b32 v233, v235
	global_store_dwordx4 v[248:249], v[232:235], off offset:128
	v_cvt_pk_bf16_f32 v236, v70, v71
	v_cvt_pk_bf16_f32 v237, v72, v73
	v_mul_f32_e32 v240, v70, v70
	v_mul_f32_e32 v241, v71, v71
	v_mul_f32_e32 v242, v72, v72
	v_mul_f32_e32 v243, v73, v73
	v_add_f32_e32 v245, v240, v241
	v_add_f32_e32 v245, v242, v245
	v_add_f32_e32 v245, v243, v245
	v_add_f32_e32 v244, v245, v244
	v_cvt_pk_bf16_f32 v238, v66, v67
	v_cvt_pk_bf16_f32 v239, v68, v69
	v_mul_f32_e32 v240, v66, v66
	v_mul_f32_e32 v241, v67, v67
	v_mul_f32_e32 v242, v68, v68
	v_mul_f32_e32 v243, v69, v69
	v_add_f32_e32 v245, v240, v241
	v_add_f32_e32 v245, v242, v245
	v_add_f32_e32 v245, v243, v245
	v_add_f32_e32 v244, v245, v244
	s_nop 1
	v_permlane16_swap_b32 v236, v238
	v_permlane16_swap_b32 v237, v239
	global_store_dwordx4 v[248:249], v[236:239], off offset:192
	ds_bpermute_b32 v251, v254, v244
	s_waitcnt lgkmcnt(0)
	v_add_f32_e32 v245, v244, v251
	ds_bpermute_b32 v251, v255, v245
	s_waitcnt lgkmcnt(0)
	v_add_f32_e32 v245, v245, v251
	s_and_saveexec_b64 s[20:21], s[18:19]
	global_store_dword v[252:253], v245, off offset:64
	s_or_b64 exec, exec, s[20:21]
	v_or_b32_e32 v248, 32, v132
	v_ashrrev_i32_e32 v249, 31, v248
	v_lshlrev_b64 v[248:249], 10, v[248:249]
	v_lshl_add_u64 v[248:249], v[136:137], 0, v[248:249]
	v_lshl_add_u64 v[248:249], v[134:135], 1, v[248:249]
	v_lshl_add_u64 v[248:249], v[248:249], 0, v[246:247]
	v_cvt_pk_bf16_f32 v232, v62, v63
	v_cvt_pk_bf16_f32 v233, v64, v65
	v_mul_f32_e32 v240, v62, v62
	v_mul_f32_e32 v241, v63, v63
	v_mul_f32_e32 v242, v64, v64
	v_mul_f32_e32 v243, v65, v65
	v_add_f32_e32 v245, v240, v241
	v_add_f32_e32 v245, v242, v245
	v_add_f32_e32 v244, v243, v245
	v_cvt_pk_bf16_f32 v234, v58, v59
	v_cvt_pk_bf16_f32 v235, v60, v61
	v_mul_f32_e32 v240, v58, v58
	v_mul_f32_e32 v241, v59, v59
	v_mul_f32_e32 v242, v60, v60
	v_mul_f32_e32 v243, v61, v61
	v_add_f32_e32 v245, v240, v241
	v_add_f32_e32 v245, v242, v245
	v_add_f32_e32 v245, v243, v245
	v_add_f32_e32 v244, v245, v244
	s_nop 1
	v_permlane16_swap_b32 v232, v234
	v_permlane16_swap_b32 v233, v235
	global_store_dwordx4 v[248:249], v[232:235], off
	v_cvt_pk_bf16_f32 v236, v54, v55
	v_cvt_pk_bf16_f32 v237, v56, v57
	v_mul_f32_e32 v240, v54, v54
	v_mul_f32_e32 v241, v55, v55
	v_mul_f32_e32 v242, v56, v56
	v_mul_f32_e32 v243, v57, v57
	v_add_f32_e32 v245, v240, v241
	v_add_f32_e32 v245, v242, v245
	v_add_f32_e32 v245, v243, v245
	v_add_f32_e32 v244, v245, v244
	v_cvt_pk_bf16_f32 v238, v50, v51
	v_cvt_pk_bf16_f32 v239, v52, v53
	v_mul_f32_e32 v240, v50, v50
	v_mul_f32_e32 v241, v51, v51
	v_mul_f32_e32 v242, v52, v52
	v_mul_f32_e32 v243, v53, v53
	v_add_f32_e32 v245, v240, v241
	v_add_f32_e32 v245, v242, v245
	v_add_f32_e32 v245, v243, v245
	v_add_f32_e32 v244, v245, v244
	s_nop 1
	v_permlane16_swap_b32 v236, v238
	v_permlane16_swap_b32 v237, v239
	global_store_dwordx4 v[248:249], v[236:239], off offset:64
; __device__ __forceinline__ unsigned pack2(float a, float b) { unsigned r; asm("v_cvt_pk_bf16_f32 %0, %1, %2" : "=v"(r) : "v"(a), "v"(b)); return r; }
;   __device__ __forceinline__ float c4(int g, int rig, int col, f32x4 v) const {
;     ...
;     uint2 u; u.x = pack2(v[0], v[1]); u.y = pack2(v[2], v[3]);
;     *(uint2*)(out + row * ld + col) = u;
;     return v[0] * v[0] + v[1] * v[1] + v[2] * v[2] + v[3] * v[3];
;   }
;   __device__ __forceinline__ void rowsum(int g, int rig, int slot, float ss) const {
;     if (slot < nslots) part[(size_t)slot * ((size_t)8 * ostride) + (size_t)g * ostride + rig] = ss;
; template <bool SWAP, class Epi, bool THIN = false> ...
;     ...
;       for (int m = 0; m < 4; ++m) {
;         const int rig = rig0 + rw + m * 16 + fr_e;
;         if constexpr (Epi::ROWSUM) {
;           float ss = 0.f;
; #pragma unroll
;           for (int n = 0; n < 8; ++n) {
;             const int col = nt * 256 + wc_e * 128 + n * 16 + fq_e * 4;
;             if (col < N) ss += epi.c4(g, rig, col, acc[m][n]);
;           }
;           ss += __shfl_xor(ss, 16); ss += __shfl_xor(ss, 32);
;           if (fq_e == 0) epi.rowsum(g, rig, nt * 2 + wc_e, ss);
	v_cvt_pk_bf16_f32 v232, v46, v47
	v_cvt_pk_bf16_f32 v233, v48, v49
	v_mul_f32_e32 v240, v46, v46
	v_mul_f32_e32 v241, v47, v47
	v_mul_f32_e32 v242, v48, v48
	v_mul_f32_e32 v243, v49, v49
	v_add_f32_e32 v245, v240, v241
	v_add_f32_e32 v245, v242, v245
	v_add_f32_e32 v245, v243, v245
	v_add_f32_e32 v244, v245, v244
	v_cvt_pk_bf16_f32 v234, v42, v43
	v_cvt_pk_bf16_f32 v235, v44, v45
	v_mul_f32_e32 v240, v42, v42
	v_mul_f32_e32 v241, v43, v43
	v_mul_f32_e32 v242, v44, v44
	v_mul_f32_e32 v243, v45, v45
	v_add_f32_e32 v245, v240, v241
	v_add_f32_e32 v245, v242, v245
	v_add_f32_e32 v245, v243, v245
	v_add_f32_e32 v244, v245, v244
	s_nop 1
	v_permlane16_swap_b32 v232, v234
	v_permlane16_swap_b32 v233, v235
	global_store_dwordx4 v[248:249], v[232:235], off offset:128
	v_cvt_pk_bf16_f32 v236, v38, v39
	v_cvt_pk_bf16_f32 v237, v40, v41
	v_mul_f32_e32 v240, v38, v38
	v_mul_f32_e32 v241, v39, v39
	v_mul_f32_e32 v242, v40, v40
	v_mul_f32_e32 v243, v41, v41
	v_add_f32_e32 v245, v240, v241
	v_add_f32_e32 v245, v242, v245
	v_add_f32_e32 v245, v243, v245
	v_add_f32_e32 v244, v245, v244
	v_cvt_pk_bf16_f32 v238, v34, v35
	v_cvt_pk_bf16_f32 v239, v36, v37
	v_mul_f32_e32 v240, v34, v34
	v_mul_f32_e32 v241, v35, v35
	v_mul_f32_e32 v242, v36, v36
	v_mul_f32_e32 v243, v37, v37
	v_add_f32_e32 v245, v240, v241
	v_add_f32_e32 v245, v242, v245
	v_add_f32_e32 v245, v243, v245
	v_add_f32_e32 v244, v245, v244
	s_nop 1
	v_permlane16_swap_b32 v236, v238
	v_permlane16_swap_b32 v237, v239
	global_store_dwordx4 v[248:249], v[236:239], off offset:192
	ds_bpermute_b32 v251, v254, v244
	s_waitcnt lgkmcnt(0)
	v_add_f32_e32 v245, v244, v251
	ds_bpermute_b32 v251, v255, v245
	s_waitcnt lgkmcnt(0)
	v_add_f32_e32 v245, v245, v251
	s_and_saveexec_b64 s[20:21], s[18:19]
	global_store_dword v[252:253], v245, off offset:128
	s_or_b64 exec, exec, s[20:21]
	v_or_b32_e32 v248, 48, v132
	v_ashrrev_i32_e32 v249, 31, v248
	v_lshlrev_b64 v[248:249], 10, v[248:249]
	v_lshl_add_u64 v[248:249], v[136:137], 0, v[248:249]
	v_lshl_add_u64 v[248:249], v[134:135], 1, v[248:249]
	v_lshl_add_u64 v[248:249], v[248:249], 0, v[246:247]
	v_cvt_pk_bf16_f32 v232, v30, v31
	v_cvt_pk_bf16_f32 v233, v32, v33
	v_mul_f32_e32 v240, v30, v30
	v_mul_f32_e32 v241, v31, v31
	v_mul_f32_e32 v242, v32, v32
	v_mul_f32_e32 v243, v33, v33
	v_add_f32_e32 v245, v240, v241
	v_add_f32_e32 v245, v242, v245
	v_add_f32_e32 v244, v243, v245
	v_cvt_pk_bf16_f32 v234, v26, v27
	v_cvt_pk_bf16_f32 v235, v28, v29
	v_mul_f32_e32 v240, v26, v26
	v_mul_f32_e32 v241, v27, v27
	v_mul_f32_e32 v242, v28, v28
	v_mul_f32_e32 v243, v29, v29
	v_add_f32_e32 v245, v240, v241
	v_add_f32_e32 v245, v242, v245
	v_add_f32_e32 v245, v243, v245
	v_add_f32_e32 v244, v245, v244
	s_nop 1
	v_permlane16_swap_b32 v232, v234
	v_permlane16_swap_b32 v233, v235
	global_store_dwordx4 v[248:249], v[232:235], off
	v_cvt_pk_bf16_f32 v236, v22, v23
	v_cvt_pk_bf16_f32 v237, v24, v25
	v_mul_f32_e32 v240, v22, v22
	v_mul_f32_e32 v241, v23, v23
	v_mul_f32_e32 v242, v24, v24
	v_mul_f32_e32 v243, v25, v25
	v_add_f32_e32 v245, v240, v241
	v_add_f32_e32 v245, v242, v245
	v_add_f32_e32 v245, v243, v245
	v_add_f32_e32 v244, v245, v244
	v_cvt_pk_bf16_f32 v238, v18, v19
	v_cvt_pk_bf16_f32 v239, v20, v21
	v_mul_f32_e32 v240, v18, v18
	v_mul_f32_e32 v241, v19, v19
	v_mul_f32_e32 v242, v20, v20
	v_mul_f32_e32 v243, v21, v21
	v_add_f32_e32 v245, v240, v241
	v_add_f32_e32 v245, v242, v245
	v_add_f32_e32 v245, v243, v245
	v_add_f32_e32 v244, v245, v244
	s_nop 1
	v_permlane16_swap_b32 v236, v238
	v_permlane16_swap_b32 v237, v239
	global_store_dwordx4 v[248:249], v[236:239], off offset:64
	v_cvt_pk_bf16_f32 v232, v14, v15
	v_cvt_pk_bf16_f32 v233, v16, v17
	v_mul_f32_e32 v240, v14, v14
	v_mul_f32_e32 v241, v15, v15
	v_mul_f32_e32 v242, v16, v16
	v_mul_f32_e32 v243, v17, v17
	v_add_f32_e32 v245, v240, v241
	v_add_f32_e32 v245, v242, v245
	v_add_f32_e32 v245, v243, v245
	v_add_f32_e32 v244, v245, v244
	v_cvt_pk_bf16_f32 v234, v6, v7
	v_cvt_pk_bf16_f32 v235, v8, v9
	v_mul_f32_e32 v240, v6, v6
	v_mul_f32_e32 v241, v7, v7
	v_mul_f32_e32 v242, v8, v8
	v_mul_f32_e32 v243, v9, v9
	v_add_f32_e32 v245, v240, v241
	v_add_f32_e32 v245, v242, v245
	v_add_f32_e32 v245, v243, v245
	v_add_f32_e32 v244, v245, v244
	s_nop 1
	v_permlane16_swap_b32 v232, v234
	v_permlane16_swap_b32 v233, v235
	global_store_dwordx4 v[248:249], v[232:235], off offset:128
	v_cvt_pk_bf16_f32 v236, v10, v11
	v_cvt_pk_bf16_f32 v237, v12, v13
	v_mul_f32_e32 v240, v10, v10
	v_mul_f32_e32 v241, v11, v11
	v_mul_f32_e32 v242, v12, v12
	v_mul_f32_e32 v243, v13, v13
	v_add_f32_e32 v245, v240, v241
	v_add_f32_e32 v245, v242, v245
	v_add_f32_e32 v245, v243, v245
	v_add_f32_e32 v244, v245, v244
	v_cvt_pk_bf16_f32 v238, v2, v3
	v_cvt_pk_bf16_f32 v239, v4, v5
	v_mul_f32_e32 v240, v2, v2
	v_mul_f32_e32 v241, v3, v3
	v_mul_f32_e32 v242, v4, v4
	v_mul_f32_e32 v243, v5, v5
	v_add_f32_e32 v245, v240, v241
	v_add_f32_e32 v245, v242, v245
	v_add_f32_e32 v245, v243, v245
	v_add_f32_e32 v244, v245, v244
	s_nop 1
	v_permlane16_swap_b32 v236, v238
	v_permlane16_swap_b32 v237, v239
	global_store_dwordx4 v[248:249], v[236:239], off offset:192
	ds_bpermute_b32 v251, v254, v244
	s_waitcnt lgkmcnt(0)
	v_add_f32_e32 v245, v244, v251
	ds_bpermute_b32 v251, v255, v245
	s_waitcnt lgkmcnt(0)
	v_add_f32_e32 v245, v245, v251
	s_and_saveexec_b64 s[20:21], s[18:19]
	global_store_dword v[252:253], v245, off offset:192
	s_or_b64 exec, exec, s[20:21]
	s_mov_b64 s[4:5], exec
	s_branch .LBB0_337

; template <bool SWAP, class Epi, bool THIN = false> ...
;     ...
;     for (int st = 0; st < ns; ++st) {
;       asm volatile("s_waitcnt vmcnt(0)" ::: "memory");
;       __builtin_amdgcn_s_barrier();
;       asm volatile("" ::: "memory");
;       if (st + 1 < ns) {
;         char* nb = smem + ((st + 1) & 1) * 65536;
;         const int ko = (st + 1) * 64;
; #pragma unroll
;         for (int i = 0; i < 4; ++i) { GLDS16(A + (size_t)(ap[i] + ko), nb + tid * 16 + i * 8192); GLDS16(Bt + (size_t)(bp[i] + ko), nb + 32768 + tid * 16 + i * 8192); }
;       }
;       const char* sa = smem + (st & 1) * 65536 + (wr * 64 + fr) * 128;
;       const char* sb = smem + (st & 1) * 65536 + 32768 + (wc * 128 + fr) * 128;
;       if constexpr (THIN) {
;         if (wc == 0) {
; #pragma unroll
;           for (int ks = 0; ks < 2; ++ks) {
;             bf16x8 af[4], bf[2];
; #pragma unroll
;             for (int m = 0; m < 4; ++m) af[m] = *(const bf16x8*)(sa + m * 2048 + (((ks * 4 + fq) ^ swz) << 4));
; #pragma unroll
;             for (int n = 0; n < 2; ++n) bf[n] = *(const bf16x8*)(sb + n * 2048 + (((ks * 4 + fq) ^ swz) << 4));
; #pragma unroll
;             for (int m = 0; m < 4; ++m)
; #pragma unroll
;               for (int n = 0; n < 2; ++n)
;                 acc[m][n] = SWAP ? __builtin_amdgcn_mfma_f32_16x16x32_bf16(bf[n], af[m], acc[m][n], 0, 0, 0)
;                                  : __builtin_amdgcn_mfma_f32_16x16x32_bf16(af[m], bf[n], acc[m][n], 0, 0, 0);
;           }
;         }
;       } else {
;       bf16x8 afA[4], afB[4], bfb[2][2];
; #pragma unroll
;       for (int m = 0; m < 4; ++m) afA[m] = *(const bf16x8*)(sa + m * 2048 + ((fq ^ swz) << 4));
; #pragma unroll
;       for (int n = 0; n < 2; ++n) bfb[0][n] = *(const bf16x8*)(sb + n * 2048 + ((fq ^ swz) << 4));
; #pragma unroll
;       for (int gq = 0; gq < 8; ++gq) {
;         const int ks = gq >> 2, nh = gq & 3;
;         if (gq < 7) {
;           const int ks2 = (gq + 1) >> 2, nh2 = (gq + 1) & 3;
; #pragma unroll
;           for (int n = 0; n < 2; ++n) bfb[(gq + 1) & 1][n] = *(const bf16x8*)(sb + (nh2 * 2 + n) * 2048 + (((ks2 * 4 + fq) ^ swz) << 4));
;         }
;         if (gq == 3) {
; #pragma unroll
;           for (int m = 0; m < 4; ++m) afB[m] = *(const bf16x8*)(sa + m * 2048 + (((4 + fq) ^ swz) << 4));
;         }
;         __builtin_amdgcn_sched_barrier(0);
; #pragma unroll
.LBB0_418:
	s_add_i32 s8, s7, 0x10000
	s_and_b32 s9, s8, 0x10000
	v_add_u32_e32 v170, s9, v138
	s_nop 0
	v_readfirstlane_b32 s9, v170
	s_and_b32 s7, s7, 0x10000
	v_or_b32_e32 v204, s7, v140
	v_add_u32_e32 v205, v204, v141
	v_add_u32_e32 v130, s7, v139
	v_add_u32_e32 v180, v130, v141
	s_waitcnt vmcnt(0)
	s_barrier
	ds_read_b128 v[168:171], v180
	ds_read_b128 v[172:175], v180 offset:2048
	ds_read_b128 v[176:179], v180 offset:4096
	ds_read_b128 v[180:183], v180 offset:6144
	ds_read_b128 v[184:187], v205 offset:32768
	ds_read_b128 v[188:191], v205 offset:34816
	ds_read_b128 v[192:195], v205 offset:36864
	ds_read_b128 v[196:199], v205 offset:38912
	v_add_u32_e32 v130, v130, v142
	s_waitcnt lgkmcnt(3)
	v_mfma_f32_16x16x32_bf16 v[126:129], v[184:187], v[168:171], v[126:129]
	s_mov_b32 m0, s9
	v_mfma_f32_16x16x32_bf16 v[110:113], v[184:187], v[172:175], v[110:113]
	global_load_lds_dwordx4 v167, s[36:37]
	v_add_u32_e32 v167, 0x80, v167
	v_mfma_f32_16x16x32_bf16 v[82:85], v[184:187], v[176:179], v[82:85]
	v_mfma_f32_16x16x32_bf16 v[50:53], v[184:187], v[180:183], v[50:53]
	ds_read_b128 v[184:187], v205 offset:40960
	ds_read_b128 v[200:203], v205 offset:43008
	s_waitcnt lgkmcnt(4)
	v_mfma_f32_16x16x32_bf16 v[122:125], v[188:191], v[168:171], v[122:125]
	s_add_u32 m0, s9, 0x8000
	v_mfma_f32_16x16x32_bf16 v[106:109], v[188:191], v[172:175], v[106:109]
	global_load_lds_dwordx4 v166, s[38:39]
	v_add_u32_e32 v166, 0x80, v166
	v_mfma_f32_16x16x32_bf16 v[78:81], v[188:191], v[176:179], v[78:81]
	v_mfma_f32_16x16x32_bf16 v[42:45], v[188:191], v[180:183], v[42:45]
	s_waitcnt lgkmcnt(3)
	v_mfma_f32_16x16x32_bf16 v[118:121], v[192:195], v[168:171], v[118:121]
	s_add_u32 m0, s9, 0x2000
	v_mfma_f32_16x16x32_bf16 v[94:97], v[192:195], v[172:175], v[94:97]
	global_load_lds_dwordx4 v165, s[36:37]
	v_add_u32_e32 v165, 0x80, v165
	v_mfma_f32_16x16x32_bf16 v[58:61], v[192:195], v[176:179], v[58:61]
	v_mfma_f32_16x16x32_bf16 v[26:29], v[192:195], v[180:183], v[26:29]
	ds_read_b128 v[188:191], v205 offset:45056
	ds_read_b128 v[192:195], v205 offset:47104
	s_waitcnt lgkmcnt(4)
	v_mfma_f32_16x16x32_bf16 v[114:117], v[196:199], v[168:171], v[114:117]
	s_add_u32 m0, s9, 0xa000
	v_mfma_f32_16x16x32_bf16 v[86:89], v[196:199], v[172:175], v[86:89]
	global_load_lds_dwordx4 v164, s[38:39]
	v_add_u32_e32 v164, 0x80, v164
	v_mfma_f32_16x16x32_bf16 v[54:57], v[196:199], v[176:179], v[54:57]
	v_mfma_f32_16x16x32_bf16 v[22:25], v[196:199], v[180:183], v[22:25]
	v_add_u32_e32 v220, v204, v142
	s_waitcnt lgkmcnt(3)
	v_mfma_f32_16x16x32_bf16 v[102:105], v[184:187], v[168:171], v[102:105]
	ds_read_b128 v[196:199], v220 offset:32768
	ds_read_b128 v[204:207], v220 offset:34816
	s_add_u32 m0, s9, 0x4000
	v_mfma_f32_16x16x32_bf16 v[74:77], v[184:187], v[172:175], v[74:77]
	global_load_lds_dwordx4 v135, s[36:37]
	v_add_u32_e32 v135, 0x80, v135
	v_mfma_f32_16x16x32_bf16 v[46:49], v[184:187], v[176:179], v[46:49]
	v_mfma_f32_16x16x32_bf16 v[10:13], v[184:187], v[180:183], v[10:13]
	ds_read_b128 v[184:187], v130
	ds_read_b128 v[208:211], v130 offset:2048
	ds_read_b128 v[212:215], v130 offset:4096
	ds_read_b128 v[216:219], v130 offset:6144
	s_waitcnt lgkmcnt(8)
	v_mfma_f32_16x16x32_bf16 v[98:101], v[200:203], v[168:171], v[98:101]
	s_add_u32 m0, s9, 0xc000
	v_mfma_f32_16x16x32_bf16 v[66:69], v[200:203], v[172:175], v[66:69]
	global_load_lds_dwordx4 v134, s[38:39]
	v_add_u32_e32 v134, 0x80, v134
	v_mfma_f32_16x16x32_bf16 v[30:33], v[200:203], v[176:179], v[30:33]
	v_mfma_f32_16x16x32_bf16 v[6:9], v[200:203], v[180:183], v[6:9]
	s_waitcnt lgkmcnt(7)
	v_mfma_f32_16x16x32_bf16 v[70:73], v[188:191], v[168:171], v[70:73]
	s_add_u32 m0, s9, 0x6000
	s_waitcnt lgkmcnt(6)
	v_mfma_f32_16x16x32_bf16 v[62:65], v[192:195], v[168:171], v[62:65]
	global_load_lds_dwordx4 v133, s[36:37]
	v_add_u32_e32 v133, 0x80, v133
	v_mfma_f32_16x16x32_bf16 v[38:41], v[188:191], v[172:175], v[38:41]
	v_mfma_f32_16x16x32_bf16 v[34:37], v[192:195], v[172:175], v[34:37]
	ds_read_b128 v[168:171], v220 offset:36864
	ds_read_b128 v[172:175], v220 offset:38912
	v_mfma_f32_16x16x32_bf16 v[18:21], v[188:191], v[176:179], v[18:21]
	s_add_u32 m0, s9, 0xe000
	v_mfma_f32_16x16x32_bf16 v[14:17], v[192:195], v[176:179], v[14:17]
	global_load_lds_dwordx4 v132, s[38:39]
	v_add_u32_e32 v132, 0x80, v132
	v_mfma_f32_16x16x32_bf16 v[2:5], v[188:191], v[180:183], v[2:5]
	v_mfma_f32_16x16x32_bf16 v[90:93], v[192:195], v[180:183], v[90:93]
	ds_read_b128 v[176:179], v220 offset:40960
	ds_read_b128 v[180:183], v220 offset:43008
	s_waitcnt lgkmcnt(7)
	v_mfma_f32_16x16x32_bf16 v[126:129], v[196:199], v[184:187], v[126:129]
	v_mfma_f32_16x16x32_bf16 v[122:125], v[204:207], v[184:187], v[122:125]
	s_waitcnt lgkmcnt(6)
	v_mfma_f32_16x16x32_bf16 v[110:113], v[196:199], v[208:211], v[110:113]
	v_mfma_f32_16x16x32_bf16 v[106:109], v[204:207], v[208:211], v[106:109]
	s_waitcnt lgkmcnt(5)
	v_mfma_f32_16x16x32_bf16 v[82:85], v[196:199], v[212:215], v[82:85]
	v_mfma_f32_16x16x32_bf16 v[78:81], v[204:207], v[212:215], v[78:81]
	s_waitcnt lgkmcnt(4)
	v_mfma_f32_16x16x32_bf16 v[50:53], v[196:199], v[216:219], v[50:53]
	v_mfma_f32_16x16x32_bf16 v[42:45], v[204:207], v[216:219], v[42:45]
	s_waitcnt lgkmcnt(3)
	v_mfma_f32_16x16x32_bf16 v[118:121], v[168:171], v[184:187], v[118:121]
	v_mfma_f32_16x16x32_bf16 v[94:97], v[168:171], v[208:211], v[94:97]
	v_mfma_f32_16x16x32_bf16 v[58:61], v[168:171], v[212:215], v[58:61]
	v_mfma_f32_16x16x32_bf16 v[26:29], v[168:171], v[216:219], v[26:29]
	ds_read_b128 v[168:171], v220 offset:45056
	ds_read_b128 v[188:191], v220 offset:47104
	s_waitcnt lgkmcnt(4)
; template <bool SWAP, class Epi, bool THIN = false> ...
;     ...
;     for (int st = 0; st < ns; ++st) {
;       asm volatile("s_waitcnt vmcnt(0)" ::: "memory");
;       __builtin_amdgcn_s_barrier();
;       asm volatile("" ::: "memory");
;       if (st + 1 < ns) {
;         char* nb = smem + ((st + 1) & 1) * 65536;
;         const int ko = (st + 1) * 64;
; #pragma unroll
;         for (int i = 0; i < 4; ++i) { GLDS16(A + (size_t)(ap[i] + ko), nb + tid * 16 + i * 8192); GLDS16(Bt + (size_t)(bp[i] + ko), nb + 32768 + tid * 16 + i * 8192); }
;       }
;       const char* sa = smem + (st & 1) * 65536 + (wr * 64 + fr) * 128;
;       const char* sb = smem + (st & 1) * 65536 + 32768 + (wc * 128 + fr) * 128;
;       if constexpr (THIN) {
;         if (wc == 0) {
; #pragma unroll
;           for (int ks = 0; ks < 2; ++ks) {
;             bf16x8 af[4], bf[2];
; #pragma unroll
;             for (int m = 0; m < 4; ++m) af[m] = *(const bf16x8*)(sa + m * 2048 + (((ks * 4 + fq) ^ swz) << 4));
; #pragma unroll
;             for (int n = 0; n < 2; ++n) bf[n] = *(const bf16x8*)(sb + n * 2048 + (((ks * 4 + fq) ^ swz) << 4));
; #pragma unroll
;             for (int m = 0; m < 4; ++m)
; #pragma unroll
;               for (int n = 0; n < 2; ++n)
;                 acc[m][n] = SWAP ? __builtin_amdgcn_mfma_f32_16x16x32_bf16(bf[n], af[m], acc[m][n], 0, 0, 0)
;                                  : __builtin_amdgcn_mfma_f32_16x16x32_bf16(af[m], bf[n], acc[m][n], 0, 0, 0);
;           }
;         }
;       } else {
;       bf16x8 afA[4], afB[4], bfb[2][2];
; #pragma unroll
;       for (int m = 0; m < 4; ++m) afA[m] = *(const bf16x8*)(sa + m * 2048 + ((fq ^ swz) << 4));
; #pragma unroll
;       for (int n = 0; n < 2; ++n) bfb[0][n] = *(const bf16x8*)(sb + n * 2048 + ((fq ^ swz) << 4));
; #pragma unroll
;       for (int gq = 0; gq < 8; ++gq) {
;         const int ks = gq >> 2, nh = gq & 3;
;         if (gq < 7) {
;           const int ks2 = (gq + 1) >> 2, nh2 = (gq + 1) & 3;
; #pragma unroll
;           for (int n = 0; n < 2; ++n) bfb[(gq + 1) & 1][n] = *(const bf16x8*)(sb + (nh2 * 2 + n) * 2048 + (((ks2 * 4 + fq) ^ swz) << 4));
;         }
;         if (gq == 3) {
; #pragma unroll
;           for (int m = 0; m < 4; ++m) afB[m] = *(const bf16x8*)(sa + m * 2048 + (((4 + fq) ^ swz) << 4));
;         }
;         __builtin_amdgcn_sched_barrier(0);
; #pragma unroll
	v_mfma_f32_16x16x32_bf16 v[114:117], v[172:175], v[184:187], v[114:117]
	v_mfma_f32_16x16x32_bf16 v[86:89], v[172:175], v[208:211], v[86:89]
	v_mfma_f32_16x16x32_bf16 v[54:57], v[172:175], v[212:215], v[54:57]
	v_mfma_f32_16x16x32_bf16 v[22:25], v[172:175], v[216:219], v[22:25]
	s_waitcnt lgkmcnt(3)
	v_mfma_f32_16x16x32_bf16 v[102:105], v[176:179], v[184:187], v[102:105]
	s_waitcnt lgkmcnt(2)
	v_mfma_f32_16x16x32_bf16 v[98:101], v[180:183], v[184:187], v[98:101]
	v_mfma_f32_16x16x32_bf16 v[74:77], v[176:179], v[208:211], v[74:77]
	v_mfma_f32_16x16x32_bf16 v[66:69], v[180:183], v[208:211], v[66:69]
	v_mfma_f32_16x16x32_bf16 v[46:49], v[176:179], v[212:215], v[46:49]
	v_mfma_f32_16x16x32_bf16 v[30:33], v[180:183], v[212:215], v[30:33]
	v_mfma_f32_16x16x32_bf16 v[10:13], v[176:179], v[216:219], v[10:13]
	v_mfma_f32_16x16x32_bf16 v[6:9], v[180:183], v[216:219], v[6:9]
	s_waitcnt lgkmcnt(1)
	v_mfma_f32_16x16x32_bf16 v[70:73], v[168:171], v[184:187], v[70:73]
	s_add_i32 s6, s6, 64
	s_cmpk_eq_i32 s6, 0x3c0
	s_mov_b32 s7, s8
	s_waitcnt lgkmcnt(0)
	v_mfma_f32_16x16x32_bf16 v[62:65], v[188:191], v[184:187], v[62:65]
	v_mfma_f32_16x16x32_bf16 v[38:41], v[168:171], v[208:211], v[38:41]
	v_mfma_f32_16x16x32_bf16 v[34:37], v[188:191], v[208:211], v[34:37]
	v_mfma_f32_16x16x32_bf16 v[18:21], v[168:171], v[212:215], v[18:21]
	v_mfma_f32_16x16x32_bf16 v[14:17], v[188:191], v[212:215], v[14:17]
	v_mfma_f32_16x16x32_bf16 v[2:5], v[168:171], v[216:219], v[2:5]
	v_mfma_f32_16x16x32_bf16 v[90:93], v[188:191], v[216:219], v[90:93]
	s_cbranch_scc0 .LBB0_418
	s_waitcnt vmcnt(0)
	s_barrier
	v_add_u32_e32 v130, v153, v141
	ds_read_b128 v[132:135], v130
	ds_read_b128 v[164:167], v130 offset:2048
	ds_read_b128 v[168:171], v130 offset:4096
	ds_read_b128 v[172:175], v130 offset:6144
	v_add_u32_e32 v130, v154, v141
	ds_read_b128 v[176:179], v130
	ds_read_b128 v[180:183], v130 offset:2048
	ds_read_b128 v[184:187], v130 offset:4096
	ds_read_b128 v[188:191], v130 offset:6144
	s_waitcnt lgkmcnt(0)
	v_mfma_f32_16x16x32_bf16 v[126:129], v[176:179], v[132:135], v[126:129]
	v_mfma_f32_16x16x32_bf16 v[110:113], v[176:179], v[164:167], v[110:113]
	v_mfma_f32_16x16x32_bf16 v[82:85], v[176:179], v[168:171], v[82:85]
	v_mfma_f32_16x16x32_bf16 v[50:53], v[176:179], v[172:175], v[50:53]
	ds_read_b128 v[176:179], v130 offset:8192
	ds_read_b128 v[192:195], v130 offset:10240
	v_mfma_f32_16x16x32_bf16 v[122:125], v[180:183], v[132:135], v[122:125]
	v_mfma_f32_16x16x32_bf16 v[106:109], v[180:183], v[164:167], v[106:109]
	v_mfma_f32_16x16x32_bf16 v[78:81], v[180:183], v[168:171], v[78:81]
	v_mfma_f32_16x16x32_bf16 v[42:45], v[180:183], v[172:175], v[42:45]
	v_mfma_f32_16x16x32_bf16 v[118:121], v[184:187], v[132:135], v[118:121]
	v_mfma_f32_16x16x32_bf16 v[180:183], v[184:187], v[164:167], v[94:97]
	v_mfma_f32_16x16x32_bf16 v[200:203], v[184:187], v[168:171], v[58:61]
	v_mfma_f32_16x16x32_bf16 v[204:207], v[188:191], v[168:171], v[54:57]
	v_mfma_f32_16x16x32_bf16 v[184:187], v[184:187], v[172:175], v[26:29]
	s_nop 2
	ds_read_b128 v[26:29], v130 offset:12288
	ds_read_b128 v[54:57], v130 offset:14336
	v_mfma_f32_16x16x32_bf16 v[114:117], v[188:191], v[132:135], v[114:117]
	v_mfma_f32_16x16x32_bf16 v[196:199], v[188:191], v[164:167], v[86:89]
	v_mfma_f32_16x16x32_bf16 v[188:191], v[188:191], v[172:175], v[22:25]
	v_add_u32_e32 v130, v154, v142
	s_waitcnt lgkmcnt(0)
	v_mfma_f32_16x16x32_bf16 v[208:211], v[192:195], v[168:171], v[30:33]
	ds_read_b128 v[22:25], v130
	ds_read_b128 v[86:89], v130 offset:2048
	s_nop 0
	v_add_u32_e32 v30, v153, v142
	v_mfma_f32_16x16x32_bf16 v[102:105], v[176:179], v[132:135], v[102:105]
	v_mfma_f32_16x16x32_bf16 v[74:77], v[176:179], v[164:167], v[74:77]
	v_mfma_f32_16x16x32_bf16 v[46:49], v[176:179], v[168:171], v[46:49]
	v_mfma_f32_16x16x32_bf16 v[10:13], v[176:179], v[172:175], v[10:13]
	ds_read_b128 v[176:179], v30
	ds_read_b128 v[212:215], v30 offset:2048
	ds_read_b128 v[216:219], v30 offset:4096
	ds_read_b128 v[220:223], v30 offset:6144
	v_mfma_f32_16x16x32_bf16 v[98:101], v[192:195], v[132:135], v[98:101]
	v_mfma_f32_16x16x32_bf16 v[66:69], v[192:195], v[164:167], v[66:69]
	v_mfma_f32_16x16x32_bf16 v[6:9], v[192:195], v[172:175], v[6:9]
	v_mfma_f32_16x16x32_bf16 v[38:41], v[26:29], v[164:167], v[38:41]
	v_mfma_f32_16x16x32_bf16 v[34:37], v[54:57], v[164:167], v[34:37]
	v_mfma_f32_16x16x32_bf16 v[192:195], v[26:29], v[168:171], v[18:21]
	v_mfma_f32_16x16x32_bf16 v[166:169], v[54:57], v[168:171], v[14:17]
	s_nop 2
	ds_read_b128 v[14:17], v130 offset:4096
	ds_read_b128 v[18:21], v130 offset:6144
	v_mfma_f32_16x16x32_bf16 v[70:73], v[26:29], v[132:135], v[70:73]
	v_mfma_f32_16x16x32_bf16 v[132:135], v[54:57], v[132:135], v[62:65]
	v_mfma_f32_16x16x32_bf16 v[2:5], v[26:29], v[172:175], v[2:5]
	v_mfma_f32_16x16x32_bf16 v[170:173], v[54:57], v[172:175], v[90:93]
	ds_read_b128 v[224:227], v130 offset:8192
	ds_read_b128 v[228:231], v130 offset:10240
	s_waitcnt lgkmcnt(0)
	v_mfma_f32_16x16x32_bf16 v[126:129], v[22:25], v[176:179], v[126:129]
	v_mfma_f32_16x16x32_bf16 v[122:125], v[86:89], v[176:179], v[122:125]
	v_mfma_f32_16x16x32_bf16 v[94:97], v[22:25], v[212:215], v[110:113]
	v_mfma_f32_16x16x32_bf16 v[90:93], v[86:89], v[212:215], v[106:109]
	v_mfma_f32_16x16x32_bf16 v[62:65], v[22:25], v[216:219], v[82:85]
	v_mfma_f32_16x16x32_bf16 v[58:61], v[86:89], v[216:219], v[78:81]
	v_mfma_f32_16x16x32_bf16 v[30:33], v[22:25], v[220:223], v[50:53]
	v_mfma_f32_16x16x32_bf16 v[26:29], v[86:89], v[220:223], v[42:45]
	v_mfma_f32_16x16x32_bf16 v[86:89], v[14:17], v[212:215], v[180:183]
	v_mfma_f32_16x16x32_bf16 v[22:25], v[14:17], v[220:223], v[184:187]
	s_nop 1
	ds_read_b128 v[180:183], v130 offset:12288
	ds_read_b128 v[184:187], v130 offset:14336
	v_mfma_f32_16x16x32_bf16 v[118:121], v[14:17], v[176:179], v[118:121]
	v_mfma_f32_16x16x32_bf16 v[114:117], v[18:21], v[176:179], v[114:117]
	v_mfma_f32_16x16x32_bf16 v[82:85], v[18:21], v[212:215], v[196:199]
	v_mfma_f32_16x16x32_bf16 v[54:57], v[14:17], v[216:219], v[200:203]
	v_mfma_f32_16x16x32_bf16 v[50:53], v[18:21], v[216:219], v[204:207]
	v_mfma_f32_16x16x32_bf16 v[18:21], v[18:21], v[220:223], v[188:191]
	v_mfma_f32_16x16x32_bf16 v[110:113], v[224:227], v[176:179], v[102:105]
	v_mfma_f32_16x16x32_bf16 v[106:109], v[228:231], v[176:179], v[98:101]
	v_mfma_f32_16x16x32_bf16 v[78:81], v[224:227], v[212:215], v[74:77]
	v_mfma_f32_16x16x32_bf16 v[74:77], v[228:231], v[212:215], v[66:69]
	v_mfma_f32_16x16x32_bf16 v[46:49], v[224:227], v[216:219], v[46:49]
	v_mfma_f32_16x16x32_bf16 v[42:45], v[228:231], v[216:219], v[208:211]
	v_mfma_f32_16x16x32_bf16 v[14:17], v[224:227], v[220:223], v[10:13]
	v_mfma_f32_16x16x32_bf16 v[10:13], v[228:231], v[220:223], v[6:9]
	s_nop 2
	v_mov_b32_e32 v6, v1
	s_waitcnt vmcnt(0) lgkmcnt(0)
	s_barrier
; __device__ __forceinline__ int get_tid512() { int t = threadIdx.x; asm volatile("" : "+v"(t)); return t; }
; __device__ __forceinline__ unsigned pack2(float a, float b) { unsigned r; asm("v_cvt_pk_bf16_f32 %0, %1, %2" : "=v"(r) : "v"(a), "v"(b)); return r; }
;   __device__ __forceinline__ float c4(int g, int rig, int col, f32x4 v) const {
;     const size_t row = (size_t)g * ostride + rig;
;     if (kpe && col >= ropecol) {
;       const int i0 = col - ropecol;
;       f32x4 o = v;
;       const float p0 = __shfl_xor(v[0], 32), p1 = __shfl_xor(v[1], 32), p2 = __shfl_xor(v[2], 32), p3 = __shfl_xor(v[3], 32);
;       const float pv[4] = {p0, p1, p2, p3};
;       if (rig >= 256) {
;         const int t = rig - 256;
;         const int quarter = i0 >> 3;
;         const float pos = (quarter < 2) ? (float)(t >> 6) : (float)(t & 63);
; #pragma unroll
;         for (int j = 0; j < 4; ++j) {
;           const int idx = (i0 & 7) + j;
;           const float inv = exp2f(-(float)idx * (13.287712379549449f / 8.0f));
;           const float ang = pos * inv;
;           const float cs = __cosf(ang), sn = __sinf(ang);
;           o[j] = v[j] * cs + ((quarter & 1) ? pv[j] : -pv[j]) * sn;
;         }
;       }
;       uint2 u; u.x = pack2(o[0], o[1]); u.y = pack2(o[2], o[3]);
;       *(uint2*)(kpe + row * 32 + i0) = u;
;       return 0.f;
;     }
;     uint2 u; u.x = pack2(v[0], v[1]); u.y = pack2(v[2], v[3]);
;     *(uint2*)(out + row * ld + col) = u;
;     return v[0] * v[0] + v[1] * v[1] + v[2] * v[2] + v[3] * v[3];
; template <bool SWAP, class Epi, bool THIN = false> ...
;     ...
;     const int te = get_tid512();
;     const int fr_e = te & 15, fq_e = (te & 63) >> 4, wr_e = te >> 7, wc_e = (te >> 6) & 1;
;     const int sub = 2 * mt + (wr_e >> 1);
;     const int g = sub / tpg, ti = sub - g * tpg;
;     const int rig0 = ti * step - halo;
;     const int rw = (wr_e & 1) * 64;
;     if constexpr (Epi::KIND == 0) {
; #pragma unroll
;       for (int m = 0; m < 4; ++m) {
;         const int rig = rig0 + rw + m * 16 + fr_e;
;         if constexpr (Epi::ROWSUM) {
;           float ss = 0.f;
; #pragma unroll
;           for (int n = 0; n < 8; ++n) {
;             const int col = nt * 256 + wc_e * 128 + n * 16 + fq_e * 4;
;             if (col < N) ss += epi.c4(g, rig, col, acc[m][n]);
	v_mfma_f32_16x16x32_bf16 v[98:101], v[184:187], v[176:179], v[132:135]
	v_ashrrev_i32_e32 v7, 8, v6
	v_add_u32_e32 v7, s5, v7
	v_mul_hi_i32 v8, v7, s23
	v_lshrrev_b32_e32 v9, 31, v8
	v_ashrrev_i32_e32 v8, 2, v8
	v_add_u32_e32 v130, v8, v9
	v_and_b32_e32 v132, 15, v6
	v_bfe_u32 v164, v6, 4, 2
	v_bfe_u32 v165, v6, 6, 1
	v_mul_lo_u32 v8, v130, s24
	v_lshrrev_b32_e32 v6, 1, v6
	v_mfma_f32_16x16x32_bf16 v[102:105], v[180:183], v[176:179], v[70:73]
	v_add_lshl_u32 v133, v8, v7, 7
	v_and_b32_e32 v135, 64, v6
	v_lshlrev_b32_e32 v134, 7, v165
	v_mfma_f32_16x16x32_bf16 v[70:73], v[180:183], v[212:215], v[38:41]
	v_or3_b32 v132, v133, v135, v132
	v_ashrrev_i32_e32 v133, 31, v132
	v_mfma_f32_16x16x32_bf16 v[66:69], v[184:187], v[212:215], v[34:37]
	v_mfma_f32_16x16x32_bf16 v[38:41], v[180:183], v[216:219], v[192:195]
	v_mfma_f32_16x16x32_bf16 v[34:37], v[184:187], v[216:219], v[166:169]
	v_mfma_f32_16x16x32_bf16 v[6:9], v[180:183], v[220:223], v[2:5]
	s_nop 1
	v_lshlrev_b32_e32 v166, 2, v164
	v_or3_b32 v134, v134, v166, s4
	v_cmp_gt_i32_e32 vcc, s27, v134
	v_mfma_f32_16x16x32_bf16 v[2:5], v[184:187], v[220:223], v[170:173]
	v_mov_b32_e32 v166, 0
	v_ashrrev_i32_e32 v135, 31, v134
	s_and_saveexec_b64 s[4:5], vcc
	s_cbranch_execz .LBB0_421
	v_mad_i64_i32 v[166:167], s[6:7], v130, s25, v[132:133]
	v_mov_b64_e32 v[170:171], s[30:31]
	v_cvt_pk_bf16_f32 v168, v126, v127
	v_mad_u64_u32 v[170:171], s[6:7], v166, s28, v[170:171]
	v_pk_mul_f32 v[126:127], v[126:127], v[126:127]
	v_cvt_pk_bf16_f32 v169, v128, v129
	v_mad_i32_i24 v171, v167, s28, v171
	v_pk_mul_f32 v[128:129], v[128:129], v[128:129]
	v_add_f32_e32 v126, v126, v127
	v_lshl_add_u64 v[166:167], v[134:135], 1, v[170:171]
	v_add_f32_e32 v126, v128, v126
	global_store_dwordx2 v[166:167], v[168:169], off
	v_add_f32_e32 v166, v129, v126

; template <bool SWAP, class Epi, bool THIN = false> ...
;     ...
;     for (int st = 0; st < ns; ++st) {
;       asm volatile("s_waitcnt vmcnt(0)" ::: "memory");
;       __builtin_amdgcn_s_barrier();
;       asm volatile("" ::: "memory");
;       if (st + 1 < ns) {
;         char* nb = smem + ((st + 1) & 1) * 65536;
;         const int ko = (st + 1) * 64;
; #pragma unroll
;         for (int i = 0; i < 4; ++i) { GLDS16(A + (size_t)(ap[i] + ko), nb + tid * 16 + i * 8192); GLDS16(Bt + (size_t)(bp[i] + ko), nb + 32768 + tid * 16 + i * 8192); }
;       }
;       const char* sa = smem + (st & 1) * 65536 + (wr * 64 + fr) * 128;
;       const char* sb = smem + (st & 1) * 65536 + 32768 + (wc * 128 + fr) * 128;
;       if constexpr (THIN) {
;         if (wc == 0) {
; #pragma unroll
;           for (int ks = 0; ks < 2; ++ks) {
;             bf16x8 af[4], bf[2];
; #pragma unroll
;             for (int m = 0; m < 4; ++m) af[m] = *(const bf16x8*)(sa + m * 2048 + (((ks * 4 + fq) ^ swz) << 4));
; #pragma unroll
;             for (int n = 0; n < 2; ++n) bf[n] = *(const bf16x8*)(sb + n * 2048 + (((ks * 4 + fq) ^ swz) << 4));
; #pragma unroll
;             for (int m = 0; m < 4; ++m)
; #pragma unroll
;               for (int n = 0; n < 2; ++n)
;                 acc[m][n] = SWAP ? __builtin_amdgcn_mfma_f32_16x16x32_bf16(bf[n], af[m], acc[m][n], 0, 0, 0)
;                                  : __builtin_amdgcn_mfma_f32_16x16x32_bf16(af[m], bf[n], acc[m][n], 0, 0, 0);
;           }
;         }
;       } else {
;       bf16x8 afA[4], afB[4], bfb[2][2];
; #pragma unroll
;       for (int m = 0; m < 4; ++m) afA[m] = *(const bf16x8*)(sa + m * 2048 + ((fq ^ swz) << 4));
; #pragma unroll
;       for (int n = 0; n < 2; ++n) bfb[0][n] = *(const bf16x8*)(sb + n * 2048 + ((fq ^ swz) << 4));
; #pragma unroll
;       for (int gq = 0; gq < 8; ++gq) {
;         const int ks = gq >> 2, nh = gq & 3;
;         if (gq < 7) {
;           const int ks2 = (gq + 1) >> 2, nh2 = (gq + 1) & 3;
; #pragma unroll
;           for (int n = 0; n < 2; ++n) bfb[(gq + 1) & 1][n] = *(const bf16x8*)(sb + (nh2 * 2 + n) * 2048 + (((ks2 * 4 + fq) ^ swz) << 4));
;         }
;         if (gq == 3) {
; #pragma unroll
;           for (int m = 0; m < 4; ++m) afB[m] = *(const bf16x8*)(sa + m * 2048 + (((4 + fq) ^ swz) << 4));
;         }
;         __builtin_amdgcn_sched_barrier(0);
; #pragma unroll
.LBB0_2116:
	s_add_i32 s8, s7, 0x10000
	s_and_b32 s9, s8, 0x10000
	v_add_u32_e32 v169, s9, v144
	s_nop 0
	v_readfirstlane_b32 s9, v169
	s_and_b32 s7, s7, 0x10000
	v_add_u32_e32 v130, s7, v145
	v_add_u32_e32 v140, v130, v147
	s_waitcnt vmcnt(0)
	s_barrier
	ds_read_b128 v[170:173], v140
	ds_read_b128 v[174:177], v140 offset:2048
	ds_read_b128 v[178:181], v140 offset:4096
	ds_read_b128 v[182:185], v140 offset:6144
	v_or_b32_e32 v140, s7, v146
	v_add_u32_e32 v141, v140, v147
	ds_read_b128 v[186:189], v141 offset:32768
	ds_read_b128 v[190:193], v141 offset:34816
	ds_read_b128 v[194:197], v141 offset:36864
	ds_read_b128 v[198:201], v141 offset:38912
	v_add_u32_e32 v130, v130, v148
	s_waitcnt lgkmcnt(3)
	v_mfma_f32_16x16x32_bf16 v[126:129], v[186:189], v[170:173], v[126:129]
	s_mov_b32 m0, s9
	v_mfma_f32_16x16x32_bf16 v[110:113], v[186:189], v[174:177], v[110:113]
	global_load_lds_dwordx4 v139, s[18:19]
	v_add_u32_e32 v139, 0x80, v139
	v_mfma_f32_16x16x32_bf16 v[82:85], v[186:189], v[178:181], v[82:85]
	v_mfma_f32_16x16x32_bf16 v[50:53], v[186:189], v[182:185], v[50:53]
	ds_read_b128 v[186:189], v141 offset:40960
	ds_read_b128 v[202:205], v141 offset:43008
	s_waitcnt lgkmcnt(4)
	v_mfma_f32_16x16x32_bf16 v[122:125], v[190:193], v[170:173], v[122:125]
	s_add_u32 m0, s9, 0x8000
	v_mfma_f32_16x16x32_bf16 v[106:109], v[190:193], v[174:177], v[106:109]
	global_load_lds_dwordx4 v138, s[24:25]
	v_add_u32_e32 v138, 0x80, v138
	v_mfma_f32_16x16x32_bf16 v[78:81], v[190:193], v[178:181], v[78:81]
	v_mfma_f32_16x16x32_bf16 v[42:45], v[190:193], v[182:185], v[42:45]
	s_waitcnt lgkmcnt(3)
	v_mfma_f32_16x16x32_bf16 v[118:121], v[194:197], v[170:173], v[118:121]
	s_add_u32 m0, s9, 0x2000
	v_mfma_f32_16x16x32_bf16 v[94:97], v[194:197], v[174:177], v[94:97]
	global_load_lds_dwordx4 v137, s[18:19]
	v_add_u32_e32 v137, 0x80, v137
	v_mfma_f32_16x16x32_bf16 v[58:61], v[194:197], v[178:181], v[58:61]
	v_mfma_f32_16x16x32_bf16 v[26:29], v[194:197], v[182:185], v[26:29]
	ds_read_b128 v[190:193], v141 offset:45056
	ds_read_b128 v[194:197], v141 offset:47104
	s_waitcnt lgkmcnt(4)
	v_mfma_f32_16x16x32_bf16 v[114:117], v[198:201], v[170:173], v[114:117]
	s_add_u32 m0, s9, 0xa000
	v_mfma_f32_16x16x32_bf16 v[86:89], v[198:201], v[174:177], v[86:89]
	global_load_lds_dwordx4 v136, s[24:25]
	v_add_u32_e32 v136, 0x80, v136
	v_mfma_f32_16x16x32_bf16 v[54:57], v[198:201], v[178:181], v[54:57]
	v_mfma_f32_16x16x32_bf16 v[22:25], v[198:201], v[182:185], v[22:25]
	v_add_u32_e32 v140, v140, v148
	s_waitcnt lgkmcnt(3)
	v_mfma_f32_16x16x32_bf16 v[102:105], v[186:189], v[170:173], v[102:105]
	ds_read_b128 v[198:201], v140 offset:32768
	ds_read_b128 v[206:209], v140 offset:34816
	s_add_u32 m0, s9, 0x4000
	v_mfma_f32_16x16x32_bf16 v[74:77], v[186:189], v[174:177], v[74:77]
	global_load_lds_dwordx4 v135, s[18:19]
	v_add_u32_e32 v135, 0x80, v135
	v_mfma_f32_16x16x32_bf16 v[46:49], v[186:189], v[178:181], v[46:49]
	v_mfma_f32_16x16x32_bf16 v[10:13], v[186:189], v[182:185], v[10:13]
	ds_read_b128 v[186:189], v130
	ds_read_b128 v[210:213], v130 offset:2048
	ds_read_b128 v[214:217], v130 offset:4096
	ds_read_b128 v[218:221], v130 offset:6144
	s_waitcnt lgkmcnt(8)
	v_mfma_f32_16x16x32_bf16 v[98:101], v[202:205], v[170:173], v[98:101]
	s_add_u32 m0, s9, 0xc000
	v_mfma_f32_16x16x32_bf16 v[66:69], v[202:205], v[174:177], v[66:69]
	global_load_lds_dwordx4 v134, s[24:25]
	v_add_u32_e32 v134, 0x80, v134
	v_mfma_f32_16x16x32_bf16 v[30:33], v[202:205], v[178:181], v[30:33]
	v_mfma_f32_16x16x32_bf16 v[6:9], v[202:205], v[182:185], v[6:9]
	s_waitcnt lgkmcnt(7)
	v_mfma_f32_16x16x32_bf16 v[70:73], v[190:193], v[170:173], v[70:73]
	s_add_u32 m0, s9, 0x6000
	s_waitcnt lgkmcnt(6)
	v_mfma_f32_16x16x32_bf16 v[62:65], v[194:197], v[170:173], v[62:65]
	global_load_lds_dwordx4 v133, s[18:19]
	v_add_u32_e32 v133, 0x80, v133
	v_mfma_f32_16x16x32_bf16 v[38:41], v[190:193], v[174:177], v[38:41]
	v_mfma_f32_16x16x32_bf16 v[34:37], v[194:197], v[174:177], v[34:37]
	ds_read_b128 v[170:173], v140 offset:36864
	ds_read_b128 v[174:177], v140 offset:38912
	v_mfma_f32_16x16x32_bf16 v[18:21], v[190:193], v[178:181], v[18:21]
	s_add_u32 m0, s9, 0xe000
	v_mfma_f32_16x16x32_bf16 v[14:17], v[194:197], v[178:181], v[14:17]
	global_load_lds_dwordx4 v132, s[24:25]
	v_add_u32_e32 v132, 0x80, v132
	v_mfma_f32_16x16x32_bf16 v[2:5], v[190:193], v[182:185], v[2:5]
	v_mfma_f32_16x16x32_bf16 v[90:93], v[194:197], v[182:185], v[90:93]
	ds_read_b128 v[178:181], v140 offset:40960
	ds_read_b128 v[182:185], v140 offset:43008
	s_waitcnt lgkmcnt(7)
	v_mfma_f32_16x16x32_bf16 v[126:129], v[198:201], v[186:189], v[126:129]
	v_mfma_f32_16x16x32_bf16 v[122:125], v[206:209], v[186:189], v[122:125]
	s_waitcnt lgkmcnt(6)
	v_mfma_f32_16x16x32_bf16 v[110:113], v[198:201], v[210:213], v[110:113]
	v_mfma_f32_16x16x32_bf16 v[106:109], v[206:209], v[210:213], v[106:109]
	s_waitcnt lgkmcnt(5)
	v_mfma_f32_16x16x32_bf16 v[82:85], v[198:201], v[214:217], v[82:85]
	v_mfma_f32_16x16x32_bf16 v[78:81], v[206:209], v[214:217], v[78:81]
	s_waitcnt lgkmcnt(4)
	v_mfma_f32_16x16x32_bf16 v[50:53], v[198:201], v[218:221], v[50:53]
	v_mfma_f32_16x16x32_bf16 v[42:45], v[206:209], v[218:221], v[42:45]
	s_waitcnt lgkmcnt(3)
	v_mfma_f32_16x16x32_bf16 v[118:121], v[170:173], v[186:189], v[118:121]
	v_mfma_f32_16x16x32_bf16 v[94:97], v[170:173], v[210:213], v[94:97]
	v_mfma_f32_16x16x32_bf16 v[58:61], v[170:173], v[214:217], v[58:61]
	v_mfma_f32_16x16x32_bf16 v[26:29], v[170:173], v[218:221], v[26:29]
	ds_read_b128 v[170:173], v140 offset:45056
	ds_read_b128 v[190:193], v140 offset:47104
	s_waitcnt lgkmcnt(4)
; template <bool SWAP, class Epi, bool THIN = false> ...
;     ...
;     for (int st = 0; st < ns; ++st) {
;       asm volatile("s_waitcnt vmcnt(0)" ::: "memory");
;       __builtin_amdgcn_s_barrier();
;       asm volatile("" ::: "memory");
;       if (st + 1 < ns) {
;         char* nb = smem + ((st + 1) & 1) * 65536;
;         const int ko = (st + 1) * 64;
; #pragma unroll
;         for (int i = 0; i < 4; ++i) { GLDS16(A + (size_t)(ap[i] + ko), nb + tid * 16 + i * 8192); GLDS16(Bt + (size_t)(bp[i] + ko), nb + 32768 + tid * 16 + i * 8192); }
;       }
;       const char* sa = smem + (st & 1) * 65536 + (wr * 64 + fr) * 128;
;       const char* sb = smem + (st & 1) * 65536 + 32768 + (wc * 128 + fr) * 128;
;       if constexpr (THIN) {
;         if (wc == 0) {
; #pragma unroll
;           for (int ks = 0; ks < 2; ++ks) {
;             bf16x8 af[4], bf[2];
; #pragma unroll
;             for (int m = 0; m < 4; ++m) af[m] = *(const bf16x8*)(sa + m * 2048 + (((ks * 4 + fq) ^ swz) << 4));
; #pragma unroll
;             for (int n = 0; n < 2; ++n) bf[n] = *(const bf16x8*)(sb + n * 2048 + (((ks * 4 + fq) ^ swz) << 4));
; #pragma unroll
;             for (int m = 0; m < 4; ++m)
; #pragma unroll
;               for (int n = 0; n < 2; ++n)
;                 acc[m][n] = SWAP ? __builtin_amdgcn_mfma_f32_16x16x32_bf16(bf[n], af[m], acc[m][n], 0, 0, 0)
;                                  : __builtin_amdgcn_mfma_f32_16x16x32_bf16(af[m], bf[n], acc[m][n], 0, 0, 0);
;           }
;         }
;       } else {
;       bf16x8 afA[4], afB[4], bfb[2][2];
; #pragma unroll
;       for (int m = 0; m < 4; ++m) afA[m] = *(const bf16x8*)(sa + m * 2048 + ((fq ^ swz) << 4));
; #pragma unroll
;       for (int n = 0; n < 2; ++n) bfb[0][n] = *(const bf16x8*)(sb + n * 2048 + ((fq ^ swz) << 4));
; #pragma unroll
;       for (int gq = 0; gq < 8; ++gq) {
;         const int ks = gq >> 2, nh = gq & 3;
;         if (gq < 7) {
;           const int ks2 = (gq + 1) >> 2, nh2 = (gq + 1) & 3;
; #pragma unroll
;           for (int n = 0; n < 2; ++n) bfb[(gq + 1) & 1][n] = *(const bf16x8*)(sb + (nh2 * 2 + n) * 2048 + (((ks2 * 4 + fq) ^ swz) << 4));
;         }
;         if (gq == 3) {
; #pragma unroll
;           for (int m = 0; m < 4; ++m) afB[m] = *(const bf16x8*)(sa + m * 2048 + (((4 + fq) ^ swz) << 4));
;         }
;         __builtin_amdgcn_sched_barrier(0);
; #pragma unroll
	v_mfma_f32_16x16x32_bf16 v[114:117], v[174:177], v[186:189], v[114:117]
	v_mfma_f32_16x16x32_bf16 v[86:89], v[174:177], v[210:213], v[86:89]
	v_mfma_f32_16x16x32_bf16 v[54:57], v[174:177], v[214:217], v[54:57]
	v_mfma_f32_16x16x32_bf16 v[22:25], v[174:177], v[218:221], v[22:25]
	s_waitcnt lgkmcnt(3)
	v_mfma_f32_16x16x32_bf16 v[102:105], v[178:181], v[186:189], v[102:105]
	s_waitcnt lgkmcnt(2)
	v_mfma_f32_16x16x32_bf16 v[98:101], v[182:185], v[186:189], v[98:101]
	v_mfma_f32_16x16x32_bf16 v[74:77], v[178:181], v[210:213], v[74:77]
	v_mfma_f32_16x16x32_bf16 v[66:69], v[182:185], v[210:213], v[66:69]
	v_mfma_f32_16x16x32_bf16 v[46:49], v[178:181], v[214:217], v[46:49]
	v_mfma_f32_16x16x32_bf16 v[30:33], v[182:185], v[214:217], v[30:33]
	v_mfma_f32_16x16x32_bf16 v[10:13], v[178:181], v[218:221], v[10:13]
	v_mfma_f32_16x16x32_bf16 v[6:9], v[182:185], v[218:221], v[6:9]
	s_waitcnt lgkmcnt(1)
	v_mfma_f32_16x16x32_bf16 v[70:73], v[170:173], v[186:189], v[70:73]
	s_add_i32 s6, s6, 64
	s_cmpk_eq_i32 s6, 0x3c0
	s_mov_b32 s7, s8
	s_waitcnt lgkmcnt(0)
	v_mfma_f32_16x16x32_bf16 v[62:65], v[190:193], v[186:189], v[62:65]
	v_mfma_f32_16x16x32_bf16 v[38:41], v[170:173], v[210:213], v[38:41]
	v_mfma_f32_16x16x32_bf16 v[34:37], v[190:193], v[210:213], v[34:37]
	v_mfma_f32_16x16x32_bf16 v[18:21], v[170:173], v[214:217], v[18:21]
	v_mfma_f32_16x16x32_bf16 v[14:17], v[190:193], v[214:217], v[14:17]
	v_mfma_f32_16x16x32_bf16 v[2:5], v[170:173], v[218:221], v[2:5]
	v_mfma_f32_16x16x32_bf16 v[90:93], v[190:193], v[218:221], v[90:93]
	s_cbranch_scc0 .LBB0_2116
	s_waitcnt vmcnt(0)
	s_barrier
	v_add_u32_e32 v130, v159, v147
	ds_read_b128 v[132:135], v130
	ds_read_b128 v[136:139], v130 offset:2048
	ds_read_b128 v[170:173], v130 offset:4096
	ds_read_b128 v[174:177], v130 offset:6144
	v_add_u32_e32 v130, v160, v147
	ds_read_b128 v[178:181], v130
	ds_read_b128 v[182:185], v130 offset:2048
	ds_read_b128 v[186:189], v130 offset:4096
	ds_read_b128 v[190:193], v130 offset:6144
	s_waitcnt lgkmcnt(0)
	v_mfma_f32_16x16x32_bf16 v[126:129], v[178:181], v[132:135], v[126:129]
	v_mfma_f32_16x16x32_bf16 v[110:113], v[178:181], v[136:139], v[110:113]
	v_mfma_f32_16x16x32_bf16 v[82:85], v[178:181], v[170:173], v[82:85]
	v_mfma_f32_16x16x32_bf16 v[50:53], v[178:181], v[174:177], v[50:53]
	ds_read_b128 v[178:181], v130 offset:8192
	ds_read_b128 v[194:197], v130 offset:10240
	v_mfma_f32_16x16x32_bf16 v[122:125], v[182:185], v[132:135], v[122:125]
	v_mfma_f32_16x16x32_bf16 v[106:109], v[182:185], v[136:139], v[106:109]
	v_mfma_f32_16x16x32_bf16 v[78:81], v[182:185], v[170:173], v[78:81]
	v_mfma_f32_16x16x32_bf16 v[42:45], v[182:185], v[174:177], v[42:45]
	v_mfma_f32_16x16x32_bf16 v[118:121], v[186:189], v[132:135], v[118:121]
	v_mfma_f32_16x16x32_bf16 v[182:185], v[186:189], v[136:139], v[94:97]
	v_mfma_f32_16x16x32_bf16 v[202:205], v[186:189], v[170:173], v[58:61]
	v_mfma_f32_16x16x32_bf16 v[206:209], v[190:193], v[170:173], v[54:57]
	v_mfma_f32_16x16x32_bf16 v[186:189], v[186:189], v[174:177], v[26:29]
	s_nop 2
	ds_read_b128 v[26:29], v130 offset:12288
	ds_read_b128 v[54:57], v130 offset:14336
	v_mfma_f32_16x16x32_bf16 v[114:117], v[190:193], v[132:135], v[114:117]
	v_mfma_f32_16x16x32_bf16 v[198:201], v[190:193], v[136:139], v[86:89]
	v_mfma_f32_16x16x32_bf16 v[190:193], v[190:193], v[174:177], v[22:25]
	v_add_u32_e32 v130, v160, v148
	s_waitcnt lgkmcnt(0)
	v_mfma_f32_16x16x32_bf16 v[210:213], v[194:197], v[170:173], v[30:33]
	ds_read_b128 v[22:25], v130
	ds_read_b128 v[86:89], v130 offset:2048
	s_nop 0
	v_add_u32_e32 v30, v159, v148
	v_mfma_f32_16x16x32_bf16 v[102:105], v[178:181], v[132:135], v[102:105]
	v_mfma_f32_16x16x32_bf16 v[74:77], v[178:181], v[136:139], v[74:77]
	v_mfma_f32_16x16x32_bf16 v[46:49], v[178:181], v[170:173], v[46:49]
	v_mfma_f32_16x16x32_bf16 v[10:13], v[178:181], v[174:177], v[10:13]
	ds_read_b128 v[178:181], v30
	ds_read_b128 v[214:217], v30 offset:2048
	ds_read_b128 v[218:221], v30 offset:4096
	ds_read_b128 v[222:225], v30 offset:6144
	v_mfma_f32_16x16x32_bf16 v[98:101], v[194:197], v[132:135], v[98:101]
	v_mfma_f32_16x16x32_bf16 v[66:69], v[194:197], v[136:139], v[66:69]
	v_mfma_f32_16x16x32_bf16 v[6:9], v[194:197], v[174:177], v[6:9]
	v_mfma_f32_16x16x32_bf16 v[38:41], v[26:29], v[136:139], v[38:41]
	v_mfma_f32_16x16x32_bf16 v[34:37], v[54:57], v[136:139], v[34:37]
	v_mfma_f32_16x16x32_bf16 v[136:139], v[26:29], v[170:173], v[18:21]
	v_mfma_f32_16x16x32_bf16 v[170:173], v[54:57], v[170:173], v[14:17]
	s_nop 2
	ds_read_b128 v[14:17], v130 offset:4096
	ds_read_b128 v[18:21], v130 offset:6144
	v_mfma_f32_16x16x32_bf16 v[70:73], v[26:29], v[132:135], v[70:73]
	v_mfma_f32_16x16x32_bf16 v[132:135], v[54:57], v[132:135], v[62:65]
	v_mfma_f32_16x16x32_bf16 v[2:5], v[26:29], v[174:177], v[2:5]
	v_mfma_f32_16x16x32_bf16 v[174:177], v[54:57], v[174:177], v[90:93]
	ds_read_b128 v[194:197], v130 offset:8192
	ds_read_b128 v[226:229], v130 offset:10240
	s_waitcnt lgkmcnt(0)
	v_mfma_f32_16x16x32_bf16 v[126:129], v[22:25], v[178:181], v[126:129]
	v_mfma_f32_16x16x32_bf16 v[122:125], v[86:89], v[178:181], v[122:125]
	v_mfma_f32_16x16x32_bf16 v[94:97], v[22:25], v[214:217], v[110:113]
	v_mfma_f32_16x16x32_bf16 v[90:93], v[86:89], v[214:217], v[106:109]
	v_mfma_f32_16x16x32_bf16 v[62:65], v[22:25], v[218:221], v[82:85]
	v_mfma_f32_16x16x32_bf16 v[58:61], v[86:89], v[218:221], v[78:81]
	v_mfma_f32_16x16x32_bf16 v[30:33], v[22:25], v[222:225], v[50:53]
	v_mfma_f32_16x16x32_bf16 v[26:29], v[86:89], v[222:225], v[42:45]
	v_mfma_f32_16x16x32_bf16 v[86:89], v[14:17], v[214:217], v[182:185]
	v_mfma_f32_16x16x32_bf16 v[22:25], v[14:17], v[222:225], v[186:189]
	s_nop 1
	ds_read_b128 v[182:185], v130 offset:12288
	ds_read_b128 v[186:189], v130 offset:14336
	v_mfma_f32_16x16x32_bf16 v[118:121], v[14:17], v[178:181], v[118:121]
	v_mfma_f32_16x16x32_bf16 v[114:117], v[18:21], v[178:181], v[114:117]
	v_mfma_f32_16x16x32_bf16 v[82:85], v[18:21], v[214:217], v[198:201]
	v_mfma_f32_16x16x32_bf16 v[54:57], v[14:17], v[218:221], v[202:205]
	v_mfma_f32_16x16x32_bf16 v[50:53], v[18:21], v[218:221], v[206:209]
	v_mfma_f32_16x16x32_bf16 v[18:21], v[18:21], v[222:225], v[190:193]
	v_mfma_f32_16x16x32_bf16 v[110:113], v[194:197], v[178:181], v[102:105]
	v_mfma_f32_16x16x32_bf16 v[106:109], v[226:229], v[178:181], v[98:101]
	v_mfma_f32_16x16x32_bf16 v[78:81], v[194:197], v[214:217], v[74:77]
	v_mfma_f32_16x16x32_bf16 v[74:77], v[226:229], v[214:217], v[66:69]
	v_mfma_f32_16x16x32_bf16 v[46:49], v[194:197], v[218:221], v[46:49]
	v_mfma_f32_16x16x32_bf16 v[42:45], v[226:229], v[218:221], v[210:213]
	v_mfma_f32_16x16x32_bf16 v[14:17], v[194:197], v[222:225], v[10:13]
	v_mfma_f32_16x16x32_bf16 v[6:9], v[226:229], v[222:225], v[6:9]
	v_mov_b32_e32 v130, v1
	s_waitcnt vmcnt(0) lgkmcnt(0)
	s_barrier
; __device__ __forceinline__ int get_tid512() { int t = threadIdx.x; asm volatile("" : "+v"(t)); return t; }
; __device__ __forceinline__ unsigned pack2(float a, float b) { unsigned r; asm("v_cvt_pk_bf16_f32 %0, %1, %2" : "=v"(r) : "v"(a), "v"(b)); return r; }
; __device__ __forceinline__ float bf2f(bf16_t h) { return __uint_as_float(((unsigned)h) << 16); }
;   __device__ __forceinline__ void c4(int g, int rig, int col, f32x4 v) const {
;     const size_t o = ((size_t)g * 2048 + rig) * 1024 + col;
;     f32x4 bs;
;     if (BASE_F32) bs = __builtin_nontemporal_load((const f32x4*)((const float*)base + o));
;     else {
;       const uint2 u = *(const uint2*)((const bf16_t*)base + o);
;       bs[0] = bf2f((bf16_t)(u.x & 0xffff)); bs[1] = bf2f((bf16_t)(u.x >> 16)); bs[2] = bf2f((bf16_t)(u.y & 0xffff)); bs[3] = bf2f((bf16_t)(u.y >> 16));
;     }
;     const f32x4 gt = *(const f32x4*)(gate + (size_t)g * 6144 + col);
;     f32x4 bi = {0.f, 0.f, 0.f, 0.f};
;     if (bias) bi = *(const f32x4*)(bias + col);
;     f32x4 r;
; #pragma unroll
;     for (int j = 0; j < 4; ++j) r[j] = bs[j] + gt[j] * (v[j] + bi[j]);
;     uint2 w; w.x = pack2(r[0], r[1]); w.y = pack2(r[2], r[3]);
;     *(uint2*)(X16 + o) = w;
;   }
; template <bool SWAP, class Epi, bool THIN = false> ...
;     ...
;     const int te = get_tid512();
;     const int fr_e = te & 15, fq_e = (te & 63) >> 4, wr_e = te >> 7, wc_e = (te >> 6) & 1;
;     const int sub = 2 * mt + (wr_e >> 1);
;     const int g = sub / tpg, ti = sub - g * tpg;
;     const int rig0 = ti * step - halo;
;     const int rw = (wr_e & 1) * 64;
;     if constexpr (Epi::KIND == 0) {
; #pragma unroll
;       for (int m = 0; m < 4; ++m) {
;         const int rig = rig0 + rw + m * 16 + fr_e;
;         if constexpr (Epi::ROWSUM) {
;           float ss = 0.f;
; #pragma unroll
;           for (int n = 0; n < 8; ++n) {
;             const int col = nt * 256 + wc_e * 128 + n * 16 + fq_e * 4;
;             if (col < N) ss += epi.c4(g, rig, col, acc[m][n]);
;           }
;           ss += __shfl_xor(ss, 16); ss += __shfl_xor(ss, 32);
;           if (fq_e == 0) epi.rowsum(g, rig, nt * 2 + wc_e, ss);
;         } else {
; #pragma unroll
;           for (int n = 0; n < 8; ++n) {
;             const int col = nt * 256 + wc_e * 128 + n * 16 + fq_e * 4;
;             if (col < N) epi.c4(g, rig, col, acc[m][n]);
	v_mfma_f32_16x16x32_bf16 v[98:101], v[186:189], v[178:181], v[132:135]
	v_ashrrev_i32_e32 v11, 8, v130
	v_add_u32_e32 v11, s5, v11
	v_ashrrev_i32_e32 v12, 31, v11
	v_lshrrev_b32_e32 v12, 28, v12
	v_add_u32_e32 v12, v11, v12
	v_ashrrev_i32_e32 v134, 4, v12
	v_lshlrev_b32_e32 v12, 11, v134
	v_lshlrev_b32_e32 v11, 7, v11
	v_sub_u32_e32 v11, v11, v12
	v_lshrrev_b32_e32 v12, 1, v130
	v_and_b32_e32 v10, 15, v130
	v_and_b32_e32 v12, 64, v12
	v_mfma_f32_16x16x32_bf16 v[102:105], v[182:185], v[178:181], v[70:73]
	v_ashrrev_i32_e32 v135, 31, v134
	v_mfma_f32_16x16x32_bf16 v[70:73], v[182:185], v[214:217], v[38:41]
	v_mfma_f32_16x16x32_bf16 v[38:41], v[182:185], v[218:221], v[136:139]
	s_nop 2
	v_or3_b32 v136, v11, v12, v10
	v_lshlrev_b32_e32 v10, 1, v130
	v_and_b32_e32 v132, 0x80, v10
	v_mfma_f32_16x16x32_bf16 v[10:13], v[182:185], v[222:225], v[2:5]
	v_ashrrev_i32_e32 v137, 31, v136
	v_lshlrev_b64 v[138:139], 21, v[134:135]
	v_lshlrev_b64 v[140:141], 10, v[136:137]
	v_lshrrev_b32_e32 v2, 2, v130
	v_and_b32_e32 v2, 12, v2
	v_mfma_f32_16x16x32_bf16 v[66:69], v[186:189], v[214:217], v[34:37]
	v_or3_b32 v132, v2, v132, s4
	v_bfe_u32 v246, v130, 4, 1
	v_mul_u32_u24_e32 v246, 24, v246
	v_mov_b32_e32 v247, 0
	v_mad_i64_i32 v[134:135], s[4:5], v134, s33, 0
	v_mfma_f32_16x16x32_bf16 v[34:37], v[186:189], v[218:221], v[170:173]
	v_lshl_add_u64 v[140:141], v[140:141], 0, v[138:139]
	v_cmp_gt_i32_e32 vcc, s34, v132
	v_ashrrev_i32_e32 v133, 31, v132
	v_mfma_f32_16x16x32_bf16 v[2:5], v[186:189], v[222:225], v[174:177]
	v_lshl_add_u64 v[134:135], s[26:27], 0, v[134:135]
	v_lshl_add_u64 v[168:169], v[132:133], 2, v[134:135]
	global_load_dwordx4 v[180:183], v[168:169], off
	global_load_dwordx4 v[184:187], v[168:169], off offset:64
	global_load_dwordx4 v[188:191], v[168:169], off offset:128
	global_load_dwordx4 v[192:195], v[168:169], off offset:192
	global_load_dwordx4 v[196:199], v[168:169], off offset:256
	global_load_dwordx4 v[200:203], v[168:169], off offset:320
	global_load_dwordx4 v[204:207], v[168:169], off offset:384
	global_load_dwordx4 v[208:211], v[168:169], off offset:448
	v_lshl_add_u64 v[178:179], v[140:141], 0, v[132:133]
	v_lshl_add_u64 v[244:245], v[140:141], 0, v[132:133]
	v_lshl_add_u64 v[244:245], v[244:245], 2, s[22:23]
	global_load_dwordx4 v[212:215], v[244:245], off nt
	global_load_dwordx4 v[216:219], v[244:245], off offset:64 nt
	global_load_dwordx4 v[220:223], v[244:245], off offset:128 nt
	global_load_dwordx4 v[224:227], v[244:245], off offset:192 nt
	global_load_dwordx4 v[228:231], v[244:245], off offset:256 nt
	global_load_dwordx4 v[232:235], v[244:245], off offset:320 nt
	global_load_dwordx4 v[236:239], v[244:245], off offset:384 nt
	global_load_dwordx4 v[240:243], v[244:245], off offset:448 nt
	s_nop 0
	v_add_f32_e32 v126, 0, v126
	v_add_f32_e32 v127, 0, v127
	v_add_f32_e32 v128, 0, v128
	v_add_f32_e32 v129, 0, v129
	s_waitcnt vmcnt(7)
	v_fma_f32 v126, v126, v180, v212
	v_fma_f32 v127, v127, v181, v213
	v_fma_f32 v128, v128, v182, v214
	v_fma_f32 v177, v129, v183, v215
	v_cvt_pk_bf16_f32 v126, v126, v127
	v_cvt_pk_bf16_f32 v127, v128, v177
	v_lshl_add_u64 v[174:175], v[140:141], 0, v[132:133]
	s_nop 0
	v_add_f32_e32 v122, 0, v122
	v_add_f32_e32 v123, 0, v123
	v_add_f32_e32 v124, 0, v124
	v_add_f32_e32 v125, 0, v125
	s_waitcnt vmcnt(6)
	v_fma_f32 v122, v122, v184, v216
	v_fma_f32 v123, v123, v185, v217
	v_fma_f32 v124, v124, v186, v218
	v_fma_f32 v173, v125, v187, v219
	v_cvt_pk_bf16_f32 v128, v122, v123
	v_cvt_pk_bf16_f32 v129, v124, v173
	v_lshl_add_u64 v[124:125], v[174:175], 1, s[20:21]
	s_nop 1
	v_permlane16_swap_b32 v126, v128
	v_permlane16_swap_b32 v127, v129
	v_lshl_add_u64 v[248:249], v[124:125], 0, v[246:247]
	s_nop 0
	global_store_dwordx4 v[248:249], v[126:129], off
	s_nop 1
	v_or_b32_e32 v122, 32, v132
	v_lshl_add_u64 v[170:171], v[140:141], 0, v[132:133]
	s_nop 0
	v_add_f32_e32 v118, 0, v118
	v_add_f32_e32 v119, 0, v119
	v_add_f32_e32 v120, 0, v120
	v_add_f32_e32 v121, 0, v121
	s_waitcnt vmcnt(6)
	v_fma_f32 v118, v118, v188, v220
	v_fma_f32 v119, v119, v189, v221
	v_fma_f32 v120, v120, v190, v222
	v_fma_f32 v129, v121, v191, v223
	v_cvt_pk_bf16_f32 v118, v118, v119
	v_cvt_pk_bf16_f32 v119, v120, v129
	v_lshl_add_u64 v[126:127], v[140:141], 0, v[132:133]
	s_nop 0
	v_add_f32_e32 v114, 0, v114
	v_add_f32_e32 v115, 0, v115
	v_add_f32_e32 v116, 0, v116
	v_add_f32_e32 v117, 0, v117
	s_waitcnt vmcnt(5)
	v_fma_f32 v114, v114, v192, v224
	v_fma_f32 v115, v115, v193, v225
	v_fma_f32 v116, v116, v194, v226
	v_fma_f32 v125, v117, v195, v227
	v_cvt_pk_bf16_f32 v120, v114, v115
	v_cvt_pk_bf16_f32 v121, v116, v125
	v_lshl_add_u64 v[116:117], v[126:127], 1, s[20:21]
	s_nop 1
	v_permlane16_swap_b32 v118, v120
	v_permlane16_swap_b32 v119, v121
	v_lshl_add_u64 v[248:249], v[116:117], 0, v[246:247]
	s_nop 0
	global_store_dwordx4 v[248:249], v[118:121], off offset:64
	s_nop 1
	v_or_b32_e32 v114, 64, v132
	v_lshl_add_u64 v[122:123], v[140:141], 0, v[132:133]
	s_nop 0
	v_add_f32_e32 v110, 0, v110
	v_add_f32_e32 v111, 0, v111
	v_add_f32_e32 v112, 0, v112
	v_add_f32_e32 v113, 0, v113
	s_waitcnt vmcnt(5)
	v_fma_f32 v110, v110, v196, v228
	v_fma_f32 v111, v111, v197, v229
	v_fma_f32 v112, v112, v198, v230
	v_fma_f32 v121, v113, v199, v231
	v_cvt_pk_bf16_f32 v110, v110, v111
	v_cvt_pk_bf16_f32 v111, v112, v121
	v_lshl_add_u64 v[118:119], v[140:141], 0, v[132:133]
	s_nop 0
	v_add_f32_e32 v106, 0, v106
	v_add_f32_e32 v107, 0, v107
	v_add_f32_e32 v108, 0, v108
	v_add_f32_e32 v109, 0, v109
	s_waitcnt vmcnt(4)
; __device__ __forceinline__ unsigned pack2(float a, float b) { unsigned r; asm("v_cvt_pk_bf16_f32 %0, %1, %2" : "=v"(r) : "v"(a), "v"(b)); return r; }
; __device__ __forceinline__ float bf2f(bf16_t h) { return __uint_as_float(((unsigned)h) << 16); }
;   __device__ __forceinline__ void c4(int g, int rig, int col, f32x4 v) const {
;     const size_t o = ((size_t)g * 2048 + rig) * 1024 + col;
;     f32x4 bs;
;     if (BASE_F32) bs = __builtin_nontemporal_load((const f32x4*)((const float*)base + o));
;     else {
;       const uint2 u = *(const uint2*)((const bf16_t*)base + o);
;       bs[0] = bf2f((bf16_t)(u.x & 0xffff)); bs[1] = bf2f((bf16_t)(u.x >> 16)); bs[2] = bf2f((bf16_t)(u.y & 0xffff)); bs[3] = bf2f((bf16_t)(u.y >> 16));
;     }
;     const f32x4 gt = *(const f32x4*)(gate + (size_t)g * 6144 + col);
;     f32x4 bi = {0.f, 0.f, 0.f, 0.f};
;     if (bias) bi = *(const f32x4*)(bias + col);
;     f32x4 r;
; #pragma unroll
;     for (int j = 0; j < 4; ++j) r[j] = bs[j] + gt[j] * (v[j] + bi[j]);
;     uint2 w; w.x = pack2(r[0], r[1]); w.y = pack2(r[2], r[3]);
;     *(uint2*)(X16 + o) = w;
;   }
; template <bool SWAP, class Epi, bool THIN = false> ...
;     ...
; #pragma unroll
;           for (int n = 0; n < 8; ++n) {
;             const int col = nt * 256 + wc_e * 128 + n * 16 + fq_e * 4;
;             if (col < N) epi.c4(g, rig, col, acc[m][n]);
	v_fma_f32 v106, v106, v200, v232
	v_fma_f32 v107, v107, v201, v233
	v_fma_f32 v108, v108, v202, v234
	v_fma_f32 v117, v109, v203, v235
	v_cvt_pk_bf16_f32 v112, v106, v107
	v_cvt_pk_bf16_f32 v113, v108, v117
	v_lshl_add_u64 v[108:109], v[118:119], 1, s[20:21]
	s_nop 1
	v_permlane16_swap_b32 v110, v112
	v_permlane16_swap_b32 v111, v113
	v_lshl_add_u64 v[248:249], v[108:109], 0, v[246:247]
	s_nop 0
	global_store_dwordx4 v[248:249], v[110:113], off offset:128
	s_nop 1
	v_or_b32_e32 v106, 0x60, v132
	v_lshl_add_u64 v[114:115], v[140:141], 0, v[132:133]
	s_nop 0
	v_add_f32_e32 v102, 0, v102
	v_add_f32_e32 v103, 0, v103
	v_add_f32_e32 v104, 0, v104
	v_add_f32_e32 v105, 0, v105
	s_waitcnt vmcnt(4)
	v_fma_f32 v102, v102, v204, v236
	v_fma_f32 v103, v103, v205, v237
	v_fma_f32 v104, v104, v206, v238
	v_fma_f32 v113, v105, v207, v239
	v_cvt_pk_bf16_f32 v102, v102, v103
	v_cvt_pk_bf16_f32 v103, v104, v113
	v_lshl_add_u64 v[110:111], v[140:141], 0, v[132:133]
	s_nop 0
	v_add_f32_e32 v98, 0, v98
	v_add_f32_e32 v99, 0, v99
	v_add_f32_e32 v100, 0, v100
	v_add_f32_e32 v101, 0, v101
	s_waitcnt vmcnt(3)
	v_fma_f32 v98, v98, v208, v240
	v_fma_f32 v99, v99, v209, v241
	v_fma_f32 v100, v100, v210, v242
	v_fma_f32 v109, v101, v211, v243
	v_cvt_pk_bf16_f32 v104, v98, v99
	v_cvt_pk_bf16_f32 v105, v100, v109
	v_lshl_add_u64 v[100:101], v[110:111], 1, s[20:21]
	s_nop 1
	v_permlane16_swap_b32 v102, v104
	v_permlane16_swap_b32 v103, v105
	v_lshl_add_u64 v[248:249], v[100:101], 0, v[246:247]
	s_nop 0
	global_store_dwordx4 v[248:249], v[102:105], off offset:192
	s_nop 1
	v_or_b32_e32 v98, 16, v136
	v_ashrrev_i32_e32 v99, 31, v98
	v_lshlrev_b64 v[98:99], 10, v[98:99]
	v_lshl_add_u64 v[98:99], v[98:99], 0, v[138:139]
	v_lshl_add_u64 v[108:109], v[98:99], 0, v[132:133]
	v_lshl_add_u64 v[244:245], v[98:99], 0, v[132:133]
	v_lshl_add_u64 v[244:245], v[244:245], 2, s[22:23]
	global_load_dwordx4 v[212:215], v[244:245], off nt
	global_load_dwordx4 v[216:219], v[244:245], off offset:64 nt
	global_load_dwordx4 v[220:223], v[244:245], off offset:128 nt
	global_load_dwordx4 v[224:227], v[244:245], off offset:192 nt
	global_load_dwordx4 v[228:231], v[244:245], off offset:256 nt
	global_load_dwordx4 v[232:235], v[244:245], off offset:320 nt
	global_load_dwordx4 v[236:239], v[244:245], off offset:384 nt
	global_load_dwordx4 v[240:243], v[244:245], off offset:448 nt
	s_nop 0
	v_add_f32_e32 v94, 0, v94
	v_add_f32_e32 v95, 0, v95
	v_add_f32_e32 v96, 0, v96
	v_add_f32_e32 v97, 0, v97
	s_waitcnt vmcnt(7)
	v_fma_f32 v94, v94, v180, v212
	v_fma_f32 v95, v95, v181, v213
	v_fma_f32 v96, v96, v182, v214
	v_fma_f32 v107, v97, v183, v215
	v_cvt_pk_bf16_f32 v94, v94, v95
	v_cvt_pk_bf16_f32 v95, v96, v107
	v_lshl_add_u64 v[104:105], v[98:99], 0, v[132:133]
	s_nop 0
	v_add_f32_e32 v90, 0, v90
	v_add_f32_e32 v91, 0, v91
	v_add_f32_e32 v92, 0, v92
	v_add_f32_e32 v93, 0, v93
	s_waitcnt vmcnt(6)
	v_fma_f32 v90, v90, v184, v216
	v_fma_f32 v91, v91, v185, v217
	v_fma_f32 v92, v92, v186, v218
	v_fma_f32 v103, v93, v187, v219
	v_cvt_pk_bf16_f32 v96, v90, v91
	v_cvt_pk_bf16_f32 v97, v92, v103
	v_lshl_add_u64 v[92:93], v[104:105], 1, s[20:21]
	s_nop 1
	v_permlane16_swap_b32 v94, v96
	v_permlane16_swap_b32 v95, v97
	v_lshl_add_u64 v[248:249], v[92:93], 0, v[246:247]
	s_nop 0
	global_store_dwordx4 v[248:249], v[94:97], off
	s_nop 1
	v_lshl_add_u64 v[100:101], v[98:99], 0, v[132:133]
	s_nop 0
	v_add_f32_e32 v86, 0, v86
	v_add_f32_e32 v87, 0, v87
	v_add_f32_e32 v88, 0, v88
	v_add_f32_e32 v89, 0, v89
	s_waitcnt vmcnt(6)
	v_fma_f32 v86, v86, v188, v220
	v_fma_f32 v87, v87, v189, v221
	v_fma_f32 v88, v88, v190, v222
	v_fma_f32 v97, v89, v191, v223
	v_cvt_pk_bf16_f32 v86, v86, v87
	v_cvt_pk_bf16_f32 v87, v88, v97
	v_lshl_add_u64 v[94:95], v[98:99], 0, v[132:133]
	s_nop 0
	v_add_f32_e32 v82, 0, v82
	v_add_f32_e32 v83, 0, v83
	v_add_f32_e32 v84, 0, v84
	v_add_f32_e32 v85, 0, v85
	s_waitcnt vmcnt(5)
	v_fma_f32 v82, v82, v192, v224
	v_fma_f32 v83, v83, v193, v225
	v_fma_f32 v84, v84, v194, v226
	v_fma_f32 v93, v85, v195, v227
	v_cvt_pk_bf16_f32 v88, v82, v83
	v_cvt_pk_bf16_f32 v89, v84, v93
	v_lshl_add_u64 v[84:85], v[94:95], 1, s[20:21]
	s_nop 1
	v_permlane16_swap_b32 v86, v88
	v_permlane16_swap_b32 v87, v89
	v_lshl_add_u64 v[248:249], v[84:85], 0, v[246:247]
	s_nop 0
	global_store_dwordx4 v[248:249], v[86:89], off offset:64
	s_nop 1
	v_lshl_add_u64 v[90:91], v[98:99], 0, v[132:133]
	s_nop 0
	v_add_f32_e32 v78, 0, v78
	v_add_f32_e32 v79, 0, v79
	v_add_f32_e32 v80, 0, v80
	v_add_f32_e32 v81, 0, v81
	s_waitcnt vmcnt(5)
	v_fma_f32 v78, v78, v196, v228
	v_fma_f32 v79, v79, v197, v229
	v_fma_f32 v80, v80, v198, v230
	v_fma_f32 v89, v81, v199, v231
	v_cvt_pk_bf16_f32 v78, v78, v79
	v_cvt_pk_bf16_f32 v79, v80, v89
	v_lshl_add_u64 v[86:87], v[98:99], 0, v[132:133]
	s_nop 0
	v_add_f32_e32 v74, 0, v74
	v_add_f32_e32 v75, 0, v75
	v_add_f32_e32 v76, 0, v76
	v_add_f32_e32 v77, 0, v77
	s_waitcnt vmcnt(4)
	v_fma_f32 v74, v74, v200, v232
	v_fma_f32 v75, v75, v201, v233
	v_fma_f32 v76, v76, v202, v234
	v_fma_f32 v85, v77, v203, v235
	v_cvt_pk_bf16_f32 v80, v74, v75
	v_cvt_pk_bf16_f32 v81, v76, v85
	v_lshl_add_u64 v[76:77], v[86:87], 1, s[20:21]
	s_nop 1
	v_permlane16_swap_b32 v78, v80
	v_permlane16_swap_b32 v79, v81
	v_lshl_add_u64 v[248:249], v[76:77], 0, v[246:247]
	s_nop 0
	global_store_dwordx4 v[248:249], v[78:81], off offset:128
	s_nop 1
	v_lshl_add_u64 v[82:83], v[98:99], 0, v[132:133]
	v_add_f32_e32 v70, 0, v70
	v_add_f32_e32 v71, 0, v71
	v_add_f32_e32 v72, 0, v72
	v_add_f32_e32 v73, 0, v73
	s_waitcnt vmcnt(4)
; __device__ __forceinline__ unsigned pack2(float a, float b) { unsigned r; asm("v_cvt_pk_bf16_f32 %0, %1, %2" : "=v"(r) : "v"(a), "v"(b)); return r; }
; __device__ __forceinline__ float bf2f(bf16_t h) { return __uint_as_float(((unsigned)h) << 16); }
;   __device__ __forceinline__ void c4(int g, int rig, int col, f32x4 v) const {
;     const size_t o = ((size_t)g * 2048 + rig) * 1024 + col;
;     f32x4 bs;
;     if (BASE_F32) bs = __builtin_nontemporal_load((const f32x4*)((const float*)base + o));
;     else {
;       const uint2 u = *(const uint2*)((const bf16_t*)base + o);
;       bs[0] = bf2f((bf16_t)(u.x & 0xffff)); bs[1] = bf2f((bf16_t)(u.x >> 16)); bs[2] = bf2f((bf16_t)(u.y & 0xffff)); bs[3] = bf2f((bf16_t)(u.y >> 16));
;     }
;     const f32x4 gt = *(const f32x4*)(gate + (size_t)g * 6144 + col);
;     f32x4 bi = {0.f, 0.f, 0.f, 0.f};
;     if (bias) bi = *(const f32x4*)(bias + col);
;     f32x4 r;
; #pragma unroll
;     for (int j = 0; j < 4; ++j) r[j] = bs[j] + gt[j] * (v[j] + bi[j]);
;     uint2 w; w.x = pack2(r[0], r[1]); w.y = pack2(r[2], r[3]);
;     *(uint2*)(X16 + o) = w;
;   }
; template <bool SWAP, class Epi, bool THIN = false> ...
;     ...
; #pragma unroll
;           for (int n = 0; n < 8; ++n) {
;             const int col = nt * 256 + wc_e * 128 + n * 16 + fq_e * 4;
;             if (col < N) epi.c4(g, rig, col, acc[m][n]);
	v_fma_f32 v70, v70, v204, v236
	v_fma_f32 v71, v71, v205, v237
	v_fma_f32 v72, v72, v206, v238
	v_fma_f32 v81, v73, v207, v239
	v_cvt_pk_bf16_f32 v70, v70, v71
	v_cvt_pk_bf16_f32 v71, v72, v81
	v_lshl_add_u64 v[78:79], v[98:99], 0, v[132:133]
	v_add_f32_e32 v66, 0, v66
	v_add_f32_e32 v67, 0, v67
	v_add_f32_e32 v68, 0, v68
	v_add_f32_e32 v69, 0, v69
	s_waitcnt vmcnt(3)
	v_fma_f32 v66, v66, v208, v240
	v_fma_f32 v67, v67, v209, v241
	v_fma_f32 v68, v68, v210, v242
	v_fma_f32 v77, v69, v211, v243
	v_cvt_pk_bf16_f32 v72, v66, v67
	v_cvt_pk_bf16_f32 v73, v68, v77
	v_lshl_add_u64 v[68:69], v[78:79], 1, s[20:21]
	s_nop 1
	v_permlane16_swap_b32 v70, v72
	v_permlane16_swap_b32 v71, v73
	v_lshl_add_u64 v[248:249], v[68:69], 0, v[246:247]
	s_nop 0
	global_store_dwordx4 v[248:249], v[70:73], off offset:192
	s_nop 1
	v_or_b32_e32 v66, 32, v136
	v_ashrrev_i32_e32 v67, 31, v66
	v_lshlrev_b64 v[66:67], 10, v[66:67]
	v_lshl_add_u64 v[66:67], v[66:67], 0, v[138:139]
	v_lshl_add_u64 v[76:77], v[66:67], 0, v[132:133]
	v_lshl_add_u64 v[244:245], v[66:67], 0, v[132:133]
	v_lshl_add_u64 v[244:245], v[244:245], 2, s[22:23]
	global_load_dwordx4 v[212:215], v[244:245], off nt
	global_load_dwordx4 v[216:219], v[244:245], off offset:64 nt
	global_load_dwordx4 v[220:223], v[244:245], off offset:128 nt
	global_load_dwordx4 v[224:227], v[244:245], off offset:192 nt
	global_load_dwordx4 v[228:231], v[244:245], off offset:256 nt
	global_load_dwordx4 v[232:235], v[244:245], off offset:320 nt
	global_load_dwordx4 v[236:239], v[244:245], off offset:384 nt
	global_load_dwordx4 v[240:243], v[244:245], off offset:448 nt
	v_add_f32_e32 v62, 0, v62
	v_add_f32_e32 v63, 0, v63
	v_add_f32_e32 v64, 0, v64
	v_add_f32_e32 v65, 0, v65
	s_waitcnt vmcnt(7)
	v_fma_f32 v62, v62, v180, v212
	v_fma_f32 v63, v63, v181, v213
	v_fma_f32 v64, v64, v182, v214
	v_fma_f32 v75, v65, v183, v215
	v_cvt_pk_bf16_f32 v62, v62, v63
	v_cvt_pk_bf16_f32 v63, v64, v75
	v_lshl_add_u64 v[72:73], v[66:67], 0, v[132:133]
	v_add_f32_e32 v58, 0, v58
	v_add_f32_e32 v59, 0, v59
	v_add_f32_e32 v60, 0, v60
	v_add_f32_e32 v61, 0, v61
	s_waitcnt vmcnt(6)
	v_fma_f32 v58, v58, v184, v216
	v_fma_f32 v59, v59, v185, v217
	v_fma_f32 v60, v60, v186, v218
	v_fma_f32 v71, v61, v187, v219
	v_cvt_pk_bf16_f32 v64, v58, v59
	v_cvt_pk_bf16_f32 v65, v60, v71
	v_lshl_add_u64 v[60:61], v[72:73], 1, s[20:21]
	s_nop 1
	v_permlane16_swap_b32 v62, v64
	v_permlane16_swap_b32 v63, v65
	v_lshl_add_u64 v[248:249], v[60:61], 0, v[246:247]
	s_nop 0
	global_store_dwordx4 v[248:249], v[62:65], off
	s_nop 1
	v_lshl_add_u64 v[68:69], v[66:67], 0, v[132:133]
	v_add_f32_e32 v54, 0, v54
	v_add_f32_e32 v55, 0, v55
	v_add_f32_e32 v56, 0, v56
	v_add_f32_e32 v57, 0, v57
	s_waitcnt vmcnt(6)
	v_fma_f32 v54, v54, v188, v220
	v_fma_f32 v55, v55, v189, v221
	v_fma_f32 v56, v56, v190, v222
	v_fma_f32 v65, v57, v191, v223
	v_cvt_pk_bf16_f32 v54, v54, v55
	v_cvt_pk_bf16_f32 v55, v56, v65
	v_lshl_add_u64 v[62:63], v[66:67], 0, v[132:133]
	v_add_f32_e32 v50, 0, v50
	v_add_f32_e32 v51, 0, v51
	v_add_f32_e32 v52, 0, v52
	v_add_f32_e32 v53, 0, v53
	s_waitcnt vmcnt(5)
	v_fma_f32 v50, v50, v192, v224
	v_fma_f32 v51, v51, v193, v225
	v_fma_f32 v52, v52, v194, v226
	v_fma_f32 v61, v53, v195, v227
	v_cvt_pk_bf16_f32 v56, v50, v51
	v_cvt_pk_bf16_f32 v57, v52, v61
	v_lshl_add_u64 v[52:53], v[62:63], 1, s[20:21]
	s_nop 1
	v_permlane16_swap_b32 v54, v56
	v_permlane16_swap_b32 v55, v57
	v_lshl_add_u64 v[248:249], v[52:53], 0, v[246:247]
	s_nop 0
	global_store_dwordx4 v[248:249], v[54:57], off offset:64
	s_nop 1
	v_lshl_add_u64 v[58:59], v[66:67], 0, v[132:133]
	v_add_f32_e32 v46, 0, v46
	v_add_f32_e32 v47, 0, v47
	v_add_f32_e32 v48, 0, v48
	v_add_f32_e32 v49, 0, v49
	s_waitcnt vmcnt(5)
	v_fma_f32 v46, v46, v196, v228
	v_fma_f32 v47, v47, v197, v229
	v_fma_f32 v48, v48, v198, v230
	v_fma_f32 v57, v49, v199, v231
	v_cvt_pk_bf16_f32 v46, v46, v47
	v_cvt_pk_bf16_f32 v47, v48, v57
	v_lshl_add_u64 v[54:55], v[66:67], 0, v[132:133]
	v_add_f32_e32 v42, 0, v42
	v_add_f32_e32 v43, 0, v43
	v_add_f32_e32 v44, 0, v44
	v_add_f32_e32 v45, 0, v45
	s_waitcnt vmcnt(4)
	v_fma_f32 v42, v42, v200, v232
	v_fma_f32 v43, v43, v201, v233
	v_fma_f32 v44, v44, v202, v234
	v_fma_f32 v53, v45, v203, v235
	v_cvt_pk_bf16_f32 v48, v42, v43
	v_cvt_pk_bf16_f32 v49, v44, v53
	v_lshl_add_u64 v[44:45], v[54:55], 1, s[20:21]
	s_nop 1
	v_permlane16_swap_b32 v46, v48
	v_permlane16_swap_b32 v47, v49
	v_lshl_add_u64 v[248:249], v[44:45], 0, v[246:247]
	s_nop 0
	global_store_dwordx4 v[248:249], v[46:49], off offset:128
	s_nop 1
	v_lshl_add_u64 v[50:51], v[66:67], 0, v[132:133]
	v_add_f32_e32 v38, 0, v38
	v_add_f32_e32 v39, 0, v39
	v_add_f32_e32 v40, 0, v40
	v_add_f32_e32 v41, 0, v41
	s_waitcnt vmcnt(4)
	v_fma_f32 v38, v38, v204, v236
	v_fma_f32 v39, v39, v205, v237
	v_fma_f32 v40, v40, v206, v238
	v_fma_f32 v49, v41, v207, v239
	v_cvt_pk_bf16_f32 v38, v38, v39
	v_cvt_pk_bf16_f32 v39, v40, v49
	v_lshl_add_u64 v[46:47], v[66:67], 0, v[132:133]
	v_add_f32_e32 v34, 0, v34
	v_add_f32_e32 v35, 0, v35
	v_add_f32_e32 v36, 0, v36
	v_add_f32_e32 v37, 0, v37
	s_waitcnt vmcnt(3)
; __device__ __forceinline__ unsigned pack2(float a, float b) { unsigned r; asm("v_cvt_pk_bf16_f32 %0, %1, %2" : "=v"(r) : "v"(a), "v"(b)); return r; }
; __device__ __forceinline__ float bf2f(bf16_t h) { return __uint_as_float(((unsigned)h) << 16); }
;   __device__ __forceinline__ void c4(int g, int rig, int col, f32x4 v) const {
;     const size_t o = ((size_t)g * 2048 + rig) * 1024 + col;
;     f32x4 bs;
;     if (BASE_F32) bs = __builtin_nontemporal_load((const f32x4*)((const float*)base + o));
;     else {
;       const uint2 u = *(const uint2*)((const bf16_t*)base + o);
;       bs[0] = bf2f((bf16_t)(u.x & 0xffff)); bs[1] = bf2f((bf16_t)(u.x >> 16)); bs[2] = bf2f((bf16_t)(u.y & 0xffff)); bs[3] = bf2f((bf16_t)(u.y >> 16));
;     }
;     const f32x4 gt = *(const f32x4*)(gate + (size_t)g * 6144 + col);
;     f32x4 bi = {0.f, 0.f, 0.f, 0.f};
;     if (bias) bi = *(const f32x4*)(bias + col);
;     f32x4 r;
; #pragma unroll
;     for (int j = 0; j < 4; ++j) r[j] = bs[j] + gt[j] * (v[j] + bi[j]);
;     uint2 w; w.x = pack2(r[0], r[1]); w.y = pack2(r[2], r[3]);
;     *(uint2*)(X16 + o) = w;
;   }
; template <bool SWAP, class Epi, bool THIN = false> ...
;     ...
; #pragma unroll
;           for (int n = 0; n < 8; ++n) {
;             const int col = nt * 256 + wc_e * 128 + n * 16 + fq_e * 4;
;             if (col < N) epi.c4(g, rig, col, acc[m][n]);
	v_fma_f32 v34, v34, v208, v240
	v_fma_f32 v35, v35, v209, v241
	v_fma_f32 v36, v36, v210, v242
	v_fma_f32 v45, v37, v211, v243
	v_cvt_pk_bf16_f32 v40, v34, v35
	v_cvt_pk_bf16_f32 v41, v36, v45
	v_lshl_add_u64 v[36:37], v[46:47], 1, s[20:21]
	s_nop 1
	v_permlane16_swap_b32 v38, v40
	v_permlane16_swap_b32 v39, v41
	v_lshl_add_u64 v[248:249], v[36:37], 0, v[246:247]
	s_nop 0
	global_store_dwordx4 v[248:249], v[38:41], off offset:192
	s_nop 1
	v_or_b32_e32 v34, 48, v136
	v_ashrrev_i32_e32 v35, 31, v34
	v_lshlrev_b64 v[34:35], 10, v[34:35]
	v_lshl_add_u64 v[34:35], v[34:35], 0, v[138:139]
	v_lshl_add_u64 v[44:45], v[34:35], 0, v[132:133]
	v_lshl_add_u64 v[244:245], v[34:35], 0, v[132:133]
	v_lshl_add_u64 v[244:245], v[244:245], 2, s[22:23]
	global_load_dwordx4 v[212:215], v[244:245], off nt
	global_load_dwordx4 v[216:219], v[244:245], off offset:64 nt
	global_load_dwordx4 v[220:223], v[244:245], off offset:128 nt
	global_load_dwordx4 v[224:227], v[244:245], off offset:192 nt
	global_load_dwordx4 v[228:231], v[244:245], off offset:256 nt
	global_load_dwordx4 v[232:235], v[244:245], off offset:320 nt
	global_load_dwordx4 v[236:239], v[244:245], off offset:384 nt
	global_load_dwordx4 v[240:243], v[244:245], off offset:448 nt
	v_add_f32_e32 v30, 0, v30
	v_add_f32_e32 v31, 0, v31
	v_add_f32_e32 v32, 0, v32
	v_add_f32_e32 v33, 0, v33
	s_waitcnt vmcnt(7)
	v_fma_f32 v30, v30, v180, v212
	v_fma_f32 v31, v31, v181, v213
	v_fma_f32 v32, v32, v182, v214
	v_fma_f32 v43, v33, v183, v215
	v_cvt_pk_bf16_f32 v30, v30, v31
	v_cvt_pk_bf16_f32 v31, v32, v43
	v_lshl_add_u64 v[40:41], v[34:35], 0, v[132:133]
	v_add_f32_e32 v26, 0, v26
	v_add_f32_e32 v27, 0, v27
	v_add_f32_e32 v28, 0, v28
	v_add_f32_e32 v29, 0, v29
	s_waitcnt vmcnt(6)
	v_fma_f32 v26, v26, v184, v216
	v_fma_f32 v27, v27, v185, v217
	v_fma_f32 v28, v28, v186, v218
	v_fma_f32 v39, v29, v187, v219
	v_cvt_pk_bf16_f32 v32, v26, v27
	v_cvt_pk_bf16_f32 v33, v28, v39
	v_lshl_add_u64 v[28:29], v[40:41], 1, s[20:21]
	s_nop 1
	v_permlane16_swap_b32 v30, v32
	v_permlane16_swap_b32 v31, v33
	v_lshl_add_u64 v[248:249], v[28:29], 0, v[246:247]
	s_nop 0
	global_store_dwordx4 v[248:249], v[30:33], off
	s_nop 1
	v_lshl_add_u64 v[36:37], v[34:35], 0, v[132:133]
	v_add_f32_e32 v22, 0, v22
	v_add_f32_e32 v23, 0, v23
	v_add_f32_e32 v24, 0, v24
	v_add_f32_e32 v25, 0, v25
	s_waitcnt vmcnt(6)
	v_fma_f32 v22, v22, v188, v220
	v_fma_f32 v23, v23, v189, v221
	v_fma_f32 v24, v24, v190, v222
	v_fma_f32 v33, v25, v191, v223
	v_cvt_pk_bf16_f32 v22, v22, v23
	v_cvt_pk_bf16_f32 v23, v24, v33
	v_lshl_add_u64 v[30:31], v[34:35], 0, v[132:133]
	v_add_f32_e32 v18, 0, v18
	v_add_f32_e32 v19, 0, v19
	v_add_f32_e32 v20, 0, v20
	v_add_f32_e32 v21, 0, v21
	s_waitcnt vmcnt(5)
	v_fma_f32 v18, v18, v192, v224
	v_fma_f32 v19, v19, v193, v225
	v_fma_f32 v20, v20, v194, v226
	v_fma_f32 v29, v21, v195, v227
	v_cvt_pk_bf16_f32 v24, v18, v19
	v_cvt_pk_bf16_f32 v25, v20, v29
	v_lshl_add_u64 v[20:21], v[30:31], 1, s[20:21]
	s_nop 1
	v_permlane16_swap_b32 v22, v24
	v_permlane16_swap_b32 v23, v25
	v_lshl_add_u64 v[248:249], v[20:21], 0, v[246:247]
	s_nop 0
	global_store_dwordx4 v[248:249], v[22:25], off offset:64
	s_nop 1
	v_lshl_add_u64 v[26:27], v[34:35], 0, v[132:133]
	v_add_f32_e32 v14, 0, v14
	v_add_f32_e32 v15, 0, v15
	v_add_f32_e32 v16, 0, v16
	v_add_f32_e32 v17, 0, v17
	s_waitcnt vmcnt(5)
	v_fma_f32 v14, v14, v196, v228
	v_fma_f32 v15, v15, v197, v229
	v_fma_f32 v16, v16, v198, v230
	v_fma_f32 v25, v17, v199, v231
	v_cvt_pk_bf16_f32 v14, v14, v15
	v_cvt_pk_bf16_f32 v15, v16, v25
	v_lshl_add_u64 v[22:23], v[34:35], 0, v[132:133]
	v_add_f32_e32 v6, 0, v6
	v_add_f32_e32 v7, 0, v7
	v_add_f32_e32 v8, 0, v8
	v_add_f32_e32 v9, 0, v9
	s_waitcnt vmcnt(4)
	v_fma_f32 v6, v6, v200, v232
	v_fma_f32 v7, v7, v201, v233
	v_fma_f32 v8, v8, v202, v234
	v_fma_f32 v21, v9, v203, v235
	v_cvt_pk_bf16_f32 v16, v6, v7
	v_cvt_pk_bf16_f32 v17, v8, v21
	v_lshl_add_u64 v[8:9], v[22:23], 1, s[20:21]
	s_nop 1
	v_permlane16_swap_b32 v14, v16
	v_permlane16_swap_b32 v15, v17
	v_lshl_add_u64 v[248:249], v[8:9], 0, v[246:247]
	s_nop 0
	global_store_dwordx4 v[248:249], v[14:17], off offset:128
	s_nop 1
	v_lshl_add_u64 v[18:19], v[34:35], 0, v[132:133]
	v_add_f32_e32 v10, 0, v10
	v_add_f32_e32 v11, 0, v11
	v_add_f32_e32 v12, 0, v12
	v_add_f32_e32 v13, 0, v13
	s_waitcnt vmcnt(4)
	v_fma_f32 v6, v10, v204, v236
	v_fma_f32 v7, v11, v205, v237
	v_fma_f32 v8, v12, v206, v238
	v_fma_f32 v17, v13, v207, v239
	v_cvt_pk_bf16_f32 v6, v6, v7
	v_cvt_pk_bf16_f32 v7, v8, v17
	v_lshl_add_u64 v[14:15], v[34:35], 0, v[132:133]
	v_add_f32_e32 v2, 0, v2
	v_add_f32_e32 v3, 0, v3
	v_add_f32_e32 v4, 0, v4
	v_add_f32_e32 v5, 0, v5
	s_waitcnt vmcnt(3)
	v_fma_f32 v2, v2, v208, v240
	v_fma_f32 v3, v3, v209, v241
	v_fma_f32 v4, v4, v210, v242
	v_fma_f32 v13, v5, v211, v243
	v_cvt_pk_bf16_f32 v8, v2, v3
	v_cvt_pk_bf16_f32 v9, v4, v13
	v_lshl_add_u64 v[4:5], v[14:15], 1, s[20:21]
	s_nop 1
	v_permlane16_swap_b32 v6, v8
	v_permlane16_swap_b32 v7, v9
	v_lshl_add_u64 v[248:249], v[4:5], 0, v[246:247]
	s_nop 0
	global_store_dwordx4 v[248:249], v[6:9], off offset:192
	s_nop 1
	s_branch .LBB0_2114

; template <bool SWAP, class Epi, bool THIN = false> ...
;     ...
;     for (int st = 0; st < ns; ++st) {
;       asm volatile("s_waitcnt vmcnt(0)" ::: "memory");
;       __builtin_amdgcn_s_barrier();
;       asm volatile("" ::: "memory");
;       if (st + 1 < ns) {
;         char* nb = smem + ((st + 1) & 1) * 65536;
;         const int ko = (st + 1) * 64;
; #pragma unroll
;         for (int i = 0; i < 4; ++i) { GLDS16(A + (size_t)(ap[i] + ko), nb + tid * 16 + i * 8192); GLDS16(Bt + (size_t)(bp[i] + ko), nb + 32768 + tid * 16 + i * 8192); }
;       }
;       const char* sa = smem + (st & 1) * 65536 + (wr * 64 + fr) * 128;
;       const char* sb = smem + (st & 1) * 65536 + 32768 + (wc * 128 + fr) * 128;
;       if constexpr (THIN) {
;         if (wc == 0) {
; #pragma unroll
;           for (int ks = 0; ks < 2; ++ks) {
;             bf16x8 af[4], bf[2];
; #pragma unroll
;             for (int m = 0; m < 4; ++m) af[m] = *(const bf16x8*)(sa + m * 2048 + (((ks * 4 + fq) ^ swz) << 4));
; #pragma unroll
;             for (int n = 0; n < 2; ++n) bf[n] = *(const bf16x8*)(sb + n * 2048 + (((ks * 4 + fq) ^ swz) << 4));
; #pragma unroll
;             for (int m = 0; m < 4; ++m)
; #pragma unroll
;               for (int n = 0; n < 2; ++n)
;                 acc[m][n] = SWAP ? __builtin_amdgcn_mfma_f32_16x16x32_bf16(bf[n], af[m], acc[m][n], 0, 0, 0)
;                                  : __builtin_amdgcn_mfma_f32_16x16x32_bf16(af[m], bf[n], acc[m][n], 0, 0, 0);
;           }
;         }
;       } else {
;       bf16x8 afA[4], afB[4], bfb[2][2];
; #pragma unroll
;       for (int m = 0; m < 4; ++m) afA[m] = *(const bf16x8*)(sa + m * 2048 + ((fq ^ swz) << 4));
; #pragma unroll
;       for (int n = 0; n < 2; ++n) bfb[0][n] = *(const bf16x8*)(sb + n * 2048 + ((fq ^ swz) << 4));
; #pragma unroll
;       for (int gq = 0; gq < 8; ++gq) {
;         const int ks = gq >> 2, nh = gq & 3;
;         if (gq < 7) {
;           const int ks2 = (gq + 1) >> 2, nh2 = (gq + 1) & 3;
; #pragma unroll
;           for (int n = 0; n < 2; ++n) bfb[(gq + 1) & 1][n] = *(const bf16x8*)(sb + (nh2 * 2 + n) * 2048 + (((ks2 * 4 + fq) ^ swz) << 4));
;         }
;         if (gq == 3) {
; #pragma unroll
;           for (int m = 0; m < 4; ++m) afB[m] = *(const bf16x8*)(sa + m * 2048 + (((4 + fq) ^ swz) << 4));
;         }
;         __builtin_amdgcn_sched_barrier(0);
; #pragma unroll
.LBB0_2334:
	s_add_i32 s8, s7, 0x10000
	s_and_b32 s9, s8, 0x10000
	v_add_u32_e32 v170, s9, v135
	s_nop 0
	v_readfirstlane_b32 s9, v170
	s_and_b32 s7, s7, 0x10000
	v_or_b32_e32 v204, s7, v139
	v_add_u32_e32 v205, v204, v140
	v_add_u32_e32 v136, s7, v138
	v_add_u32_e32 v180, v136, v140
	s_waitcnt vmcnt(0)
	s_barrier
	ds_read_b128 v[168:171], v180
	ds_read_b128 v[172:175], v180 offset:2048
	ds_read_b128 v[176:179], v180 offset:4096
	ds_read_b128 v[180:183], v180 offset:6144
	ds_read_b128 v[184:187], v205 offset:32768
	ds_read_b128 v[188:191], v205 offset:34816
	ds_read_b128 v[192:195], v205 offset:36864
	ds_read_b128 v[196:199], v205 offset:38912
	v_add_u32_e32 v136, v136, v141
	s_waitcnt lgkmcnt(3)
	v_mfma_f32_16x16x32_bf16 v[126:129], v[184:187], v[168:171], v[126:129]
	s_mov_b32 m0, s9
	v_mfma_f32_16x16x32_bf16 v[110:113], v[184:187], v[172:175], v[110:113]
	global_load_lds_dwordx4 v167, s[16:17]
	v_add_u32_e32 v167, 0x80, v167
	v_mfma_f32_16x16x32_bf16 v[82:85], v[184:187], v[176:179], v[82:85]
	v_mfma_f32_16x16x32_bf16 v[50:53], v[184:187], v[180:183], v[50:53]
	ds_read_b128 v[184:187], v205 offset:40960
	ds_read_b128 v[200:203], v205 offset:43008
	s_waitcnt lgkmcnt(4)
	v_mfma_f32_16x16x32_bf16 v[122:125], v[188:191], v[168:171], v[122:125]
	s_add_u32 m0, s9, 0x8000
	v_mfma_f32_16x16x32_bf16 v[106:109], v[188:191], v[172:175], v[106:109]
	global_load_lds_dwordx4 v166, s[18:19]
	v_add_u32_e32 v166, 0x80, v166
	v_mfma_f32_16x16x32_bf16 v[78:81], v[188:191], v[176:179], v[78:81]
	v_mfma_f32_16x16x32_bf16 v[42:45], v[188:191], v[180:183], v[42:45]
	s_waitcnt lgkmcnt(3)
	v_mfma_f32_16x16x32_bf16 v[118:121], v[192:195], v[168:171], v[118:121]
	s_add_u32 m0, s9, 0x2000
	v_mfma_f32_16x16x32_bf16 v[94:97], v[192:195], v[172:175], v[94:97]
	global_load_lds_dwordx4 v165, s[16:17]
	v_add_u32_e32 v165, 0x80, v165
	v_mfma_f32_16x16x32_bf16 v[58:61], v[192:195], v[176:179], v[58:61]
	v_mfma_f32_16x16x32_bf16 v[26:29], v[192:195], v[180:183], v[26:29]
	ds_read_b128 v[188:191], v205 offset:45056
	ds_read_b128 v[192:195], v205 offset:47104
	s_waitcnt lgkmcnt(4)
	v_mfma_f32_16x16x32_bf16 v[114:117], v[196:199], v[168:171], v[114:117]
	s_add_u32 m0, s9, 0xa000
	v_mfma_f32_16x16x32_bf16 v[90:93], v[196:199], v[172:175], v[90:93]
	global_load_lds_dwordx4 v164, s[18:19]
	v_add_u32_e32 v164, 0x80, v164
	v_mfma_f32_16x16x32_bf16 v[54:57], v[196:199], v[176:179], v[54:57]
	v_mfma_f32_16x16x32_bf16 v[22:25], v[196:199], v[180:183], v[22:25]
	v_add_u32_e32 v220, v204, v141
	s_waitcnt lgkmcnt(3)
	v_mfma_f32_16x16x32_bf16 v[102:105], v[184:187], v[168:171], v[102:105]
	ds_read_b128 v[196:199], v220 offset:32768
	ds_read_b128 v[204:207], v220 offset:34816
	s_add_u32 m0, s9, 0x4000
	v_mfma_f32_16x16x32_bf16 v[74:77], v[184:187], v[172:175], v[74:77]
	global_load_lds_dwordx4 v163, s[16:17]
	v_add_u32_e32 v163, 0x80, v163
	v_mfma_f32_16x16x32_bf16 v[46:49], v[184:187], v[176:179], v[46:49]
	v_mfma_f32_16x16x32_bf16 v[10:13], v[184:187], v[180:183], v[10:13]
	ds_read_b128 v[184:187], v136
	ds_read_b128 v[208:211], v136 offset:2048
	ds_read_b128 v[212:215], v136 offset:4096
	ds_read_b128 v[216:219], v136 offset:6144
	s_waitcnt lgkmcnt(8)
	v_mfma_f32_16x16x32_bf16 v[98:101], v[200:203], v[168:171], v[98:101]
	s_add_u32 m0, s9, 0xc000
	v_mfma_f32_16x16x32_bf16 v[66:69], v[200:203], v[172:175], v[66:69]
	global_load_lds_dwordx4 v162, s[18:19]
	v_add_u32_e32 v162, 0x80, v162
	v_mfma_f32_16x16x32_bf16 v[30:33], v[200:203], v[176:179], v[30:33]
	v_mfma_f32_16x16x32_bf16 v[6:9], v[200:203], v[180:183], v[6:9]
	s_waitcnt lgkmcnt(7)
	v_mfma_f32_16x16x32_bf16 v[70:73], v[188:191], v[168:171], v[70:73]
	s_add_u32 m0, s9, 0x6000
	s_waitcnt lgkmcnt(6)
	v_mfma_f32_16x16x32_bf16 v[62:65], v[192:195], v[168:171], v[62:65]
	global_load_lds_dwordx4 v161, s[16:17]
	v_add_u32_e32 v161, 0x80, v161
	v_mfma_f32_16x16x32_bf16 v[38:41], v[188:191], v[172:175], v[38:41]
	v_mfma_f32_16x16x32_bf16 v[34:37], v[192:195], v[172:175], v[34:37]
	ds_read_b128 v[168:171], v220 offset:36864
	ds_read_b128 v[172:175], v220 offset:38912
	v_mfma_f32_16x16x32_bf16 v[18:21], v[188:191], v[176:179], v[18:21]
	s_add_u32 m0, s9, 0xe000
	v_mfma_f32_16x16x32_bf16 v[14:17], v[192:195], v[176:179], v[14:17]
	global_load_lds_dwordx4 v160, s[18:19]
	v_add_u32_e32 v160, 0x80, v160
	v_mfma_f32_16x16x32_bf16 v[2:5], v[188:191], v[180:183], v[2:5]
	v_mfma_f32_16x16x32_bf16 v[86:89], v[192:195], v[180:183], v[86:89]
	ds_read_b128 v[176:179], v220 offset:40960
	ds_read_b128 v[180:183], v220 offset:43008
	s_waitcnt lgkmcnt(7)
	v_mfma_f32_16x16x32_bf16 v[126:129], v[196:199], v[184:187], v[126:129]
	v_mfma_f32_16x16x32_bf16 v[122:125], v[204:207], v[184:187], v[122:125]
	s_waitcnt lgkmcnt(6)
	v_mfma_f32_16x16x32_bf16 v[110:113], v[196:199], v[208:211], v[110:113]
	v_mfma_f32_16x16x32_bf16 v[106:109], v[204:207], v[208:211], v[106:109]
	s_waitcnt lgkmcnt(5)
	v_mfma_f32_16x16x32_bf16 v[82:85], v[196:199], v[212:215], v[82:85]
	v_mfma_f32_16x16x32_bf16 v[78:81], v[204:207], v[212:215], v[78:81]
	s_waitcnt lgkmcnt(4)
	v_mfma_f32_16x16x32_bf16 v[50:53], v[196:199], v[216:219], v[50:53]
	v_mfma_f32_16x16x32_bf16 v[42:45], v[204:207], v[216:219], v[42:45]
	s_waitcnt lgkmcnt(3)
	v_mfma_f32_16x16x32_bf16 v[118:121], v[168:171], v[184:187], v[118:121]
	v_mfma_f32_16x16x32_bf16 v[94:97], v[168:171], v[208:211], v[94:97]
	v_mfma_f32_16x16x32_bf16 v[58:61], v[168:171], v[212:215], v[58:61]
	v_mfma_f32_16x16x32_bf16 v[26:29], v[168:171], v[216:219], v[26:29]
	ds_read_b128 v[168:171], v220 offset:45056
	ds_read_b128 v[188:191], v220 offset:47104
	s_waitcnt lgkmcnt(4)
; template <bool SWAP, class Epi, bool THIN = false> ...
;     ...
;     for (int st = 0; st < ns; ++st) {
;       asm volatile("s_waitcnt vmcnt(0)" ::: "memory");
;       __builtin_amdgcn_s_barrier();
;       asm volatile("" ::: "memory");
;       if (st + 1 < ns) {
;         char* nb = smem + ((st + 1) & 1) * 65536;
;         const int ko = (st + 1) * 64;
; #pragma unroll
;         for (int i = 0; i < 4; ++i) { GLDS16(A + (size_t)(ap[i] + ko), nb + tid * 16 + i * 8192); GLDS16(Bt + (size_t)(bp[i] + ko), nb + 32768 + tid * 16 + i * 8192); }
;       }
;       const char* sa = smem + (st & 1) * 65536 + (wr * 64 + fr) * 128;
;       const char* sb = smem + (st & 1) * 65536 + 32768 + (wc * 128 + fr) * 128;
;       if constexpr (THIN) {
;         if (wc == 0) {
; #pragma unroll
;           for (int ks = 0; ks < 2; ++ks) {
;             bf16x8 af[4], bf[2];
; #pragma unroll
;             for (int m = 0; m < 4; ++m) af[m] = *(const bf16x8*)(sa + m * 2048 + (((ks * 4 + fq) ^ swz) << 4));
; #pragma unroll
;             for (int n = 0; n < 2; ++n) bf[n] = *(const bf16x8*)(sb + n * 2048 + (((ks * 4 + fq) ^ swz) << 4));
; #pragma unroll
;             for (int m = 0; m < 4; ++m)
; #pragma unroll
;               for (int n = 0; n < 2; ++n)
;                 acc[m][n] = SWAP ? __builtin_amdgcn_mfma_f32_16x16x32_bf16(bf[n], af[m], acc[m][n], 0, 0, 0)
;                                  : __builtin_amdgcn_mfma_f32_16x16x32_bf16(af[m], bf[n], acc[m][n], 0, 0, 0);
;           }
;         }
;       } else {
;       bf16x8 afA[4], afB[4], bfb[2][2];
; #pragma unroll
;       for (int m = 0; m < 4; ++m) afA[m] = *(const bf16x8*)(sa + m * 2048 + ((fq ^ swz) << 4));
; #pragma unroll
;       for (int n = 0; n < 2; ++n) bfb[0][n] = *(const bf16x8*)(sb + n * 2048 + ((fq ^ swz) << 4));
; #pragma unroll
;       for (int gq = 0; gq < 8; ++gq) {
;         const int ks = gq >> 2, nh = gq & 3;
;         if (gq < 7) {
;           const int ks2 = (gq + 1) >> 2, nh2 = (gq + 1) & 3;
; #pragma unroll
;           for (int n = 0; n < 2; ++n) bfb[(gq + 1) & 1][n] = *(const bf16x8*)(sb + (nh2 * 2 + n) * 2048 + (((ks2 * 4 + fq) ^ swz) << 4));
;         }
;         if (gq == 3) {
; #pragma unroll
;           for (int m = 0; m < 4; ++m) afB[m] = *(const bf16x8*)(sa + m * 2048 + (((4 + fq) ^ swz) << 4));
;         }
;         __builtin_amdgcn_sched_barrier(0);
; #pragma unroll
	v_mfma_f32_16x16x32_bf16 v[114:117], v[172:175], v[184:187], v[114:117]
	v_mfma_f32_16x16x32_bf16 v[90:93], v[172:175], v[208:211], v[90:93]
	v_mfma_f32_16x16x32_bf16 v[54:57], v[172:175], v[212:215], v[54:57]
	v_mfma_f32_16x16x32_bf16 v[22:25], v[172:175], v[216:219], v[22:25]
	s_waitcnt lgkmcnt(3)
	v_mfma_f32_16x16x32_bf16 v[102:105], v[176:179], v[184:187], v[102:105]
	s_waitcnt lgkmcnt(2)
	v_mfma_f32_16x16x32_bf16 v[98:101], v[180:183], v[184:187], v[98:101]
	v_mfma_f32_16x16x32_bf16 v[74:77], v[176:179], v[208:211], v[74:77]
	v_mfma_f32_16x16x32_bf16 v[66:69], v[180:183], v[208:211], v[66:69]
	v_mfma_f32_16x16x32_bf16 v[46:49], v[176:179], v[212:215], v[46:49]
	v_mfma_f32_16x16x32_bf16 v[30:33], v[180:183], v[212:215], v[30:33]
	v_mfma_f32_16x16x32_bf16 v[10:13], v[176:179], v[216:219], v[10:13]
	v_mfma_f32_16x16x32_bf16 v[6:9], v[180:183], v[216:219], v[6:9]
	s_waitcnt lgkmcnt(1)
	v_mfma_f32_16x16x32_bf16 v[70:73], v[168:171], v[184:187], v[70:73]
	s_add_i32 s5, s5, 64
	s_cmpk_eq_i32 s5, 0x3c0
	s_mov_b32 s7, s8
	s_waitcnt lgkmcnt(0)
	v_mfma_f32_16x16x32_bf16 v[62:65], v[188:191], v[184:187], v[62:65]
	v_mfma_f32_16x16x32_bf16 v[38:41], v[168:171], v[208:211], v[38:41]
	v_mfma_f32_16x16x32_bf16 v[34:37], v[188:191], v[208:211], v[34:37]
	v_mfma_f32_16x16x32_bf16 v[18:21], v[168:171], v[212:215], v[18:21]
	v_mfma_f32_16x16x32_bf16 v[14:17], v[188:191], v[212:215], v[14:17]
	v_mfma_f32_16x16x32_bf16 v[2:5], v[168:171], v[216:219], v[2:5]
	v_mfma_f32_16x16x32_bf16 v[86:89], v[188:191], v[216:219], v[86:89]
	s_cbranch_scc0 .LBB0_2334
	s_waitcnt vmcnt(0)
	s_barrier
	v_add_u32_e32 v136, v150, v140
	ds_read_b128 v[160:163], v136
	ds_read_b128 v[164:167], v136 offset:2048
	ds_read_b128 v[168:171], v136 offset:4096
	ds_read_b128 v[172:175], v136 offset:6144
	v_add_u32_e32 v136, v151, v140
	ds_read_b128 v[176:179], v136
	ds_read_b128 v[180:183], v136 offset:2048
	ds_read_b128 v[184:187], v136 offset:4096
	ds_read_b128 v[188:191], v136 offset:6144
	s_waitcnt lgkmcnt(0)
	v_mfma_f32_16x16x32_bf16 v[126:129], v[176:179], v[160:163], v[126:129]
	v_mfma_f32_16x16x32_bf16 v[110:113], v[176:179], v[164:167], v[110:113]
	v_mfma_f32_16x16x32_bf16 v[82:85], v[176:179], v[168:171], v[82:85]
	v_mfma_f32_16x16x32_bf16 v[50:53], v[176:179], v[172:175], v[50:53]
	ds_read_b128 v[176:179], v136 offset:8192
	ds_read_b128 v[192:195], v136 offset:10240
	v_mfma_f32_16x16x32_bf16 v[122:125], v[180:183], v[160:163], v[122:125]
	v_mfma_f32_16x16x32_bf16 v[106:109], v[180:183], v[164:167], v[106:109]
	v_mfma_f32_16x16x32_bf16 v[78:81], v[180:183], v[168:171], v[78:81]
	v_mfma_f32_16x16x32_bf16 v[42:45], v[180:183], v[172:175], v[42:45]
	v_mfma_f32_16x16x32_bf16 v[118:121], v[184:187], v[160:163], v[118:121]
	v_mfma_f32_16x16x32_bf16 v[94:97], v[184:187], v[164:167], v[94:97]
	v_mfma_f32_16x16x32_bf16 v[58:61], v[184:187], v[168:171], v[58:61]
	v_mfma_f32_16x16x32_bf16 v[26:29], v[184:187], v[172:175], v[26:29]
	ds_read_b128 v[180:183], v136 offset:12288
	ds_read_b128 v[184:187], v136 offset:14336
	v_mfma_f32_16x16x32_bf16 v[114:117], v[188:191], v[160:163], v[114:117]
	v_mfma_f32_16x16x32_bf16 v[90:93], v[188:191], v[164:167], v[90:93]
	v_mfma_f32_16x16x32_bf16 v[54:57], v[188:191], v[168:171], v[54:57]
	v_mfma_f32_16x16x32_bf16 v[22:25], v[188:191], v[172:175], v[22:25]
	v_add_u32_e32 v136, v151, v141
	v_add_u32_e32 v208, v150, v141
	s_waitcnt lgkmcnt(0)
	v_mfma_f32_16x16x32_bf16 v[102:105], v[176:179], v[160:163], v[102:105]
	v_mfma_f32_16x16x32_bf16 v[74:77], v[176:179], v[164:167], v[74:77]
	v_mfma_f32_16x16x32_bf16 v[188:191], v[192:195], v[164:167], v[66:69]
	v_mfma_f32_16x16x32_bf16 v[196:199], v[176:179], v[168:171], v[46:49]
	s_nop 2
	ds_read_b128 v[46:49], v136
	ds_read_b128 v[66:69], v136 offset:2048
	v_mfma_f32_16x16x32_bf16 v[10:13], v[176:179], v[172:175], v[10:13]
	ds_read_b128 v[176:179], v208
	ds_read_b128 v[200:203], v208 offset:2048
	ds_read_b128 v[204:207], v208 offset:4096
	ds_read_b128 v[208:211], v208 offset:6144
	v_mfma_f32_16x16x32_bf16 v[98:101], v[192:195], v[160:163], v[98:101]
	v_mfma_f32_16x16x32_bf16 v[30:33], v[192:195], v[168:171], v[30:33]
	v_mfma_f32_16x16x32_bf16 v[6:9], v[192:195], v[172:175], v[6:9]
	v_mfma_f32_16x16x32_bf16 v[192:195], v[180:183], v[164:167], v[38:41]
	v_mfma_f32_16x16x32_bf16 v[164:167], v[184:187], v[164:167], v[34:37]
	v_mfma_f32_16x16x32_bf16 v[18:21], v[180:183], v[168:171], v[18:21]
	v_mfma_f32_16x16x32_bf16 v[168:171], v[184:187], v[168:171], v[14:17]
	s_nop 2
	ds_read_b128 v[14:17], v136 offset:4096
	ds_read_b128 v[34:37], v136 offset:6144
	v_mfma_f32_16x16x32_bf16 v[70:73], v[180:183], v[160:163], v[70:73]
	v_mfma_f32_16x16x32_bf16 v[2:5], v[180:183], v[172:175], v[2:5]
	v_mfma_f32_16x16x32_bf16 v[160:163], v[184:187], v[160:163], v[62:65]
	v_mfma_f32_16x16x32_bf16 v[86:89], v[184:187], v[172:175], v[86:89]
	s_waitcnt lgkmcnt(0)
	v_mfma_f32_16x16x32_bf16 v[172:175], v[46:49], v[208:211], v[50:53]
	s_nop 2
	ds_read_b128 v[50:53], v136 offset:8192
	ds_read_b128 v[180:183], v136 offset:10240
	v_mfma_f32_16x16x32_bf16 v[126:129], v[46:49], v[176:179], v[126:129]
	v_mfma_f32_16x16x32_bf16 v[122:125], v[66:69], v[176:179], v[122:125]
	v_mfma_f32_16x16x32_bf16 v[110:113], v[46:49], v[200:203], v[110:113]
	v_mfma_f32_16x16x32_bf16 v[106:109], v[66:69], v[200:203], v[106:109]
	v_mfma_f32_16x16x32_bf16 v[82:85], v[46:49], v[204:207], v[82:85]
	v_mfma_f32_16x16x32_bf16 v[78:81], v[66:69], v[204:207], v[78:81]
	v_mfma_f32_16x16x32_bf16 v[184:187], v[66:69], v[208:211], v[42:45]
	ds_read_b128 v[224:227], v136 offset:12288
	ds_read_b128 v[228:231], v136 offset:14336
	v_mfma_f32_16x16x32_bf16 v[118:121], v[14:17], v[176:179], v[118:121]
	v_mfma_f32_16x16x32_bf16 v[114:117], v[34:37], v[176:179], v[114:117]
	v_mfma_f32_16x16x32_bf16 v[94:97], v[14:17], v[200:203], v[94:97]
	v_mfma_f32_16x16x32_bf16 v[90:93], v[34:37], v[200:203], v[90:93]
	v_mfma_f32_16x16x32_bf16 v[212:215], v[14:17], v[204:207], v[58:61]
	v_mfma_f32_16x16x32_bf16 v[216:219], v[34:37], v[204:207], v[54:57]
	v_mfma_f32_16x16x32_bf16 v[220:223], v[14:17], v[208:211], v[26:29]
	v_mfma_f32_16x16x32_bf16 v[66:69], v[34:37], v[208:211], v[22:25]
	s_waitcnt lgkmcnt(0)
	v_mfma_f32_16x16x32_bf16 v[38:41], v[180:183], v[204:207], v[30:33]
	v_mfma_f32_16x16x32_bf16 v[62:65], v[50:53], v[176:179], v[102:105]
	v_mfma_f32_16x16x32_bf16 v[46:49], v[180:183], v[176:179], v[98:101]
	v_mfma_f32_16x16x32_bf16 v[58:61], v[50:53], v[200:203], v[74:77]
	v_mfma_f32_16x16x32_bf16 v[42:45], v[180:183], v[200:203], v[188:191]
	v_mfma_f32_16x16x32_bf16 v[54:57], v[50:53], v[204:207], v[196:199]
	v_mfma_f32_16x16x32_bf16 v[50:53], v[50:53], v[208:211], v[10:13]
	v_mfma_f32_16x16x32_bf16 v[34:37], v[180:183], v[208:211], v[6:9]
	s_nop 2
	v_mov_b32_e32 v8, v1
	s_waitcnt vmcnt(0)
	v_mfma_f32_16x16x32_bf16 v[30:33], v[224:227], v[176:179], v[70:73]
	s_barrier
; __device__ __forceinline__ unsigned pack2(float a, float b) { unsigned r; asm("v_cvt_pk_bf16_f32 %0, %1, %2" : "=v"(r) : "v"(a), "v"(b)); return r; }
; template <bool SWAP, class Epi, bool THIN = false> ...
;     ...
;       bf16_t* Zw = (bf16_t*)smem + ((wr_e >> 1) * 2 + wc_e) * (128 * 132);
;       const int nt2w = nt * 2 + wc_e;
; #pragma unroll
;       for (int n = 0; n < 8; ++n) {
;         const int cl = n * 16 + fq_e * 4;
;         f32x4 b4 = {0.f, 0.f, 0.f, 0.f};
;         if (epi.pre_bias) b4 = *(const f32x4*)(epi.pre_bias + epi.norig(nt2w, cl));
; #pragma unroll
;         for (int m = 0; m < 4; ++m) {
;           const int rl = rw + m * 16 + fr_e;
;           const int pos = rig0 + rl;
;           const bool ok = pos >= 0 && pos < grows;
;           f32x4 vv = acc[m][n] + b4;
;           if (!ok) vv = (f32x4){0.f, 0.f, 0.f, 0.f};
;           uint2 u; u.x = pack2(vv[0], vv[1]); u.y = pack2(vv[2], vv[3]);
;           *(uint2*)(Zw + rl * 132 + cl) = u;
;         }
;       }
	v_mfma_f32_16x16x32_bf16 v[22:25], v[224:227], v[204:207], v[18:21]
	s_nop 0
	v_ashrrev_i32_e32 v71, 8, v8
	v_add_u32_e32 v6, s4, v71
	v_mul_hi_i32 v7, v6, s26
	v_lshrrev_b32_e32 v9, 31, v7
	v_ashrrev_i32_e32 v7, 3, v7
	v_add_u32_e32 v70, v7, v9
	v_and_b32_e32 v73, 15, v8
	v_mad_u64_u32 v[6:7], s[4:5], v70, s27, v[6:7]
	v_lshrrev_b32_e32 v75, 1, v8
	v_bfe_u32 v74, v8, 6, 1
	v_mul_lo_u32 v72, v6, s28
	v_and_or_b32 v73, v75, 64, v73
	v_add_u32_e32 v98, v72, v73
	v_lshl_or_b32 v74, v71, 1, v74
	v_mul_lo_u32 v74, v74, s29
	v_add_u32_e32 v99, -1, v98
	v_mfma_f32_16x16x32_bf16 v[18:21], v[224:227], v[208:211], v[2:5]
	v_add_f32_e64 v76, v126, 0
	v_add_f32_e64 v77, v127, 0
	v_cmp_gt_u32_e32 vcc, s30, v99
	s_lshl_b32 s24, s6, 7
	v_mfma_f32_16x16x32_bf16 v[2:5], v[228:231], v[208:211], v[86:89]
	v_add_f32_e64 v84, v84, 0
	v_add_f32_e64 v85, v85, 0
	v_pk_add_f32 v[82:83], v[82:83], 0 op_sel_hi:[1,0]
	v_pk_add_f32 v[66:67], v[66:67], 0 op_sel_hi:[1,0]
	v_and_or_b32 v86, v75, 24, v74
	v_pk_add_f32 v[74:75], v[128:129], 0 op_sel_hi:[1,0]
	v_add_u32_e32 v88, 15, v98
	v_cndmask_b32_e32 v87, 0, v74, vcc
	v_cndmask_b32_e32 v75, 0, v75, vcc
	v_cndmask_b32_e32 v74, 0, v76, vcc
	v_cndmask_b32_e32 v76, 0, v77, vcc
	v_cvt_pk_bf16_f32 v74, v74, v76
	v_cvt_pk_bf16_f32 v75, v87, v75
	v_mad_u32_u24 v73, v73, s31, v86
	v_pk_add_f32 v[76:77], v[112:113], 0 op_sel_hi:[1,0]
	v_pk_add_f32 v[86:87], v[110:111], 0 op_sel_hi:[1,0]
	v_cmp_gt_u32_e64 s[4:5], s30, v88
	v_mfma_f32_16x16x32_bf16 v[26:29], v[224:227], v[200:203], v[192:195]
	v_add_f32_e64 v62, v62, 0
	v_add_f32_e64 v63, v63, 0
	v_cndmask_b32_e64 v88, 0, v76, s[4:5]
	v_cndmask_b32_e64 v76, 0, v86, s[4:5]
	v_cndmask_b32_e64 v86, 0, v87, s[4:5]
	v_cvt_pk_bf16_f32 v76, v76, v86
	v_add_u32_e32 v86, 31, v98
	v_cndmask_b32_e64 v77, 0, v77, s[4:5]
	v_cmp_gt_u32_e64 s[6:7], s30, v86
	v_cvt_pk_bf16_f32 v77, v88, v77
	v_add_u32_e32 v88, 47, v98
	v_pk_add_f32 v[86:87], v[172:173], 0 op_sel_hi:[1,0]
	v_cndmask_b32_e64 v84, 0, v84, s[6:7]
	v_cndmask_b32_e64 v85, 0, v85, s[6:7]
	v_cndmask_b32_e64 v82, 0, v82, s[6:7]
	v_cndmask_b32_e64 v83, 0, v83, s[6:7]
	v_cvt_pk_bf16_f32 v82, v82, v83
	v_cvt_pk_bf16_f32 v83, v84, v85
	v_pk_add_f32 v[84:85], v[174:175], 0 op_sel_hi:[1,0]
	v_cmp_gt_u32_e64 s[8:9], s30, v88
	v_mfma_f32_16x16x32_bf16 v[14:17], v[228:231], v[176:179], v[160:163]
	v_add_f32_e64 v28, v28, 0
	v_add_f32_e64 v29, v29, 0
	v_cndmask_b32_e64 v88, 0, v84, s[8:9]
	v_cndmask_b32_e64 v85, 0, v85, s[8:9]
	v_cndmask_b32_e64 v84, 0, v86, s[8:9]
	v_cndmask_b32_e64 v86, 0, v87, s[8:9]
	v_cvt_pk_bf16_f32 v84, v84, v86
	v_cvt_pk_bf16_f32 v85, v88, v85
	v_pk_add_f32 v[86:87], v[124:125], 0 op_sel_hi:[1,0]
	v_pk_add_f32 v[88:89], v[122:123], 0 op_sel_hi:[1,0]
	v_cndmask_b32_e32 v98, 0, v86, vcc
	v_cndmask_b32_e32 v87, 0, v87, vcc
	v_cndmask_b32_e32 v86, 0, v88, vcc
	v_cndmask_b32_e32 v88, 0, v89, vcc
	v_cvt_pk_bf16_f32 v86, v86, v88
	v_cvt_pk_bf16_f32 v87, v98, v87
	ds_write2_b64 v73, v[74:75], v[86:87] offset1:4
	v_pk_add_f32 v[74:75], v[108:109], 0 op_sel_hi:[1,0]
	v_pk_add_f32 v[86:87], v[106:107], 0 op_sel_hi:[1,0]
	v_cndmask_b32_e64 v88, 0, v74, s[4:5]
	v_cndmask_b32_e64 v75, 0, v75, s[4:5]
	v_cndmask_b32_e64 v74, 0, v86, s[4:5]
	v_cndmask_b32_e64 v86, 0, v87, s[4:5]
	v_cvt_pk_bf16_f32 v74, v74, v86
	v_cvt_pk_bf16_f32 v75, v88, v75
	v_add_u32_e32 v86, 0x1000, v73
	ds_write2_b64 v86, v[76:77], v[74:75] offset0:16 offset1:20
	v_pk_add_f32 v[74:75], v[80:81], 0 op_sel_hi:[1,0]
	v_pk_add_f32 v[76:77], v[78:79], 0 op_sel_hi:[1,0]
	v_cndmask_b32_e64 v78, 0, v74, s[6:7]
	v_cndmask_b32_e64 v75, 0, v75, s[6:7]
	v_cndmask_b32_e64 v74, 0, v76, s[6:7]
	v_cndmask_b32_e64 v76, 0, v77, s[6:7]
	v_cvt_pk_bf16_f32 v74, v74, v76
	v_cvt_pk_bf16_f32 v75, v78, v75
	v_add_u32_e32 v87, 0x2000, v73
	ds_write2_b64 v87, v[82:83], v[74:75] offset0:32 offset1:36
	v_pk_add_f32 v[74:75], v[186:187], 0 op_sel_hi:[1,0]
	v_pk_add_f32 v[76:77], v[184:185], 0 op_sel_hi:[1,0]
	v_cndmask_b32_e64 v78, 0, v74, s[8:9]
	v_cndmask_b32_e64 v75, 0, v75, s[8:9]
	v_cndmask_b32_e64 v74, 0, v76, s[8:9]
	v_cndmask_b32_e64 v76, 0, v77, s[8:9]
	v_cvt_pk_bf16_f32 v74, v74, v76
	v_cvt_pk_bf16_f32 v75, v78, v75
	v_add_u32_e32 v88, 0x3000, v73
	ds_write2_b64 v88, v[84:85], v[74:75] offset0:48 offset1:52
	v_pk_add_f32 v[74:75], v[120:121], 0 op_sel_hi:[1,0]
	v_pk_add_f32 v[76:77], v[118:119], 0 op_sel_hi:[1,0]
	v_cndmask_b32_e32 v78, 0, v74, vcc
	v_cndmask_b32_e32 v75, 0, v75, vcc
	v_cndmask_b32_e32 v74, 0, v76, vcc
	v_cndmask_b32_e32 v76, 0, v77, vcc
	v_cvt_pk_bf16_f32 v74, v74, v76
	v_cvt_pk_bf16_f32 v75, v78, v75
	v_pk_add_f32 v[76:77], v[96:97], 0 op_sel_hi:[1,0]
	v_pk_add_f32 v[78:79], v[94:95], 0 op_sel_hi:[1,0]
	v_cndmask_b32_e64 v80, 0, v76, s[4:5]
	v_cndmask_b32_e64 v77, 0, v77, s[4:5]
	v_cndmask_b32_e64 v76, 0, v78, s[4:5]
	v_cndmask_b32_e64 v78, 0, v79, s[4:5]
	v_cvt_pk_bf16_f32 v76, v76, v78
	v_cvt_pk_bf16_f32 v77, v80, v77
	v_pk_add_f32 v[78:79], v[214:215], 0 op_sel_hi:[1,0]
	v_pk_add_f32 v[80:81], v[212:213], 0 op_sel_hi:[1,0]
	v_cndmask_b32_e64 v82, 0, v78, s[6:7]
	v_cndmask_b32_e64 v79, 0, v79, s[6:7]
	v_cndmask_b32_e64 v78, 0, v80, s[6:7]
	v_cndmask_b32_e64 v80, 0, v81, s[6:7]
	v_cvt_pk_bf16_f32 v78, v78, v80
	v_cvt_pk_bf16_f32 v79, v82, v79
	v_pk_add_f32 v[80:81], v[222:223], 0 op_sel_hi:[1,0]
	v_pk_add_f32 v[82:83], v[220:221], 0 op_sel_hi:[1,0]
	v_cndmask_b32_e64 v84, 0, v80, s[8:9]
	v_cndmask_b32_e64 v81, 0, v81, s[8:9]
	v_cndmask_b32_e64 v80, 0, v82, s[8:9]
	v_cndmask_b32_e64 v82, 0, v83, s[8:9]
	v_cvt_pk_bf16_f32 v80, v80, v82
	v_cvt_pk_bf16_f32 v81, v84, v81
	v_pk_add_f32 v[82:83], v[116:117], 0 op_sel_hi:[1,0]
	v_pk_add_f32 v[84:85], v[114:115], 0 op_sel_hi:[1,0]
; __device__ __forceinline__ unsigned pack2(float a, float b) { unsigned r; asm("v_cvt_pk_bf16_f32 %0, %1, %2" : "=v"(r) : "v"(a), "v"(b)); return r; }
; template <bool SWAP, class Epi, bool THIN = false> ...
;     ...
;       bf16_t* Zw = (bf16_t*)smem + ((wr_e >> 1) * 2 + wc_e) * (128 * 132);
;       const int nt2w = nt * 2 + wc_e;
; #pragma unroll
;       for (int n = 0; n < 8; ++n) {
;         const int cl = n * 16 + fq_e * 4;
;         f32x4 b4 = {0.f, 0.f, 0.f, 0.f};
;         if (epi.pre_bias) b4 = *(const f32x4*)(epi.pre_bias + epi.norig(nt2w, cl));
; #pragma unroll
;         for (int m = 0; m < 4; ++m) {
;           const int rl = rw + m * 16 + fr_e;
;           const int pos = rig0 + rl;
;           const bool ok = pos >= 0 && pos < grows;
;           f32x4 vv = acc[m][n] + b4;
;           if (!ok) vv = (f32x4){0.f, 0.f, 0.f, 0.f};
;           uint2 u; u.x = pack2(vv[0], vv[1]); u.y = pack2(vv[2], vv[3]);
;           *(uint2*)(Zw + rl * 132 + cl) = u;
;         }
;       }
	v_cndmask_b32_e32 v89, 0, v82, vcc
	v_cndmask_b32_e32 v83, 0, v83, vcc
	v_cndmask_b32_e32 v82, 0, v84, vcc
	v_mfma_f32_16x16x32_bf16 v[10:13], v[228:231], v[200:203], v[164:167]
	v_cndmask_b32_e32 v84, 0, v85, vcc
	v_cvt_pk_bf16_f32 v82, v82, v84
	v_cvt_pk_bf16_f32 v83, v89, v83
	v_mfma_f32_16x16x32_bf16 v[6:9], v[228:231], v[204:207], v[168:171]
	ds_write2_b64 v73, v[74:75], v[82:83] offset0:8 offset1:12
	v_pk_add_f32 v[74:75], v[92:93], 0 op_sel_hi:[1,0]
	v_pk_add_f32 v[82:83], v[90:91], 0 op_sel_hi:[1,0]
	v_cndmask_b32_e64 v84, 0, v74, s[4:5]
	v_cndmask_b32_e64 v75, 0, v75, s[4:5]
	v_cndmask_b32_e64 v74, 0, v82, s[4:5]
	v_cndmask_b32_e64 v82, 0, v83, s[4:5]
	v_cvt_pk_bf16_f32 v74, v74, v82
	v_cvt_pk_bf16_f32 v75, v84, v75
	v_pk_add_f32 v[26:27], v[26:27], 0 op_sel_hi:[1,0]
	ds_write2_b64 v86, v[76:77], v[74:75] offset0:24 offset1:28
	v_pk_add_f32 v[74:75], v[218:219], 0 op_sel_hi:[1,0]
	v_pk_add_f32 v[76:77], v[216:217], 0 op_sel_hi:[1,0]
	v_pk_add_f32 v[58:59], v[58:59], 0 op_sel_hi:[1,0]
	v_pk_add_f32 v[54:55], v[54:55], 0 op_sel_hi:[1,0]
	v_pk_add_f32 v[50:51], v[50:51], 0 op_sel_hi:[1,0]
	v_pk_add_f32 v[46:47], v[46:47], 0 op_sel_hi:[1,0]
	v_pk_add_f32 v[42:43], v[42:43], 0 op_sel_hi:[1,0]
	v_pk_add_f32 v[38:39], v[38:39], 0 op_sel_hi:[1,0]
	v_pk_add_f32 v[34:35], v[34:35], 0 op_sel_hi:[1,0]
	v_pk_add_f32 v[30:31], v[30:31], 0 op_sel_hi:[1,0]
	v_cndmask_b32_e64 v28, 0, v28, s[4:5]
	v_cndmask_b32_e64 v26, 0, v26, s[4:5]
	v_cndmask_b32_e64 v27, 0, v27, s[4:5]
	v_pk_add_f32 v[22:23], v[22:23], 0 op_sel_hi:[1,0]
	v_pk_add_f32 v[18:19], v[18:19], 0 op_sel_hi:[1,0]
	v_pk_add_f32 v[14:15], v[14:15], 0 op_sel_hi:[1,0]
	v_pk_add_f32 v[10:11], v[10:11], 0 op_sel_hi:[1,0]
	v_pk_add_f32 v[6:7], v[6:7], 0 op_sel_hi:[1,0]
	v_pk_add_f32 v[2:3], v[2:3], 0 op_sel_hi:[1,0]
	v_cndmask_b32_e64 v82, 0, v74, s[6:7]
	v_cndmask_b32_e64 v75, 0, v75, s[6:7]
	v_cndmask_b32_e64 v74, 0, v76, s[6:7]
	v_pk_add_f32 v[68:69], v[68:69], 0 op_sel_hi:[1,0]
	v_cndmask_b32_e64 v66, 0, v66, s[8:9]
	v_cndmask_b32_e64 v67, 0, v67, s[8:9]
	v_pk_add_f32 v[64:65], v[64:65], 0 op_sel_hi:[1,0]
	v_cndmask_b32_e32 v62, 0, v62, vcc
	v_cndmask_b32_e32 v63, 0, v63, vcc
	v_pk_add_f32 v[60:61], v[60:61], 0 op_sel_hi:[1,0]
	v_cndmask_b32_e64 v58, 0, v58, s[4:5]
	v_cndmask_b32_e64 v59, 0, v59, s[4:5]
	v_pk_add_f32 v[56:57], v[56:57], 0 op_sel_hi:[1,0]
	v_cndmask_b32_e64 v54, 0, v54, s[6:7]
	v_cndmask_b32_e64 v55, 0, v55, s[6:7]
	v_pk_add_f32 v[52:53], v[52:53], 0 op_sel_hi:[1,0]
	v_cndmask_b32_e64 v50, 0, v50, s[8:9]
	v_cndmask_b32_e64 v51, 0, v51, s[8:9]
	v_pk_add_f32 v[48:49], v[48:49], 0 op_sel_hi:[1,0]
	v_cndmask_b32_e32 v46, 0, v46, vcc
	v_cndmask_b32_e32 v47, 0, v47, vcc
	v_pk_add_f32 v[44:45], v[44:45], 0 op_sel_hi:[1,0]
	v_cndmask_b32_e64 v42, 0, v42, s[4:5]
	v_cndmask_b32_e64 v43, 0, v43, s[4:5]
	v_pk_add_f32 v[40:41], v[40:41], 0 op_sel_hi:[1,0]
	v_cndmask_b32_e64 v38, 0, v38, s[6:7]
	v_cndmask_b32_e64 v39, 0, v39, s[6:7]
	v_pk_add_f32 v[36:37], v[36:37], 0 op_sel_hi:[1,0]
	v_cndmask_b32_e64 v34, 0, v34, s[8:9]
	v_cndmask_b32_e64 v35, 0, v35, s[8:9]
	v_pk_add_f32 v[32:33], v[32:33], 0 op_sel_hi:[1,0]
	v_cndmask_b32_e32 v30, 0, v30, vcc
	v_cndmask_b32_e32 v31, 0, v31, vcc
	v_cndmask_b32_e64 v29, 0, v29, s[4:5]
	v_cvt_pk_bf16_f32 v26, v26, v27
	v_cvt_pk_bf16_f32 v27, v28, v29
	v_pk_add_f32 v[24:25], v[24:25], 0 op_sel_hi:[1,0]
	v_cndmask_b32_e64 v22, 0, v22, s[6:7]
	v_cndmask_b32_e64 v23, 0, v23, s[6:7]
	v_pk_add_f32 v[20:21], v[20:21], 0 op_sel_hi:[1,0]
	v_cndmask_b32_e64 v18, 0, v18, s[8:9]
	v_cndmask_b32_e64 v19, 0, v19, s[8:9]
	v_pk_add_f32 v[16:17], v[16:17], 0 op_sel_hi:[1,0]
	v_cndmask_b32_e32 v14, 0, v14, vcc
	v_cndmask_b32_e32 v15, 0, v15, vcc
	v_pk_add_f32 v[12:13], v[12:13], 0 op_sel_hi:[1,0]
	v_cndmask_b32_e64 v10, 0, v10, s[4:5]
	v_cndmask_b32_e64 v11, 0, v11, s[4:5]
	v_pk_add_f32 v[8:9], v[8:9], 0 op_sel_hi:[1,0]
	v_cndmask_b32_e64 v6, 0, v6, s[6:7]
	v_cndmask_b32_e64 v7, 0, v7, s[6:7]
	v_pk_add_f32 v[4:5], v[4:5], 0 op_sel_hi:[1,0]
	v_cndmask_b32_e64 v2, 0, v2, s[8:9]
	v_cndmask_b32_e64 v3, 0, v3, s[8:9]
	v_mov_b32_e32 v28, v142
	v_cndmask_b32_e64 v76, 0, v77, s[6:7]
	v_cvt_pk_bf16_f32 v74, v74, v76
	v_cvt_pk_bf16_f32 v75, v82, v75
	ds_write2_b64 v87, v[78:79], v[74:75] offset0:40 offset1:44
	v_cndmask_b32_e64 v68, 0, v68, s[8:9]
	v_cndmask_b32_e64 v69, 0, v69, s[8:9]
	v_cvt_pk_bf16_f32 v66, v66, v67
	v_cvt_pk_bf16_f32 v67, v68, v69
	ds_write2_b64 v88, v[80:81], v[66:67] offset0:56 offset1:60
	v_cndmask_b32_e32 v64, 0, v64, vcc
	v_cndmask_b32_e32 v65, 0, v65, vcc
	v_cvt_pk_bf16_f32 v62, v62, v63
	v_cvt_pk_bf16_f32 v63, v64, v65
	v_cndmask_b32_e64 v60, 0, v60, s[4:5]
	v_cndmask_b32_e64 v61, 0, v61, s[4:5]
	v_cvt_pk_bf16_f32 v58, v58, v59
	v_cvt_pk_bf16_f32 v59, v60, v61
	v_cndmask_b32_e64 v56, 0, v56, s[6:7]
	v_cndmask_b32_e64 v57, 0, v57, s[6:7]
	v_cvt_pk_bf16_f32 v54, v54, v55
	v_cvt_pk_bf16_f32 v55, v56, v57
	v_cndmask_b32_e64 v52, 0, v52, s[8:9]
	v_cndmask_b32_e64 v53, 0, v53, s[8:9]
	v_cvt_pk_bf16_f32 v50, v50, v51
	v_cvt_pk_bf16_f32 v51, v52, v53
	v_cndmask_b32_e32 v48, 0, v48, vcc
	v_cndmask_b32_e32 v49, 0, v49, vcc
	v_cvt_pk_bf16_f32 v46, v46, v47
	v_cvt_pk_bf16_f32 v47, v48, v49
	ds_write2_b64 v73, v[62:63], v[46:47] offset0:16 offset1:20
	v_cndmask_b32_e64 v44, 0, v44, s[4:5]
	v_cndmask_b32_e64 v45, 0, v45, s[4:5]
	v_cvt_pk_bf16_f32 v42, v42, v43
	v_cvt_pk_bf16_f32 v43, v44, v45
	ds_write2_b64 v86, v[58:59], v[42:43] offset0:32 offset1:36
	v_cndmask_b32_e64 v40, 0, v40, s[6:7]
	v_cndmask_b32_e64 v41, 0, v41, s[6:7]
	v_cvt_pk_bf16_f32 v38, v38, v39
; __device__ __forceinline__ unsigned pack2(float a, float b) { unsigned r; asm("v_cvt_pk_bf16_f32 %0, %1, %2" : "=v"(r) : "v"(a), "v"(b)); return r; }
;   template <class F>
;   __device__ __forceinline__ void finish(const bf16_t* Z, int g, int rig0, int nt, F&& pre) const {
;     ...
;       if (MODE == 0) {
;         const int f2 = (tid & 31) * 2, q8 = tid >> 5;
;         const int q0 = 1 + 16 * q8, q1 = (q0 + 16 < 127) ? q0 + 16 : 127;
;         const int na = norig(nt, f2), ng = norig(nt, 64 + f2);
;         const f32x2 a0 = *(const f32x2*)(cw + na), a1 = *(const f32x2*)(cw + NC + na), a2 = *(const f32x2*)(cw + 2 * NC + na), ab = *(const f32x2*)(cb + na);
;         const f32x2 g0 = *(const f32x2*)(cw + ng), g1 = *(const f32x2*)(cw + NC + ng), g2 = *(const f32x2*)(cw + 2 * NC + ng), gb = *(const f32x2*)(cb + ng);
;         pre();
;         f32x2 am = ldz(Z, q0 - 1, f2), ac = ldz(Z, q0, f2);
;         f32x2 gm = ldz(Z, q0 - 1, 64 + f2), gc = ldz(Z, q0, 64 + f2);
; #pragma unroll 4
;         for (int pl = q0; pl < q1; ++pl) {
;           const f32x2 an = ldz(Z, pl + 1, f2), gn = ldz(Z, pl + 1, 64 + f2);
;           const int pos = rig0 + pl;
;           if (pos < 2048) {
;             const f32x2 av = a0 * am + a1 * ac + a2 * an + ab;
;             const f32x2 gv = g0 * gm + g1 * gc + g2 * gn + gb;
;             const float s0 = av[0] * gv[0] * __builtin_amdgcn_rcpf(1.f + __expf(-gv[0]));
;             const float s1 = av[1] * gv[1] * __builtin_amdgcn_rcpf(1.f + __expf(-gv[1]));
;             *(unsigned*)(o0 + ((size_t)g * 2048 + pos) * 2816 + nt * 64 + f2) = pack2(s0, s1);
; template <bool SWAP, class Epi, bool THIN = false> ...
;     ...
;       __syncthreads();
;       {
;         auto no_pre = []() {};
;         const bf16_t* Zr = (const bf16_t*)smem + ((wr_e >> 1) * 2) * (128 * 132);
;         epi.finish(Zr, g, rig0, nt * 2, no_pre);
	v_cvt_pk_bf16_f32 v39, v40, v41
	ds_write2_b64 v87, v[54:55], v[38:39] offset0:48 offset1:52
	v_cndmask_b32_e64 v36, 0, v36, s[8:9]
	v_cndmask_b32_e64 v37, 0, v37, s[8:9]
	v_cvt_pk_bf16_f32 v34, v34, v35
	v_cvt_pk_bf16_f32 v35, v36, v37
	ds_write2_b64 v88, v[50:51], v[34:35] offset0:64 offset1:68
	v_cndmask_b32_e32 v32, 0, v32, vcc
	v_cndmask_b32_e32 v33, 0, v33, vcc
	v_cvt_pk_bf16_f32 v30, v30, v31
	v_cvt_pk_bf16_f32 v31, v32, v33
	v_cndmask_b32_e64 v24, 0, v24, s[6:7]
	v_cndmask_b32_e64 v25, 0, v25, s[6:7]
	v_cvt_pk_bf16_f32 v22, v22, v23
	v_cvt_pk_bf16_f32 v23, v24, v25
	v_cndmask_b32_e64 v20, 0, v20, s[8:9]
	v_cndmask_b32_e64 v21, 0, v21, s[8:9]
	v_cvt_pk_bf16_f32 v18, v18, v19
	v_cvt_pk_bf16_f32 v19, v20, v21
	v_cndmask_b32_e32 v16, 0, v16, vcc
	v_cndmask_b32_e32 v17, 0, v17, vcc
	v_cvt_pk_bf16_f32 v14, v14, v15
	v_cvt_pk_bf16_f32 v15, v16, v17
	ds_write2_b64 v73, v[30:31], v[14:15] offset0:24 offset1:28
	v_cndmask_b32_e64 v12, 0, v12, s[4:5]
	v_cndmask_b32_e64 v13, 0, v13, s[4:5]
	v_cvt_pk_bf16_f32 v10, v10, v11
	v_cvt_pk_bf16_f32 v11, v12, v13
	ds_write2_b64 v86, v[26:27], v[10:11] offset0:40 offset1:44
	v_cndmask_b32_e64 v8, 0, v8, s[6:7]
	v_cndmask_b32_e64 v9, 0, v9, s[6:7]
	v_cvt_pk_bf16_f32 v6, v6, v7
	v_cvt_pk_bf16_f32 v7, v8, v9
	ds_write2_b64 v87, v[22:23], v[6:7] offset0:56 offset1:60
	v_cndmask_b32_e64 v4, 0, v4, s[8:9]
	v_cndmask_b32_e64 v5, 0, v5, s[8:9]
	v_cvt_pk_bf16_f32 v2, v2, v3
	v_cvt_pk_bf16_f32 v3, v4, v5
	ds_write2_b64 v88, v[18:19], v[2:3] offset0:72 offset1:76
	s_waitcnt lgkmcnt(0)
	s_barrier
	s_nop 0
	v_ashrrev_i32_e32 v29, 1, v28
	v_and_b32_e32 v38, -16, v29
	v_min_i32_e32 v2, 0x6e, v38
	v_or_b32_e32 v20, 1, v38
	v_add_u32_e32 v3, 17, v2
	v_cmp_ge_i32_e32 vcc, v20, v3
	s_and_saveexec_b64 s[4:5], vcc
	s_xor_b64 s[4:5], exec, s[4:5]
	s_ashr_i32 s25, s24, 31
	s_or_saveexec_b64 s[4:5], s[4:5]
	v_mul_i32_i24_e32 v2, 0x10800, v71
	v_mov_b64_e32 v[22:23], s[24:25]
	v_ashrrev_i32_e32 v71, 31, v70
	s_xor_b64 exec, exec, s[4:5]
	s_cbranch_execz .LBB0_2345
	v_lshlrev_b32_e32 v4, 1, v28
	v_and_b32_e32 v21, 62, v4
	v_or_b32_e32 v4, s24, v21
	s_add_i32 s6, s24, 0xb00
	v_ashrrev_i32_e32 v5, 31, v4
	v_or_b32_e32 v12, s6, v21
	v_lshlrev_b64 v[10:11], 2, v[4:5]
	v_lshl_add_u64 v[14:15], s[12:13], 0, v[10:11]
	v_lshl_add_u64 v[18:19], s[22:23], 0, v[10:11]
	v_ashrrev_i32_e32 v13, 31, v12
	v_lshl_add_u64 v[16:17], s[20:21], 0, v[10:11]
	global_load_dwordx2 v[4:5], v[14:15], off
	global_load_dwordx2 v[6:7], v[16:17], off
	global_load_dwordx2 v[8:9], v[18:19], off
	v_lshlrev_b64 v[18:19], 2, v[12:13]
	v_lshl_add_u64 v[10:11], s[14:15], 0, v[10:11]
	v_lshl_add_u64 v[22:23], s[12:13], 0, v[18:19]
	global_load_dwordx2 v[10:11], v[10:11], off
	v_lshl_add_u64 v[24:25], s[20:21], 0, v[18:19]
	v_lshl_add_u64 v[26:27], s[22:23], 0, v[18:19]
	global_load_dwordx2 v[12:13], v[22:23], off
	global_load_dwordx2 v[14:15], v[24:25], off
	global_load_dwordx2 v[16:17], v[26:27], off
	v_lshl_add_u64 v[18:19], s[14:15], 0, v[18:19]
	global_load_dwordx2 v[18:19], v[18:19], off
	s_ashr_i32 s25, s24, 31
	v_mov_b64_e32 v[106:107], s[24:25]
	v_mov_b32_e32 v117, 0
	v_lshlrev_b32_e32 v88, 1, v142
	v_and_b32_e32 v116, 62, v88
	v_add3_u32 v88, v116, s24, 64
	s_add_i32 s38, s24, 0xb40
	v_ashrrev_i32_e32 v89, 31, v88
	v_lshl_add_u64 v[90:91], v[116:117], 0, v[106:107]
	v_or_b32_e32 v96, s38, v116
	v_lshlrev_b64 v[94:95], 2, v[90:91]
	v_lshlrev_b64 v[88:89], 2, v[88:89]
	v_lshl_add_u64 v[98:99], s[12:13], 0, v[94:95]
	v_lshl_add_u64 v[102:103], s[22:23], 0, v[88:89]
	v_ashrrev_i32_e32 v97, 31, v96
	v_lshl_add_u64 v[100:101], s[20:21], 0, v[88:89]
	global_load_dwordx2 v[88:89], v[98:99], off offset:256
	global_load_dwordx2 v[90:91], v[100:101], off
	global_load_dwordx2 v[92:93], v[102:103], off
	v_lshlrev_b64 v[102:103], 2, v[96:97]
	v_lshl_add_u64 v[94:95], s[14:15], 0, v[94:95]
	v_lshl_add_u64 v[108:109], s[12:13], 0, v[102:103]
	global_load_dwordx2 v[94:95], v[94:95], off offset:256
	v_lshl_add_u64 v[110:111], s[20:21], 0, v[102:103]
	v_lshl_add_u64 v[114:115], s[22:23], 0, v[102:103]
	global_load_dwordx2 v[96:97], v[108:109], off
	global_load_dwordx2 v[98:99], v[110:111], off
	global_load_dwordx2 v[100:101], v[114:115], off
	v_lshl_add_u64 v[102:103], s[14:15], 0, v[102:103]
	global_load_dwordx2 v[102:103], v[102:103], off
	v_lshlrev_b32_e32 v136, 1, v21
	v_mul_lo_u32 v22, v38, s31
	v_mul_lo_u32 v20, v20, s31
	v_add3_u32 v22, v2, v22, v136
	v_add3_u32 v20, v2, v20, v136
	ds_read2_b32 v[22:23], v22 offset1:32
	ds_read2_b32 v[20:21], v20 offset1:32
	s_ashr_i32 s25, s24, 31
	s_lshl_b64 s[6:7], s[24:25], 1
	s_add_u32 s6, s10, s6
	s_addc_u32 s7, s11, s7
	v_lshrrev_b32_e32 v29, 4, v29
	v_and_b32_e32 v28, 31, v28
	s_waitcnt lgkmcnt(1)
	v_lshlrev_b32_e32 v32, 16, v23
	v_and_b32_e32 v33, 0xffff0000, v23
	v_lshlrev_b32_e32 v34, 16, v22
	v_and_b32_e32 v35, 0xffff0000, v22
	v_lshl_add_u64 v[22:23], s[6:7], 0, v[136:137]
	v_mad_u64_u32 v[30:31], s[6:7], v29, s33, v[2:3]
	v_lshlrev_b32_e32 v28, 2, v28
	s_waitcnt lgkmcnt(0)
	v_lshlrev_b32_e32 v24, 16, v21
	v_and_b32_e32 v25, 0xffff0000, v21
	v_lshlrev_b32_e32 v26, 16, v20
	v_and_b32_e32 v27, 0xffff0000, v20
	v_lshlrev_b64 v[20:21], 11, v[70:71]
	v_add3_u32 v39, v30, v28, s34
	s_mov_b32 s98, 0x1600
	s_mov_b32 s99, 0
	v_add_u32_e32 v48, v72, v38
	v_ashrrev_i32_e32 v49, 31, v48
	v_lshl_add_u64 v[48:49], v[20:21], 0, v[48:49]
	v_mad_u64_u32 v[50:51], s[38:39], v48, s35, v[22:23]
	v_mad_i32_i24 v51, v49, s35, v51
	s_mov_b64 s[6:7], 0
	s_waitcnt vmcnt(0)
	ds_read2_b32 v[44:45], v39 offset1:32
	s_branch .LBB0_2340

; template <bool SWAP, class Epi, bool THIN = false> ...
;     ...
;     for (int st = 0; st < ns; ++st) {
;       asm volatile("s_waitcnt vmcnt(0)" ::: "memory");
;       __builtin_amdgcn_s_barrier();
;       asm volatile("" ::: "memory");
;       if (st + 1 < ns) {
;         char* nb = smem + ((st + 1) & 1) * 65536;
;         const int ko = (st + 1) * 64;
; #pragma unroll
;         for (int i = 0; i < 4; ++i) { GLDS16(A + (size_t)(ap[i] + ko), nb + tid * 16 + i * 8192); GLDS16(Bt + (size_t)(bp[i] + ko), nb + 32768 + tid * 16 + i * 8192); }
;       }
;       const char* sa = smem + (st & 1) * 65536 + (wr * 64 + fr) * 128;
;       const char* sb = smem + (st & 1) * 65536 + 32768 + (wc * 128 + fr) * 128;
;       if constexpr (THIN) {
;         if (wc == 0) {
; #pragma unroll
;           for (int ks = 0; ks < 2; ++ks) {
;             bf16x8 af[4], bf[2];
; #pragma unroll
;             for (int m = 0; m < 4; ++m) af[m] = *(const bf16x8*)(sa + m * 2048 + (((ks * 4 + fq) ^ swz) << 4));
; #pragma unroll
;             for (int n = 0; n < 2; ++n) bf[n] = *(const bf16x8*)(sb + n * 2048 + (((ks * 4 + fq) ^ swz) << 4));
; #pragma unroll
;             for (int m = 0; m < 4; ++m)
; #pragma unroll
;               for (int n = 0; n < 2; ++n)
;                 acc[m][n] = SWAP ? __builtin_amdgcn_mfma_f32_16x16x32_bf16(bf[n], af[m], acc[m][n], 0, 0, 0)
;                                  : __builtin_amdgcn_mfma_f32_16x16x32_bf16(af[m], bf[n], acc[m][n], 0, 0, 0);
;           }
;         }
;       } else {
;       bf16x8 afA[4], afB[4], bfb[2][2];
; #pragma unroll
;       for (int m = 0; m < 4; ++m) afA[m] = *(const bf16x8*)(sa + m * 2048 + ((fq ^ swz) << 4));
; #pragma unroll
;       for (int n = 0; n < 2; ++n) bfb[0][n] = *(const bf16x8*)(sb + n * 2048 + ((fq ^ swz) << 4));
; #pragma unroll
;       for (int gq = 0; gq < 8; ++gq) {
;         const int ks = gq >> 2, nh = gq & 3;
;         if (gq < 7) {
;           const int ks2 = (gq + 1) >> 2, nh2 = (gq + 1) & 3;
; #pragma unroll
;           for (int n = 0; n < 2; ++n) bfb[(gq + 1) & 1][n] = *(const bf16x8*)(sb + (nh2 * 2 + n) * 2048 + (((ks2 * 4 + fq) ^ swz) << 4));
;         }
;         if (gq == 3) {
; #pragma unroll
;           for (int m = 0; m < 4; ++m) afB[m] = *(const bf16x8*)(sa + m * 2048 + (((4 + fq) ^ swz) << 4));
;         }
;         __builtin_amdgcn_sched_barrier(0);
; #pragma unroll
.LBB0_2429:
	s_add_i32 s9, s7, 0x10000
	s_and_b32 s8, s9, 0x10000
	v_add_u32_e32 v139, s8, v144
	s_nop 0
	v_readfirstlane_b32 s10, v139
	s_and_b32 s7, s7, 0x10000
	v_add_u32_e32 v130, s7, v145
	v_add_u32_e32 v139, v130, v147
	s_waitcnt vmcnt(0)
	s_barrier
	ds_read_b128 v[168:171], v139
	ds_read_b128 v[172:175], v139 offset:2048
	ds_read_b128 v[176:179], v139 offset:4096
	ds_read_b128 v[180:183], v139 offset:6144
	v_or_b32_e32 v139, s7, v146
	v_add_u32_e32 v141, v139, v147
	ds_read_b128 v[184:187], v141 offset:32768
	ds_read_b128 v[188:191], v141 offset:34816
	ds_read_b128 v[192:195], v141 offset:36864
	ds_read_b128 v[196:199], v141 offset:38912
	v_add_u32_e32 v130, v130, v148
	s_waitcnt lgkmcnt(3)
	v_mfma_f32_16x16x32_bf16 v[126:129], v[184:187], v[168:171], v[126:129]
	s_mov_b32 m0, s10
	v_mfma_f32_16x16x32_bf16 v[110:113], v[184:187], v[172:175], v[110:113]
	global_load_lds_dwordx4 v138, s[22:23]
	v_add_u32_e32 v138, 0x80, v138
	v_mfma_f32_16x16x32_bf16 v[82:85], v[184:187], v[176:179], v[82:85]
	v_mfma_f32_16x16x32_bf16 v[50:53], v[184:187], v[180:183], v[50:53]
	ds_read_b128 v[184:187], v141 offset:40960
	ds_read_b128 v[200:203], v141 offset:43008
	s_waitcnt lgkmcnt(4)
	v_mfma_f32_16x16x32_bf16 v[122:125], v[188:191], v[168:171], v[122:125]
	s_add_u32 m0, s10, 0x8000
	v_mfma_f32_16x16x32_bf16 v[106:109], v[188:191], v[172:175], v[106:109]
	global_load_lds_dwordx4 v137, s[18:19]
	v_add_u32_e32 v137, 0x80, v137
	v_mfma_f32_16x16x32_bf16 v[78:81], v[188:191], v[176:179], v[78:81]
	v_mfma_f32_16x16x32_bf16 v[38:41], v[188:191], v[180:183], v[38:41]
	s_waitcnt lgkmcnt(3)
	v_mfma_f32_16x16x32_bf16 v[118:121], v[192:195], v[168:171], v[118:121]
	s_add_u32 m0, s10, 0x2000
	v_mfma_f32_16x16x32_bf16 v[94:97], v[192:195], v[172:175], v[94:97]
	global_load_lds_dwordx4 v136, s[22:23]
	v_add_u32_e32 v136, 0x80, v136
	v_mfma_f32_16x16x32_bf16 v[58:61], v[192:195], v[176:179], v[58:61]
	v_mfma_f32_16x16x32_bf16 v[26:29], v[192:195], v[180:183], v[26:29]
	ds_read_b128 v[188:191], v141 offset:45056
	ds_read_b128 v[192:195], v141 offset:47104
	s_waitcnt lgkmcnt(4)
	v_mfma_f32_16x16x32_bf16 v[114:117], v[196:199], v[168:171], v[114:117]
	s_add_u32 m0, s10, 0xa000
	v_mfma_f32_16x16x32_bf16 v[86:89], v[196:199], v[172:175], v[86:89]
	global_load_lds_dwordx4 v135, s[18:19]
	v_add_u32_e32 v135, 0x80, v135
	v_mfma_f32_16x16x32_bf16 v[54:57], v[196:199], v[176:179], v[54:57]
	v_mfma_f32_16x16x32_bf16 v[22:25], v[196:199], v[180:183], v[22:25]
	v_add_u32_e32 v139, v139, v148
	s_waitcnt lgkmcnt(3)
	v_mfma_f32_16x16x32_bf16 v[102:105], v[184:187], v[168:171], v[102:105]
	ds_read_b128 v[196:199], v139 offset:32768
	ds_read_b128 v[204:207], v139 offset:34816
	s_add_u32 m0, s10, 0x4000
	v_mfma_f32_16x16x32_bf16 v[74:77], v[184:187], v[172:175], v[74:77]
	global_load_lds_dwordx4 v134, s[22:23]
	v_add_u32_e32 v134, 0x80, v134
	v_mfma_f32_16x16x32_bf16 v[46:49], v[184:187], v[176:179], v[46:49]
	v_mfma_f32_16x16x32_bf16 v[10:13], v[184:187], v[180:183], v[10:13]
	ds_read_b128 v[184:187], v130
	ds_read_b128 v[208:211], v130 offset:2048
	ds_read_b128 v[212:215], v130 offset:4096
	ds_read_b128 v[216:219], v130 offset:6144
	s_waitcnt lgkmcnt(8)
	v_mfma_f32_16x16x32_bf16 v[98:101], v[200:203], v[168:171], v[98:101]
	s_add_u32 m0, s10, 0xc000
	v_mfma_f32_16x16x32_bf16 v[66:69], v[200:203], v[172:175], v[66:69]
	global_load_lds_dwordx4 v133, s[18:19]
	v_add_u32_e32 v133, 0x80, v133
	v_mfma_f32_16x16x32_bf16 v[34:37], v[200:203], v[176:179], v[34:37]
	v_mfma_f32_16x16x32_bf16 v[6:9], v[200:203], v[180:183], v[6:9]
	s_waitcnt lgkmcnt(7)
	v_mfma_f32_16x16x32_bf16 v[70:73], v[188:191], v[168:171], v[70:73]
	s_add_u32 m0, s10, 0x6000
	s_waitcnt lgkmcnt(6)
	v_mfma_f32_16x16x32_bf16 v[62:65], v[192:195], v[168:171], v[62:65]
	global_load_lds_dwordx4 v132, s[22:23]
	v_add_u32_e32 v132, 0x80, v132
	v_mfma_f32_16x16x32_bf16 v[42:45], v[188:191], v[172:175], v[42:45]
	v_mfma_f32_16x16x32_bf16 v[30:33], v[192:195], v[172:175], v[30:33]
	ds_read_b128 v[168:171], v139 offset:36864
	ds_read_b128 v[172:175], v139 offset:38912
	v_mfma_f32_16x16x32_bf16 v[18:21], v[188:191], v[176:179], v[18:21]
	s_add_u32 m0, s10, 0xe000
	v_mfma_f32_16x16x32_bf16 v[14:17], v[192:195], v[176:179], v[14:17]
	global_load_lds_dwordx4 v140, s[18:19]
	v_add_u32_e32 v140, 0x80, v140
	v_mfma_f32_16x16x32_bf16 v[2:5], v[188:191], v[180:183], v[2:5]
	v_mfma_f32_16x16x32_bf16 v[90:93], v[192:195], v[180:183], v[90:93]
	ds_read_b128 v[176:179], v139 offset:40960
	ds_read_b128 v[180:183], v139 offset:43008
	s_waitcnt lgkmcnt(7)
	v_mfma_f32_16x16x32_bf16 v[126:129], v[196:199], v[184:187], v[126:129]
	v_mfma_f32_16x16x32_bf16 v[122:125], v[204:207], v[184:187], v[122:125]
	s_waitcnt lgkmcnt(6)
	v_mfma_f32_16x16x32_bf16 v[110:113], v[196:199], v[208:211], v[110:113]
	v_mfma_f32_16x16x32_bf16 v[106:109], v[204:207], v[208:211], v[106:109]
	s_waitcnt lgkmcnt(5)
	v_mfma_f32_16x16x32_bf16 v[82:85], v[196:199], v[212:215], v[82:85]
	v_mfma_f32_16x16x32_bf16 v[78:81], v[204:207], v[212:215], v[78:81]
	s_waitcnt lgkmcnt(4)
	v_mfma_f32_16x16x32_bf16 v[50:53], v[196:199], v[216:219], v[50:53]
	v_mfma_f32_16x16x32_bf16 v[38:41], v[204:207], v[216:219], v[38:41]
	s_waitcnt lgkmcnt(3)
	v_mfma_f32_16x16x32_bf16 v[118:121], v[168:171], v[184:187], v[118:121]
	v_mfma_f32_16x16x32_bf16 v[94:97], v[168:171], v[208:211], v[94:97]
	v_mfma_f32_16x16x32_bf16 v[58:61], v[168:171], v[212:215], v[58:61]
	v_mfma_f32_16x16x32_bf16 v[26:29], v[168:171], v[216:219], v[26:29]
	ds_read_b128 v[168:171], v139 offset:45056
	ds_read_b128 v[188:191], v139 offset:47104
	s_waitcnt lgkmcnt(4)
; template <bool SWAP, class Epi, bool THIN = false> ...
;     ...
;     for (int st = 0; st < ns; ++st) {
;       asm volatile("s_waitcnt vmcnt(0)" ::: "memory");
;       __builtin_amdgcn_s_barrier();
;       asm volatile("" ::: "memory");
;       if (st + 1 < ns) {
;         char* nb = smem + ((st + 1) & 1) * 65536;
;         const int ko = (st + 1) * 64;
; #pragma unroll
;         for (int i = 0; i < 4; ++i) { GLDS16(A + (size_t)(ap[i] + ko), nb + tid * 16 + i * 8192); GLDS16(Bt + (size_t)(bp[i] + ko), nb + 32768 + tid * 16 + i * 8192); }
;       }
;       const char* sa = smem + (st & 1) * 65536 + (wr * 64 + fr) * 128;
;       const char* sb = smem + (st & 1) * 65536 + 32768 + (wc * 128 + fr) * 128;
;       if constexpr (THIN) {
;         if (wc == 0) {
; #pragma unroll
;           for (int ks = 0; ks < 2; ++ks) {
;             bf16x8 af[4], bf[2];
; #pragma unroll
;             for (int m = 0; m < 4; ++m) af[m] = *(const bf16x8*)(sa + m * 2048 + (((ks * 4 + fq) ^ swz) << 4));
; #pragma unroll
;             for (int n = 0; n < 2; ++n) bf[n] = *(const bf16x8*)(sb + n * 2048 + (((ks * 4 + fq) ^ swz) << 4));
; #pragma unroll
;             for (int m = 0; m < 4; ++m)
; #pragma unroll
;               for (int n = 0; n < 2; ++n)
;                 acc[m][n] = SWAP ? __builtin_amdgcn_mfma_f32_16x16x32_bf16(bf[n], af[m], acc[m][n], 0, 0, 0)
;                                  : __builtin_amdgcn_mfma_f32_16x16x32_bf16(af[m], bf[n], acc[m][n], 0, 0, 0);
;           }
;         }
;       } else {
;       bf16x8 afA[4], afB[4], bfb[2][2];
; #pragma unroll
;       for (int m = 0; m < 4; ++m) afA[m] = *(const bf16x8*)(sa + m * 2048 + ((fq ^ swz) << 4));
; #pragma unroll
;       for (int n = 0; n < 2; ++n) bfb[0][n] = *(const bf16x8*)(sb + n * 2048 + ((fq ^ swz) << 4));
; #pragma unroll
;       for (int gq = 0; gq < 8; ++gq) {
;         const int ks = gq >> 2, nh = gq & 3;
;         if (gq < 7) {
;           const int ks2 = (gq + 1) >> 2, nh2 = (gq + 1) & 3;
; #pragma unroll
;           for (int n = 0; n < 2; ++n) bfb[(gq + 1) & 1][n] = *(const bf16x8*)(sb + (nh2 * 2 + n) * 2048 + (((ks2 * 4 + fq) ^ swz) << 4));
;         }
;         if (gq == 3) {
; #pragma unroll
;           for (int m = 0; m < 4; ++m) afB[m] = *(const bf16x8*)(sa + m * 2048 + (((4 + fq) ^ swz) << 4));
;         }
;         __builtin_amdgcn_sched_barrier(0);
; #pragma unroll
	v_mfma_f32_16x16x32_bf16 v[114:117], v[172:175], v[184:187], v[114:117]
	v_mfma_f32_16x16x32_bf16 v[86:89], v[172:175], v[208:211], v[86:89]
	v_mfma_f32_16x16x32_bf16 v[54:57], v[172:175], v[212:215], v[54:57]
	v_mfma_f32_16x16x32_bf16 v[22:25], v[172:175], v[216:219], v[22:25]
	s_waitcnt lgkmcnt(3)
	v_mfma_f32_16x16x32_bf16 v[102:105], v[176:179], v[184:187], v[102:105]
	s_waitcnt lgkmcnt(2)
	v_mfma_f32_16x16x32_bf16 v[98:101], v[180:183], v[184:187], v[98:101]
	v_mfma_f32_16x16x32_bf16 v[74:77], v[176:179], v[208:211], v[74:77]
	v_mfma_f32_16x16x32_bf16 v[66:69], v[180:183], v[208:211], v[66:69]
	v_mfma_f32_16x16x32_bf16 v[46:49], v[176:179], v[212:215], v[46:49]
	v_mfma_f32_16x16x32_bf16 v[34:37], v[180:183], v[212:215], v[34:37]
	v_mfma_f32_16x16x32_bf16 v[10:13], v[176:179], v[216:219], v[10:13]
	v_mfma_f32_16x16x32_bf16 v[6:9], v[180:183], v[216:219], v[6:9]
	s_waitcnt lgkmcnt(1)
	v_mfma_f32_16x16x32_bf16 v[70:73], v[168:171], v[184:187], v[70:73]
	s_add_i32 s6, s6, 64
	s_cmpk_eq_i32 s6, 0xac0
	s_mov_b32 s7, s9
	s_waitcnt lgkmcnt(0)
	v_mfma_f32_16x16x32_bf16 v[62:65], v[188:191], v[184:187], v[62:65]
	v_mfma_f32_16x16x32_bf16 v[42:45], v[168:171], v[208:211], v[42:45]
	v_mfma_f32_16x16x32_bf16 v[30:33], v[188:191], v[208:211], v[30:33]
	v_mfma_f32_16x16x32_bf16 v[18:21], v[168:171], v[212:215], v[18:21]
	v_mfma_f32_16x16x32_bf16 v[14:17], v[188:191], v[212:215], v[14:17]
	v_mfma_f32_16x16x32_bf16 v[2:5], v[168:171], v[216:219], v[2:5]
	v_mfma_f32_16x16x32_bf16 v[90:93], v[188:191], v[216:219], v[90:93]
	s_cbranch_scc0 .LBB0_2429
	v_add_u32_e32 v130, s8, v145
	s_waitcnt vmcnt(0)
	s_barrier
	v_add_u32_e32 v140, v130, v147
	ds_read_b128 v[132:135], v140
	ds_read_b128 v[136:139], v140 offset:2048
	ds_read_b128 v[168:171], v140 offset:4096
	ds_read_b128 v[172:175], v140 offset:6144
	v_add_u32_e32 v140, s8, v146
	v_add_u32_e32 v141, v140, v147
	ds_read_b128 v[176:179], v141 offset:32768
	ds_read_b128 v[180:183], v141 offset:34816
	ds_read_b128 v[184:187], v141 offset:36864
	ds_read_b128 v[188:191], v141 offset:38912
	v_add_u32_e32 v130, v130, v148
	s_waitcnt lgkmcnt(0)
	v_mfma_f32_16x16x32_bf16 v[126:129], v[176:179], v[132:135], v[126:129]
	v_mfma_f32_16x16x32_bf16 v[110:113], v[176:179], v[136:139], v[110:113]
	v_mfma_f32_16x16x32_bf16 v[82:85], v[176:179], v[168:171], v[82:85]
	v_mfma_f32_16x16x32_bf16 v[50:53], v[176:179], v[172:175], v[50:53]
	ds_read_b128 v[176:179], v141 offset:40960
	ds_read_b128 v[192:195], v141 offset:43008
	v_mfma_f32_16x16x32_bf16 v[122:125], v[180:183], v[132:135], v[122:125]
	v_mfma_f32_16x16x32_bf16 v[106:109], v[180:183], v[136:139], v[106:109]
	v_mfma_f32_16x16x32_bf16 v[78:81], v[180:183], v[168:171], v[78:81]
	v_mfma_f32_16x16x32_bf16 v[38:41], v[180:183], v[172:175], v[38:41]
	v_mfma_f32_16x16x32_bf16 v[118:121], v[184:187], v[132:135], v[118:121]
	v_mfma_f32_16x16x32_bf16 v[180:183], v[184:187], v[136:139], v[94:97]
	v_mfma_f32_16x16x32_bf16 v[200:203], v[184:187], v[168:171], v[58:61]
	v_mfma_f32_16x16x32_bf16 v[204:207], v[188:191], v[168:171], v[54:57]
	v_mfma_f32_16x16x32_bf16 v[184:187], v[184:187], v[172:175], v[26:29]
	s_nop 2
	ds_read_b128 v[26:29], v141 offset:45056
	ds_read_b128 v[54:57], v141 offset:47104
	v_mfma_f32_16x16x32_bf16 v[114:117], v[188:191], v[132:135], v[114:117]
	v_mfma_f32_16x16x32_bf16 v[196:199], v[188:191], v[136:139], v[86:89]
	v_mfma_f32_16x16x32_bf16 v[188:191], v[188:191], v[172:175], v[22:25]
	v_add_u32_e32 v140, v140, v148
	s_waitcnt lgkmcnt(0)
	v_mfma_f32_16x16x32_bf16 v[102:105], v[176:179], v[132:135], v[102:105]
	ds_read_b128 v[22:25], v140 offset:32768
	ds_read_b128 v[86:89], v140 offset:34816
	v_mfma_f32_16x16x32_bf16 v[74:77], v[176:179], v[136:139], v[74:77]
	v_mfma_f32_16x16x32_bf16 v[46:49], v[176:179], v[168:171], v[46:49]
	v_mfma_f32_16x16x32_bf16 v[10:13], v[176:179], v[172:175], v[10:13]
	ds_read_b128 v[176:179], v130
	ds_read_b128 v[208:211], v130 offset:2048
	ds_read_b128 v[212:215], v130 offset:4096
	ds_read_b128 v[216:219], v130 offset:6144
	v_mfma_f32_16x16x32_bf16 v[98:101], v[192:195], v[132:135], v[98:101]
	v_mfma_f32_16x16x32_bf16 v[66:69], v[192:195], v[136:139], v[66:69]
	v_mfma_f32_16x16x32_bf16 v[34:37], v[192:195], v[168:171], v[34:37]
	v_mfma_f32_16x16x32_bf16 v[6:9], v[192:195], v[172:175], v[6:9]
	v_mfma_f32_16x16x32_bf16 v[220:223], v[26:29], v[168:171], v[18:21]
	v_mfma_f32_16x16x32_bf16 v[168:171], v[54:57], v[168:171], v[14:17]
	s_nop 2
	ds_read_b128 v[14:17], v140 offset:36864
	ds_read_b128 v[18:21], v140 offset:38912
	v_mfma_f32_16x16x32_bf16 v[70:73], v[26:29], v[132:135], v[70:73]
	v_mfma_f32_16x16x32_bf16 v[132:135], v[54:57], v[132:135], v[62:65]
	v_mfma_f32_16x16x32_bf16 v[192:195], v[26:29], v[136:139], v[42:45]
	v_mfma_f32_16x16x32_bf16 v[136:139], v[54:57], v[136:139], v[30:33]
	v_mfma_f32_16x16x32_bf16 v[2:5], v[26:29], v[172:175], v[2:5]
	v_mfma_f32_16x16x32_bf16 v[172:175], v[54:57], v[172:175], v[90:93]
	ds_read_b128 v[224:227], v140 offset:40960
	ds_read_b128 v[228:231], v140 offset:43008
	s_waitcnt lgkmcnt(0)
	v_mfma_f32_16x16x32_bf16 v[126:129], v[22:25], v[176:179], v[126:129]
	v_mfma_f32_16x16x32_bf16 v[122:125], v[86:89], v[176:179], v[122:125]
	v_mfma_f32_16x16x32_bf16 v[94:97], v[22:25], v[208:211], v[110:113]
	v_mfma_f32_16x16x32_bf16 v[90:93], v[86:89], v[208:211], v[106:109]
	v_mfma_f32_16x16x32_bf16 v[62:65], v[22:25], v[212:215], v[82:85]
	v_mfma_f32_16x16x32_bf16 v[58:61], v[86:89], v[212:215], v[78:81]
	v_mfma_f32_16x16x32_bf16 v[30:33], v[22:25], v[216:219], v[50:53]
	v_mfma_f32_16x16x32_bf16 v[26:29], v[86:89], v[216:219], v[38:41]
	v_mfma_f32_16x16x32_bf16 v[86:89], v[14:17], v[208:211], v[180:183]
	v_mfma_f32_16x16x32_bf16 v[22:25], v[14:17], v[216:219], v[184:187]
	s_nop 1
	ds_read_b128 v[180:183], v140 offset:45056
	ds_read_b128 v[184:187], v140 offset:47104
	v_mfma_f32_16x16x32_bf16 v[118:121], v[14:17], v[176:179], v[118:121]
	v_mfma_f32_16x16x32_bf16 v[114:117], v[18:21], v[176:179], v[114:117]
	v_mfma_f32_16x16x32_bf16 v[82:85], v[18:21], v[208:211], v[196:199]
	v_mfma_f32_16x16x32_bf16 v[54:57], v[14:17], v[212:215], v[200:203]
	v_mfma_f32_16x16x32_bf16 v[50:53], v[18:21], v[212:215], v[204:207]
	v_mfma_f32_16x16x32_bf16 v[18:21], v[18:21], v[216:219], v[188:191]
	v_mfma_f32_16x16x32_bf16 v[110:113], v[224:227], v[176:179], v[102:105]
	v_mfma_f32_16x16x32_bf16 v[106:109], v[228:231], v[176:179], v[98:101]
	v_mfma_f32_16x16x32_bf16 v[78:81], v[224:227], v[208:211], v[74:77]
	v_mfma_f32_16x16x32_bf16 v[74:77], v[228:231], v[208:211], v[66:69]
	v_mfma_f32_16x16x32_bf16 v[46:49], v[224:227], v[212:215], v[46:49]
	v_mfma_f32_16x16x32_bf16 v[42:45], v[228:231], v[212:215], v[34:37]
	v_mfma_f32_16x16x32_bf16 v[14:17], v[224:227], v[216:219], v[10:13]
	v_mfma_f32_16x16x32_bf16 v[10:13], v[228:231], v[216:219], v[6:9]
	v_mov_b32_e32 v130, v1
	s_waitcnt vmcnt(0) lgkmcnt(0)
	s_barrier
; __device__ __forceinline__ int get_tid512() { int t = threadIdx.x; asm volatile("" : "+v"(t)); return t; }
; __device__ __forceinline__ unsigned pack2(float a, float b) { unsigned r; asm("v_cvt_pk_bf16_f32 %0, %1, %2" : "=v"(r) : "v"(a), "v"(b)); return r; }
; __device__ __forceinline__ float bf2f(bf16_t h) { return __uint_as_float(((unsigned)h) << 16); }
;   __device__ __forceinline__ void c4(int g, int rig, int col, f32x4 v) const {
;     const size_t o = ((size_t)g * 2048 + rig) * 1024 + col;
;     f32x4 bs;
;     if (BASE_F32) bs = __builtin_nontemporal_load((const f32x4*)((const float*)base + o));
;     else {
;       const uint2 u = *(const uint2*)((const bf16_t*)base + o);
;       bs[0] = bf2f((bf16_t)(u.x & 0xffff)); bs[1] = bf2f((bf16_t)(u.x >> 16)); bs[2] = bf2f((bf16_t)(u.y & 0xffff)); bs[3] = bf2f((bf16_t)(u.y >> 16));
;     }
;     const f32x4 gt = *(const f32x4*)(gate + (size_t)g * 6144 + col);
;     f32x4 bi = {0.f, 0.f, 0.f, 0.f};
;     if (bias) bi = *(const f32x4*)(bias + col);
;     f32x4 r;
; #pragma unroll
;     for (int j = 0; j < 4; ++j) r[j] = bs[j] + gt[j] * (v[j] + bi[j]);
;     uint2 w; w.x = pack2(r[0], r[1]); w.y = pack2(r[2], r[3]);
;     *(uint2*)(X16 + o) = w;
;   }
; template <bool SWAP, class Epi, bool THIN = false> ...
;     ...
;     const int te = get_tid512();
;     const int fr_e = te & 15, fq_e = (te & 63) >> 4, wr_e = te >> 7, wc_e = (te >> 6) & 1;
;     const int sub = 2 * mt + (wr_e >> 1);
;     const int g = sub / tpg, ti = sub - g * tpg;
;     const int rig0 = ti * step - halo;
;     const int rw = (wr_e & 1) * 64;
;     if constexpr (Epi::KIND == 0) {
; #pragma unroll
;       for (int m = 0; m < 4; ++m) {
;         const int rig = rig0 + rw + m * 16 + fr_e;
;         if constexpr (Epi::ROWSUM) {
;           float ss = 0.f;
; #pragma unroll
;           for (int n = 0; n < 8; ++n) {
;             const int col = nt * 256 + wc_e * 128 + n * 16 + fq_e * 4;
;             if (col < N) ss += epi.c4(g, rig, col, acc[m][n]);
;           }
;           ss += __shfl_xor(ss, 16); ss += __shfl_xor(ss, 32);
;           if (fq_e == 0) epi.rowsum(g, rig, nt * 2 + wc_e, ss);
;         } else {
; #pragma unroll
;           for (int n = 0; n < 8; ++n) {
;             const int col = nt * 256 + wc_e * 128 + n * 16 + fq_e * 4;
;             if (col < N) epi.c4(g, rig, col, acc[m][n]);
	v_mfma_f32_16x16x32_bf16 v[98:101], v[184:187], v[176:179], v[132:135]
	v_ashrrev_i32_e32 v7, 8, v130
	v_add_u32_e32 v7, s5, v7
	v_ashrrev_i32_e32 v8, 31, v7
	v_lshrrev_b32_e32 v8, 28, v8
	v_add_u32_e32 v8, v7, v8
	v_ashrrev_i32_e32 v134, 4, v8
	v_lshlrev_b32_e32 v8, 11, v134
	v_lshlrev_b32_e32 v7, 7, v7
	v_sub_u32_e32 v7, v7, v8
	v_lshrrev_b32_e32 v8, 1, v130
	v_and_b32_e32 v6, 15, v130
	v_and_b32_e32 v8, 64, v8
	v_mfma_f32_16x16x32_bf16 v[66:69], v[184:187], v[208:211], v[136:139]
	v_ashrrev_i32_e32 v135, 31, v134
	s_nop 1
	v_or3_b32 v136, v7, v8, v6
	v_lshlrev_b32_e32 v6, 1, v130
	v_and_b32_e32 v132, 0x80, v6
	v_mfma_f32_16x16x32_bf16 v[6:9], v[180:183], v[216:219], v[2:5]
	v_ashrrev_i32_e32 v137, 31, v136
	v_lshlrev_b64 v[138:139], 21, v[134:135]
	v_lshlrev_b64 v[140:141], 10, v[136:137]
	v_lshrrev_b32_e32 v2, 2, v130
	v_and_b32_e32 v2, 12, v2
	v_mfma_f32_16x16x32_bf16 v[102:105], v[180:183], v[176:179], v[70:73]
	v_or3_b32 v132, v2, v132, s4
	v_mad_i64_i32 v[134:135], s[4:5], v134, s31, 0
	v_mfma_f32_16x16x32_bf16 v[70:73], v[180:183], v[208:211], v[192:195]
	v_lshl_add_u64 v[140:141], v[140:141], 0, v[138:139]
	v_cmp_gt_i32_e32 vcc, s34, v132
	v_ashrrev_i32_e32 v133, 31, v132
	v_bfe_u32 v246, v130, 4, 1
	v_mul_u32_u24_e32 v246, 24, v246
	v_mov_b32_e32 v247, 0
	v_mfma_f32_16x16x32_bf16 v[38:41], v[180:183], v[212:215], v[220:223]
	v_lshl_add_u64 v[134:135], s[24:25], 0, v[134:135]
	v_lshl_add_u64 v[140:141], v[140:141], 1, s[20:21]
	v_mfma_f32_16x16x32_bf16 v[34:37], v[184:187], v[212:215], v[168:171]
	v_mfma_f32_16x16x32_bf16 v[2:5], v[184:187], v[216:219], v[172:175]
	v_lshl_add_u64 v[218:219], v[132:133], 2, v[134:135]
	global_load_dwordx4 v[198:201], v[218:219], off
	global_load_dwordx4 v[202:205], v[218:219], off offset:64
	global_load_dwordx4 v[206:209], v[218:219], off offset:128
	global_load_dwordx4 v[210:213], v[218:219], off offset:192
	global_load_dwordx4 v[214:217], v[218:219], off offset:256
	global_load_dwordx4 v[224:227], v[218:219], off offset:320
	global_load_dwordx4 v[228:231], v[218:219], off offset:384
	global_load_dwordx4 v[232:235], v[218:219], off offset:448
	s_nop 0
	v_lshl_add_u64 v[172:173], v[132:133], 1, v[140:141]
	v_lshl_add_u64 v[196:197], v[132:133], 1, v[140:141]
	global_load_dwordx2 v[176:177], v[196:197], off
	global_load_dwordx2 v[178:179], v[196:197], off offset:32
	global_load_dwordx2 v[180:181], v[196:197], off offset:64
	global_load_dwordx2 v[182:183], v[196:197], off offset:96
	global_load_dwordx2 v[184:185], v[196:197], off offset:128
	global_load_dwordx2 v[186:187], v[196:197], off offset:160
	global_load_dwordx2 v[188:189], v[196:197], off offset:192
	global_load_dwordx2 v[190:191], v[196:197], off offset:224
	v_add_f32_e32 v126, 0, v126
	v_add_f32_e32 v127, 0, v127
	v_add_f32_e32 v128, 0, v128
	v_add_f32_e32 v129, 0, v129
	s_waitcnt vmcnt(7)
	v_lshlrev_b32_e32 v130, 16, v176
	v_and_b32_e32 v137, 0xffff0000, v176
	v_lshlrev_b32_e32 v167, 16, v177
	v_and_b32_e32 v174, 0xffff0000, v177
	v_fmac_f32_e32 v130, v126, v198
	v_fmac_f32_e32 v137, v127, v199
	v_fmac_f32_e32 v167, v128, v200
	v_fmac_f32_e32 v174, v129, v201
	v_cvt_pk_bf16_f32 v126, v130, v137
	v_cvt_pk_bf16_f32 v127, v167, v174
	v_lshl_add_u64 v[168:169], v[132:133], 1, v[140:141]
	v_add_f32_e32 v122, 0, v122
	v_add_f32_e32 v123, 0, v123
	v_add_f32_e32 v124, 0, v124
	v_add_f32_e32 v125, 0, v125
	s_waitcnt vmcnt(6)
	v_lshlrev_b32_e32 v130, 16, v178
	v_and_b32_e32 v137, 0xffff0000, v178
	v_lshlrev_b32_e32 v167, 16, v179
	v_and_b32_e32 v170, 0xffff0000, v179
	v_fmac_f32_e32 v130, v122, v202
	v_fmac_f32_e32 v137, v123, v203
	v_fmac_f32_e32 v167, v124, v204
	v_fmac_f32_e32 v170, v125, v205
	v_cvt_pk_bf16_f32 v128, v130, v137
	v_cvt_pk_bf16_f32 v129, v167, v170
	s_nop 1
	v_permlane16_swap_b32 v126, v128
	v_permlane16_swap_b32 v127, v129
	v_lshl_add_u64 v[248:249], v[168:169], 0, v[246:247]
	s_nop 0
	global_store_dwordx4 v[248:249], v[126:129], off
	s_nop 1
	v_or_b32_e32 v122, 32, v132
	v_lshl_add_u64 v[126:127], v[132:133], 1, v[140:141]
	v_add_f32_e32 v118, 0, v118
	v_add_f32_e32 v119, 0, v119
	v_add_f32_e32 v120, 0, v120
	v_add_f32_e32 v121, 0, v121
	s_waitcnt vmcnt(6)
	v_lshlrev_b32_e32 v130, 16, v180
	v_and_b32_e32 v128, 0xffff0000, v180
	v_lshlrev_b32_e32 v137, 16, v181
	v_and_b32_e32 v129, 0xffff0000, v181
	v_fmac_f32_e32 v130, v118, v206
	v_fmac_f32_e32 v128, v119, v207
	v_fmac_f32_e32 v137, v120, v208
	v_fmac_f32_e32 v129, v121, v209
	v_cvt_pk_bf16_f32 v118, v130, v128
	v_cvt_pk_bf16_f32 v119, v137, v129
	v_lshl_add_u64 v[122:123], v[132:133], 1, v[140:141]
	v_add_f32_e32 v114, 0, v114
	v_add_f32_e32 v115, 0, v115
	v_add_f32_e32 v116, 0, v116
	v_add_f32_e32 v117, 0, v117
	s_waitcnt vmcnt(5)
	v_lshlrev_b32_e32 v126, 16, v182
	v_and_b32_e32 v124, 0xffff0000, v182
	v_lshlrev_b32_e32 v127, 16, v183
	v_and_b32_e32 v125, 0xffff0000, v183
	v_fmac_f32_e32 v126, v114, v210
	v_fmac_f32_e32 v124, v115, v211
	v_fmac_f32_e32 v127, v116, v212
	v_fmac_f32_e32 v125, v117, v213
	v_cvt_pk_bf16_f32 v120, v126, v124
	v_cvt_pk_bf16_f32 v121, v127, v125
	s_nop 1
	v_permlane16_swap_b32 v118, v120
	v_permlane16_swap_b32 v119, v121
	v_lshl_add_u64 v[248:249], v[122:123], 0, v[246:247]
	s_nop 0
	global_store_dwordx4 v[248:249], v[118:121], off offset:64
	s_nop 1
	v_or_b32_e32 v114, 64, v132
	v_lshl_add_u64 v[118:119], v[132:133], 1, v[140:141]
	v_add_f32_e32 v110, 0, v110
	v_add_f32_e32 v111, 0, v111
	v_add_f32_e32 v112, 0, v112
	v_add_f32_e32 v113, 0, v113
	s_waitcnt vmcnt(5)
; __device__ __forceinline__ unsigned pack2(float a, float b) { unsigned r; asm("v_cvt_pk_bf16_f32 %0, %1, %2" : "=v"(r) : "v"(a), "v"(b)); return r; }
; __device__ __forceinline__ float bf2f(bf16_t h) { return __uint_as_float(((unsigned)h) << 16); }
;   __device__ __forceinline__ void c4(int g, int rig, int col, f32x4 v) const {
;     const size_t o = ((size_t)g * 2048 + rig) * 1024 + col;
;     f32x4 bs;
;     if (BASE_F32) bs = __builtin_nontemporal_load((const f32x4*)((const float*)base + o));
;     else {
;       const uint2 u = *(const uint2*)((const bf16_t*)base + o);
;       bs[0] = bf2f((bf16_t)(u.x & 0xffff)); bs[1] = bf2f((bf16_t)(u.x >> 16)); bs[2] = bf2f((bf16_t)(u.y & 0xffff)); bs[3] = bf2f((bf16_t)(u.y >> 16));
;     }
;     const f32x4 gt = *(const f32x4*)(gate + (size_t)g * 6144 + col);
;     f32x4 bi = {0.f, 0.f, 0.f, 0.f};
;     if (bias) bi = *(const f32x4*)(bias + col);
;     f32x4 r;
; #pragma unroll
;     for (int j = 0; j < 4; ++j) r[j] = bs[j] + gt[j] * (v[j] + bi[j]);
;     uint2 w; w.x = pack2(r[0], r[1]); w.y = pack2(r[2], r[3]);
;     *(uint2*)(X16 + o) = w;
;   }
; template <bool SWAP, class Epi, bool THIN = false> ...
;     ...
; #pragma unroll
;           for (int n = 0; n < 8; ++n) {
;             const int col = nt * 256 + wc_e * 128 + n * 16 + fq_e * 4;
;             if (col < N) epi.c4(g, rig, col, acc[m][n]);
	v_lshlrev_b32_e32 v122, 16, v184
	v_and_b32_e32 v120, 0xffff0000, v184
	v_lshlrev_b32_e32 v123, 16, v185
	v_and_b32_e32 v121, 0xffff0000, v185
	v_fmac_f32_e32 v122, v110, v214
	v_fmac_f32_e32 v120, v111, v215
	v_fmac_f32_e32 v123, v112, v216
	v_fmac_f32_e32 v121, v113, v217
	v_cvt_pk_bf16_f32 v110, v122, v120
	v_cvt_pk_bf16_f32 v111, v123, v121
	v_lshl_add_u64 v[114:115], v[132:133], 1, v[140:141]
	v_add_f32_e32 v106, 0, v106
	v_add_f32_e32 v107, 0, v107
	v_add_f32_e32 v108, 0, v108
	v_add_f32_e32 v109, 0, v109
	s_waitcnt vmcnt(4)
	v_lshlrev_b32_e32 v118, 16, v186
	v_and_b32_e32 v116, 0xffff0000, v186
	v_lshlrev_b32_e32 v119, 16, v187
	v_and_b32_e32 v117, 0xffff0000, v187
	v_fmac_f32_e32 v118, v106, v224
	v_fmac_f32_e32 v116, v107, v225
	v_fmac_f32_e32 v119, v108, v226
	v_fmac_f32_e32 v117, v109, v227
	v_cvt_pk_bf16_f32 v112, v118, v116
	v_cvt_pk_bf16_f32 v113, v119, v117
	s_nop 1
	v_permlane16_swap_b32 v110, v112
	v_permlane16_swap_b32 v111, v113
	v_lshl_add_u64 v[248:249], v[114:115], 0, v[246:247]
	s_nop 0
	global_store_dwordx4 v[248:249], v[110:113], off offset:128
	s_nop 1
	v_or_b32_e32 v106, 0x60, v132
	v_lshl_add_u64 v[110:111], v[132:133], 1, v[140:141]
	v_add_f32_e32 v102, 0, v102
	v_add_f32_e32 v103, 0, v103
	v_add_f32_e32 v104, 0, v104
	v_add_f32_e32 v105, 0, v105
	s_waitcnt vmcnt(4)
	v_lshlrev_b32_e32 v114, 16, v188
	v_and_b32_e32 v112, 0xffff0000, v188
	v_lshlrev_b32_e32 v115, 16, v189
	v_and_b32_e32 v113, 0xffff0000, v189
	v_fmac_f32_e32 v114, v102, v228
	v_fmac_f32_e32 v112, v103, v229
	v_fmac_f32_e32 v115, v104, v230
	v_fmac_f32_e32 v113, v105, v231
	v_cvt_pk_bf16_f32 v102, v114, v112
	v_cvt_pk_bf16_f32 v103, v115, v113
	v_lshl_add_u64 v[106:107], v[132:133], 1, v[140:141]
	v_add_f32_e32 v98, 0, v98
	v_add_f32_e32 v99, 0, v99
	v_add_f32_e32 v100, 0, v100
	v_add_f32_e32 v101, 0, v101
	s_waitcnt vmcnt(3)
	v_lshlrev_b32_e32 v110, 16, v190
	v_and_b32_e32 v108, 0xffff0000, v190
	v_lshlrev_b32_e32 v111, 16, v191
	v_and_b32_e32 v109, 0xffff0000, v191
	v_fmac_f32_e32 v110, v98, v232
	v_fmac_f32_e32 v108, v99, v233
	v_fmac_f32_e32 v111, v100, v234
	v_fmac_f32_e32 v109, v101, v235
	v_cvt_pk_bf16_f32 v104, v110, v108
	v_cvt_pk_bf16_f32 v105, v111, v109
	s_nop 1
	v_permlane16_swap_b32 v102, v104
	v_permlane16_swap_b32 v103, v105
	v_lshl_add_u64 v[248:249], v[106:107], 0, v[246:247]
	s_nop 0
	global_store_dwordx4 v[248:249], v[102:105], off offset:192
	s_nop 1
	v_or_b32_e32 v98, 16, v136
	v_ashrrev_i32_e32 v99, 31, v98
	v_lshlrev_b64 v[98:99], 10, v[98:99]
	v_lshl_add_u64 v[98:99], v[98:99], 0, v[138:139]
	v_lshl_add_u64 v[98:99], v[98:99], 1, s[20:21]
	v_lshl_add_u64 v[104:105], v[132:133], 1, v[98:99]
	v_lshl_add_u64 v[196:197], v[132:133], 1, v[98:99]
	global_load_dwordx2 v[176:177], v[196:197], off
	global_load_dwordx2 v[178:179], v[196:197], off offset:32
	global_load_dwordx2 v[180:181], v[196:197], off offset:64
	global_load_dwordx2 v[182:183], v[196:197], off offset:96
	global_load_dwordx2 v[184:185], v[196:197], off offset:128
	global_load_dwordx2 v[186:187], v[196:197], off offset:160
	global_load_dwordx2 v[188:189], v[196:197], off offset:192
	global_load_dwordx2 v[190:191], v[196:197], off offset:224
	v_add_f32_e32 v94, 0, v94
	v_add_f32_e32 v95, 0, v95
	v_add_f32_e32 v96, 0, v96
	v_add_f32_e32 v97, 0, v97
	s_waitcnt vmcnt(7)
	v_lshlrev_b32_e32 v108, 16, v176
	v_and_b32_e32 v106, 0xffff0000, v176
	v_lshlrev_b32_e32 v109, 16, v177
	v_and_b32_e32 v107, 0xffff0000, v177
	v_fmac_f32_e32 v108, v94, v198
	v_fmac_f32_e32 v106, v95, v199
	v_fmac_f32_e32 v109, v96, v200
	v_fmac_f32_e32 v107, v97, v201
	v_cvt_pk_bf16_f32 v94, v108, v106
	v_cvt_pk_bf16_f32 v95, v109, v107
	v_lshl_add_u64 v[100:101], v[132:133], 1, v[98:99]
	v_add_f32_e32 v90, 0, v90
	v_add_f32_e32 v91, 0, v91
	v_add_f32_e32 v92, 0, v92
	v_add_f32_e32 v93, 0, v93
	s_waitcnt vmcnt(6)
	v_lshlrev_b32_e32 v104, 16, v178
	v_and_b32_e32 v102, 0xffff0000, v178
	v_lshlrev_b32_e32 v105, 16, v179
	v_and_b32_e32 v103, 0xffff0000, v179
	v_fmac_f32_e32 v104, v90, v202
	v_fmac_f32_e32 v102, v91, v203
	v_fmac_f32_e32 v105, v92, v204
	v_fmac_f32_e32 v103, v93, v205
	v_cvt_pk_bf16_f32 v96, v104, v102
	v_cvt_pk_bf16_f32 v97, v105, v103
	s_nop 1
	v_permlane16_swap_b32 v94, v96
	v_permlane16_swap_b32 v95, v97
	v_lshl_add_u64 v[248:249], v[100:101], 0, v[246:247]
	s_nop 0
	global_store_dwordx4 v[248:249], v[94:97], off
	s_nop 1
	v_lshl_add_u64 v[94:95], v[132:133], 1, v[98:99]
	v_add_f32_e32 v86, 0, v86
	v_add_f32_e32 v87, 0, v87
	v_add_f32_e32 v88, 0, v88
	v_add_f32_e32 v89, 0, v89
	s_waitcnt vmcnt(6)
	v_lshlrev_b32_e32 v100, 16, v180
	v_and_b32_e32 v96, 0xffff0000, v180
	v_lshlrev_b32_e32 v101, 16, v181
	v_and_b32_e32 v97, 0xffff0000, v181
	v_fmac_f32_e32 v100, v86, v206
	v_fmac_f32_e32 v96, v87, v207
	v_fmac_f32_e32 v101, v88, v208
	v_fmac_f32_e32 v97, v89, v209
	v_cvt_pk_bf16_f32 v86, v100, v96
	v_cvt_pk_bf16_f32 v87, v101, v97
	v_lshl_add_u64 v[90:91], v[132:133], 1, v[98:99]
	v_add_f32_e32 v82, 0, v82
	v_add_f32_e32 v83, 0, v83
	v_add_f32_e32 v84, 0, v84
	v_add_f32_e32 v85, 0, v85
	s_waitcnt vmcnt(5)
	v_lshlrev_b32_e32 v94, 16, v182
	v_and_b32_e32 v92, 0xffff0000, v182
	v_lshlrev_b32_e32 v95, 16, v183
	v_and_b32_e32 v93, 0xffff0000, v183
	v_fmac_f32_e32 v94, v82, v210
	v_fmac_f32_e32 v92, v83, v211
	v_fmac_f32_e32 v95, v84, v212
	v_fmac_f32_e32 v93, v85, v213
	v_cvt_pk_bf16_f32 v88, v94, v92
	v_cvt_pk_bf16_f32 v89, v95, v93
	s_nop 1
	v_permlane16_swap_b32 v86, v88
	v_permlane16_swap_b32 v87, v89
	v_lshl_add_u64 v[248:249], v[90:91], 0, v[246:247]
	s_nop 0
	global_store_dwordx4 v[248:249], v[86:89], off offset:64
	s_nop 1
	v_lshl_add_u64 v[86:87], v[132:133], 1, v[98:99]
	v_add_f32_e32 v78, 0, v78
	v_add_f32_e32 v79, 0, v79
	v_add_f32_e32 v80, 0, v80
	v_add_f32_e32 v81, 0, v81
	s_waitcnt vmcnt(5)
; __device__ __forceinline__ unsigned pack2(float a, float b) { unsigned r; asm("v_cvt_pk_bf16_f32 %0, %1, %2" : "=v"(r) : "v"(a), "v"(b)); return r; }
; __device__ __forceinline__ float bf2f(bf16_t h) { return __uint_as_float(((unsigned)h) << 16); }
;   __device__ __forceinline__ void c4(int g, int rig, int col, f32x4 v) const {
;     const size_t o = ((size_t)g * 2048 + rig) * 1024 + col;
;     f32x4 bs;
;     if (BASE_F32) bs = __builtin_nontemporal_load((const f32x4*)((const float*)base + o));
;     else {
;       const uint2 u = *(const uint2*)((const bf16_t*)base + o);
;       bs[0] = bf2f((bf16_t)(u.x & 0xffff)); bs[1] = bf2f((bf16_t)(u.x >> 16)); bs[2] = bf2f((bf16_t)(u.y & 0xffff)); bs[3] = bf2f((bf16_t)(u.y >> 16));
;     }
;     const f32x4 gt = *(const f32x4*)(gate + (size_t)g * 6144 + col);
;     f32x4 bi = {0.f, 0.f, 0.f, 0.f};
;     if (bias) bi = *(const f32x4*)(bias + col);
;     f32x4 r;
; #pragma unroll
;     for (int j = 0; j < 4; ++j) r[j] = bs[j] + gt[j] * (v[j] + bi[j]);
;     uint2 w; w.x = pack2(r[0], r[1]); w.y = pack2(r[2], r[3]);
;     *(uint2*)(X16 + o) = w;
;   }
; template <bool SWAP, class Epi, bool THIN = false> ...
;     ...
; #pragma unroll
;           for (int n = 0; n < 8; ++n) {
;             const int col = nt * 256 + wc_e * 128 + n * 16 + fq_e * 4;
;             if (col < N) epi.c4(g, rig, col, acc[m][n]);
	v_lshlrev_b32_e32 v90, 16, v184
	v_and_b32_e32 v88, 0xffff0000, v184
	v_lshlrev_b32_e32 v91, 16, v185
	v_and_b32_e32 v89, 0xffff0000, v185
	v_fmac_f32_e32 v90, v78, v214
	v_fmac_f32_e32 v88, v79, v215
	v_fmac_f32_e32 v91, v80, v216
	v_fmac_f32_e32 v89, v81, v217
	v_cvt_pk_bf16_f32 v78, v90, v88
	v_cvt_pk_bf16_f32 v79, v91, v89
	v_lshl_add_u64 v[82:83], v[132:133], 1, v[98:99]
	v_add_f32_e32 v74, 0, v74
	v_add_f32_e32 v75, 0, v75
	v_add_f32_e32 v76, 0, v76
	v_add_f32_e32 v77, 0, v77
	s_waitcnt vmcnt(4)
	v_lshlrev_b32_e32 v86, 16, v186
	v_and_b32_e32 v84, 0xffff0000, v186
	v_lshlrev_b32_e32 v87, 16, v187
	v_and_b32_e32 v85, 0xffff0000, v187
	v_fmac_f32_e32 v86, v74, v224
	v_fmac_f32_e32 v84, v75, v225
	v_fmac_f32_e32 v87, v76, v226
	v_fmac_f32_e32 v85, v77, v227
	v_cvt_pk_bf16_f32 v80, v86, v84
	v_cvt_pk_bf16_f32 v81, v87, v85
	s_nop 1
	v_permlane16_swap_b32 v78, v80
	v_permlane16_swap_b32 v79, v81
	v_lshl_add_u64 v[248:249], v[82:83], 0, v[246:247]
	s_nop 0
	global_store_dwordx4 v[248:249], v[78:81], off offset:128
	s_nop 1
	v_lshl_add_u64 v[78:79], v[132:133], 1, v[98:99]
	v_add_f32_e32 v70, 0, v70
	v_add_f32_e32 v71, 0, v71
	v_add_f32_e32 v72, 0, v72
	v_add_f32_e32 v73, 0, v73
	s_waitcnt vmcnt(4)
	v_lshlrev_b32_e32 v82, 16, v188
	v_and_b32_e32 v80, 0xffff0000, v188
	v_lshlrev_b32_e32 v83, 16, v189
	v_and_b32_e32 v81, 0xffff0000, v189
	v_fmac_f32_e32 v82, v70, v228
	v_fmac_f32_e32 v80, v71, v229
	v_fmac_f32_e32 v83, v72, v230
	v_fmac_f32_e32 v81, v73, v231
	v_cvt_pk_bf16_f32 v70, v82, v80
	v_cvt_pk_bf16_f32 v71, v83, v81
	v_lshl_add_u64 v[74:75], v[132:133], 1, v[98:99]
	v_add_f32_e32 v66, 0, v66
	v_add_f32_e32 v67, 0, v67
	v_add_f32_e32 v68, 0, v68
	v_add_f32_e32 v69, 0, v69
	s_waitcnt vmcnt(3)
	v_lshlrev_b32_e32 v78, 16, v190
	v_and_b32_e32 v76, 0xffff0000, v190
	v_lshlrev_b32_e32 v79, 16, v191
	v_and_b32_e32 v77, 0xffff0000, v191
	v_fmac_f32_e32 v78, v66, v232
	v_fmac_f32_e32 v76, v67, v233
	v_fmac_f32_e32 v79, v68, v234
	v_fmac_f32_e32 v77, v69, v235
	v_cvt_pk_bf16_f32 v72, v78, v76
	v_cvt_pk_bf16_f32 v73, v79, v77
	s_nop 1
	v_permlane16_swap_b32 v70, v72
	v_permlane16_swap_b32 v71, v73
	v_lshl_add_u64 v[248:249], v[74:75], 0, v[246:247]
	s_nop 0
	global_store_dwordx4 v[248:249], v[70:73], off offset:192
	s_nop 1
	v_or_b32_e32 v66, 32, v136
	v_ashrrev_i32_e32 v67, 31, v66
	v_lshlrev_b64 v[66:67], 10, v[66:67]
	v_lshl_add_u64 v[66:67], v[66:67], 0, v[138:139]
	v_lshl_add_u64 v[66:67], v[66:67], 1, s[20:21]
	v_lshl_add_u64 v[72:73], v[132:133], 1, v[66:67]
	v_lshl_add_u64 v[196:197], v[132:133], 1, v[66:67]
	global_load_dwordx2 v[176:177], v[196:197], off
	global_load_dwordx2 v[178:179], v[196:197], off offset:32
	global_load_dwordx2 v[180:181], v[196:197], off offset:64
	global_load_dwordx2 v[182:183], v[196:197], off offset:96
	global_load_dwordx2 v[184:185], v[196:197], off offset:128
	global_load_dwordx2 v[186:187], v[196:197], off offset:160
	global_load_dwordx2 v[188:189], v[196:197], off offset:192
	global_load_dwordx2 v[190:191], v[196:197], off offset:224
	v_add_f32_e32 v62, 0, v62
	v_add_f32_e32 v63, 0, v63
	v_add_f32_e32 v64, 0, v64
	v_add_f32_e32 v65, 0, v65
	s_waitcnt vmcnt(7)
	v_lshlrev_b32_e32 v76, 16, v176
	v_and_b32_e32 v74, 0xffff0000, v176
	v_lshlrev_b32_e32 v77, 16, v177
	v_and_b32_e32 v75, 0xffff0000, v177
	v_fmac_f32_e32 v76, v62, v198
	v_fmac_f32_e32 v74, v63, v199
	v_fmac_f32_e32 v77, v64, v200
	v_fmac_f32_e32 v75, v65, v201
	v_cvt_pk_bf16_f32 v62, v76, v74
	v_cvt_pk_bf16_f32 v63, v77, v75
	v_lshl_add_u64 v[68:69], v[132:133], 1, v[66:67]
	v_add_f32_e32 v58, 0, v58
	v_add_f32_e32 v59, 0, v59
	v_add_f32_e32 v60, 0, v60
	v_add_f32_e32 v61, 0, v61
	s_waitcnt vmcnt(6)
	v_lshlrev_b32_e32 v72, 16, v178
	v_and_b32_e32 v70, 0xffff0000, v178
	v_lshlrev_b32_e32 v73, 16, v179
	v_and_b32_e32 v71, 0xffff0000, v179
	v_fmac_f32_e32 v72, v58, v202
	v_fmac_f32_e32 v70, v59, v203
	v_fmac_f32_e32 v73, v60, v204
	v_fmac_f32_e32 v71, v61, v205
	v_cvt_pk_bf16_f32 v64, v72, v70
	v_cvt_pk_bf16_f32 v65, v73, v71
	s_nop 1
	v_permlane16_swap_b32 v62, v64
	v_permlane16_swap_b32 v63, v65
	v_lshl_add_u64 v[248:249], v[68:69], 0, v[246:247]
	s_nop 0
	global_store_dwordx4 v[248:249], v[62:65], off
	s_nop 1
	v_lshl_add_u64 v[62:63], v[132:133], 1, v[66:67]
	v_add_f32_e32 v54, 0, v54
	v_add_f32_e32 v55, 0, v55
	v_add_f32_e32 v56, 0, v56
	v_add_f32_e32 v57, 0, v57
	s_waitcnt vmcnt(6)
	v_lshlrev_b32_e32 v68, 16, v180
	v_and_b32_e32 v64, 0xffff0000, v180
	v_lshlrev_b32_e32 v69, 16, v181
	v_and_b32_e32 v65, 0xffff0000, v181
	v_fmac_f32_e32 v68, v54, v206
	v_fmac_f32_e32 v64, v55, v207
	v_fmac_f32_e32 v69, v56, v208
	v_fmac_f32_e32 v65, v57, v209
	v_cvt_pk_bf16_f32 v54, v68, v64
	v_cvt_pk_bf16_f32 v55, v69, v65
	v_lshl_add_u64 v[58:59], v[132:133], 1, v[66:67]
	v_add_f32_e32 v50, 0, v50
	v_add_f32_e32 v51, 0, v51
	v_add_f32_e32 v52, 0, v52
	v_add_f32_e32 v53, 0, v53
	s_waitcnt vmcnt(5)
	v_lshlrev_b32_e32 v62, 16, v182
	v_and_b32_e32 v60, 0xffff0000, v182
	v_lshlrev_b32_e32 v63, 16, v183
	v_and_b32_e32 v61, 0xffff0000, v183
	v_fmac_f32_e32 v62, v50, v210
	v_fmac_f32_e32 v60, v51, v211
	v_fmac_f32_e32 v63, v52, v212
	v_fmac_f32_e32 v61, v53, v213
	v_cvt_pk_bf16_f32 v56, v62, v60
	v_cvt_pk_bf16_f32 v57, v63, v61
	s_nop 1
	v_permlane16_swap_b32 v54, v56
	v_permlane16_swap_b32 v55, v57
	v_lshl_add_u64 v[248:249], v[58:59], 0, v[246:247]
	s_nop 0
	global_store_dwordx4 v[248:249], v[54:57], off offset:64
	s_nop 1
	v_lshl_add_u64 v[54:55], v[132:133], 1, v[66:67]
	v_add_f32_e32 v46, 0, v46
	v_add_f32_e32 v47, 0, v47
	v_add_f32_e32 v48, 0, v48
	v_add_f32_e32 v49, 0, v49
	s_waitcnt vmcnt(5)
; __device__ __forceinline__ unsigned pack2(float a, float b) { unsigned r; asm("v_cvt_pk_bf16_f32 %0, %1, %2" : "=v"(r) : "v"(a), "v"(b)); return r; }
; __device__ __forceinline__ float bf2f(bf16_t h) { return __uint_as_float(((unsigned)h) << 16); }
;   __device__ __forceinline__ void c4(int g, int rig, int col, f32x4 v) const {
;     const size_t o = ((size_t)g * 2048 + rig) * 1024 + col;
;     f32x4 bs;
;     if (BASE_F32) bs = __builtin_nontemporal_load((const f32x4*)((const float*)base + o));
;     else {
;       const uint2 u = *(const uint2*)((const bf16_t*)base + o);
;       bs[0] = bf2f((bf16_t)(u.x & 0xffff)); bs[1] = bf2f((bf16_t)(u.x >> 16)); bs[2] = bf2f((bf16_t)(u.y & 0xffff)); bs[3] = bf2f((bf16_t)(u.y >> 16));
;     }
;     const f32x4 gt = *(const f32x4*)(gate + (size_t)g * 6144 + col);
;     f32x4 bi = {0.f, 0.f, 0.f, 0.f};
;     if (bias) bi = *(const f32x4*)(bias + col);
;     f32x4 r;
; #pragma unroll
;     for (int j = 0; j < 4; ++j) r[j] = bs[j] + gt[j] * (v[j] + bi[j]);
;     uint2 w; w.x = pack2(r[0], r[1]); w.y = pack2(r[2], r[3]);
;     *(uint2*)(X16 + o) = w;
;   }
; template <bool SWAP, class Epi, bool THIN = false> ...
;     ...
; #pragma unroll
;           for (int n = 0; n < 8; ++n) {
;             const int col = nt * 256 + wc_e * 128 + n * 16 + fq_e * 4;
;             if (col < N) epi.c4(g, rig, col, acc[m][n]);
	v_lshlrev_b32_e32 v58, 16, v184
	v_and_b32_e32 v56, 0xffff0000, v184
	v_lshlrev_b32_e32 v59, 16, v185
	v_and_b32_e32 v57, 0xffff0000, v185
	v_fmac_f32_e32 v58, v46, v214
	v_fmac_f32_e32 v56, v47, v215
	v_fmac_f32_e32 v59, v48, v216
	v_fmac_f32_e32 v57, v49, v217
	v_cvt_pk_bf16_f32 v46, v58, v56
	v_cvt_pk_bf16_f32 v47, v59, v57
	v_lshl_add_u64 v[50:51], v[132:133], 1, v[66:67]
	v_add_f32_e32 v42, 0, v42
	v_add_f32_e32 v43, 0, v43
	v_add_f32_e32 v44, 0, v44
	v_add_f32_e32 v45, 0, v45
	s_waitcnt vmcnt(4)
	v_lshlrev_b32_e32 v54, 16, v186
	v_and_b32_e32 v52, 0xffff0000, v186
	v_lshlrev_b32_e32 v55, 16, v187
	v_and_b32_e32 v53, 0xffff0000, v187
	v_fmac_f32_e32 v54, v42, v224
	v_fmac_f32_e32 v52, v43, v225
	v_fmac_f32_e32 v55, v44, v226
	v_fmac_f32_e32 v53, v45, v227
	v_cvt_pk_bf16_f32 v48, v54, v52
	v_cvt_pk_bf16_f32 v49, v55, v53
	s_nop 1
	v_permlane16_swap_b32 v46, v48
	v_permlane16_swap_b32 v47, v49
	v_lshl_add_u64 v[248:249], v[50:51], 0, v[246:247]
	s_nop 0
	global_store_dwordx4 v[248:249], v[46:49], off offset:128
	s_nop 1
	v_lshl_add_u64 v[46:47], v[132:133], 1, v[66:67]
	v_add_f32_e32 v38, 0, v38
	v_add_f32_e32 v39, 0, v39
	v_add_f32_e32 v40, 0, v40
	v_add_f32_e32 v41, 0, v41
	s_waitcnt vmcnt(4)
	v_lshlrev_b32_e32 v50, 16, v188
	v_and_b32_e32 v48, 0xffff0000, v188
	v_lshlrev_b32_e32 v51, 16, v189
	v_and_b32_e32 v49, 0xffff0000, v189
	v_fmac_f32_e32 v50, v38, v228
	v_fmac_f32_e32 v48, v39, v229
	v_fmac_f32_e32 v51, v40, v230
	v_fmac_f32_e32 v49, v41, v231
	v_cvt_pk_bf16_f32 v38, v50, v48
	v_cvt_pk_bf16_f32 v39, v51, v49
	v_lshl_add_u64 v[42:43], v[132:133], 1, v[66:67]
	v_add_f32_e32 v34, 0, v34
	v_add_f32_e32 v35, 0, v35
	v_add_f32_e32 v36, 0, v36
	v_add_f32_e32 v37, 0, v37
	s_waitcnt vmcnt(3)
	v_lshlrev_b32_e32 v46, 16, v190
	v_and_b32_e32 v44, 0xffff0000, v190
	v_lshlrev_b32_e32 v47, 16, v191
	v_and_b32_e32 v45, 0xffff0000, v191
	v_fmac_f32_e32 v46, v34, v232
	v_fmac_f32_e32 v44, v35, v233
	v_fmac_f32_e32 v47, v36, v234
	v_fmac_f32_e32 v45, v37, v235
	v_cvt_pk_bf16_f32 v40, v46, v44
	v_cvt_pk_bf16_f32 v41, v47, v45
	s_nop 1
	v_permlane16_swap_b32 v38, v40
	v_permlane16_swap_b32 v39, v41
	v_lshl_add_u64 v[248:249], v[42:43], 0, v[246:247]
	s_nop 0
	global_store_dwordx4 v[248:249], v[38:41], off offset:192
	s_nop 1
	v_or_b32_e32 v34, 48, v136
	v_ashrrev_i32_e32 v35, 31, v34
	v_lshlrev_b64 v[34:35], 10, v[34:35]
	v_lshl_add_u64 v[34:35], v[34:35], 0, v[138:139]
	v_lshl_add_u64 v[34:35], v[34:35], 1, s[20:21]
	v_lshl_add_u64 v[40:41], v[132:133], 1, v[34:35]
	v_lshl_add_u64 v[196:197], v[132:133], 1, v[34:35]
	global_load_dwordx2 v[176:177], v[196:197], off
	global_load_dwordx2 v[178:179], v[196:197], off offset:32
	global_load_dwordx2 v[180:181], v[196:197], off offset:64
	global_load_dwordx2 v[182:183], v[196:197], off offset:96
	global_load_dwordx2 v[184:185], v[196:197], off offset:128
	global_load_dwordx2 v[186:187], v[196:197], off offset:160
	global_load_dwordx2 v[188:189], v[196:197], off offset:192
	global_load_dwordx2 v[190:191], v[196:197], off offset:224
	v_add_f32_e32 v30, 0, v30
	v_add_f32_e32 v31, 0, v31
	v_add_f32_e32 v32, 0, v32
	v_add_f32_e32 v33, 0, v33
	s_waitcnt vmcnt(7)
	v_lshlrev_b32_e32 v44, 16, v176
	v_and_b32_e32 v42, 0xffff0000, v176
	v_lshlrev_b32_e32 v45, 16, v177
	v_and_b32_e32 v43, 0xffff0000, v177
	v_fmac_f32_e32 v44, v30, v198
	v_fmac_f32_e32 v42, v31, v199
	v_fmac_f32_e32 v45, v32, v200
	v_fmac_f32_e32 v43, v33, v201
	v_cvt_pk_bf16_f32 v30, v44, v42
	v_cvt_pk_bf16_f32 v31, v45, v43
	v_lshl_add_u64 v[36:37], v[132:133], 1, v[34:35]
	v_add_f32_e32 v26, 0, v26
	v_add_f32_e32 v27, 0, v27
	v_add_f32_e32 v28, 0, v28
	v_add_f32_e32 v29, 0, v29
	s_waitcnt vmcnt(6)
; __device__ __forceinline__ unsigned pack2(float a, float b) { unsigned r; asm("v_cvt_pk_bf16_f32 %0, %1, %2" : "=v"(r) : "v"(a), "v"(b)); return r; }
; __device__ __forceinline__ float bf2f(bf16_t h) { return __uint_as_float(((unsigned)h) << 16); }
;   __device__ __forceinline__ void c4(int g, int rig, int col, f32x4 v) const {
;     const size_t o = ((size_t)g * 2048 + rig) * 1024 + col;
;     f32x4 bs;
;     if (BASE_F32) bs = __builtin_nontemporal_load((const f32x4*)((const float*)base + o));
;     else {
;       const uint2 u = *(const uint2*)((const bf16_t*)base + o);
;       bs[0] = bf2f((bf16_t)(u.x & 0xffff)); bs[1] = bf2f((bf16_t)(u.x >> 16)); bs[2] = bf2f((bf16_t)(u.y & 0xffff)); bs[3] = bf2f((bf16_t)(u.y >> 16));
;     }
;     const f32x4 gt = *(const f32x4*)(gate + (size_t)g * 6144 + col);
;     f32x4 bi = {0.f, 0.f, 0.f, 0.f};
;     if (bias) bi = *(const f32x4*)(bias + col);
;     f32x4 r;
; #pragma unroll
;     for (int j = 0; j < 4; ++j) r[j] = bs[j] + gt[j] * (v[j] + bi[j]);
;     uint2 w; w.x = pack2(r[0], r[1]); w.y = pack2(r[2], r[3]);
;     *(uint2*)(X16 + o) = w;
;   }
	v_lshlrev_b32_e32 v40, 16, v178
	v_and_b32_e32 v38, 0xffff0000, v178
	v_lshlrev_b32_e32 v41, 16, v179
	v_and_b32_e32 v39, 0xffff0000, v179
	v_fmac_f32_e32 v40, v26, v202
	v_fmac_f32_e32 v38, v27, v203
	v_fmac_f32_e32 v41, v28, v204
	v_fmac_f32_e32 v39, v29, v205
	v_cvt_pk_bf16_f32 v32, v40, v38
	v_cvt_pk_bf16_f32 v33, v41, v39
	s_nop 1
	v_permlane16_swap_b32 v30, v32
	v_permlane16_swap_b32 v31, v33
	v_lshl_add_u64 v[248:249], v[36:37], 0, v[246:247]
	s_nop 0
	global_store_dwordx4 v[248:249], v[30:33], off
	s_nop 1
	v_lshl_add_u64 v[30:31], v[132:133], 1, v[34:35]
	v_add_f32_e32 v22, 0, v22
	v_add_f32_e32 v23, 0, v23
	v_add_f32_e32 v24, 0, v24
	v_add_f32_e32 v25, 0, v25
	s_waitcnt vmcnt(6)
	v_lshlrev_b32_e32 v36, 16, v180
	v_and_b32_e32 v32, 0xffff0000, v180
	v_lshlrev_b32_e32 v37, 16, v181
	v_and_b32_e32 v33, 0xffff0000, v181
	v_fmac_f32_e32 v36, v22, v206
	v_fmac_f32_e32 v32, v23, v207
	v_fmac_f32_e32 v37, v24, v208
	v_fmac_f32_e32 v33, v25, v209
	v_cvt_pk_bf16_f32 v22, v36, v32
	v_cvt_pk_bf16_f32 v23, v37, v33
	v_lshl_add_u64 v[26:27], v[132:133], 1, v[34:35]
	v_add_f32_e32 v18, 0, v18
	v_add_f32_e32 v19, 0, v19
	v_add_f32_e32 v20, 0, v20
	v_add_f32_e32 v21, 0, v21
	s_waitcnt vmcnt(5)
	v_lshlrev_b32_e32 v30, 16, v182
	v_and_b32_e32 v28, 0xffff0000, v182
	v_lshlrev_b32_e32 v31, 16, v183
	v_and_b32_e32 v29, 0xffff0000, v183
	v_fmac_f32_e32 v30, v18, v210
	v_fmac_f32_e32 v28, v19, v211
	v_fmac_f32_e32 v31, v20, v212
	v_fmac_f32_e32 v29, v21, v213
	v_cvt_pk_bf16_f32 v24, v30, v28
	v_cvt_pk_bf16_f32 v25, v31, v29
	s_nop 1
	v_permlane16_swap_b32 v22, v24
	v_permlane16_swap_b32 v23, v25
	v_lshl_add_u64 v[248:249], v[26:27], 0, v[246:247]
	s_nop 0
	global_store_dwordx4 v[248:249], v[22:25], off offset:64
	s_nop 1
	v_lshl_add_u64 v[22:23], v[132:133], 1, v[34:35]
	v_add_f32_e32 v14, 0, v14
	v_add_f32_e32 v15, 0, v15
	v_add_f32_e32 v16, 0, v16
	v_add_f32_e32 v17, 0, v17
	s_waitcnt vmcnt(5)
	v_lshlrev_b32_e32 v26, 16, v184
	v_and_b32_e32 v24, 0xffff0000, v184
	v_lshlrev_b32_e32 v27, 16, v185
	v_and_b32_e32 v25, 0xffff0000, v185
	v_fmac_f32_e32 v26, v14, v214
	v_fmac_f32_e32 v24, v15, v215
	v_fmac_f32_e32 v27, v16, v216
	v_fmac_f32_e32 v25, v17, v217
	v_cvt_pk_bf16_f32 v14, v26, v24
	v_cvt_pk_bf16_f32 v15, v27, v25
	v_lshl_add_u64 v[18:19], v[132:133], 1, v[34:35]
	v_add_f32_e32 v10, 0, v10
	v_add_f32_e32 v11, 0, v11
	v_add_f32_e32 v12, 0, v12
	v_add_f32_e32 v13, 0, v13
	s_waitcnt vmcnt(4)
	v_lshlrev_b32_e32 v22, 16, v186
	v_and_b32_e32 v20, 0xffff0000, v186
	v_lshlrev_b32_e32 v23, 16, v187
	v_and_b32_e32 v21, 0xffff0000, v187
	v_fmac_f32_e32 v22, v10, v224
	v_fmac_f32_e32 v20, v11, v225
	v_fmac_f32_e32 v23, v12, v226
	v_fmac_f32_e32 v21, v13, v227
	v_cvt_pk_bf16_f32 v16, v22, v20
	v_cvt_pk_bf16_f32 v17, v23, v21
	s_nop 1
	v_permlane16_swap_b32 v14, v16
	v_permlane16_swap_b32 v15, v17
	v_lshl_add_u64 v[248:249], v[18:19], 0, v[246:247]
	s_nop 0
	global_store_dwordx4 v[248:249], v[14:17], off offset:128
	s_nop 1
	v_lshl_add_u64 v[14:15], v[132:133], 1, v[34:35]
	v_add_f32_e32 v6, 0, v6
	v_add_f32_e32 v7, 0, v7
	v_add_f32_e32 v8, 0, v8
	v_add_f32_e32 v9, 0, v9
	s_waitcnt vmcnt(4)
	v_lshlrev_b32_e32 v18, 16, v188
	v_and_b32_e32 v16, 0xffff0000, v188
	v_lshlrev_b32_e32 v19, 16, v189
	v_and_b32_e32 v17, 0xffff0000, v189
	v_fmac_f32_e32 v18, v6, v228
	v_fmac_f32_e32 v16, v7, v229
	v_fmac_f32_e32 v19, v8, v230
	v_fmac_f32_e32 v17, v9, v231
	v_cvt_pk_bf16_f32 v6, v18, v16
	v_cvt_pk_bf16_f32 v7, v19, v17
	v_lshl_add_u64 v[10:11], v[132:133], 1, v[34:35]
	v_add_f32_e32 v2, 0, v2
	v_add_f32_e32 v3, 0, v3
	v_add_f32_e32 v4, 0, v4
	v_add_f32_e32 v5, 0, v5
	s_waitcnt vmcnt(3)
	v_lshlrev_b32_e32 v14, 16, v190
	v_and_b32_e32 v12, 0xffff0000, v190
	v_lshlrev_b32_e32 v15, 16, v191
	v_and_b32_e32 v13, 0xffff0000, v191
	v_fmac_f32_e32 v14, v2, v232
	v_fmac_f32_e32 v12, v3, v233
	v_fmac_f32_e32 v15, v4, v234
	v_fmac_f32_e32 v13, v5, v235
	v_cvt_pk_bf16_f32 v8, v14, v12
	v_cvt_pk_bf16_f32 v9, v15, v13
	s_nop 1
	v_permlane16_swap_b32 v6, v8
	v_permlane16_swap_b32 v7, v9
	v_lshl_add_u64 v[248:249], v[10:11], 0, v[246:247]
	s_nop 0
	global_store_dwordx4 v[248:249], v[6:9], off offset:192
	s_nop 1
	s_branch .LBB0_2427

; template <bool SWAP, class Epi, bool THIN = false> ...
;     ...
;     for (int st = 0; st < ns; ++st) {
;       asm volatile("s_waitcnt vmcnt(0)" ::: "memory");
;       __builtin_amdgcn_s_barrier();
;       asm volatile("" ::: "memory");
;       if (st + 1 < ns) {
;         char* nb = smem + ((st + 1) & 1) * 65536;
;         const int ko = (st + 1) * 64;
; #pragma unroll
;         for (int i = 0; i < 4; ++i) { GLDS16(A + (size_t)(ap[i] + ko), nb + tid * 16 + i * 8192); GLDS16(Bt + (size_t)(bp[i] + ko), nb + 32768 + tid * 16 + i * 8192); }
;       }
;       const char* sa = smem + (st & 1) * 65536 + (wr * 64 + fr) * 128;
;       const char* sb = smem + (st & 1) * 65536 + 32768 + (wc * 128 + fr) * 128;
;       if constexpr (THIN) {
;         if (wc == 0) {
; #pragma unroll
;           for (int ks = 0; ks < 2; ++ks) {
;             bf16x8 af[4], bf[2];
; #pragma unroll
;             for (int m = 0; m < 4; ++m) af[m] = *(const bf16x8*)(sa + m * 2048 + (((ks * 4 + fq) ^ swz) << 4));
; #pragma unroll
;             for (int n = 0; n < 2; ++n) bf[n] = *(const bf16x8*)(sb + n * 2048 + (((ks * 4 + fq) ^ swz) << 4));
; #pragma unroll
;             for (int m = 0; m < 4; ++m)
; #pragma unroll
;               for (int n = 0; n < 2; ++n)
;                 acc[m][n] = SWAP ? __builtin_amdgcn_mfma_f32_16x16x32_bf16(bf[n], af[m], acc[m][n], 0, 0, 0)
;                                  : __builtin_amdgcn_mfma_f32_16x16x32_bf16(af[m], bf[n], acc[m][n], 0, 0, 0);
;           }
;         }
;       } else {
;       bf16x8 afA[4], afB[4], bfb[2][2];
; #pragma unroll
;       for (int m = 0; m < 4; ++m) afA[m] = *(const bf16x8*)(sa + m * 2048 + ((fq ^ swz) << 4));
; #pragma unroll
;       for (int n = 0; n < 2; ++n) bfb[0][n] = *(const bf16x8*)(sb + n * 2048 + ((fq ^ swz) << 4));
; #pragma unroll
;       for (int gq = 0; gq < 8; ++gq) {
;         const int ks = gq >> 2, nh = gq & 3;
;         if (gq < 7) {
;           const int ks2 = (gq + 1) >> 2, nh2 = (gq + 1) & 3;
; #pragma unroll
;           for (int n = 0; n < 2; ++n) bfb[(gq + 1) & 1][n] = *(const bf16x8*)(sb + (nh2 * 2 + n) * 2048 + (((ks2 * 4 + fq) ^ swz) << 4));
;         }
;         if (gq == 3) {
; #pragma unroll
;           for (int m = 0; m < 4; ++m) afB[m] = *(const bf16x8*)(sa + m * 2048 + (((4 + fq) ^ swz) << 4));
;         }
;         __builtin_amdgcn_sched_barrier(0);
; #pragma unroll
.LBB0_2643:
	s_add_i32 s8, s7, 0x10000
	s_and_b32 s9, s8, 0x10000
	v_add_u32_e32 v167, s9, v142
	s_nop 0
	v_readfirstlane_b32 s9, v167
	s_and_b32 s7, s7, 0x10000
	v_add_u32_e32 v130, s7, v143
	v_add_u32_e32 v167, v130, v145
	s_waitcnt vmcnt(0)
	s_barrier
	ds_read_b128 v[168:171], v167
	ds_read_b128 v[172:175], v167 offset:2048
	ds_read_b128 v[176:179], v167 offset:4096
	ds_read_b128 v[180:183], v167 offset:6144
	v_or_b32_e32 v167, s7, v144
	v_add_u32_e32 v204, v167, v145
	ds_read_b128 v[184:187], v204 offset:32768
	ds_read_b128 v[188:191], v204 offset:34816
	ds_read_b128 v[192:195], v204 offset:36864
	ds_read_b128 v[196:199], v204 offset:38912
	v_add_u32_e32 v130, v130, v146
	s_waitcnt lgkmcnt(3)
	v_mfma_f32_16x16x32_bf16 v[126:129], v[184:187], v[168:171], v[126:129]
	s_mov_b32 m0, s9
	v_mfma_f32_16x16x32_bf16 v[110:113], v[184:187], v[172:175], v[110:113]
	global_load_lds_dwordx4 v139, s[18:19]
	v_add_u32_e32 v139, 0x80, v139
	v_mfma_f32_16x16x32_bf16 v[82:85], v[184:187], v[176:179], v[82:85]
	v_mfma_f32_16x16x32_bf16 v[50:53], v[184:187], v[180:183], v[50:53]
	ds_read_b128 v[184:187], v204 offset:40960
	ds_read_b128 v[200:203], v204 offset:43008
	s_waitcnt lgkmcnt(4)
	v_mfma_f32_16x16x32_bf16 v[122:125], v[188:191], v[168:171], v[122:125]
	s_add_u32 m0, s9, 0x8000
	v_mfma_f32_16x16x32_bf16 v[106:109], v[188:191], v[172:175], v[106:109]
	global_load_lds_dwordx4 v138, s[24:25]
	v_add_u32_e32 v138, 0x80, v138
	v_mfma_f32_16x16x32_bf16 v[78:81], v[188:191], v[176:179], v[78:81]
	v_mfma_f32_16x16x32_bf16 v[42:45], v[188:191], v[180:183], v[42:45]
	s_waitcnt lgkmcnt(3)
	v_mfma_f32_16x16x32_bf16 v[118:121], v[192:195], v[168:171], v[118:121]
	s_add_u32 m0, s9, 0x2000
	v_mfma_f32_16x16x32_bf16 v[94:97], v[192:195], v[172:175], v[94:97]
	global_load_lds_dwordx4 v137, s[18:19]
	v_add_u32_e32 v137, 0x80, v137
	v_mfma_f32_16x16x32_bf16 v[58:61], v[192:195], v[176:179], v[58:61]
	v_mfma_f32_16x16x32_bf16 v[26:29], v[192:195], v[180:183], v[26:29]
	ds_read_b128 v[188:191], v204 offset:45056
	ds_read_b128 v[192:195], v204 offset:47104
	s_waitcnt lgkmcnt(4)
	v_mfma_f32_16x16x32_bf16 v[114:117], v[196:199], v[168:171], v[114:117]
	s_add_u32 m0, s9, 0xa000
	v_mfma_f32_16x16x32_bf16 v[86:89], v[196:199], v[172:175], v[86:89]
	global_load_lds_dwordx4 v136, s[24:25]
	v_add_u32_e32 v136, 0x80, v136
	v_mfma_f32_16x16x32_bf16 v[54:57], v[196:199], v[176:179], v[54:57]
	v_mfma_f32_16x16x32_bf16 v[22:25], v[196:199], v[180:183], v[22:25]
	v_add_u32_e32 v167, v167, v146
	s_waitcnt lgkmcnt(3)
	v_mfma_f32_16x16x32_bf16 v[102:105], v[184:187], v[168:171], v[102:105]
	ds_read_b128 v[196:199], v167 offset:32768
	ds_read_b128 v[204:207], v167 offset:34816
	s_add_u32 m0, s9, 0x4000
	v_mfma_f32_16x16x32_bf16 v[74:77], v[184:187], v[172:175], v[74:77]
	global_load_lds_dwordx4 v135, s[18:19]
	v_add_u32_e32 v135, 0x80, v135
	v_mfma_f32_16x16x32_bf16 v[46:49], v[184:187], v[176:179], v[46:49]
	v_mfma_f32_16x16x32_bf16 v[10:13], v[184:187], v[180:183], v[10:13]
	ds_read_b128 v[184:187], v130
	ds_read_b128 v[208:211], v130 offset:2048
	ds_read_b128 v[212:215], v130 offset:4096
	ds_read_b128 v[216:219], v130 offset:6144
	s_waitcnt lgkmcnt(8)
	v_mfma_f32_16x16x32_bf16 v[98:101], v[200:203], v[168:171], v[98:101]
	s_add_u32 m0, s9, 0xc000
	v_mfma_f32_16x16x32_bf16 v[66:69], v[200:203], v[172:175], v[66:69]
	global_load_lds_dwordx4 v134, s[24:25]
	v_add_u32_e32 v134, 0x80, v134
	v_mfma_f32_16x16x32_bf16 v[30:33], v[200:203], v[176:179], v[30:33]
	v_mfma_f32_16x16x32_bf16 v[6:9], v[200:203], v[180:183], v[6:9]
	s_waitcnt lgkmcnt(7)
	v_mfma_f32_16x16x32_bf16 v[70:73], v[188:191], v[168:171], v[70:73]
	s_add_u32 m0, s9, 0x6000
	s_waitcnt lgkmcnt(6)
	v_mfma_f32_16x16x32_bf16 v[62:65], v[192:195], v[168:171], v[62:65]
	global_load_lds_dwordx4 v133, s[18:19]
	v_add_u32_e32 v133, 0x80, v133
	v_mfma_f32_16x16x32_bf16 v[38:41], v[188:191], v[172:175], v[38:41]
	v_mfma_f32_16x16x32_bf16 v[34:37], v[192:195], v[172:175], v[34:37]
	ds_read_b128 v[168:171], v167 offset:36864
	ds_read_b128 v[172:175], v167 offset:38912
	v_mfma_f32_16x16x32_bf16 v[18:21], v[188:191], v[176:179], v[18:21]
	s_add_u32 m0, s9, 0xe000
	v_mfma_f32_16x16x32_bf16 v[14:17], v[192:195], v[176:179], v[14:17]
	global_load_lds_dwordx4 v132, s[24:25]
	v_add_u32_e32 v132, 0x80, v132
	v_mfma_f32_16x16x32_bf16 v[2:5], v[188:191], v[180:183], v[2:5]
	v_mfma_f32_16x16x32_bf16 v[90:93], v[192:195], v[180:183], v[90:93]
	ds_read_b128 v[176:179], v167 offset:40960
	ds_read_b128 v[180:183], v167 offset:43008
	s_waitcnt lgkmcnt(7)
	v_mfma_f32_16x16x32_bf16 v[126:129], v[196:199], v[184:187], v[126:129]
	v_mfma_f32_16x16x32_bf16 v[122:125], v[204:207], v[184:187], v[122:125]
	s_waitcnt lgkmcnt(6)
	v_mfma_f32_16x16x32_bf16 v[110:113], v[196:199], v[208:211], v[110:113]
	v_mfma_f32_16x16x32_bf16 v[106:109], v[204:207], v[208:211], v[106:109]
	s_waitcnt lgkmcnt(5)
	v_mfma_f32_16x16x32_bf16 v[82:85], v[196:199], v[212:215], v[82:85]
	v_mfma_f32_16x16x32_bf16 v[78:81], v[204:207], v[212:215], v[78:81]
	s_waitcnt lgkmcnt(4)
	v_mfma_f32_16x16x32_bf16 v[50:53], v[196:199], v[216:219], v[50:53]
	v_mfma_f32_16x16x32_bf16 v[42:45], v[204:207], v[216:219], v[42:45]
	s_waitcnt lgkmcnt(3)
	v_mfma_f32_16x16x32_bf16 v[118:121], v[168:171], v[184:187], v[118:121]
	v_mfma_f32_16x16x32_bf16 v[94:97], v[168:171], v[208:211], v[94:97]
	v_mfma_f32_16x16x32_bf16 v[58:61], v[168:171], v[212:215], v[58:61]
	v_mfma_f32_16x16x32_bf16 v[26:29], v[168:171], v[216:219], v[26:29]
	ds_read_b128 v[168:171], v167 offset:45056
	ds_read_b128 v[188:191], v167 offset:47104
	s_waitcnt lgkmcnt(4)
; template <bool SWAP, class Epi, bool THIN = false> ...
;     ...
;     for (int st = 0; st < ns; ++st) {
;       asm volatile("s_waitcnt vmcnt(0)" ::: "memory");
;       __builtin_amdgcn_s_barrier();
;       asm volatile("" ::: "memory");
;       if (st + 1 < ns) {
;         char* nb = smem + ((st + 1) & 1) * 65536;
;         const int ko = (st + 1) * 64;
; #pragma unroll
;         for (int i = 0; i < 4; ++i) { GLDS16(A + (size_t)(ap[i] + ko), nb + tid * 16 + i * 8192); GLDS16(Bt + (size_t)(bp[i] + ko), nb + 32768 + tid * 16 + i * 8192); }
;       }
;       const char* sa = smem + (st & 1) * 65536 + (wr * 64 + fr) * 128;
;       const char* sb = smem + (st & 1) * 65536 + 32768 + (wc * 128 + fr) * 128;
;       if constexpr (THIN) {
;         if (wc == 0) {
; #pragma unroll
;           for (int ks = 0; ks < 2; ++ks) {
;             bf16x8 af[4], bf[2];
; #pragma unroll
;             for (int m = 0; m < 4; ++m) af[m] = *(const bf16x8*)(sa + m * 2048 + (((ks * 4 + fq) ^ swz) << 4));
; #pragma unroll
;             for (int n = 0; n < 2; ++n) bf[n] = *(const bf16x8*)(sb + n * 2048 + (((ks * 4 + fq) ^ swz) << 4));
; #pragma unroll
;             for (int m = 0; m < 4; ++m)
; #pragma unroll
;               for (int n = 0; n < 2; ++n)
;                 acc[m][n] = SWAP ? __builtin_amdgcn_mfma_f32_16x16x32_bf16(bf[n], af[m], acc[m][n], 0, 0, 0)
;                                  : __builtin_amdgcn_mfma_f32_16x16x32_bf16(af[m], bf[n], acc[m][n], 0, 0, 0);
;           }
;         }
;       } else {
;       bf16x8 afA[4], afB[4], bfb[2][2];
; #pragma unroll
;       for (int m = 0; m < 4; ++m) afA[m] = *(const bf16x8*)(sa + m * 2048 + ((fq ^ swz) << 4));
; #pragma unroll
;       for (int n = 0; n < 2; ++n) bfb[0][n] = *(const bf16x8*)(sb + n * 2048 + ((fq ^ swz) << 4));
; #pragma unroll
;       for (int gq = 0; gq < 8; ++gq) {
;         const int ks = gq >> 2, nh = gq & 3;
;         if (gq < 7) {
;           const int ks2 = (gq + 1) >> 2, nh2 = (gq + 1) & 3;
; #pragma unroll
;           for (int n = 0; n < 2; ++n) bfb[(gq + 1) & 1][n] = *(const bf16x8*)(sb + (nh2 * 2 + n) * 2048 + (((ks2 * 4 + fq) ^ swz) << 4));
;         }
;         if (gq == 3) {
; #pragma unroll
;           for (int m = 0; m < 4; ++m) afB[m] = *(const bf16x8*)(sa + m * 2048 + (((4 + fq) ^ swz) << 4));
;         }
;         __builtin_amdgcn_sched_barrier(0);
; #pragma unroll
	v_mfma_f32_16x16x32_bf16 v[114:117], v[172:175], v[184:187], v[114:117]
	v_mfma_f32_16x16x32_bf16 v[86:89], v[172:175], v[208:211], v[86:89]
	v_mfma_f32_16x16x32_bf16 v[54:57], v[172:175], v[212:215], v[54:57]
	v_mfma_f32_16x16x32_bf16 v[22:25], v[172:175], v[216:219], v[22:25]
	s_waitcnt lgkmcnt(3)
	v_mfma_f32_16x16x32_bf16 v[102:105], v[176:179], v[184:187], v[102:105]
	s_waitcnt lgkmcnt(2)
	v_mfma_f32_16x16x32_bf16 v[98:101], v[180:183], v[184:187], v[98:101]
	v_mfma_f32_16x16x32_bf16 v[74:77], v[176:179], v[208:211], v[74:77]
	v_mfma_f32_16x16x32_bf16 v[66:69], v[180:183], v[208:211], v[66:69]
	v_mfma_f32_16x16x32_bf16 v[46:49], v[176:179], v[212:215], v[46:49]
	v_mfma_f32_16x16x32_bf16 v[30:33], v[180:183], v[212:215], v[30:33]
	v_mfma_f32_16x16x32_bf16 v[10:13], v[176:179], v[216:219], v[10:13]
	v_mfma_f32_16x16x32_bf16 v[6:9], v[180:183], v[216:219], v[6:9]
	s_waitcnt lgkmcnt(1)
	v_mfma_f32_16x16x32_bf16 v[70:73], v[168:171], v[184:187], v[70:73]
	s_add_i32 s6, s6, 64
	s_cmpk_eq_i32 s6, 0x3c0
	s_mov_b32 s7, s8
	s_waitcnt lgkmcnt(0)
	v_mfma_f32_16x16x32_bf16 v[62:65], v[188:191], v[184:187], v[62:65]
	v_mfma_f32_16x16x32_bf16 v[38:41], v[168:171], v[208:211], v[38:41]
	v_mfma_f32_16x16x32_bf16 v[34:37], v[188:191], v[208:211], v[34:37]
	v_mfma_f32_16x16x32_bf16 v[18:21], v[168:171], v[212:215], v[18:21]
	v_mfma_f32_16x16x32_bf16 v[14:17], v[188:191], v[212:215], v[14:17]
	v_mfma_f32_16x16x32_bf16 v[2:5], v[168:171], v[216:219], v[2:5]
	v_mfma_f32_16x16x32_bf16 v[90:93], v[188:191], v[216:219], v[90:93]
	s_cbranch_scc0 .LBB0_2643
	s_waitcnt vmcnt(0)
	s_barrier
	v_add_u32_e32 v130, v157, v145
	ds_read_b128 v[132:135], v130
	ds_read_b128 v[136:139], v130 offset:2048
	ds_read_b128 v[168:171], v130 offset:4096
	ds_read_b128 v[172:175], v130 offset:6144
	v_add_u32_e32 v130, v158, v145
	ds_read_b128 v[176:179], v130
	ds_read_b128 v[180:183], v130 offset:2048
	ds_read_b128 v[184:187], v130 offset:4096
	ds_read_b128 v[188:191], v130 offset:6144
	s_waitcnt lgkmcnt(0)
	v_mfma_f32_16x16x32_bf16 v[126:129], v[176:179], v[132:135], v[126:129]
	v_mfma_f32_16x16x32_bf16 v[110:113], v[176:179], v[136:139], v[110:113]
	v_mfma_f32_16x16x32_bf16 v[82:85], v[176:179], v[168:171], v[82:85]
	v_mfma_f32_16x16x32_bf16 v[50:53], v[176:179], v[172:175], v[50:53]
	ds_read_b128 v[176:179], v130 offset:8192
	ds_read_b128 v[192:195], v130 offset:10240
	v_mfma_f32_16x16x32_bf16 v[122:125], v[180:183], v[132:135], v[122:125]
	v_mfma_f32_16x16x32_bf16 v[106:109], v[180:183], v[136:139], v[106:109]
	v_mfma_f32_16x16x32_bf16 v[78:81], v[180:183], v[168:171], v[78:81]
	v_mfma_f32_16x16x32_bf16 v[42:45], v[180:183], v[172:175], v[42:45]
	v_mfma_f32_16x16x32_bf16 v[118:121], v[184:187], v[132:135], v[118:121]
	v_mfma_f32_16x16x32_bf16 v[180:183], v[184:187], v[136:139], v[94:97]
	v_mfma_f32_16x16x32_bf16 v[200:203], v[184:187], v[168:171], v[58:61]
	v_mfma_f32_16x16x32_bf16 v[204:207], v[188:191], v[168:171], v[54:57]
	v_mfma_f32_16x16x32_bf16 v[184:187], v[184:187], v[172:175], v[26:29]
	s_nop 2
	ds_read_b128 v[26:29], v130 offset:12288
	ds_read_b128 v[54:57], v130 offset:14336
	v_mfma_f32_16x16x32_bf16 v[114:117], v[188:191], v[132:135], v[114:117]
	v_mfma_f32_16x16x32_bf16 v[196:199], v[188:191], v[136:139], v[86:89]
	v_mfma_f32_16x16x32_bf16 v[188:191], v[188:191], v[172:175], v[22:25]
	v_add_u32_e32 v130, v158, v146
	s_waitcnt lgkmcnt(0)
	v_mfma_f32_16x16x32_bf16 v[208:211], v[192:195], v[168:171], v[30:33]
	ds_read_b128 v[22:25], v130
	ds_read_b128 v[86:89], v130 offset:2048
	s_nop 0
	v_add_u32_e32 v30, v157, v146
	v_mfma_f32_16x16x32_bf16 v[102:105], v[176:179], v[132:135], v[102:105]
	v_mfma_f32_16x16x32_bf16 v[74:77], v[176:179], v[136:139], v[74:77]
	v_mfma_f32_16x16x32_bf16 v[46:49], v[176:179], v[168:171], v[46:49]
	v_mfma_f32_16x16x32_bf16 v[10:13], v[176:179], v[172:175], v[10:13]
	ds_read_b128 v[176:179], v30
	ds_read_b128 v[212:215], v30 offset:2048
	ds_read_b128 v[216:219], v30 offset:4096
	ds_read_b128 v[220:223], v30 offset:6144
	v_mfma_f32_16x16x32_bf16 v[98:101], v[192:195], v[132:135], v[98:101]
	v_mfma_f32_16x16x32_bf16 v[66:69], v[192:195], v[136:139], v[66:69]
	v_mfma_f32_16x16x32_bf16 v[6:9], v[192:195], v[172:175], v[6:9]
	v_mfma_f32_16x16x32_bf16 v[224:227], v[26:29], v[136:139], v[38:41]
	v_mfma_f32_16x16x32_bf16 v[34:37], v[54:57], v[136:139], v[34:37]
	v_mfma_f32_16x16x32_bf16 v[136:139], v[26:29], v[168:171], v[18:21]
	v_mfma_f32_16x16x32_bf16 v[168:171], v[54:57], v[168:171], v[14:17]
	s_nop 2
	ds_read_b128 v[14:17], v130 offset:4096
	ds_read_b128 v[18:21], v130 offset:6144
	v_mfma_f32_16x16x32_bf16 v[192:195], v[26:29], v[132:135], v[70:73]
	v_mfma_f32_16x16x32_bf16 v[132:135], v[54:57], v[132:135], v[62:65]
	v_mfma_f32_16x16x32_bf16 v[2:5], v[26:29], v[172:175], v[2:5]
	v_mfma_f32_16x16x32_bf16 v[172:175], v[54:57], v[172:175], v[90:93]
	ds_read_b128 v[228:231], v130 offset:8192
	ds_read_b128 v[232:235], v130 offset:10240
	s_waitcnt lgkmcnt(0)
	v_mfma_f32_16x16x32_bf16 v[126:129], v[22:25], v[176:179], v[126:129]
	v_mfma_f32_16x16x32_bf16 v[122:125], v[86:89], v[176:179], v[122:125]
	v_mfma_f32_16x16x32_bf16 v[94:97], v[22:25], v[212:215], v[110:113]
	v_mfma_f32_16x16x32_bf16 v[90:93], v[86:89], v[212:215], v[106:109]
	v_mfma_f32_16x16x32_bf16 v[62:65], v[22:25], v[216:219], v[82:85]
	v_mfma_f32_16x16x32_bf16 v[58:61], v[86:89], v[216:219], v[78:81]
	v_mfma_f32_16x16x32_bf16 v[30:33], v[22:25], v[220:223], v[50:53]
	v_mfma_f32_16x16x32_bf16 v[26:29], v[86:89], v[220:223], v[42:45]
	v_mfma_f32_16x16x32_bf16 v[86:89], v[14:17], v[212:215], v[180:183]
	v_mfma_f32_16x16x32_bf16 v[22:25], v[14:17], v[220:223], v[184:187]
	s_nop 1
	ds_read_b128 v[180:183], v130 offset:12288
	ds_read_b128 v[184:187], v130 offset:14336
	v_mfma_f32_16x16x32_bf16 v[118:121], v[14:17], v[176:179], v[118:121]
	v_mfma_f32_16x16x32_bf16 v[114:117], v[18:21], v[176:179], v[114:117]
	v_mfma_f32_16x16x32_bf16 v[82:85], v[18:21], v[212:215], v[196:199]
	v_mfma_f32_16x16x32_bf16 v[54:57], v[14:17], v[216:219], v[200:203]
	v_mfma_f32_16x16x32_bf16 v[50:53], v[18:21], v[216:219], v[204:207]
	v_mfma_f32_16x16x32_bf16 v[18:21], v[18:21], v[220:223], v[188:191]
	v_mfma_f32_16x16x32_bf16 v[110:113], v[228:231], v[176:179], v[102:105]
	v_mfma_f32_16x16x32_bf16 v[106:109], v[232:235], v[176:179], v[98:101]
	v_mfma_f32_16x16x32_bf16 v[78:81], v[228:231], v[212:215], v[74:77]
	v_mfma_f32_16x16x32_bf16 v[70:73], v[232:235], v[212:215], v[66:69]
	v_mfma_f32_16x16x32_bf16 v[46:49], v[228:231], v[216:219], v[46:49]
	v_mfma_f32_16x16x32_bf16 v[38:41], v[232:235], v[216:219], v[208:211]
	v_mfma_f32_16x16x32_bf16 v[14:17], v[228:231], v[220:223], v[10:13]
	v_mfma_f32_16x16x32_bf16 v[6:9], v[232:235], v[220:223], v[6:9]
	v_mov_b32_e32 v130, v1
	s_waitcnt vmcnt(0) lgkmcnt(0)
	s_barrier
; __device__ __forceinline__ int get_tid512() { int t = threadIdx.x; asm volatile("" : "+v"(t)); return t; }
; __device__ __forceinline__ unsigned pack2(float a, float b) { unsigned r; asm("v_cvt_pk_bf16_f32 %0, %1, %2" : "=v"(r) : "v"(a), "v"(b)); return r; }
;   __device__ __forceinline__ void c4(int g, int rig, int col, f32x4 v) const {
;     const size_t row = (size_t)g * 2048 + rig;
;     const f32x4 b4 = *(const f32x4*)(bias + col);
;     uint2 u; u.x = pack2(v[0] + b4[0], v[1] + b4[1]); u.y = pack2(v[2] + b4[2], v[3] + b4[3]);
;     *(uint2*)(out + row * ld + col) = u;
;   }
; template <bool SWAP, class Epi, bool THIN = false> ...
;     ...
;     const int te = get_tid512();
;     const int fr_e = te & 15, fq_e = (te & 63) >> 4, wr_e = te >> 7, wc_e = (te >> 6) & 1;
;     const int sub = 2 * mt + (wr_e >> 1);
;     const int g = sub / tpg, ti = sub - g * tpg;
;     const int rig0 = ti * step - halo;
;     const int rw = (wr_e & 1) * 64;
;     if constexpr (Epi::KIND == 0) {
; #pragma unroll
;       for (int m = 0; m < 4; ++m) {
;         const int rig = rig0 + rw + m * 16 + fr_e;
;         if constexpr (Epi::ROWSUM) {
;           float ss = 0.f;
; #pragma unroll
;           for (int n = 0; n < 8; ++n) {
;             const int col = nt * 256 + wc_e * 128 + n * 16 + fq_e * 4;
;             if (col < N) ss += epi.c4(g, rig, col, acc[m][n]);
;           }
;           ss += __shfl_xor(ss, 16); ss += __shfl_xor(ss, 32);
;           if (fq_e == 0) epi.rowsum(g, rig, nt * 2 + wc_e, ss);
;         } else {
; #pragma unroll
;           for (int n = 0; n < 8; ++n) {
;             const int col = nt * 256 + wc_e * 128 + n * 16 + fq_e * 4;
;             if (col < N) epi.c4(g, rig, col, acc[m][n]);
;           }
	v_mfma_f32_16x16x32_bf16 v[102:105], v[180:183], v[176:179], v[192:195]
	v_ashrrev_i32_e32 v11, 8, v130
	v_add_u32_e32 v11, s5, v11
	v_ashrrev_i32_e32 v12, 31, v11
	v_lshrrev_b32_e32 v12, 28, v12
	v_add_u32_e32 v12, v11, v12
	v_mfma_f32_16x16x32_bf16 v[98:101], v[184:187], v[176:179], v[132:135]
	v_ashrrev_i32_e32 v176, 4, v12
	v_lshlrev_b32_e32 v12, 11, v176
	v_lshlrev_b32_e32 v11, 7, v11
	v_sub_u32_e32 v11, v11, v12
	v_lshrrev_b32_e32 v12, 1, v130
	v_and_b32_e32 v10, 15, v130
	v_bfe_u32 v246, v130, 4, 1
	v_mul_u32_u24_e32 v246, 24, v246
	v_mov_b32_e32 v247, 0
	v_and_b32_e32 v12, 64, v12
	v_or3_b32 v134, v11, v12, v10
	v_lshlrev_b32_e32 v10, 1, v130
	v_and_b32_e32 v132, 0x80, v10
	v_mfma_f32_16x16x32_bf16 v[10:13], v[180:183], v[220:223], v[2:5]
	v_ashrrev_i32_e32 v177, 31, v176
	v_ashrrev_i32_e32 v135, 31, v134
	s_nop 0
	v_lshrrev_b32_e32 v2, 2, v130
	v_and_b32_e32 v2, 12, v2
	v_mfma_f32_16x16x32_bf16 v[74:77], v[180:183], v[212:215], v[224:227]
	v_or3_b32 v132, v2, v132, s4
	v_cmp_gt_i32_e32 vcc, s31, v132
	v_ashrrev_i32_e32 v133, 31, v132
	v_mfma_f32_16x16x32_bf16 v[66:69], v[184:187], v[212:215], v[34:37]
	v_mfma_f32_16x16x32_bf16 v[42:45], v[180:183], v[216:219], v[136:139]
	v_mfma_f32_16x16x32_bf16 v[34:37], v[184:187], v[216:219], v[168:171]
	s_nop 1
	v_lshlrev_b64 v[136:137], 11, v[176:177]
	v_lshl_add_u64 v[138:139], v[136:137], 0, v[134:135]
	v_lshlrev_b64 v[138:139], 11, v[138:139]
	v_mfma_f32_16x16x32_bf16 v[2:5], v[184:187], v[220:223], v[172:175]
	v_lshl_add_u64 v[138:139], s[20:21], 0, v[138:139]
	v_lshl_add_u64 v[188:189], v[132:133], 2, s[22:23]
	global_load_dwordx4 v[196:199], v[188:189], off
	global_load_dwordx4 v[200:203], v[188:189], off offset:64
	global_load_dwordx4 v[204:207], v[188:189], off offset:128
	global_load_dwordx4 v[208:211], v[188:189], off offset:192
	global_load_dwordx4 v[228:231], v[188:189], off offset:256
	global_load_dwordx4 v[232:235], v[188:189], off offset:320
	global_load_dwordx4 v[236:239], v[188:189], off offset:384
	global_load_dwordx4 v[240:243], v[188:189], off offset:448
	s_waitcnt vmcnt(0)
	v_add_f32_e32 v126, v126, v196
	v_add_f32_e32 v127, v127, v197
	v_add_f32_e32 v128, v128, v198
	v_add_f32_e32 v129, v129, v199
	v_cvt_pk_bf16_f32 v126, v126, v127
	v_cvt_pk_bf16_f32 v127, v128, v129
	v_add_f32_e32 v122, v122, v200
	v_add_f32_e32 v123, v123, v201
	v_add_f32_e32 v124, v124, v202
	v_add_f32_e32 v125, v125, v203
	v_cvt_pk_bf16_f32 v128, v122, v123
	v_cvt_pk_bf16_f32 v129, v124, v125
	v_lshl_add_u64 v[124:125], v[132:133], 1, v[138:139]
	s_nop 1
	v_permlane16_swap_b32 v126, v128
	v_permlane16_swap_b32 v127, v129
	v_lshl_add_u64 v[248:249], v[124:125], 0, v[246:247]
	s_nop 0
	global_store_dwordx4 v[248:249], v[126:129], off
	s_nop 1
	v_or_b32_e32 v122, 32, v132
	v_add_f32_e32 v118, v118, v204
	v_add_f32_e32 v119, v119, v205
	v_add_f32_e32 v120, v120, v206
	v_add_f32_e32 v121, v121, v207
	v_cvt_pk_bf16_f32 v118, v118, v119
	v_cvt_pk_bf16_f32 v119, v120, v121
	v_add_f32_e32 v114, v114, v208
	v_add_f32_e32 v115, v115, v209
	v_add_f32_e32 v116, v116, v210
	v_add_f32_e32 v117, v117, v211
	v_cvt_pk_bf16_f32 v120, v114, v115
	v_cvt_pk_bf16_f32 v121, v116, v117
	v_lshl_add_u64 v[116:117], v[132:133], 1, v[138:139]
	s_nop 1
	v_permlane16_swap_b32 v118, v120
	v_permlane16_swap_b32 v119, v121
	v_lshl_add_u64 v[248:249], v[116:117], 0, v[246:247]
	s_nop 0
	global_store_dwordx4 v[248:249], v[118:121], off offset:64
	s_nop 1
	v_or_b32_e32 v114, 64, v132
	v_add_f32_e32 v110, v110, v228
	v_add_f32_e32 v111, v111, v229
	v_add_f32_e32 v112, v112, v230
	v_add_f32_e32 v113, v113, v231
	v_cvt_pk_bf16_f32 v110, v110, v111
	v_cvt_pk_bf16_f32 v111, v112, v113
	v_add_f32_e32 v106, v106, v232
	v_add_f32_e32 v107, v107, v233
	v_add_f32_e32 v108, v108, v234
	v_add_f32_e32 v109, v109, v235
	v_cvt_pk_bf16_f32 v112, v106, v107
	v_cvt_pk_bf16_f32 v113, v108, v109
	v_lshl_add_u64 v[108:109], v[132:133], 1, v[138:139]
	s_nop 1
	v_permlane16_swap_b32 v110, v112
	v_permlane16_swap_b32 v111, v113
	v_lshl_add_u64 v[248:249], v[108:109], 0, v[246:247]
	s_nop 0
	global_store_dwordx4 v[248:249], v[110:113], off offset:128
	s_nop 1
	v_or_b32_e32 v106, 0x60, v132
	v_add_f32_e32 v102, v102, v236
	v_add_f32_e32 v103, v103, v237
	v_add_f32_e32 v104, v104, v238
	v_add_f32_e32 v105, v105, v239
	v_cvt_pk_bf16_f32 v102, v102, v103
	v_cvt_pk_bf16_f32 v103, v104, v105
	v_add_f32_e32 v98, v98, v240
	v_add_f32_e32 v99, v99, v241
	v_add_f32_e32 v100, v100, v242
	v_add_f32_e32 v101, v101, v243
	v_cvt_pk_bf16_f32 v104, v98, v99
	v_cvt_pk_bf16_f32 v105, v100, v101
	v_lshl_add_u64 v[100:101], v[132:133], 1, v[138:139]
	s_nop 1
	v_permlane16_swap_b32 v102, v104
	v_permlane16_swap_b32 v103, v105
	v_lshl_add_u64 v[248:249], v[100:101], 0, v[246:247]
	s_nop 0
	global_store_dwordx4 v[248:249], v[102:105], off offset:192
	s_nop 1
	v_or_b32_e32 v98, 16, v134
	v_ashrrev_i32_e32 v99, 31, v98
	v_lshl_add_u64 v[98:99], v[136:137], 0, v[98:99]
	v_lshlrev_b64 v[98:99], 11, v[98:99]
	v_lshl_add_u64 v[98:99], s[20:21], 0, v[98:99]
	v_add_f32_e32 v94, v94, v196
	v_add_f32_e32 v95, v95, v197
	v_add_f32_e32 v96, v96, v198
	v_add_f32_e32 v97, v97, v199
	v_cvt_pk_bf16_f32 v94, v94, v95
	v_cvt_pk_bf16_f32 v95, v96, v97
	v_add_f32_e32 v90, v90, v200
	v_add_f32_e32 v91, v91, v201
	v_add_f32_e32 v92, v92, v202
	v_add_f32_e32 v93, v93, v203
	v_cvt_pk_bf16_f32 v96, v90, v91
	v_cvt_pk_bf16_f32 v97, v92, v93
	v_lshl_add_u64 v[92:93], v[132:133], 1, v[98:99]
	s_nop 1
	v_permlane16_swap_b32 v94, v96
	v_permlane16_swap_b32 v95, v97
	v_lshl_add_u64 v[248:249], v[92:93], 0, v[246:247]
	s_nop 0
	global_store_dwordx4 v[248:249], v[94:97], off
	s_nop 1
	v_add_f32_e32 v86, v86, v204
; __device__ __forceinline__ unsigned pack2(float a, float b) { unsigned r; asm("v_cvt_pk_bf16_f32 %0, %1, %2" : "=v"(r) : "v"(a), "v"(b)); return r; }
;   __device__ __forceinline__ void c4(int g, int rig, int col, f32x4 v) const {
;     const size_t row = (size_t)g * 2048 + rig;
;     const f32x4 b4 = *(const f32x4*)(bias + col);
;     uint2 u; u.x = pack2(v[0] + b4[0], v[1] + b4[1]); u.y = pack2(v[2] + b4[2], v[3] + b4[3]);
;     *(uint2*)(out + row * ld + col) = u;
;   }
; template <bool SWAP, class Epi, bool THIN = false> ...
;     ...
; #pragma unroll
;           for (int n = 0; n < 8; ++n) {
;             const int col = nt * 256 + wc_e * 128 + n * 16 + fq_e * 4;
;             if (col < N) epi.c4(g, rig, col, acc[m][n]);
;           }
	v_add_f32_e32 v87, v87, v205
	v_add_f32_e32 v88, v88, v206
	v_add_f32_e32 v89, v89, v207
	v_cvt_pk_bf16_f32 v86, v86, v87
	v_cvt_pk_bf16_f32 v87, v88, v89
	v_add_f32_e32 v82, v82, v208
	v_add_f32_e32 v83, v83, v209
	v_add_f32_e32 v84, v84, v210
	v_add_f32_e32 v85, v85, v211
	v_cvt_pk_bf16_f32 v88, v82, v83
	v_cvt_pk_bf16_f32 v89, v84, v85
	v_lshl_add_u64 v[84:85], v[132:133], 1, v[98:99]
	s_nop 1
	v_permlane16_swap_b32 v86, v88
	v_permlane16_swap_b32 v87, v89
	v_lshl_add_u64 v[248:249], v[84:85], 0, v[246:247]
	s_nop 0
	global_store_dwordx4 v[248:249], v[86:89], off offset:64
	s_nop 1
	v_add_f32_e32 v78, v78, v228
	v_add_f32_e32 v79, v79, v229
	v_add_f32_e32 v80, v80, v230
	v_add_f32_e32 v81, v81, v231
	v_cvt_pk_bf16_f32 v78, v78, v79
	v_cvt_pk_bf16_f32 v79, v80, v81
	v_add_f32_e32 v70, v70, v232
	v_add_f32_e32 v71, v71, v233
	v_add_f32_e32 v72, v72, v234
	v_add_f32_e32 v73, v73, v235
	v_cvt_pk_bf16_f32 v80, v70, v71
	v_cvt_pk_bf16_f32 v81, v72, v73
	v_lshl_add_u64 v[72:73], v[132:133], 1, v[98:99]
	s_nop 1
	v_permlane16_swap_b32 v78, v80
	v_permlane16_swap_b32 v79, v81
	v_lshl_add_u64 v[248:249], v[72:73], 0, v[246:247]
	s_nop 0
	global_store_dwordx4 v[248:249], v[78:81], off offset:128
	s_nop 1
	v_add_f32_e32 v70, v74, v236
	v_add_f32_e32 v71, v75, v237
	v_add_f32_e32 v72, v76, v238
	v_add_f32_e32 v73, v77, v239
	v_cvt_pk_bf16_f32 v70, v70, v71
	v_cvt_pk_bf16_f32 v71, v72, v73
	v_add_f32_e32 v66, v66, v240
	v_add_f32_e32 v67, v67, v241
	v_add_f32_e32 v68, v68, v242
	v_add_f32_e32 v69, v69, v243
	v_cvt_pk_bf16_f32 v72, v66, v67
	v_cvt_pk_bf16_f32 v73, v68, v69
	v_lshl_add_u64 v[68:69], v[132:133], 1, v[98:99]
	s_nop 1
	v_permlane16_swap_b32 v70, v72
	v_permlane16_swap_b32 v71, v73
	v_lshl_add_u64 v[248:249], v[68:69], 0, v[246:247]
	s_nop 0
	global_store_dwordx4 v[248:249], v[70:73], off offset:192
	s_nop 1
	v_or_b32_e32 v66, 32, v134
	v_ashrrev_i32_e32 v67, 31, v66
	v_lshl_add_u64 v[66:67], v[136:137], 0, v[66:67]
	v_lshlrev_b64 v[66:67], 11, v[66:67]
	v_lshl_add_u64 v[66:67], s[20:21], 0, v[66:67]
	v_add_f32_e32 v62, v62, v196
	v_add_f32_e32 v63, v63, v197
	v_add_f32_e32 v64, v64, v198
	v_add_f32_e32 v65, v65, v199
	v_cvt_pk_bf16_f32 v62, v62, v63
	v_cvt_pk_bf16_f32 v63, v64, v65
	v_add_f32_e32 v58, v58, v200
	v_add_f32_e32 v59, v59, v201
	v_add_f32_e32 v60, v60, v202
	v_add_f32_e32 v61, v61, v203
	v_cvt_pk_bf16_f32 v64, v58, v59
	v_cvt_pk_bf16_f32 v65, v60, v61
	v_lshl_add_u64 v[60:61], v[132:133], 1, v[66:67]
	s_nop 1
	v_permlane16_swap_b32 v62, v64
	v_permlane16_swap_b32 v63, v65
	v_lshl_add_u64 v[248:249], v[60:61], 0, v[246:247]
	s_nop 0
	global_store_dwordx4 v[248:249], v[62:65], off
	s_nop 1
	v_add_f32_e32 v54, v54, v204
	v_add_f32_e32 v55, v55, v205
	v_add_f32_e32 v56, v56, v206
	v_add_f32_e32 v57, v57, v207
	v_cvt_pk_bf16_f32 v54, v54, v55
	v_cvt_pk_bf16_f32 v55, v56, v57
	v_add_f32_e32 v50, v50, v208
	v_add_f32_e32 v51, v51, v209
	v_add_f32_e32 v52, v52, v210
	v_add_f32_e32 v53, v53, v211
	v_cvt_pk_bf16_f32 v56, v50, v51
	v_cvt_pk_bf16_f32 v57, v52, v53
	v_lshl_add_u64 v[52:53], v[132:133], 1, v[66:67]
	s_nop 1
	v_permlane16_swap_b32 v54, v56
	v_permlane16_swap_b32 v55, v57
	v_lshl_add_u64 v[248:249], v[52:53], 0, v[246:247]
	s_nop 0
	global_store_dwordx4 v[248:249], v[54:57], off offset:64
	s_nop 1
	v_add_f32_e32 v46, v46, v228
	v_add_f32_e32 v47, v47, v229
	v_add_f32_e32 v48, v48, v230
	v_add_f32_e32 v49, v49, v231
	v_cvt_pk_bf16_f32 v46, v46, v47
	v_cvt_pk_bf16_f32 v47, v48, v49
	v_add_f32_e32 v38, v38, v232
	v_add_f32_e32 v39, v39, v233
	v_add_f32_e32 v40, v40, v234
	v_add_f32_e32 v41, v41, v235
; __device__ __forceinline__ unsigned pack2(float a, float b) { unsigned r; asm("v_cvt_pk_bf16_f32 %0, %1, %2" : "=v"(r) : "v"(a), "v"(b)); return r; }
;   __device__ __forceinline__ void c4(int g, int rig, int col, f32x4 v) const {
;     const size_t row = (size_t)g * 2048 + rig;
;     const f32x4 b4 = *(const f32x4*)(bias + col);
;     uint2 u; u.x = pack2(v[0] + b4[0], v[1] + b4[1]); u.y = pack2(v[2] + b4[2], v[3] + b4[3]);
;     *(uint2*)(out + row * ld + col) = u;
;   }
; template <bool SWAP, class Epi, bool THIN = false> ...
;     ...
; #pragma unroll
;           for (int n = 0; n < 8; ++n) {
;             const int col = nt * 256 + wc_e * 128 + n * 16 + fq_e * 4;
;             if (col < N) epi.c4(g, rig, col, acc[m][n]);
;           }
	v_cvt_pk_bf16_f32 v48, v38, v39
	v_cvt_pk_bf16_f32 v49, v40, v41
	v_lshl_add_u64 v[40:41], v[132:133], 1, v[66:67]
	s_nop 1
	v_permlane16_swap_b32 v46, v48
	v_permlane16_swap_b32 v47, v49
	v_lshl_add_u64 v[248:249], v[40:41], 0, v[246:247]
	s_nop 0
	global_store_dwordx4 v[248:249], v[46:49], off offset:128
	s_nop 1
	v_add_f32_e32 v38, v42, v236
	v_add_f32_e32 v39, v43, v237
	v_add_f32_e32 v40, v44, v238
	v_add_f32_e32 v41, v45, v239
	v_cvt_pk_bf16_f32 v38, v38, v39
	v_cvt_pk_bf16_f32 v39, v40, v41
	v_add_f32_e32 v34, v34, v240
	v_add_f32_e32 v35, v35, v241
	v_add_f32_e32 v36, v36, v242
	v_add_f32_e32 v37, v37, v243
	v_cvt_pk_bf16_f32 v40, v34, v35
	v_cvt_pk_bf16_f32 v41, v36, v37
	v_lshl_add_u64 v[36:37], v[132:133], 1, v[66:67]
	s_nop 1
	v_permlane16_swap_b32 v38, v40
	v_permlane16_swap_b32 v39, v41
	v_lshl_add_u64 v[248:249], v[36:37], 0, v[246:247]
	s_nop 0
	global_store_dwordx4 v[248:249], v[38:41], off offset:192
	s_nop 1
	v_or_b32_e32 v34, 48, v134
	v_ashrrev_i32_e32 v35, 31, v34
	v_lshl_add_u64 v[34:35], v[136:137], 0, v[34:35]
	v_lshlrev_b64 v[34:35], 11, v[34:35]
	v_lshl_add_u64 v[34:35], s[20:21], 0, v[34:35]
	v_add_f32_e32 v30, v30, v196
	v_add_f32_e32 v31, v31, v197
	v_add_f32_e32 v32, v32, v198
	v_add_f32_e32 v33, v33, v199
	v_cvt_pk_bf16_f32 v30, v30, v31
	v_cvt_pk_bf16_f32 v31, v32, v33
	v_add_f32_e32 v26, v26, v200
	v_add_f32_e32 v27, v27, v201
	v_add_f32_e32 v28, v28, v202
	v_add_f32_e32 v29, v29, v203
	v_cvt_pk_bf16_f32 v32, v26, v27
	v_cvt_pk_bf16_f32 v33, v28, v29
	v_lshl_add_u64 v[28:29], v[132:133], 1, v[34:35]
	s_nop 1
	v_permlane16_swap_b32 v30, v32
	v_permlane16_swap_b32 v31, v33
	v_lshl_add_u64 v[248:249], v[28:29], 0, v[246:247]
	s_nop 0
	global_store_dwordx4 v[248:249], v[30:33], off
	s_nop 1
	v_add_f32_e32 v22, v22, v204
	v_add_f32_e32 v23, v23, v205
	v_add_f32_e32 v24, v24, v206
	v_add_f32_e32 v25, v25, v207
	v_cvt_pk_bf16_f32 v22, v22, v23
	v_cvt_pk_bf16_f32 v23, v24, v25
	v_add_f32_e32 v18, v18, v208
	v_add_f32_e32 v19, v19, v209
	v_add_f32_e32 v20, v20, v210
	v_add_f32_e32 v21, v21, v211
	v_cvt_pk_bf16_f32 v24, v18, v19
	v_cvt_pk_bf16_f32 v25, v20, v21
	v_lshl_add_u64 v[20:21], v[132:133], 1, v[34:35]
	s_nop 1
	v_permlane16_swap_b32 v22, v24
	v_permlane16_swap_b32 v23, v25
	v_lshl_add_u64 v[248:249], v[20:21], 0, v[246:247]
	s_nop 0
	global_store_dwordx4 v[248:249], v[22:25], off offset:64
	s_nop 1
	v_add_f32_e32 v14, v14, v228
	v_add_f32_e32 v15, v15, v229
	v_add_f32_e32 v16, v16, v230
	v_add_f32_e32 v17, v17, v231
	v_cvt_pk_bf16_f32 v14, v14, v15
	v_cvt_pk_bf16_f32 v15, v16, v17
	v_add_f32_e32 v6, v6, v232
	v_add_f32_e32 v7, v7, v233
	v_add_f32_e32 v8, v8, v234
	v_add_f32_e32 v9, v9, v235
	v_cvt_pk_bf16_f32 v16, v6, v7
	v_cvt_pk_bf16_f32 v17, v8, v9
	v_lshl_add_u64 v[8:9], v[132:133], 1, v[34:35]
	s_nop 1
	v_permlane16_swap_b32 v14, v16
	v_permlane16_swap_b32 v15, v17
	v_lshl_add_u64 v[248:249], v[8:9], 0, v[246:247]
	s_nop 0
	global_store_dwordx4 v[248:249], v[14:17], off offset:128
	s_nop 1
	v_add_f32_e32 v6, v10, v236
	v_add_f32_e32 v7, v11, v237
	v_add_f32_e32 v8, v12, v238
	v_add_f32_e32 v9, v13, v239
	v_cvt_pk_bf16_f32 v6, v6, v7
	v_cvt_pk_bf16_f32 v7, v8, v9
	v_add_f32_e32 v2, v2, v240
	v_add_f32_e32 v3, v3, v241
	v_add_f32_e32 v4, v4, v242
	v_add_f32_e32 v5, v5, v243
	v_cvt_pk_bf16_f32 v8, v2, v3
	v_cvt_pk_bf16_f32 v9, v4, v5
	v_lshl_add_u64 v[4:5], v[132:133], 1, v[34:35]
	s_nop 1
	v_permlane16_swap_b32 v6, v8
	v_permlane16_swap_b32 v7, v9
	v_lshl_add_u64 v[248:249], v[4:5], 0, v[246:247]
	s_nop 0
	global_store_dwordx4 v[248:249], v[6:9], off offset:192
	s_nop 1
	s_branch .LBB0_2641

; template <bool SWAP, class Epi, bool THIN = false> ...
;     ...
;     for (int st = 0; st < ns; ++st) {
;       asm volatile("s_waitcnt vmcnt(0)" ::: "memory");
;       __builtin_amdgcn_s_barrier();
;       asm volatile("" ::: "memory");
;       if (st + 1 < ns) {
;         char* nb = smem + ((st + 1) & 1) * 65536;
;         const int ko = (st + 1) * 64;
; #pragma unroll
;         for (int i = 0; i < 4; ++i) { GLDS16(A + (size_t)(ap[i] + ko), nb + tid * 16 + i * 8192); GLDS16(Bt + (size_t)(bp[i] + ko), nb + 32768 + tid * 16 + i * 8192); }
;       }
;       const char* sa = smem + (st & 1) * 65536 + (wr * 64 + fr) * 128;
;       const char* sb = smem + (st & 1) * 65536 + 32768 + (wc * 128 + fr) * 128;
;       if constexpr (THIN) {
;         if (wc == 0) {
; #pragma unroll
;           for (int ks = 0; ks < 2; ++ks) {
;             bf16x8 af[4], bf[2];
; #pragma unroll
;             for (int m = 0; m < 4; ++m) af[m] = *(const bf16x8*)(sa + m * 2048 + (((ks * 4 + fq) ^ swz) << 4));
; #pragma unroll
;             for (int n = 0; n < 2; ++n) bf[n] = *(const bf16x8*)(sb + n * 2048 + (((ks * 4 + fq) ^ swz) << 4));
; #pragma unroll
;             for (int m = 0; m < 4; ++m)
; #pragma unroll
;               for (int n = 0; n < 2; ++n)
;                 acc[m][n] = SWAP ? __builtin_amdgcn_mfma_f32_16x16x32_bf16(bf[n], af[m], acc[m][n], 0, 0, 0)
;                                  : __builtin_amdgcn_mfma_f32_16x16x32_bf16(af[m], bf[n], acc[m][n], 0, 0, 0);
;           }
;         }
;       } else {
;       bf16x8 afA[4], afB[4], bfb[2][2];
; #pragma unroll
;       for (int m = 0; m < 4; ++m) afA[m] = *(const bf16x8*)(sa + m * 2048 + ((fq ^ swz) << 4));
; #pragma unroll
;       for (int n = 0; n < 2; ++n) bfb[0][n] = *(const bf16x8*)(sb + n * 2048 + ((fq ^ swz) << 4));
; #pragma unroll
;       for (int gq = 0; gq < 8; ++gq) {
;         const int ks = gq >> 2, nh = gq & 3;
;         if (gq < 7) {
;           const int ks2 = (gq + 1) >> 2, nh2 = (gq + 1) & 3;
; #pragma unroll
;           for (int n = 0; n < 2; ++n) bfb[(gq + 1) & 1][n] = *(const bf16x8*)(sb + (nh2 * 2 + n) * 2048 + (((ks2 * 4 + fq) ^ swz) << 4));
;         }
;         if (gq == 3) {
; #pragma unroll
;           for (int m = 0; m < 4; ++m) afB[m] = *(const bf16x8*)(sa + m * 2048 + (((4 + fq) ^ swz) << 4));
;         }
;         __builtin_amdgcn_sched_barrier(0);
; #pragma unroll
.LBB0_2714:
	s_add_i32 s8, s7, 0x10000
	s_and_b32 s9, s8, 0x10000
	v_add_u32_e32 v167, s9, v138
	s_nop 0
	v_readfirstlane_b32 s9, v167
	s_and_b32 s7, s7, 0x10000
	v_add_u32_e32 v130, s7, v139
	v_add_u32_e32 v167, v130, v141
	s_waitcnt vmcnt(0)
	s_barrier
	ds_read_b128 v[168:171], v167
	ds_read_b128 v[172:175], v167 offset:2048
	ds_read_b128 v[176:179], v167 offset:4096
	ds_read_b128 v[180:183], v167 offset:6144
	v_or_b32_e32 v167, s7, v140
	v_add_u32_e32 v204, v167, v141
	ds_read_b128 v[184:187], v204 offset:32768
	ds_read_b128 v[188:191], v204 offset:34816
	ds_read_b128 v[192:195], v204 offset:36864
	ds_read_b128 v[196:199], v204 offset:38912
	v_add_u32_e32 v130, v130, v142
	s_waitcnt lgkmcnt(3)
	v_mfma_f32_16x16x32_bf16 v[126:129], v[168:171], v[184:187], v[126:129]
	s_mov_b32 m0, s9
	v_mfma_f32_16x16x32_bf16 v[110:113], v[172:175], v[184:187], v[110:113]
	global_load_lds_dwordx4 v166, s[18:19]
	v_add_u32_e32 v166, 0x80, v166
	v_mfma_f32_16x16x32_bf16 v[82:85], v[176:179], v[184:187], v[82:85]
	v_mfma_f32_16x16x32_bf16 v[50:53], v[180:183], v[184:187], v[50:53]
	ds_read_b128 v[184:187], v204 offset:40960
	ds_read_b128 v[200:203], v204 offset:43008
	s_waitcnt lgkmcnt(4)
	v_mfma_f32_16x16x32_bf16 v[122:125], v[168:171], v[188:191], v[122:125]
	s_add_u32 m0, s9, 0x8000
	v_mfma_f32_16x16x32_bf16 v[106:109], v[172:175], v[188:191], v[106:109]
	global_load_lds_dwordx4 v165, s[24:25]
	v_add_u32_e32 v165, 0x80, v165
	v_mfma_f32_16x16x32_bf16 v[78:81], v[176:179], v[188:191], v[78:81]
	v_mfma_f32_16x16x32_bf16 v[42:45], v[180:183], v[188:191], v[42:45]
	s_waitcnt lgkmcnt(3)
	v_mfma_f32_16x16x32_bf16 v[118:121], v[168:171], v[192:195], v[118:121]
	s_add_u32 m0, s9, 0x2000
	v_mfma_f32_16x16x32_bf16 v[94:97], v[172:175], v[192:195], v[94:97]
	global_load_lds_dwordx4 v164, s[18:19]
	v_add_u32_e32 v164, 0x80, v164
	v_mfma_f32_16x16x32_bf16 v[58:61], v[176:179], v[192:195], v[58:61]
	v_mfma_f32_16x16x32_bf16 v[26:29], v[180:183], v[192:195], v[26:29]
	ds_read_b128 v[188:191], v204 offset:45056
	ds_read_b128 v[192:195], v204 offset:47104
	s_waitcnt lgkmcnt(4)
	v_mfma_f32_16x16x32_bf16 v[114:117], v[168:171], v[196:199], v[114:117]
	s_add_u32 m0, s9, 0xa000
	v_mfma_f32_16x16x32_bf16 v[86:89], v[172:175], v[196:199], v[86:89]
	global_load_lds_dwordx4 v163, s[24:25]
	v_add_u32_e32 v163, 0x80, v163
	v_mfma_f32_16x16x32_bf16 v[54:57], v[176:179], v[196:199], v[54:57]
	v_mfma_f32_16x16x32_bf16 v[22:25], v[180:183], v[196:199], v[22:25]
	v_add_u32_e32 v167, v167, v142
	s_waitcnt lgkmcnt(3)
	v_mfma_f32_16x16x32_bf16 v[102:105], v[168:171], v[184:187], v[102:105]
	ds_read_b128 v[196:199], v167 offset:32768
	ds_read_b128 v[204:207], v167 offset:34816
	s_add_u32 m0, s9, 0x4000
	v_mfma_f32_16x16x32_bf16 v[74:77], v[172:175], v[184:187], v[74:77]
	global_load_lds_dwordx4 v135, s[18:19]
	v_add_u32_e32 v135, 0x80, v135
	v_mfma_f32_16x16x32_bf16 v[46:49], v[176:179], v[184:187], v[46:49]
	v_mfma_f32_16x16x32_bf16 v[10:13], v[180:183], v[184:187], v[10:13]
	ds_read_b128 v[184:187], v130
	ds_read_b128 v[208:211], v130 offset:2048
	ds_read_b128 v[212:215], v130 offset:4096
	ds_read_b128 v[216:219], v130 offset:6144
	s_waitcnt lgkmcnt(8)
	v_mfma_f32_16x16x32_bf16 v[98:101], v[168:171], v[200:203], v[98:101]
	s_add_u32 m0, s9, 0xc000
	v_mfma_f32_16x16x32_bf16 v[66:69], v[172:175], v[200:203], v[66:69]
	global_load_lds_dwordx4 v134, s[24:25]
	v_add_u32_e32 v134, 0x80, v134
	v_mfma_f32_16x16x32_bf16 v[30:33], v[176:179], v[200:203], v[30:33]
	v_mfma_f32_16x16x32_bf16 v[6:9], v[180:183], v[200:203], v[6:9]
	s_waitcnt lgkmcnt(7)
	v_mfma_f32_16x16x32_bf16 v[70:73], v[168:171], v[188:191], v[70:73]
	s_add_u32 m0, s9, 0x6000
	s_waitcnt lgkmcnt(6)
	v_mfma_f32_16x16x32_bf16 v[62:65], v[168:171], v[192:195], v[62:65]
	global_load_lds_dwordx4 v133, s[18:19]
	v_add_u32_e32 v133, 0x80, v133
	v_mfma_f32_16x16x32_bf16 v[38:41], v[172:175], v[188:191], v[38:41]
	v_mfma_f32_16x16x32_bf16 v[34:37], v[172:175], v[192:195], v[34:37]
	ds_read_b128 v[168:171], v167 offset:36864
	ds_read_b128 v[172:175], v167 offset:38912
	v_mfma_f32_16x16x32_bf16 v[18:21], v[176:179], v[188:191], v[18:21]
	s_add_u32 m0, s9, 0xe000
	v_mfma_f32_16x16x32_bf16 v[14:17], v[176:179], v[192:195], v[14:17]
	global_load_lds_dwordx4 v132, s[24:25]
	v_add_u32_e32 v132, 0x80, v132
	v_mfma_f32_16x16x32_bf16 v[2:5], v[180:183], v[188:191], v[2:5]
	v_mfma_f32_16x16x32_bf16 v[90:93], v[180:183], v[192:195], v[90:93]
	ds_read_b128 v[176:179], v167 offset:40960
	ds_read_b128 v[180:183], v167 offset:43008
	s_waitcnt lgkmcnt(7)
	v_mfma_f32_16x16x32_bf16 v[126:129], v[184:187], v[196:199], v[126:129]
	v_mfma_f32_16x16x32_bf16 v[122:125], v[184:187], v[204:207], v[122:125]
	s_waitcnt lgkmcnt(6)
	v_mfma_f32_16x16x32_bf16 v[110:113], v[208:211], v[196:199], v[110:113]
	v_mfma_f32_16x16x32_bf16 v[106:109], v[208:211], v[204:207], v[106:109]
	s_waitcnt lgkmcnt(5)
	v_mfma_f32_16x16x32_bf16 v[82:85], v[212:215], v[196:199], v[82:85]
	v_mfma_f32_16x16x32_bf16 v[78:81], v[212:215], v[204:207], v[78:81]
	s_waitcnt lgkmcnt(4)
	v_mfma_f32_16x16x32_bf16 v[50:53], v[216:219], v[196:199], v[50:53]
	v_mfma_f32_16x16x32_bf16 v[42:45], v[216:219], v[204:207], v[42:45]
	s_waitcnt lgkmcnt(3)
	v_mfma_f32_16x16x32_bf16 v[118:121], v[184:187], v[168:171], v[118:121]
	v_mfma_f32_16x16x32_bf16 v[94:97], v[208:211], v[168:171], v[94:97]
	v_mfma_f32_16x16x32_bf16 v[58:61], v[212:215], v[168:171], v[58:61]
	v_mfma_f32_16x16x32_bf16 v[26:29], v[216:219], v[168:171], v[26:29]
	ds_read_b128 v[168:171], v167 offset:45056
	ds_read_b128 v[188:191], v167 offset:47104
	s_waitcnt lgkmcnt(4)
; template <bool SWAP, class Epi, bool THIN = false> ...
;     ...
;     for (int st = 0; st < ns; ++st) {
;       asm volatile("s_waitcnt vmcnt(0)" ::: "memory");
;       __builtin_amdgcn_s_barrier();
;       asm volatile("" ::: "memory");
;       if (st + 1 < ns) {
;         char* nb = smem + ((st + 1) & 1) * 65536;
;         const int ko = (st + 1) * 64;
; #pragma unroll
;         for (int i = 0; i < 4; ++i) { GLDS16(A + (size_t)(ap[i] + ko), nb + tid * 16 + i * 8192); GLDS16(Bt + (size_t)(bp[i] + ko), nb + 32768 + tid * 16 + i * 8192); }
;       }
;       const char* sa = smem + (st & 1) * 65536 + (wr * 64 + fr) * 128;
;       const char* sb = smem + (st & 1) * 65536 + 32768 + (wc * 128 + fr) * 128;
;       if constexpr (THIN) {
;         if (wc == 0) {
; #pragma unroll
;           for (int ks = 0; ks < 2; ++ks) {
;             bf16x8 af[4], bf[2];
; #pragma unroll
;             for (int m = 0; m < 4; ++m) af[m] = *(const bf16x8*)(sa + m * 2048 + (((ks * 4 + fq) ^ swz) << 4));
; #pragma unroll
;             for (int n = 0; n < 2; ++n) bf[n] = *(const bf16x8*)(sb + n * 2048 + (((ks * 4 + fq) ^ swz) << 4));
; #pragma unroll
;             for (int m = 0; m < 4; ++m)
; #pragma unroll
;               for (int n = 0; n < 2; ++n)
;                 acc[m][n] = SWAP ? __builtin_amdgcn_mfma_f32_16x16x32_bf16(bf[n], af[m], acc[m][n], 0, 0, 0)
;                                  : __builtin_amdgcn_mfma_f32_16x16x32_bf16(af[m], bf[n], acc[m][n], 0, 0, 0);
;           }
;         }
;       } else {
;       bf16x8 afA[4], afB[4], bfb[2][2];
; #pragma unroll
;       for (int m = 0; m < 4; ++m) afA[m] = *(const bf16x8*)(sa + m * 2048 + ((fq ^ swz) << 4));
; #pragma unroll
;       for (int n = 0; n < 2; ++n) bfb[0][n] = *(const bf16x8*)(sb + n * 2048 + ((fq ^ swz) << 4));
; #pragma unroll
;       for (int gq = 0; gq < 8; ++gq) {
;         const int ks = gq >> 2, nh = gq & 3;
;         if (gq < 7) {
;           const int ks2 = (gq + 1) >> 2, nh2 = (gq + 1) & 3;
; #pragma unroll
;           for (int n = 0; n < 2; ++n) bfb[(gq + 1) & 1][n] = *(const bf16x8*)(sb + (nh2 * 2 + n) * 2048 + (((ks2 * 4 + fq) ^ swz) << 4));
;         }
;         if (gq == 3) {
; #pragma unroll
;           for (int m = 0; m < 4; ++m) afB[m] = *(const bf16x8*)(sa + m * 2048 + (((4 + fq) ^ swz) << 4));
;         }
;         __builtin_amdgcn_sched_barrier(0);
; #pragma unroll
	v_mfma_f32_16x16x32_bf16 v[114:117], v[184:187], v[172:175], v[114:117]
	v_mfma_f32_16x16x32_bf16 v[86:89], v[208:211], v[172:175], v[86:89]
	v_mfma_f32_16x16x32_bf16 v[54:57], v[212:215], v[172:175], v[54:57]
	v_mfma_f32_16x16x32_bf16 v[22:25], v[216:219], v[172:175], v[22:25]
	s_waitcnt lgkmcnt(3)
	v_mfma_f32_16x16x32_bf16 v[102:105], v[184:187], v[176:179], v[102:105]
	s_waitcnt lgkmcnt(2)
	v_mfma_f32_16x16x32_bf16 v[98:101], v[184:187], v[180:183], v[98:101]
	v_mfma_f32_16x16x32_bf16 v[74:77], v[208:211], v[176:179], v[74:77]
	v_mfma_f32_16x16x32_bf16 v[66:69], v[208:211], v[180:183], v[66:69]
	v_mfma_f32_16x16x32_bf16 v[46:49], v[212:215], v[176:179], v[46:49]
	v_mfma_f32_16x16x32_bf16 v[30:33], v[212:215], v[180:183], v[30:33]
	v_mfma_f32_16x16x32_bf16 v[10:13], v[216:219], v[176:179], v[10:13]
	v_mfma_f32_16x16x32_bf16 v[6:9], v[216:219], v[180:183], v[6:9]
	s_waitcnt lgkmcnt(1)
	v_mfma_f32_16x16x32_bf16 v[70:73], v[184:187], v[168:171], v[70:73]
	s_add_i32 s6, s6, 64
	s_cmpk_eq_i32 s6, 0x3c0
	s_mov_b32 s7, s8
	s_waitcnt lgkmcnt(0)
	v_mfma_f32_16x16x32_bf16 v[62:65], v[184:187], v[188:191], v[62:65]
	v_mfma_f32_16x16x32_bf16 v[38:41], v[208:211], v[168:171], v[38:41]
	v_mfma_f32_16x16x32_bf16 v[34:37], v[208:211], v[188:191], v[34:37]
	v_mfma_f32_16x16x32_bf16 v[18:21], v[212:215], v[168:171], v[18:21]
	v_mfma_f32_16x16x32_bf16 v[14:17], v[212:215], v[188:191], v[14:17]
	v_mfma_f32_16x16x32_bf16 v[2:5], v[216:219], v[168:171], v[2:5]
	v_mfma_f32_16x16x32_bf16 v[90:93], v[216:219], v[188:191], v[90:93]
	s_cbranch_scc0 .LBB0_2714
	s_waitcnt vmcnt(0)
	s_barrier
	v_add_u32_e32 v130, v153, v141
	ds_read_b128 v[132:135], v130
	ds_read_b128 v[164:167], v130 offset:2048
	ds_read_b128 v[168:171], v130 offset:4096
	ds_read_b128 v[172:175], v130 offset:6144
	v_add_u32_e32 v130, v154, v141
	ds_read_b128 v[176:179], v130
	ds_read_b128 v[180:183], v130 offset:2048
	ds_read_b128 v[184:187], v130 offset:4096
	ds_read_b128 v[188:191], v130 offset:6144
	s_waitcnt lgkmcnt(0)
	v_mfma_f32_16x16x32_bf16 v[126:129], v[132:135], v[176:179], v[126:129]
	v_mfma_f32_16x16x32_bf16 v[110:113], v[164:167], v[176:179], v[110:113]
	v_mfma_f32_16x16x32_bf16 v[82:85], v[168:171], v[176:179], v[82:85]
	v_mfma_f32_16x16x32_bf16 v[50:53], v[172:175], v[176:179], v[50:53]
	ds_read_b128 v[176:179], v130 offset:8192
	ds_read_b128 v[192:195], v130 offset:10240
	v_mfma_f32_16x16x32_bf16 v[122:125], v[132:135], v[180:183], v[122:125]
	v_mfma_f32_16x16x32_bf16 v[106:109], v[164:167], v[180:183], v[106:109]
	v_mfma_f32_16x16x32_bf16 v[78:81], v[168:171], v[180:183], v[78:81]
	v_mfma_f32_16x16x32_bf16 v[42:45], v[172:175], v[180:183], v[42:45]
	v_mfma_f32_16x16x32_bf16 v[118:121], v[132:135], v[184:187], v[118:121]
	v_mfma_f32_16x16x32_bf16 v[180:183], v[164:167], v[184:187], v[94:97]
	v_mfma_f32_16x16x32_bf16 v[200:203], v[168:171], v[184:187], v[58:61]
	v_mfma_f32_16x16x32_bf16 v[204:207], v[168:171], v[188:191], v[54:57]
	v_mfma_f32_16x16x32_bf16 v[184:187], v[172:175], v[184:187], v[26:29]
	s_nop 2
	ds_read_b128 v[26:29], v130 offset:12288
	ds_read_b128 v[54:57], v130 offset:14336
	v_mfma_f32_16x16x32_bf16 v[114:117], v[132:135], v[188:191], v[114:117]
	v_mfma_f32_16x16x32_bf16 v[196:199], v[164:167], v[188:191], v[86:89]
	v_mfma_f32_16x16x32_bf16 v[188:191], v[172:175], v[188:191], v[22:25]
	v_add_u32_e32 v130, v154, v142
	s_waitcnt lgkmcnt(0)
	v_mfma_f32_16x16x32_bf16 v[208:211], v[168:171], v[192:195], v[30:33]
	ds_read_b128 v[22:25], v130
	ds_read_b128 v[86:89], v130 offset:2048
	s_nop 0
	v_add_u32_e32 v30, v153, v142
	v_mfma_f32_16x16x32_bf16 v[102:105], v[132:135], v[176:179], v[102:105]
	v_mfma_f32_16x16x32_bf16 v[74:77], v[164:167], v[176:179], v[74:77]
	v_mfma_f32_16x16x32_bf16 v[46:49], v[168:171], v[176:179], v[46:49]
	v_mfma_f32_16x16x32_bf16 v[10:13], v[172:175], v[176:179], v[10:13]
	ds_read_b128 v[176:179], v30
	ds_read_b128 v[212:215], v30 offset:2048
	ds_read_b128 v[216:219], v30 offset:4096
	ds_read_b128 v[220:223], v30 offset:6144
	v_mfma_f32_16x16x32_bf16 v[98:101], v[132:135], v[192:195], v[98:101]
	v_mfma_f32_16x16x32_bf16 v[66:69], v[164:167], v[192:195], v[66:69]
	v_mfma_f32_16x16x32_bf16 v[6:9], v[172:175], v[192:195], v[6:9]
	v_mfma_f32_16x16x32_bf16 v[192:195], v[164:167], v[26:29], v[38:41]
	v_mfma_f32_16x16x32_bf16 v[34:37], v[164:167], v[54:57], v[34:37]
	v_mfma_f32_16x16x32_bf16 v[164:167], v[168:171], v[26:29], v[18:21]
	v_mfma_f32_16x16x32_bf16 v[168:171], v[168:171], v[54:57], v[14:17]
	s_nop 2
	ds_read_b128 v[14:17], v130 offset:4096
	ds_read_b128 v[18:21], v130 offset:6144
	v_mfma_f32_16x16x32_bf16 v[70:73], v[132:135], v[26:29], v[70:73]
	v_mfma_f32_16x16x32_bf16 v[132:135], v[132:135], v[54:57], v[62:65]
	v_mfma_f32_16x16x32_bf16 v[2:5], v[172:175], v[26:29], v[2:5]
	v_mfma_f32_16x16x32_bf16 v[172:175], v[172:175], v[54:57], v[90:93]
	ds_read_b128 v[224:227], v130 offset:8192
	ds_read_b128 v[228:231], v130 offset:10240
	s_waitcnt lgkmcnt(0)
	v_mfma_f32_16x16x32_bf16 v[126:129], v[176:179], v[22:25], v[126:129]
	v_mfma_f32_16x16x32_bf16 v[122:125], v[176:179], v[86:89], v[122:125]
	v_mfma_f32_16x16x32_bf16 v[94:97], v[212:215], v[22:25], v[110:113]
	v_mfma_f32_16x16x32_bf16 v[90:93], v[212:215], v[86:89], v[106:109]
	v_mfma_f32_16x16x32_bf16 v[62:65], v[216:219], v[22:25], v[82:85]
	v_mfma_f32_16x16x32_bf16 v[58:61], v[216:219], v[86:89], v[78:81]
	v_mfma_f32_16x16x32_bf16 v[30:33], v[220:223], v[22:25], v[50:53]
	v_mfma_f32_16x16x32_bf16 v[26:29], v[220:223], v[86:89], v[42:45]
	v_mfma_f32_16x16x32_bf16 v[86:89], v[212:215], v[14:17], v[180:183]
	v_mfma_f32_16x16x32_bf16 v[22:25], v[220:223], v[14:17], v[184:187]
	s_nop 1
	ds_read_b128 v[180:183], v130 offset:12288
	ds_read_b128 v[184:187], v130 offset:14336
	v_mfma_f32_16x16x32_bf16 v[118:121], v[176:179], v[14:17], v[118:121]
	v_mfma_f32_16x16x32_bf16 v[114:117], v[176:179], v[18:21], v[114:117]
	v_mfma_f32_16x16x32_bf16 v[82:85], v[212:215], v[18:21], v[196:199]
	v_mfma_f32_16x16x32_bf16 v[54:57], v[216:219], v[14:17], v[200:203]
	v_mfma_f32_16x16x32_bf16 v[50:53], v[216:219], v[18:21], v[204:207]
	v_mfma_f32_16x16x32_bf16 v[18:21], v[220:223], v[18:21], v[188:191]
	v_mfma_f32_16x16x32_bf16 v[110:113], v[176:179], v[224:227], v[102:105]
	v_mfma_f32_16x16x32_bf16 v[106:109], v[176:179], v[228:231], v[98:101]
	v_mfma_f32_16x16x32_bf16 v[78:81], v[212:215], v[224:227], v[74:77]
	v_mfma_f32_16x16x32_bf16 v[74:77], v[212:215], v[228:231], v[66:69]
	v_mfma_f32_16x16x32_bf16 v[46:49], v[216:219], v[224:227], v[46:49]
	v_mfma_f32_16x16x32_bf16 v[38:41], v[216:219], v[228:231], v[208:211]
	v_mfma_f32_16x16x32_bf16 v[14:17], v[220:223], v[224:227], v[10:13]
	v_mfma_f32_16x16x32_bf16 v[6:9], v[220:223], v[228:231], v[6:9]
	v_mov_b32_e32 v130, v1
	s_waitcnt vmcnt(0) lgkmcnt(0)
	s_barrier
; __device__ __forceinline__ unsigned pack2(float a, float b) { unsigned r; asm("v_cvt_pk_bf16_f32 %0, %1, %2" : "=v"(r) : "v"(a), "v"(b)); return r; }
;   __device__ __forceinline__ void r4(int g, int rig, int col, f32x4 v) const {
;     const float b = bias[col];
;     uint2 u; u.x = pack2(v[0] + b, v[1] + b); u.y = pack2(v[2] + b, v[3] + b);
;     *(uint2*)(out + (size_t)col * 16384 + (size_t)g * 2048 + rig) = u;
;   }
; template <bool SWAP, class Epi, bool THIN = false> ...
;     ...
;     } else if constexpr (Epi::KIND == 1) {
; #pragma unroll
;       for (int m = 0; m < 4; ++m) {
;         const int rig = rig0 + rw + m * 16 + fq_e * 4;
; #pragma unroll
;         for (int n = 0; n < 8; ++n) {
;           const int col = nt * 256 + wc_e * 128 + n * 16 + fr_e;
;           if (col < N) epi.r4(g, rig, col, acc[m][n]);
;         }
;       }
	v_mfma_f32_16x16x32_bf16 v[98:101], v[176:179], v[184:187], v[132:135]
	v_ashrrev_i32_e32 v10, 8, v130
	v_add_u32_e32 v10, s5, v10
	v_ashrrev_i32_e32 v11, 31, v10
	v_lshrrev_b32_e32 v11, 28, v11
	v_add_u32_e32 v11, v10, v11
	v_ashrrev_i32_e32 v132, 4, v11
	v_lshlrev_b32_e32 v11, 11, v132
	v_lshlrev_b32_e32 v10, 7, v10
	v_sub_u32_e32 v10, v10, v11
	v_lshrrev_b32_e32 v11, 1, v130
	v_lshrrev_b32_e32 v12, 2, v130
	v_and_b32_e32 v11, 64, v11
	v_and_b32_e32 v12, 12, v12
	v_mfma_f32_16x16x32_bf16 v[42:45], v[216:219], v[180:183], v[164:167]
	v_and_b32_e32 v133, 15, v130
	s_nop 1
	v_or3_b32 v164, v10, v11, v12
	v_mfma_f32_16x16x32_bf16 v[10:13], v[220:223], v[180:183], v[2:5]
	v_ashrrev_i32_e32 v165, 31, v164
	s_nop 1
	v_lshlrev_b32_e32 v2, 1, v130
	v_and_b32_e32 v2, 0x80, v2
	v_mfma_f32_16x16x32_bf16 v[102:105], v[176:179], v[180:183], v[70:73]
	v_or3_b32 v134, v133, v2, s4
	v_ashrrev_i32_e32 v133, 31, v132
	v_lshlrev_b64 v[132:133], 12, v[132:133]
	v_mfma_f32_16x16x32_bf16 v[70:73], v[212:215], v[180:183], v[192:195]
	v_lshl_add_u64 v[132:133], s[20:21], 0, v[132:133]
	v_lshl_add_u64 v[132:133], v[164:165], 1, v[132:133]
	v_cmp_gt_i32_e32 vcc, s30, v134
	v_mfma_f32_16x16x32_bf16 v[66:69], v[212:215], v[184:187], v[34:37]
	v_ashrrev_i32_e32 v135, 31, v134
	v_mfma_f32_16x16x32_bf16 v[34:37], v[216:219], v[184:187], v[168:171]
	v_mfma_f32_16x16x32_bf16 v[2:5], v[220:223], v[184:187], v[172:175]
	v_lshlrev_b32_e32 v236, 2, v134
	global_load_dword v237, v236, s[22:23]
	global_load_dword v238, v236, s[22:23] offset:64
	global_load_dword v239, v236, s[22:23] offset:128
	global_load_dword v240, v236, s[22:23] offset:192
	global_load_dword v241, v236, s[22:23] offset:256
	global_load_dword v242, v236, s[22:23] offset:320
	global_load_dword v243, v236, s[22:23] offset:384
	global_load_dword v244, v236, s[22:23] offset:448
	s_waitcnt vmcnt(0)
	v_bfe_u32 v246, v1, 4, 1
	v_mul_u32_u24_e32 v246, 24, v246
	v_mov_b32_e32 v247, 0
	v_lshlrev_b64 v[232:233], 15, v[134:135]
	v_lshl_add_u64 v[234:235], v[132:133], 0, v[232:233]
	v_lshl_add_u64 v[234:235], v[234:235], 0, v[246:247]
	v_add_f32_e32 v126, v126, v237
	v_add_f32_e32 v127, v127, v237
	v_add_f32_e32 v128, v128, v237
	v_add_f32_e32 v129, v129, v237
	v_add_f32_e32 v94, v94, v237
	v_add_f32_e32 v95, v95, v237
	v_add_f32_e32 v96, v96, v237
	v_add_f32_e32 v97, v97, v237
	v_cvt_pk_bf16_f32 v126, v126, v127
	v_cvt_pk_bf16_f32 v127, v128, v129
	v_cvt_pk_bf16_f32 v128, v94, v95
	v_cvt_pk_bf16_f32 v129, v96, v97
	s_nop 1
	v_permlane16_swap_b32 v126, v128
	v_permlane16_swap_b32 v127, v129
	global_store_dwordx4 v[234:235], v[126:129], off
	v_add_f32_e32 v62, v62, v237
	v_add_f32_e32 v63, v63, v237
	v_add_f32_e32 v64, v64, v237
	v_add_f32_e32 v65, v65, v237
	v_add_f32_e32 v30, v30, v237
	v_add_f32_e32 v31, v31, v237
	v_add_f32_e32 v32, v32, v237
	v_add_f32_e32 v33, v33, v237
	v_cvt_pk_bf16_f32 v62, v62, v63
	v_cvt_pk_bf16_f32 v63, v64, v65
	v_cvt_pk_bf16_f32 v64, v30, v31
	v_cvt_pk_bf16_f32 v65, v32, v33
	s_nop 1
	v_permlane16_swap_b32 v62, v64
	v_permlane16_swap_b32 v63, v65
	global_store_dwordx4 v[234:235], v[62:65], off offset:64
	s_nop 1
	v_or_b32_e32 v232, 16, v134
	v_ashrrev_i32_e32 v233, 31, v232
	v_lshlrev_b64 v[232:233], 15, v[232:233]
	v_lshl_add_u64 v[234:235], v[132:133], 0, v[232:233]
	v_lshl_add_u64 v[234:235], v[234:235], 0, v[246:247]
	v_add_f32_e32 v122, v122, v238
	v_add_f32_e32 v123, v123, v238
	v_add_f32_e32 v124, v124, v238
	v_add_f32_e32 v125, v125, v238
	v_add_f32_e32 v90, v90, v238
	v_add_f32_e32 v91, v91, v238
	v_add_f32_e32 v92, v92, v238
	v_add_f32_e32 v93, v93, v238
	v_cvt_pk_bf16_f32 v122, v122, v123
	v_cvt_pk_bf16_f32 v123, v124, v125
	v_cvt_pk_bf16_f32 v124, v90, v91
	v_cvt_pk_bf16_f32 v125, v92, v93
	s_nop 1
	v_permlane16_swap_b32 v122, v124
	v_permlane16_swap_b32 v123, v125
	global_store_dwordx4 v[234:235], v[122:125], off
	v_add_f32_e32 v58, v58, v238
	v_add_f32_e32 v59, v59, v238
	v_add_f32_e32 v60, v60, v238
	v_add_f32_e32 v61, v61, v238
	v_add_f32_e32 v26, v26, v238
	v_add_f32_e32 v27, v27, v238
	v_add_f32_e32 v28, v28, v238
	v_add_f32_e32 v29, v29, v238
	v_cvt_pk_bf16_f32 v58, v58, v59
	v_cvt_pk_bf16_f32 v59, v60, v61
	v_cvt_pk_bf16_f32 v60, v26, v27
	v_cvt_pk_bf16_f32 v61, v28, v29
	s_nop 1
	v_permlane16_swap_b32 v58, v60
	v_permlane16_swap_b32 v59, v61
	global_store_dwordx4 v[234:235], v[58:61], off offset:64
	s_nop 1
	v_or_b32_e32 v232, 32, v134
	v_ashrrev_i32_e32 v233, 31, v232
	v_lshlrev_b64 v[232:233], 15, v[232:233]
	v_lshl_add_u64 v[234:235], v[132:133], 0, v[232:233]
	v_lshl_add_u64 v[234:235], v[234:235], 0, v[246:247]
	v_add_f32_e32 v118, v118, v239
	v_add_f32_e32 v119, v119, v239
	v_add_f32_e32 v120, v120, v239
	v_add_f32_e32 v121, v121, v239
	v_add_f32_e32 v86, v86, v239
	v_add_f32_e32 v87, v87, v239
	v_add_f32_e32 v88, v88, v239
	v_add_f32_e32 v89, v89, v239
	v_cvt_pk_bf16_f32 v118, v118, v119
	v_cvt_pk_bf16_f32 v119, v120, v121
	v_cvt_pk_bf16_f32 v120, v86, v87
	v_cvt_pk_bf16_f32 v121, v88, v89
	s_nop 1
	v_permlane16_swap_b32 v118, v120
	v_permlane16_swap_b32 v119, v121
	global_store_dwordx4 v[234:235], v[118:121], off
	v_add_f32_e32 v54, v54, v239
	v_add_f32_e32 v55, v55, v239
	v_add_f32_e32 v56, v56, v239
	v_add_f32_e32 v57, v57, v239
	v_add_f32_e32 v22, v22, v239
	v_add_f32_e32 v23, v23, v239
	v_add_f32_e32 v24, v24, v239
	v_add_f32_e32 v25, v25, v239
	v_cvt_pk_bf16_f32 v54, v54, v55
	v_cvt_pk_bf16_f32 v55, v56, v57
	v_cvt_pk_bf16_f32 v56, v22, v23
	v_cvt_pk_bf16_f32 v57, v24, v25
	s_nop 1
	v_permlane16_swap_b32 v54, v56
	v_permlane16_swap_b32 v55, v57
	global_store_dwordx4 v[234:235], v[54:57], off offset:64
	s_nop 1
	v_or_b32_e32 v232, 48, v134
; __device__ __forceinline__ unsigned pack2(float a, float b) { unsigned r; asm("v_cvt_pk_bf16_f32 %0, %1, %2" : "=v"(r) : "v"(a), "v"(b)); return r; }
;   __device__ __forceinline__ void r4(int g, int rig, int col, f32x4 v) const {
;     const float b = bias[col];
;     uint2 u; u.x = pack2(v[0] + b, v[1] + b); u.y = pack2(v[2] + b, v[3] + b);
;     *(uint2*)(out + (size_t)col * 16384 + (size_t)g * 2048 + rig) = u;
;   }
; template <bool SWAP, class Epi, bool THIN = false> ...
;     ...
;     } else if constexpr (Epi::KIND == 1) {
; #pragma unroll
;       for (int m = 0; m < 4; ++m) {
;         const int rig = rig0 + rw + m * 16 + fq_e * 4;
; #pragma unroll
;         for (int n = 0; n < 8; ++n) {
;           const int col = nt * 256 + wc_e * 128 + n * 16 + fr_e;
;           if (col < N) epi.r4(g, rig, col, acc[m][n]);
;         }
;       }
	v_ashrrev_i32_e32 v233, 31, v232
	v_lshlrev_b64 v[232:233], 15, v[232:233]
	v_lshl_add_u64 v[234:235], v[132:133], 0, v[232:233]
	v_lshl_add_u64 v[234:235], v[234:235], 0, v[246:247]
	v_add_f32_e32 v114, v114, v240
	v_add_f32_e32 v115, v115, v240
	v_add_f32_e32 v116, v116, v240
	v_add_f32_e32 v117, v117, v240
	v_add_f32_e32 v82, v82, v240
	v_add_f32_e32 v83, v83, v240
	v_add_f32_e32 v84, v84, v240
	v_add_f32_e32 v85, v85, v240
	v_cvt_pk_bf16_f32 v114, v114, v115
	v_cvt_pk_bf16_f32 v115, v116, v117
	v_cvt_pk_bf16_f32 v116, v82, v83
	v_cvt_pk_bf16_f32 v117, v84, v85
	s_nop 1
	v_permlane16_swap_b32 v114, v116
	v_permlane16_swap_b32 v115, v117
	global_store_dwordx4 v[234:235], v[114:117], off
	v_add_f32_e32 v50, v50, v240
	v_add_f32_e32 v51, v51, v240
	v_add_f32_e32 v52, v52, v240
	v_add_f32_e32 v53, v53, v240
	v_add_f32_e32 v18, v18, v240
	v_add_f32_e32 v19, v19, v240
	v_add_f32_e32 v20, v20, v240
	v_add_f32_e32 v21, v21, v240
	v_cvt_pk_bf16_f32 v50, v50, v51
	v_cvt_pk_bf16_f32 v51, v52, v53
	v_cvt_pk_bf16_f32 v52, v18, v19
	v_cvt_pk_bf16_f32 v53, v20, v21
	s_nop 1
	v_permlane16_swap_b32 v50, v52
	v_permlane16_swap_b32 v51, v53
	global_store_dwordx4 v[234:235], v[50:53], off offset:64
	s_nop 1
	v_or_b32_e32 v232, 64, v134
	v_ashrrev_i32_e32 v233, 31, v232
	v_lshlrev_b64 v[232:233], 15, v[232:233]
	v_lshl_add_u64 v[234:235], v[132:133], 0, v[232:233]
	v_lshl_add_u64 v[234:235], v[234:235], 0, v[246:247]
	v_add_f32_e32 v110, v110, v241
	v_add_f32_e32 v111, v111, v241
	v_add_f32_e32 v112, v112, v241
	v_add_f32_e32 v113, v113, v241
	v_add_f32_e32 v78, v78, v241
	v_add_f32_e32 v79, v79, v241
	v_add_f32_e32 v80, v80, v241
	v_add_f32_e32 v81, v81, v241
	v_cvt_pk_bf16_f32 v110, v110, v111
	v_cvt_pk_bf16_f32 v111, v112, v113
	v_cvt_pk_bf16_f32 v112, v78, v79
	v_cvt_pk_bf16_f32 v113, v80, v81
	s_nop 1
	v_permlane16_swap_b32 v110, v112
	v_permlane16_swap_b32 v111, v113
	global_store_dwordx4 v[234:235], v[110:113], off
	v_add_f32_e32 v46, v46, v241
	v_add_f32_e32 v47, v47, v241
	v_add_f32_e32 v48, v48, v241
	v_add_f32_e32 v49, v49, v241
	v_add_f32_e32 v14, v14, v241
	v_add_f32_e32 v15, v15, v241
	v_add_f32_e32 v16, v16, v241
	v_add_f32_e32 v17, v17, v241
	v_cvt_pk_bf16_f32 v46, v46, v47
	v_cvt_pk_bf16_f32 v47, v48, v49
	v_cvt_pk_bf16_f32 v48, v14, v15
	v_cvt_pk_bf16_f32 v49, v16, v17
	s_nop 1
	v_permlane16_swap_b32 v46, v48
	v_permlane16_swap_b32 v47, v49
	global_store_dwordx4 v[234:235], v[46:49], off offset:64
	s_nop 1
	v_or_b32_e32 v232, 80, v134
	v_ashrrev_i32_e32 v233, 31, v232
	v_lshlrev_b64 v[232:233], 15, v[232:233]
	v_lshl_add_u64 v[234:235], v[132:133], 0, v[232:233]
	v_lshl_add_u64 v[234:235], v[234:235], 0, v[246:247]
	v_add_f32_e32 v106, v106, v242
	v_add_f32_e32 v107, v107, v242
	v_add_f32_e32 v108, v108, v242
	v_add_f32_e32 v109, v109, v242
	v_add_f32_e32 v74, v74, v242
	v_add_f32_e32 v75, v75, v242
	v_add_f32_e32 v76, v76, v242
	v_add_f32_e32 v77, v77, v242
	v_cvt_pk_bf16_f32 v106, v106, v107
	v_cvt_pk_bf16_f32 v107, v108, v109
	v_cvt_pk_bf16_f32 v108, v74, v75
	v_cvt_pk_bf16_f32 v109, v76, v77
	s_nop 1
	v_permlane16_swap_b32 v106, v108
	v_permlane16_swap_b32 v107, v109
	global_store_dwordx4 v[234:235], v[106:109], off
	v_add_f32_e32 v38, v38, v242
	v_add_f32_e32 v39, v39, v242
	v_add_f32_e32 v40, v40, v242
	v_add_f32_e32 v41, v41, v242
	v_add_f32_e32 v6, v6, v242
	v_add_f32_e32 v7, v7, v242
	v_add_f32_e32 v8, v8, v242
	v_add_f32_e32 v9, v9, v242
	v_cvt_pk_bf16_f32 v38, v38, v39
	v_cvt_pk_bf16_f32 v39, v40, v41
	v_cvt_pk_bf16_f32 v40, v6, v7
	v_cvt_pk_bf16_f32 v41, v8, v9
	s_nop 1
	v_permlane16_swap_b32 v38, v40
	v_permlane16_swap_b32 v39, v41
	global_store_dwordx4 v[234:235], v[38:41], off offset:64
	s_nop 1
	v_or_b32_e32 v232, 96, v134
	v_ashrrev_i32_e32 v233, 31, v232
	v_lshlrev_b64 v[232:233], 15, v[232:233]
	v_lshl_add_u64 v[234:235], v[132:133], 0, v[232:233]
	v_lshl_add_u64 v[234:235], v[234:235], 0, v[246:247]
	v_add_f32_e32 v102, v102, v243
	v_add_f32_e32 v103, v103, v243
	v_add_f32_e32 v104, v104, v243
	v_add_f32_e32 v105, v105, v243
	v_add_f32_e32 v70, v70, v243
	v_add_f32_e32 v71, v71, v243
	v_add_f32_e32 v72, v72, v243
	v_add_f32_e32 v73, v73, v243
	v_cvt_pk_bf16_f32 v102, v102, v103
	v_cvt_pk_bf16_f32 v103, v104, v105
	v_cvt_pk_bf16_f32 v104, v70, v71
	v_cvt_pk_bf16_f32 v105, v72, v73
	s_nop 1
	v_permlane16_swap_b32 v102, v104
	v_permlane16_swap_b32 v103, v105
	global_store_dwordx4 v[234:235], v[102:105], off
	v_add_f32_e32 v42, v42, v243
	v_add_f32_e32 v43, v43, v243
	v_add_f32_e32 v44, v44, v243
	v_add_f32_e32 v45, v45, v243
	v_add_f32_e32 v10, v10, v243
	v_add_f32_e32 v11, v11, v243
	v_add_f32_e32 v12, v12, v243
	v_add_f32_e32 v13, v13, v243
	v_cvt_pk_bf16_f32 v42, v42, v43
	v_cvt_pk_bf16_f32 v43, v44, v45
	v_cvt_pk_bf16_f32 v44, v10, v11
	v_cvt_pk_bf16_f32 v45, v12, v13
	s_nop 1
	v_permlane16_swap_b32 v42, v44
	v_permlane16_swap_b32 v43, v45
	global_store_dwordx4 v[234:235], v[42:45], off offset:64
	s_nop 1
	v_or_b32_e32 v232, 112, v134
	v_ashrrev_i32_e32 v233, 31, v232
	v_lshlrev_b64 v[232:233], 15, v[232:233]
	v_lshl_add_u64 v[234:235], v[132:133], 0, v[232:233]
	v_lshl_add_u64 v[234:235], v[234:235], 0, v[246:247]
	v_add_f32_e32 v98, v98, v244
	v_add_f32_e32 v99, v99, v244
	v_add_f32_e32 v100, v100, v244
	v_add_f32_e32 v101, v101, v244
	v_add_f32_e32 v66, v66, v244
	v_add_f32_e32 v67, v67, v244
	v_add_f32_e32 v68, v68, v244
	v_add_f32_e32 v69, v69, v244
	v_cvt_pk_bf16_f32 v98, v98, v99
	v_cvt_pk_bf16_f32 v99, v100, v101
	v_cvt_pk_bf16_f32 v100, v66, v67
	v_cvt_pk_bf16_f32 v101, v68, v69
	s_nop 1
	v_permlane16_swap_b32 v98, v100
	v_permlane16_swap_b32 v99, v101
	global_store_dwordx4 v[234:235], v[98:101], off
	v_add_f32_e32 v34, v34, v244
	v_add_f32_e32 v35, v35, v244
	v_add_f32_e32 v36, v36, v244
	v_add_f32_e32 v37, v37, v244
	v_add_f32_e32 v2, v2, v244
	v_add_f32_e32 v3, v3, v244
	v_add_f32_e32 v4, v4, v244
	v_add_f32_e32 v5, v5, v244
	v_cvt_pk_bf16_f32 v34, v34, v35
	v_cvt_pk_bf16_f32 v35, v36, v37
	v_cvt_pk_bf16_f32 v36, v2, v3
	v_cvt_pk_bf16_f32 v37, v4, v5
	s_nop 1
	v_permlane16_swap_b32 v34, v36
	v_permlane16_swap_b32 v35, v37
	global_store_dwordx4 v[234:235], v[34:37], off offset:64
	s_nop 1
	s_branch .LBB0_2712

; template <bool SWAP, class Epi, bool THIN = false> ...
;     ...
;     for (int st = 0; st < ns; ++st) {
;       asm volatile("s_waitcnt vmcnt(0)" ::: "memory");
;       __builtin_amdgcn_s_barrier();
;       asm volatile("" ::: "memory");
;       if (st + 1 < ns) {
;         char* nb = smem + ((st + 1) & 1) * 65536;
;         const int ko = (st + 1) * 64;
; #pragma unroll
;         for (int i = 0; i < 4; ++i) { GLDS16(A + (size_t)(ap[i] + ko), nb + tid * 16 + i * 8192); GLDS16(Bt + (size_t)(bp[i] + ko), nb + 32768 + tid * 16 + i * 8192); }
;       }
;       const char* sa = smem + (st & 1) * 65536 + (wr * 64 + fr) * 128;
;       const char* sb = smem + (st & 1) * 65536 + 32768 + (wc * 128 + fr) * 128;
;       if constexpr (THIN) {
;         if (wc == 0) {
; #pragma unroll
;           for (int ks = 0; ks < 2; ++ks) {
;             bf16x8 af[4], bf[2];
; #pragma unroll
;             for (int m = 0; m < 4; ++m) af[m] = *(const bf16x8*)(sa + m * 2048 + (((ks * 4 + fq) ^ swz) << 4));
; #pragma unroll
;             for (int n = 0; n < 2; ++n) bf[n] = *(const bf16x8*)(sb + n * 2048 + (((ks * 4 + fq) ^ swz) << 4));
; #pragma unroll
;             for (int m = 0; m < 4; ++m)
; #pragma unroll
;               for (int n = 0; n < 2; ++n)
;                 acc[m][n] = SWAP ? __builtin_amdgcn_mfma_f32_16x16x32_bf16(bf[n], af[m], acc[m][n], 0, 0, 0)
;                                  : __builtin_amdgcn_mfma_f32_16x16x32_bf16(af[m], bf[n], acc[m][n], 0, 0, 0);
;           }
;         }
;       } else {
;       bf16x8 afA[4], afB[4], bfb[2][2];
; #pragma unroll
;       for (int m = 0; m < 4; ++m) afA[m] = *(const bf16x8*)(sa + m * 2048 + ((fq ^ swz) << 4));
; #pragma unroll
;       for (int n = 0; n < 2; ++n) bfb[0][n] = *(const bf16x8*)(sb + n * 2048 + ((fq ^ swz) << 4));
; #pragma unroll
;       for (int gq = 0; gq < 8; ++gq) {
;         const int ks = gq >> 2, nh = gq & 3;
;         if (gq < 7) {
;           const int ks2 = (gq + 1) >> 2, nh2 = (gq + 1) & 3;
; #pragma unroll
;           for (int n = 0; n < 2; ++n) bfb[(gq + 1) & 1][n] = *(const bf16x8*)(sb + (nh2 * 2 + n) * 2048 + (((ks2 * 4 + fq) ^ swz) << 4));
;         }
;         if (gq == 3) {
; #pragma unroll
;           for (int m = 0; m < 4; ++m) afB[m] = *(const bf16x8*)(sa + m * 2048 + (((4 + fq) ^ swz) << 4));
;         }
;         __builtin_amdgcn_sched_barrier(0);
; #pragma unroll
.LBB0_3112:
	s_add_i32 s9, s7, 0x10000
	s_and_b32 s8, s9, 0x10000
	v_add_u32_e32 v142, s8, v156
	s_nop 0
	v_readfirstlane_b32 s10, v142
	s_and_b32 s7, s7, 0x10000
	v_add_u32_e32 v138, s7, v157
	v_add_u32_e32 v152, v138, v159
	s_waitcnt vmcnt(0)
	s_barrier
	ds_read_b128 v[140:143], v152
	ds_read_b128 v[144:147], v152 offset:2048
	ds_read_b128 v[148:151], v152 offset:4096
	ds_read_b128 v[180:183], v152 offset:6144
	v_or_b32_e32 v152, s7, v158
	v_add_u32_e32 v153, v152, v159
	ds_read_b128 v[184:187], v153 offset:32768
	ds_read_b128 v[188:191], v153 offset:34816
	ds_read_b128 v[192:195], v153 offset:36864
	ds_read_b128 v[196:199], v153 offset:38912
	v_add_u32_e32 v138, v138, v160
	s_waitcnt lgkmcnt(3)
	v_mfma_f32_16x16x32_bf16 v[126:129], v[184:187], v[140:143], v[126:129]
	s_mov_b32 m0, s10
	v_mfma_f32_16x16x32_bf16 v[110:113], v[184:187], v[144:147], v[110:113]
	global_load_lds_dwordx4 v137, s[22:23]
	v_add_u32_e32 v137, 0x80, v137
	v_mfma_f32_16x16x32_bf16 v[82:85], v[184:187], v[148:151], v[82:85]
	v_mfma_f32_16x16x32_bf16 v[50:53], v[184:187], v[180:183], v[50:53]
	ds_read_b128 v[184:187], v153 offset:40960
	ds_read_b128 v[200:203], v153 offset:43008
	s_waitcnt lgkmcnt(4)
	v_mfma_f32_16x16x32_bf16 v[122:125], v[188:191], v[140:143], v[122:125]
	s_add_u32 m0, s10, 0x8000
	v_mfma_f32_16x16x32_bf16 v[106:109], v[188:191], v[144:147], v[106:109]
	global_load_lds_dwordx4 v136, s[28:29]
	v_add_u32_e32 v136, 0x80, v136
	v_mfma_f32_16x16x32_bf16 v[78:81], v[188:191], v[148:151], v[78:81]
	v_mfma_f32_16x16x32_bf16 v[38:41], v[188:191], v[180:183], v[38:41]
	s_waitcnt lgkmcnt(3)
	v_mfma_f32_16x16x32_bf16 v[118:121], v[192:195], v[140:143], v[118:121]
	s_add_u32 m0, s10, 0x2000
	v_mfma_f32_16x16x32_bf16 v[94:97], v[192:195], v[144:147], v[94:97]
	global_load_lds_dwordx4 v135, s[22:23]
	v_add_u32_e32 v135, 0x80, v135
	v_mfma_f32_16x16x32_bf16 v[58:61], v[192:195], v[148:151], v[58:61]
	v_mfma_f32_16x16x32_bf16 v[26:29], v[192:195], v[180:183], v[26:29]
	ds_read_b128 v[188:191], v153 offset:45056
	ds_read_b128 v[192:195], v153 offset:47104
	s_waitcnt lgkmcnt(4)
	v_mfma_f32_16x16x32_bf16 v[114:117], v[196:199], v[140:143], v[114:117]
	s_add_u32 m0, s10, 0xa000
	v_mfma_f32_16x16x32_bf16 v[86:89], v[196:199], v[144:147], v[86:89]
	global_load_lds_dwordx4 v134, s[28:29]
	v_add_u32_e32 v134, 0x80, v134
	v_mfma_f32_16x16x32_bf16 v[54:57], v[196:199], v[148:151], v[54:57]
	v_mfma_f32_16x16x32_bf16 v[22:25], v[196:199], v[180:183], v[22:25]
	v_add_u32_e32 v152, v152, v160
	s_waitcnt lgkmcnt(3)
	v_mfma_f32_16x16x32_bf16 v[102:105], v[184:187], v[140:143], v[102:105]
	ds_read_b128 v[196:199], v152 offset:32768
	ds_read_b128 v[204:207], v152 offset:34816
	s_add_u32 m0, s10, 0x4000
	v_mfma_f32_16x16x32_bf16 v[74:77], v[184:187], v[144:147], v[74:77]
	global_load_lds_dwordx4 v133, s[22:23]
	v_add_u32_e32 v133, 0x80, v133
	v_mfma_f32_16x16x32_bf16 v[46:49], v[184:187], v[148:151], v[46:49]
	v_mfma_f32_16x16x32_bf16 v[10:13], v[184:187], v[180:183], v[10:13]
	ds_read_b128 v[184:187], v138
	ds_read_b128 v[208:211], v138 offset:2048
	ds_read_b128 v[212:215], v138 offset:4096
	ds_read_b128 v[216:219], v138 offset:6144
	s_waitcnt lgkmcnt(8)
	v_mfma_f32_16x16x32_bf16 v[98:101], v[200:203], v[140:143], v[98:101]
	s_add_u32 m0, s10, 0xc000
	v_mfma_f32_16x16x32_bf16 v[66:69], v[200:203], v[144:147], v[66:69]
	global_load_lds_dwordx4 v132, s[28:29]
	v_add_u32_e32 v132, 0x80, v132
	v_mfma_f32_16x16x32_bf16 v[34:37], v[200:203], v[148:151], v[34:37]
	v_mfma_f32_16x16x32_bf16 v[6:9], v[200:203], v[180:183], v[6:9]
	s_waitcnt lgkmcnt(7)
	v_mfma_f32_16x16x32_bf16 v[70:73], v[188:191], v[140:143], v[70:73]
	s_add_u32 m0, s10, 0x6000
	s_waitcnt lgkmcnt(6)
	v_mfma_f32_16x16x32_bf16 v[62:65], v[192:195], v[140:143], v[62:65]
	global_load_lds_dwordx4 v131, s[22:23]
	v_add_u32_e32 v131, 0x80, v131
	v_mfma_f32_16x16x32_bf16 v[42:45], v[188:191], v[144:147], v[42:45]
	v_mfma_f32_16x16x32_bf16 v[30:33], v[192:195], v[144:147], v[30:33]
	ds_read_b128 v[140:143], v152 offset:36864
	ds_read_b128 v[144:147], v152 offset:38912
	v_mfma_f32_16x16x32_bf16 v[18:21], v[188:191], v[148:151], v[18:21]
	s_add_u32 m0, s10, 0xe000
	v_mfma_f32_16x16x32_bf16 v[14:17], v[192:195], v[148:151], v[14:17]
	global_load_lds_dwordx4 v130, s[28:29]
	v_add_u32_e32 v130, 0x80, v130
	v_mfma_f32_16x16x32_bf16 v[2:5], v[188:191], v[180:183], v[2:5]
	v_mfma_f32_16x16x32_bf16 v[90:93], v[192:195], v[180:183], v[90:93]
	ds_read_b128 v[148:151], v152 offset:40960
	ds_read_b128 v[180:183], v152 offset:43008
	s_waitcnt lgkmcnt(7)
	v_mfma_f32_16x16x32_bf16 v[126:129], v[196:199], v[184:187], v[126:129]
	v_mfma_f32_16x16x32_bf16 v[122:125], v[204:207], v[184:187], v[122:125]
	s_waitcnt lgkmcnt(6)
	v_mfma_f32_16x16x32_bf16 v[110:113], v[196:199], v[208:211], v[110:113]
	v_mfma_f32_16x16x32_bf16 v[106:109], v[204:207], v[208:211], v[106:109]
	s_waitcnt lgkmcnt(5)
	v_mfma_f32_16x16x32_bf16 v[82:85], v[196:199], v[212:215], v[82:85]
	v_mfma_f32_16x16x32_bf16 v[78:81], v[204:207], v[212:215], v[78:81]
	s_waitcnt lgkmcnt(4)
	v_mfma_f32_16x16x32_bf16 v[50:53], v[196:199], v[216:219], v[50:53]
	v_mfma_f32_16x16x32_bf16 v[38:41], v[204:207], v[216:219], v[38:41]
	s_waitcnt lgkmcnt(3)
	v_mfma_f32_16x16x32_bf16 v[118:121], v[140:143], v[184:187], v[118:121]
	v_mfma_f32_16x16x32_bf16 v[94:97], v[140:143], v[208:211], v[94:97]
	v_mfma_f32_16x16x32_bf16 v[58:61], v[140:143], v[212:215], v[58:61]
	v_mfma_f32_16x16x32_bf16 v[26:29], v[140:143], v[216:219], v[26:29]
	ds_read_b128 v[140:143], v152 offset:45056
	ds_read_b128 v[188:191], v152 offset:47104
	s_waitcnt lgkmcnt(4)
; template <bool SWAP, class Epi, bool THIN = false> ...
;     ...
;     for (int st = 0; st < ns; ++st) {
;       asm volatile("s_waitcnt vmcnt(0)" ::: "memory");
;       __builtin_amdgcn_s_barrier();
;       asm volatile("" ::: "memory");
;       if (st + 1 < ns) {
;         char* nb = smem + ((st + 1) & 1) * 65536;
;         const int ko = (st + 1) * 64;
; #pragma unroll
;         for (int i = 0; i < 4; ++i) { GLDS16(A + (size_t)(ap[i] + ko), nb + tid * 16 + i * 8192); GLDS16(Bt + (size_t)(bp[i] + ko), nb + 32768 + tid * 16 + i * 8192); }
;       }
;       const char* sa = smem + (st & 1) * 65536 + (wr * 64 + fr) * 128;
;       const char* sb = smem + (st & 1) * 65536 + 32768 + (wc * 128 + fr) * 128;
;       if constexpr (THIN) {
;         if (wc == 0) {
; #pragma unroll
;           for (int ks = 0; ks < 2; ++ks) {
;             bf16x8 af[4], bf[2];
; #pragma unroll
;             for (int m = 0; m < 4; ++m) af[m] = *(const bf16x8*)(sa + m * 2048 + (((ks * 4 + fq) ^ swz) << 4));
; #pragma unroll
;             for (int n = 0; n < 2; ++n) bf[n] = *(const bf16x8*)(sb + n * 2048 + (((ks * 4 + fq) ^ swz) << 4));
; #pragma unroll
;             for (int m = 0; m < 4; ++m)
; #pragma unroll
;               for (int n = 0; n < 2; ++n)
;                 acc[m][n] = SWAP ? __builtin_amdgcn_mfma_f32_16x16x32_bf16(bf[n], af[m], acc[m][n], 0, 0, 0)
;                                  : __builtin_amdgcn_mfma_f32_16x16x32_bf16(af[m], bf[n], acc[m][n], 0, 0, 0);
;           }
;         }
;       } else {
;       bf16x8 afA[4], afB[4], bfb[2][2];
; #pragma unroll
;       for (int m = 0; m < 4; ++m) afA[m] = *(const bf16x8*)(sa + m * 2048 + ((fq ^ swz) << 4));
; #pragma unroll
;       for (int n = 0; n < 2; ++n) bfb[0][n] = *(const bf16x8*)(sb + n * 2048 + ((fq ^ swz) << 4));
; #pragma unroll
;       for (int gq = 0; gq < 8; ++gq) {
;         const int ks = gq >> 2, nh = gq & 3;
;         if (gq < 7) {
;           const int ks2 = (gq + 1) >> 2, nh2 = (gq + 1) & 3;
; #pragma unroll
;           for (int n = 0; n < 2; ++n) bfb[(gq + 1) & 1][n] = *(const bf16x8*)(sb + (nh2 * 2 + n) * 2048 + (((ks2 * 4 + fq) ^ swz) << 4));
;         }
;         if (gq == 3) {
; #pragma unroll
;           for (int m = 0; m < 4; ++m) afB[m] = *(const bf16x8*)(sa + m * 2048 + (((4 + fq) ^ swz) << 4));
;         }
;         __builtin_amdgcn_sched_barrier(0);
; #pragma unroll
	v_mfma_f32_16x16x32_bf16 v[114:117], v[144:147], v[184:187], v[114:117]
	v_mfma_f32_16x16x32_bf16 v[86:89], v[144:147], v[208:211], v[86:89]
	v_mfma_f32_16x16x32_bf16 v[54:57], v[144:147], v[212:215], v[54:57]
	v_mfma_f32_16x16x32_bf16 v[22:25], v[144:147], v[216:219], v[22:25]
	s_waitcnt lgkmcnt(3)
	v_mfma_f32_16x16x32_bf16 v[102:105], v[148:151], v[184:187], v[102:105]
	s_waitcnt lgkmcnt(2)
	v_mfma_f32_16x16x32_bf16 v[98:101], v[180:183], v[184:187], v[98:101]
	v_mfma_f32_16x16x32_bf16 v[74:77], v[148:151], v[208:211], v[74:77]
	v_mfma_f32_16x16x32_bf16 v[66:69], v[180:183], v[208:211], v[66:69]
	v_mfma_f32_16x16x32_bf16 v[46:49], v[148:151], v[212:215], v[46:49]
	v_mfma_f32_16x16x32_bf16 v[34:37], v[180:183], v[212:215], v[34:37]
	v_mfma_f32_16x16x32_bf16 v[10:13], v[148:151], v[216:219], v[10:13]
	v_mfma_f32_16x16x32_bf16 v[6:9], v[180:183], v[216:219], v[6:9]
	s_waitcnt lgkmcnt(1)
	v_mfma_f32_16x16x32_bf16 v[70:73], v[140:143], v[184:187], v[70:73]
	s_add_i32 s6, s6, 64
	s_cmpk_eq_i32 s6, 0x3c0
	s_mov_b32 s7, s9
	s_waitcnt lgkmcnt(0)
	v_mfma_f32_16x16x32_bf16 v[62:65], v[188:191], v[184:187], v[62:65]
	v_mfma_f32_16x16x32_bf16 v[42:45], v[140:143], v[208:211], v[42:45]
	v_mfma_f32_16x16x32_bf16 v[30:33], v[188:191], v[208:211], v[30:33]
	v_mfma_f32_16x16x32_bf16 v[18:21], v[140:143], v[212:215], v[18:21]
	v_mfma_f32_16x16x32_bf16 v[14:17], v[188:191], v[212:215], v[14:17]
	v_mfma_f32_16x16x32_bf16 v[2:5], v[140:143], v[216:219], v[2:5]
	v_mfma_f32_16x16x32_bf16 v[90:93], v[188:191], v[216:219], v[90:93]
	s_cbranch_scc0 .LBB0_3112
	v_add_u32_e32 v138, s8, v157
	v_add_u32_e32 v152, s8, v158
	s_waitcnt vmcnt(0)
	s_barrier
	v_add_u32_e32 v144, v138, v159
	v_add_u32_e32 v153, v152, v159
	ds_read_b128 v[130:133], v144
	ds_read_b128 v[134:137], v144 offset:2048
	ds_read_b128 v[140:143], v144 offset:4096
	ds_read_b128 v[144:147], v144 offset:6144
	ds_read_b128 v[148:151], v153 offset:32768
	ds_read_b128 v[180:183], v153 offset:34816
	ds_read_b128 v[184:187], v153 offset:36864
	ds_read_b128 v[188:191], v153 offset:38912
	v_add_u32_e32 v138, v138, v160
	s_waitcnt lgkmcnt(0)
	v_mfma_f32_16x16x32_bf16 v[126:129], v[148:151], v[130:133], v[126:129]
	v_mfma_f32_16x16x32_bf16 v[110:113], v[148:151], v[134:137], v[110:113]
	v_mfma_f32_16x16x32_bf16 v[82:85], v[148:151], v[140:143], v[82:85]
	v_mfma_f32_16x16x32_bf16 v[50:53], v[148:151], v[144:147], v[50:53]
	ds_read_b128 v[148:151], v153 offset:40960
	ds_read_b128 v[192:195], v153 offset:43008
	v_mfma_f32_16x16x32_bf16 v[122:125], v[180:183], v[130:133], v[122:125]
	v_mfma_f32_16x16x32_bf16 v[106:109], v[180:183], v[134:137], v[106:109]
	v_mfma_f32_16x16x32_bf16 v[78:81], v[180:183], v[140:143], v[78:81]
	v_mfma_f32_16x16x32_bf16 v[38:41], v[180:183], v[144:147], v[38:41]
	v_mfma_f32_16x16x32_bf16 v[118:121], v[184:187], v[130:133], v[118:121]
	v_mfma_f32_16x16x32_bf16 v[180:183], v[184:187], v[134:137], v[94:97]
	v_mfma_f32_16x16x32_bf16 v[200:203], v[184:187], v[140:143], v[58:61]
	v_mfma_f32_16x16x32_bf16 v[204:207], v[188:191], v[140:143], v[54:57]
	v_mfma_f32_16x16x32_bf16 v[184:187], v[184:187], v[144:147], v[26:29]
	s_nop 2
	ds_read_b128 v[26:29], v153 offset:45056
	ds_read_b128 v[54:57], v153 offset:47104
	v_mfma_f32_16x16x32_bf16 v[114:117], v[188:191], v[130:133], v[114:117]
	v_mfma_f32_16x16x32_bf16 v[196:199], v[188:191], v[134:137], v[86:89]
	v_mfma_f32_16x16x32_bf16 v[188:191], v[188:191], v[144:147], v[22:25]
	v_add_u32_e32 v152, v152, v160
	s_waitcnt lgkmcnt(0)
	v_mfma_f32_16x16x32_bf16 v[102:105], v[148:151], v[130:133], v[102:105]
	ds_read_b128 v[22:25], v152 offset:32768
	ds_read_b128 v[86:89], v152 offset:34816
	v_mfma_f32_16x16x32_bf16 v[74:77], v[148:151], v[134:137], v[74:77]
	v_mfma_f32_16x16x32_bf16 v[46:49], v[148:151], v[140:143], v[46:49]
	v_mfma_f32_16x16x32_bf16 v[10:13], v[148:151], v[144:147], v[10:13]
	ds_read_b128 v[148:151], v138
	ds_read_b128 v[208:211], v138 offset:2048
	ds_read_b128 v[212:215], v138 offset:4096
	ds_read_b128 v[216:219], v138 offset:6144
	v_mfma_f32_16x16x32_bf16 v[98:101], v[192:195], v[130:133], v[98:101]
	v_mfma_f32_16x16x32_bf16 v[66:69], v[192:195], v[134:137], v[66:69]
	v_mfma_f32_16x16x32_bf16 v[34:37], v[192:195], v[140:143], v[34:37]
	v_mfma_f32_16x16x32_bf16 v[6:9], v[192:195], v[144:147], v[6:9]
	v_mfma_f32_16x16x32_bf16 v[220:223], v[26:29], v[140:143], v[18:21]
	v_mfma_f32_16x16x32_bf16 v[140:143], v[54:57], v[140:143], v[14:17]
	s_nop 2
	ds_read_b128 v[14:17], v152 offset:36864
	ds_read_b128 v[18:21], v152 offset:38912
	v_mfma_f32_16x16x32_bf16 v[70:73], v[26:29], v[130:133], v[70:73]
	v_mfma_f32_16x16x32_bf16 v[2:5], v[26:29], v[144:147], v[2:5]
	v_mfma_f32_16x16x32_bf16 v[130:133], v[54:57], v[130:133], v[62:65]
	v_mfma_f32_16x16x32_bf16 v[192:195], v[26:29], v[134:137], v[42:45]
	v_mfma_f32_16x16x32_bf16 v[134:137], v[54:57], v[134:137], v[30:33]
	v_mfma_f32_16x16x32_bf16 v[224:227], v[54:57], v[144:147], v[90:93]
	ds_read_b128 v[144:147], v152 offset:40960
	ds_read_b128 v[228:231], v152 offset:43008
	s_waitcnt lgkmcnt(0)
	v_mfma_f32_16x16x32_bf16 v[126:129], v[22:25], v[148:151], v[126:129]
	v_mfma_f32_16x16x32_bf16 v[122:125], v[86:89], v[148:151], v[122:125]
	v_mfma_f32_16x16x32_bf16 v[94:97], v[22:25], v[208:211], v[110:113]
	v_mfma_f32_16x16x32_bf16 v[90:93], v[86:89], v[208:211], v[106:109]
	v_mfma_f32_16x16x32_bf16 v[62:65], v[22:25], v[212:215], v[82:85]
	v_mfma_f32_16x16x32_bf16 v[58:61], v[86:89], v[212:215], v[78:81]
	v_mfma_f32_16x16x32_bf16 v[30:33], v[22:25], v[216:219], v[50:53]
	v_mfma_f32_16x16x32_bf16 v[26:29], v[86:89], v[216:219], v[38:41]
	v_mfma_f32_16x16x32_bf16 v[86:89], v[14:17], v[208:211], v[180:183]
	v_mfma_f32_16x16x32_bf16 v[22:25], v[14:17], v[216:219], v[184:187]
	s_nop 1
	ds_read_b128 v[180:183], v152 offset:45056
	ds_read_b128 v[184:187], v152 offset:47104
	v_mfma_f32_16x16x32_bf16 v[118:121], v[14:17], v[148:151], v[118:121]
	v_mfma_f32_16x16x32_bf16 v[114:117], v[18:21], v[148:151], v[114:117]
	v_mfma_f32_16x16x32_bf16 v[82:85], v[18:21], v[208:211], v[196:199]
	v_mfma_f32_16x16x32_bf16 v[54:57], v[14:17], v[212:215], v[200:203]
	v_mfma_f32_16x16x32_bf16 v[50:53], v[18:21], v[212:215], v[204:207]
	v_mfma_f32_16x16x32_bf16 v[18:21], v[18:21], v[216:219], v[188:191]
	v_mfma_f32_16x16x32_bf16 v[110:113], v[144:147], v[148:151], v[102:105]
	v_mfma_f32_16x16x32_bf16 v[106:109], v[228:231], v[148:151], v[98:101]
	v_mfma_f32_16x16x32_bf16 v[78:81], v[144:147], v[208:211], v[74:77]
	v_mfma_f32_16x16x32_bf16 v[74:77], v[228:231], v[208:211], v[66:69]
	v_mfma_f32_16x16x32_bf16 v[46:49], v[144:147], v[212:215], v[46:49]
	v_mfma_f32_16x16x32_bf16 v[42:45], v[228:231], v[212:215], v[34:37]
	v_mfma_f32_16x16x32_bf16 v[14:17], v[144:147], v[216:219], v[10:13]
	v_mfma_f32_16x16x32_bf16 v[10:13], v[228:231], v[216:219], v[6:9]
	v_mov_b32_e32 v138, v1
	s_waitcnt vmcnt(0) lgkmcnt(0)
	s_barrier
; __device__ __forceinline__ int get_tid512() { int t = threadIdx.x; asm volatile("" : "+v"(t)); return t; }
; __device__ __forceinline__ float bf2f(bf16_t h) { return __uint_as_float(((unsigned)h) << 16); }
;   __device__ __forceinline__ void c4(int g, int rig, int col, f32x4 v) const {
;     const size_t o = ((size_t)g * 2048 + rig) * 1024 + col;
;     f32x4 bs;
;     if (BASE_F32) bs = __builtin_nontemporal_load((const f32x4*)((const float*)base + o));
;     else {
;       const uint2 u = *(const uint2*)((const bf16_t*)base + o);
;       bs[0] = bf2f((bf16_t)(u.x & 0xffff)); bs[1] = bf2f((bf16_t)(u.x >> 16)); bs[2] = bf2f((bf16_t)(u.y & 0xffff)); bs[3] = bf2f((bf16_t)(u.y >> 16));
;     }
;     const f32x4 gt = *(const f32x4*)(gate + (size_t)g * 6144 + col);
;     f32x4 bi = {0.f, 0.f, 0.f, 0.f};
;     if (bias) bi = *(const f32x4*)(bias + col);
; template <bool SWAP, class Epi, bool THIN = false> ...
;     ...
;     const int te = get_tid512();
;     const int fr_e = te & 15, fq_e = (te & 63) >> 4, wr_e = te >> 7, wc_e = (te >> 6) & 1;
;     const int sub = 2 * mt + (wr_e >> 1);
;     const int g = sub / tpg, ti = sub - g * tpg;
;     const int rig0 = ti * step - halo;
;     const int rw = (wr_e & 1) * 64;
;     if constexpr (Epi::KIND == 0) {
; #pragma unroll
;       for (int m = 0; m < 4; ++m) {
;         const int rig = rig0 + rw + m * 16 + fr_e;
;         if constexpr (Epi::ROWSUM) {
;           float ss = 0.f;
	v_mfma_f32_16x16x32_bf16 v[98:101], v[184:187], v[148:151], v[130:133]
	v_ashrrev_i32_e32 v7, 8, v138
	v_add_u32_e32 v7, s5, v7
	v_ashrrev_i32_e32 v8, 31, v7
	v_lshrrev_b32_e32 v8, 28, v8
	v_add_u32_e32 v8, v7, v8
	v_ashrrev_i32_e32 v130, 4, v8
	v_lshlrev_b32_e32 v8, 11, v130
	v_lshlrev_b32_e32 v7, 7, v7
	v_sub_u32_e32 v7, v7, v8
	v_lshrrev_b32_e32 v8, 1, v138
	v_and_b32_e32 v6, 15, v138
	v_and_b32_e32 v8, 64, v8
	v_or3_b32 v144, v7, v8, v6
	v_lshlrev_b32_e32 v6, 1, v138
	v_and_b32_e32 v131, 0x80, v6
	v_mfma_f32_16x16x32_bf16 v[6:9], v[180:183], v[216:219], v[2:5]
	v_ashrrev_i32_e32 v145, 31, v144
	v_lshlrev_b64 v[132:133], 10, v[144:145]
	s_nop 0
	v_lshrrev_b32_e32 v2, 2, v138
	v_and_b32_e32 v2, 12, v2
	v_mfma_f32_16x16x32_bf16 v[102:105], v[180:183], v[148:151], v[70:73]
	v_mfma_f32_16x16x32_bf16 v[70:73], v[180:183], v[208:211], v[192:195]
	v_mfma_f32_16x16x32_bf16 v[66:69], v[184:187], v[208:211], v[134:137]
	v_mfma_f32_16x16x32_bf16 v[38:41], v[180:183], v[212:215], v[220:223]
	v_mfma_f32_16x16x32_bf16 v[34:37], v[184:187], v[212:215], v[140:143]
	s_nop 2
	v_or3_b32 v140, v2, v131, s4
	v_mfma_f32_16x16x32_bf16 v[2:5], v[184:187], v[216:219], v[224:227]
	v_ashrrev_i32_e32 v131, 31, v130
	v_lshlrev_b64 v[146:147], 21, v[130:131]
	v_mad_i64_i32 v[130:131], s[4:5], v130, s39, 0
	v_lshl_add_u64 v[132:133], v[132:133], 0, v[146:147]
	v_lshl_add_u64 v[142:143], s[30:31], 0, v[130:131]
	v_cndmask_b32_e64 v130, 0, 1, s[34:35]
	v_cmp_gt_i32_e64 s[6:7], s40, v140
	v_ashrrev_i32_e32 v141, 31, v140
	v_lshl_add_u64 v[148:149], v[132:133], 1, s[24:25]
	v_cmp_ne_u32_e64 s[4:5], 1, v130
	v_bfe_u32 v248, v1, 4, 1
	v_mul_u32_u24_e32 v248, 24, v248
	v_mov_b32_e32 v249, 0
	v_lshl_add_u64 v[130:131], v[140:141], 2, v[142:143]
	global_load_dwordx4 v[180:183], v[130:131], off
	global_load_dwordx4 v[184:187], v[130:131], off offset:64
	global_load_dwordx4 v[188:191], v[130:131], off offset:128
	global_load_dwordx4 v[192:195], v[130:131], off offset:192
	global_load_dwordx4 v[196:199], v[130:131], off offset:256
	global_load_dwordx4 v[200:203], v[130:131], off offset:320
	global_load_dwordx4 v[204:207], v[130:131], off offset:384
	global_load_dwordx4 v[208:211], v[130:131], off offset:448
	s_and_b64 vcc, exec, s[4:5]
	s_cbranch_vccnz .Lhout_nobias
	v_lshl_add_u64 v[132:133], v[140:141], 2, s[26:27]
	global_load_dwordx4 v[212:215], v[132:133], off
	global_load_dwordx4 v[216:219], v[132:133], off offset:64
	global_load_dwordx4 v[220:223], v[132:133], off offset:128
	global_load_dwordx4 v[224:227], v[132:133], off offset:192
	global_load_dwordx4 v[228:231], v[132:133], off offset:256
	global_load_dwordx4 v[232:235], v[132:133], off offset:320
	global_load_dwordx4 v[236:239], v[132:133], off offset:384
	global_load_dwordx4 v[240:243], v[132:133], off offset:448
	s_branch .Lhout_bias

; template <bool SWAP, class Epi, bool THIN = false> ...
;     ...
;     for (int st = 0; st < ns; ++st) {
;       asm volatile("s_waitcnt vmcnt(0)" ::: "memory");
;       __builtin_amdgcn_s_barrier();
;       asm volatile("" ::: "memory");
;       if (st + 1 < ns) {
;         char* nb = smem + ((st + 1) & 1) * 65536;
;         const int ko = (st + 1) * 64;
; #pragma unroll
;         for (int i = 0; i < 4; ++i) { GLDS16(A + (size_t)(ap[i] + ko), nb + tid * 16 + i * 8192); GLDS16(Bt + (size_t)(bp[i] + ko), nb + 32768 + tid * 16 + i * 8192); }
;       }
;       const char* sa = smem + (st & 1) * 65536 + (wr * 64 + fr) * 128;
;       const char* sb = smem + (st & 1) * 65536 + 32768 + (wc * 128 + fr) * 128;
;       if constexpr (THIN) {
;         if (wc == 0) {
; #pragma unroll
;           for (int ks = 0; ks < 2; ++ks) {
;             bf16x8 af[4], bf[2];
; #pragma unroll
;             for (int m = 0; m < 4; ++m) af[m] = *(const bf16x8*)(sa + m * 2048 + (((ks * 4 + fq) ^ swz) << 4));
; #pragma unroll
;             for (int n = 0; n < 2; ++n) bf[n] = *(const bf16x8*)(sb + n * 2048 + (((ks * 4 + fq) ^ swz) << 4));
; #pragma unroll
;             for (int m = 0; m < 4; ++m)
; #pragma unroll
;               for (int n = 0; n < 2; ++n)
;                 acc[m][n] = SWAP ? __builtin_amdgcn_mfma_f32_16x16x32_bf16(bf[n], af[m], acc[m][n], 0, 0, 0)
;                                  : __builtin_amdgcn_mfma_f32_16x16x32_bf16(af[m], bf[n], acc[m][n], 0, 0, 0);
;           }
;         }
;       } else {
;       bf16x8 afA[4], afB[4], bfb[2][2];
; #pragma unroll
;       for (int m = 0; m < 4; ++m) afA[m] = *(const bf16x8*)(sa + m * 2048 + ((fq ^ swz) << 4));
; #pragma unroll
;       for (int n = 0; n < 2; ++n) bfb[0][n] = *(const bf16x8*)(sb + n * 2048 + ((fq ^ swz) << 4));
; #pragma unroll
;       for (int gq = 0; gq < 8; ++gq) {
;         const int ks = gq >> 2, nh = gq & 3;
;         if (gq < 7) {
;           const int ks2 = (gq + 1) >> 2, nh2 = (gq + 1) & 3;
; #pragma unroll
;           for (int n = 0; n < 2; ++n) bfb[(gq + 1) & 1][n] = *(const bf16x8*)(sb + (nh2 * 2 + n) * 2048 + (((ks2 * 4 + fq) ^ swz) << 4));
;         }
;         if (gq == 3) {
; #pragma unroll
;           for (int m = 0; m < 4; ++m) afB[m] = *(const bf16x8*)(sa + m * 2048 + (((4 + fq) ^ swz) << 4));
;         }
;         __builtin_amdgcn_sched_barrier(0);
; #pragma unroll
.LBB0_3424:
	s_add_i32 s8, s7, 0x10000
	s_and_b32 s9, s8, 0x10000
	v_add_u32_e32 v170, s9, v135
	s_nop 0
	v_readfirstlane_b32 s9, v170
	s_and_b32 s7, s7, 0x10000
	v_or_b32_e32 v204, s7, v139
	v_add_u32_e32 v205, v204, v140
	v_add_u32_e32 v136, s7, v138
	v_add_u32_e32 v180, v136, v140
	s_waitcnt vmcnt(0)
	s_barrier
	ds_read_b128 v[168:171], v180
	ds_read_b128 v[172:175], v180 offset:2048
	ds_read_b128 v[176:179], v180 offset:4096
	ds_read_b128 v[180:183], v180 offset:6144
	ds_read_b128 v[184:187], v205 offset:32768
	ds_read_b128 v[188:191], v205 offset:34816
	ds_read_b128 v[192:195], v205 offset:36864
	ds_read_b128 v[196:199], v205 offset:38912
	v_add_u32_e32 v136, v136, v141
	s_waitcnt lgkmcnt(3)
	v_mfma_f32_16x16x32_bf16 v[126:129], v[184:187], v[168:171], v[126:129]
	s_mov_b32 m0, s9
	v_mfma_f32_16x16x32_bf16 v[110:113], v[184:187], v[172:175], v[110:113]
	global_load_lds_dwordx4 v167, s[14:15]
	v_add_u32_e32 v167, 0x80, v167
	v_mfma_f32_16x16x32_bf16 v[82:85], v[184:187], v[176:179], v[82:85]
	v_mfma_f32_16x16x32_bf16 v[50:53], v[184:187], v[180:183], v[50:53]
	ds_read_b128 v[184:187], v205 offset:40960
	ds_read_b128 v[200:203], v205 offset:43008
	s_waitcnt lgkmcnt(4)
	v_mfma_f32_16x16x32_bf16 v[122:125], v[188:191], v[168:171], v[122:125]
	s_add_u32 m0, s9, 0x8000
	v_mfma_f32_16x16x32_bf16 v[106:109], v[188:191], v[172:175], v[106:109]
	global_load_lds_dwordx4 v166, s[10:11]
	v_add_u32_e32 v166, 0x80, v166
	v_mfma_f32_16x16x32_bf16 v[78:81], v[188:191], v[176:179], v[78:81]
	v_mfma_f32_16x16x32_bf16 v[42:45], v[188:191], v[180:183], v[42:45]
	s_waitcnt lgkmcnt(3)
	v_mfma_f32_16x16x32_bf16 v[118:121], v[192:195], v[168:171], v[118:121]
	s_add_u32 m0, s9, 0x2000
	v_mfma_f32_16x16x32_bf16 v[94:97], v[192:195], v[172:175], v[94:97]
	global_load_lds_dwordx4 v165, s[14:15]
	v_add_u32_e32 v165, 0x80, v165
	v_mfma_f32_16x16x32_bf16 v[58:61], v[192:195], v[176:179], v[58:61]
	v_mfma_f32_16x16x32_bf16 v[26:29], v[192:195], v[180:183], v[26:29]
	ds_read_b128 v[188:191], v205 offset:45056
	ds_read_b128 v[192:195], v205 offset:47104
	s_waitcnt lgkmcnt(4)
	v_mfma_f32_16x16x32_bf16 v[114:117], v[196:199], v[168:171], v[114:117]
	s_add_u32 m0, s9, 0xa000
	v_mfma_f32_16x16x32_bf16 v[90:93], v[196:199], v[172:175], v[90:93]
	global_load_lds_dwordx4 v164, s[10:11]
	v_add_u32_e32 v164, 0x80, v164
	v_mfma_f32_16x16x32_bf16 v[54:57], v[196:199], v[176:179], v[54:57]
	v_mfma_f32_16x16x32_bf16 v[22:25], v[196:199], v[180:183], v[22:25]
	v_add_u32_e32 v220, v204, v141
	s_waitcnt lgkmcnt(3)
	v_mfma_f32_16x16x32_bf16 v[102:105], v[184:187], v[168:171], v[102:105]
	ds_read_b128 v[196:199], v220 offset:32768
	ds_read_b128 v[204:207], v220 offset:34816
	s_add_u32 m0, s9, 0x4000
	v_mfma_f32_16x16x32_bf16 v[74:77], v[184:187], v[172:175], v[74:77]
	global_load_lds_dwordx4 v163, s[14:15]
	v_add_u32_e32 v163, 0x80, v163
	v_mfma_f32_16x16x32_bf16 v[46:49], v[184:187], v[176:179], v[46:49]
	v_mfma_f32_16x16x32_bf16 v[10:13], v[184:187], v[180:183], v[10:13]
	ds_read_b128 v[184:187], v136
	ds_read_b128 v[208:211], v136 offset:2048
	ds_read_b128 v[212:215], v136 offset:4096
	ds_read_b128 v[216:219], v136 offset:6144
	s_waitcnt lgkmcnt(8)
	v_mfma_f32_16x16x32_bf16 v[98:101], v[200:203], v[168:171], v[98:101]
	s_add_u32 m0, s9, 0xc000
	v_mfma_f32_16x16x32_bf16 v[66:69], v[200:203], v[172:175], v[66:69]
	global_load_lds_dwordx4 v162, s[10:11]
	v_add_u32_e32 v162, 0x80, v162
	v_mfma_f32_16x16x32_bf16 v[30:33], v[200:203], v[176:179], v[30:33]
	v_mfma_f32_16x16x32_bf16 v[6:9], v[200:203], v[180:183], v[6:9]
	s_waitcnt lgkmcnt(7)
	v_mfma_f32_16x16x32_bf16 v[70:73], v[188:191], v[168:171], v[70:73]
	s_add_u32 m0, s9, 0x6000
	s_waitcnt lgkmcnt(6)
	v_mfma_f32_16x16x32_bf16 v[62:65], v[192:195], v[168:171], v[62:65]
	global_load_lds_dwordx4 v161, s[14:15]
	v_add_u32_e32 v161, 0x80, v161
	v_mfma_f32_16x16x32_bf16 v[38:41], v[188:191], v[172:175], v[38:41]
	v_mfma_f32_16x16x32_bf16 v[34:37], v[192:195], v[172:175], v[34:37]
	ds_read_b128 v[168:171], v220 offset:36864
	ds_read_b128 v[172:175], v220 offset:38912
	v_mfma_f32_16x16x32_bf16 v[18:21], v[188:191], v[176:179], v[18:21]
	s_add_u32 m0, s9, 0xe000
	v_mfma_f32_16x16x32_bf16 v[14:17], v[192:195], v[176:179], v[14:17]
	global_load_lds_dwordx4 v160, s[10:11]
	v_add_u32_e32 v160, 0x80, v160
	v_mfma_f32_16x16x32_bf16 v[2:5], v[188:191], v[180:183], v[2:5]
	v_mfma_f32_16x16x32_bf16 v[86:89], v[192:195], v[180:183], v[86:89]
	ds_read_b128 v[176:179], v220 offset:40960
	ds_read_b128 v[180:183], v220 offset:43008
	s_waitcnt lgkmcnt(7)
	v_mfma_f32_16x16x32_bf16 v[126:129], v[196:199], v[184:187], v[126:129]
	v_mfma_f32_16x16x32_bf16 v[122:125], v[204:207], v[184:187], v[122:125]
	s_waitcnt lgkmcnt(6)
	v_mfma_f32_16x16x32_bf16 v[110:113], v[196:199], v[208:211], v[110:113]
	v_mfma_f32_16x16x32_bf16 v[106:109], v[204:207], v[208:211], v[106:109]
	s_waitcnt lgkmcnt(5)
	v_mfma_f32_16x16x32_bf16 v[82:85], v[196:199], v[212:215], v[82:85]
	v_mfma_f32_16x16x32_bf16 v[78:81], v[204:207], v[212:215], v[78:81]
	s_waitcnt lgkmcnt(4)
	v_mfma_f32_16x16x32_bf16 v[50:53], v[196:199], v[216:219], v[50:53]
	v_mfma_f32_16x16x32_bf16 v[42:45], v[204:207], v[216:219], v[42:45]
	s_waitcnt lgkmcnt(3)
	v_mfma_f32_16x16x32_bf16 v[118:121], v[168:171], v[184:187], v[118:121]
	v_mfma_f32_16x16x32_bf16 v[94:97], v[168:171], v[208:211], v[94:97]
	v_mfma_f32_16x16x32_bf16 v[58:61], v[168:171], v[212:215], v[58:61]
	v_mfma_f32_16x16x32_bf16 v[26:29], v[168:171], v[216:219], v[26:29]
	ds_read_b128 v[168:171], v220 offset:45056
	ds_read_b128 v[188:191], v220 offset:47104
	s_waitcnt lgkmcnt(4)
; template <bool SWAP, class Epi, bool THIN = false> ...
;     ...
;     for (int st = 0; st < ns; ++st) {
;       asm volatile("s_waitcnt vmcnt(0)" ::: "memory");
;       __builtin_amdgcn_s_barrier();
;       asm volatile("" ::: "memory");
;       if (st + 1 < ns) {
;         char* nb = smem + ((st + 1) & 1) * 65536;
;         const int ko = (st + 1) * 64;
; #pragma unroll
;         for (int i = 0; i < 4; ++i) { GLDS16(A + (size_t)(ap[i] + ko), nb + tid * 16 + i * 8192); GLDS16(Bt + (size_t)(bp[i] + ko), nb + 32768 + tid * 16 + i * 8192); }
;       }
;       const char* sa = smem + (st & 1) * 65536 + (wr * 64 + fr) * 128;
;       const char* sb = smem + (st & 1) * 65536 + 32768 + (wc * 128 + fr) * 128;
;       if constexpr (THIN) {
;         if (wc == 0) {
; #pragma unroll
;           for (int ks = 0; ks < 2; ++ks) {
;             bf16x8 af[4], bf[2];
; #pragma unroll
;             for (int m = 0; m < 4; ++m) af[m] = *(const bf16x8*)(sa + m * 2048 + (((ks * 4 + fq) ^ swz) << 4));
; #pragma unroll
;             for (int n = 0; n < 2; ++n) bf[n] = *(const bf16x8*)(sb + n * 2048 + (((ks * 4 + fq) ^ swz) << 4));
; #pragma unroll
;             for (int m = 0; m < 4; ++m)
; #pragma unroll
;               for (int n = 0; n < 2; ++n)
;                 acc[m][n] = SWAP ? __builtin_amdgcn_mfma_f32_16x16x32_bf16(bf[n], af[m], acc[m][n], 0, 0, 0)
;                                  : __builtin_amdgcn_mfma_f32_16x16x32_bf16(af[m], bf[n], acc[m][n], 0, 0, 0);
;           }
;         }
;       } else {
;       bf16x8 afA[4], afB[4], bfb[2][2];
; #pragma unroll
;       for (int m = 0; m < 4; ++m) afA[m] = *(const bf16x8*)(sa + m * 2048 + ((fq ^ swz) << 4));
; #pragma unroll
;       for (int n = 0; n < 2; ++n) bfb[0][n] = *(const bf16x8*)(sb + n * 2048 + ((fq ^ swz) << 4));
; #pragma unroll
;       for (int gq = 0; gq < 8; ++gq) {
;         const int ks = gq >> 2, nh = gq & 3;
;         if (gq < 7) {
;           const int ks2 = (gq + 1) >> 2, nh2 = (gq + 1) & 3;
; #pragma unroll
;           for (int n = 0; n < 2; ++n) bfb[(gq + 1) & 1][n] = *(const bf16x8*)(sb + (nh2 * 2 + n) * 2048 + (((ks2 * 4 + fq) ^ swz) << 4));
;         }
;         if (gq == 3) {
; #pragma unroll
;           for (int m = 0; m < 4; ++m) afB[m] = *(const bf16x8*)(sa + m * 2048 + (((4 + fq) ^ swz) << 4));
;         }
;         __builtin_amdgcn_sched_barrier(0);
; #pragma unroll
	v_mfma_f32_16x16x32_bf16 v[114:117], v[172:175], v[184:187], v[114:117]
	v_mfma_f32_16x16x32_bf16 v[90:93], v[172:175], v[208:211], v[90:93]
	v_mfma_f32_16x16x32_bf16 v[54:57], v[172:175], v[212:215], v[54:57]
	v_mfma_f32_16x16x32_bf16 v[22:25], v[172:175], v[216:219], v[22:25]
	s_waitcnt lgkmcnt(3)
	v_mfma_f32_16x16x32_bf16 v[102:105], v[176:179], v[184:187], v[102:105]
	s_waitcnt lgkmcnt(2)
	v_mfma_f32_16x16x32_bf16 v[98:101], v[180:183], v[184:187], v[98:101]
	v_mfma_f32_16x16x32_bf16 v[74:77], v[176:179], v[208:211], v[74:77]
	v_mfma_f32_16x16x32_bf16 v[66:69], v[180:183], v[208:211], v[66:69]
	v_mfma_f32_16x16x32_bf16 v[46:49], v[176:179], v[212:215], v[46:49]
	v_mfma_f32_16x16x32_bf16 v[30:33], v[180:183], v[212:215], v[30:33]
	v_mfma_f32_16x16x32_bf16 v[10:13], v[176:179], v[216:219], v[10:13]
	v_mfma_f32_16x16x32_bf16 v[6:9], v[180:183], v[216:219], v[6:9]
	s_waitcnt lgkmcnt(1)
	v_mfma_f32_16x16x32_bf16 v[70:73], v[168:171], v[184:187], v[70:73]
	s_add_i32 s5, s5, 64
	s_cmpk_eq_i32 s5, 0x3c0
	s_mov_b32 s7, s8
	s_waitcnt lgkmcnt(0)
	v_mfma_f32_16x16x32_bf16 v[62:65], v[188:191], v[184:187], v[62:65]
	v_mfma_f32_16x16x32_bf16 v[38:41], v[168:171], v[208:211], v[38:41]
	v_mfma_f32_16x16x32_bf16 v[34:37], v[188:191], v[208:211], v[34:37]
	v_mfma_f32_16x16x32_bf16 v[18:21], v[168:171], v[212:215], v[18:21]
	v_mfma_f32_16x16x32_bf16 v[14:17], v[188:191], v[212:215], v[14:17]
	v_mfma_f32_16x16x32_bf16 v[2:5], v[168:171], v[216:219], v[2:5]
	v_mfma_f32_16x16x32_bf16 v[86:89], v[188:191], v[216:219], v[86:89]
	s_cbranch_scc0 .LBB0_3424
	s_waitcnt vmcnt(0)
	s_barrier
	v_add_u32_e32 v136, v150, v140
	ds_read_b128 v[160:163], v136
	ds_read_b128 v[164:167], v136 offset:2048
	ds_read_b128 v[168:171], v136 offset:4096
	ds_read_b128 v[172:175], v136 offset:6144
	v_add_u32_e32 v136, v151, v140
	ds_read_b128 v[176:179], v136
	ds_read_b128 v[180:183], v136 offset:2048
	ds_read_b128 v[184:187], v136 offset:4096
	ds_read_b128 v[188:191], v136 offset:6144
	s_waitcnt lgkmcnt(0)
	v_mfma_f32_16x16x32_bf16 v[126:129], v[176:179], v[160:163], v[126:129]
	v_mfma_f32_16x16x32_bf16 v[110:113], v[176:179], v[164:167], v[110:113]
	v_mfma_f32_16x16x32_bf16 v[82:85], v[176:179], v[168:171], v[82:85]
	v_mfma_f32_16x16x32_bf16 v[50:53], v[176:179], v[172:175], v[50:53]
	ds_read_b128 v[176:179], v136 offset:8192
	ds_read_b128 v[192:195], v136 offset:10240
	v_mfma_f32_16x16x32_bf16 v[122:125], v[180:183], v[160:163], v[122:125]
	v_mfma_f32_16x16x32_bf16 v[106:109], v[180:183], v[164:167], v[106:109]
	v_mfma_f32_16x16x32_bf16 v[78:81], v[180:183], v[168:171], v[78:81]
	v_mfma_f32_16x16x32_bf16 v[42:45], v[180:183], v[172:175], v[42:45]
	v_mfma_f32_16x16x32_bf16 v[118:121], v[184:187], v[160:163], v[118:121]
	v_mfma_f32_16x16x32_bf16 v[94:97], v[184:187], v[164:167], v[94:97]
	v_mfma_f32_16x16x32_bf16 v[58:61], v[184:187], v[168:171], v[58:61]
	v_mfma_f32_16x16x32_bf16 v[26:29], v[184:187], v[172:175], v[26:29]
	ds_read_b128 v[180:183], v136 offset:12288
	ds_read_b128 v[184:187], v136 offset:14336
	v_mfma_f32_16x16x32_bf16 v[114:117], v[188:191], v[160:163], v[114:117]
	v_mfma_f32_16x16x32_bf16 v[90:93], v[188:191], v[164:167], v[90:93]
	v_mfma_f32_16x16x32_bf16 v[54:57], v[188:191], v[168:171], v[54:57]
	v_mfma_f32_16x16x32_bf16 v[22:25], v[188:191], v[172:175], v[22:25]
	v_add_u32_e32 v136, v151, v141
	v_add_u32_e32 v208, v150, v141
	s_waitcnt lgkmcnt(0)
	v_mfma_f32_16x16x32_bf16 v[102:105], v[176:179], v[160:163], v[102:105]
	v_mfma_f32_16x16x32_bf16 v[74:77], v[176:179], v[164:167], v[74:77]
	v_mfma_f32_16x16x32_bf16 v[188:191], v[192:195], v[164:167], v[66:69]
	v_mfma_f32_16x16x32_bf16 v[196:199], v[176:179], v[168:171], v[46:49]
	s_nop 2
	ds_read_b128 v[46:49], v136
	ds_read_b128 v[66:69], v136 offset:2048
	v_mfma_f32_16x16x32_bf16 v[10:13], v[176:179], v[172:175], v[10:13]
	ds_read_b128 v[176:179], v208
	ds_read_b128 v[200:203], v208 offset:2048
	ds_read_b128 v[204:207], v208 offset:4096
	ds_read_b128 v[208:211], v208 offset:6144
	v_mfma_f32_16x16x32_bf16 v[98:101], v[192:195], v[160:163], v[98:101]
	v_mfma_f32_16x16x32_bf16 v[30:33], v[192:195], v[168:171], v[30:33]
	v_mfma_f32_16x16x32_bf16 v[6:9], v[192:195], v[172:175], v[6:9]
	v_mfma_f32_16x16x32_bf16 v[192:195], v[180:183], v[164:167], v[38:41]
	v_mfma_f32_16x16x32_bf16 v[164:167], v[184:187], v[164:167], v[34:37]
	v_mfma_f32_16x16x32_bf16 v[18:21], v[180:183], v[168:171], v[18:21]
	v_mfma_f32_16x16x32_bf16 v[168:171], v[184:187], v[168:171], v[14:17]
	s_nop 2
	ds_read_b128 v[14:17], v136 offset:4096
	ds_read_b128 v[34:37], v136 offset:6144
	v_mfma_f32_16x16x32_bf16 v[70:73], v[180:183], v[160:163], v[70:73]
	v_mfma_f32_16x16x32_bf16 v[2:5], v[180:183], v[172:175], v[2:5]
	v_mfma_f32_16x16x32_bf16 v[160:163], v[184:187], v[160:163], v[62:65]
	v_mfma_f32_16x16x32_bf16 v[86:89], v[184:187], v[172:175], v[86:89]
	s_waitcnt lgkmcnt(0)
	v_mfma_f32_16x16x32_bf16 v[172:175], v[46:49], v[208:211], v[50:53]
	s_nop 2
	ds_read_b128 v[50:53], v136 offset:8192
	ds_read_b128 v[180:183], v136 offset:10240
	v_mfma_f32_16x16x32_bf16 v[126:129], v[46:49], v[176:179], v[126:129]
	v_mfma_f32_16x16x32_bf16 v[122:125], v[66:69], v[176:179], v[122:125]
	v_mfma_f32_16x16x32_bf16 v[110:113], v[46:49], v[200:203], v[110:113]
	v_mfma_f32_16x16x32_bf16 v[106:109], v[66:69], v[200:203], v[106:109]
	v_mfma_f32_16x16x32_bf16 v[82:85], v[46:49], v[204:207], v[82:85]
	v_mfma_f32_16x16x32_bf16 v[78:81], v[66:69], v[204:207], v[78:81]
	v_mfma_f32_16x16x32_bf16 v[184:187], v[66:69], v[208:211], v[42:45]
	ds_read_b128 v[224:227], v136 offset:12288
	ds_read_b128 v[228:231], v136 offset:14336
	v_mfma_f32_16x16x32_bf16 v[118:121], v[14:17], v[176:179], v[118:121]
	v_mfma_f32_16x16x32_bf16 v[114:117], v[34:37], v[176:179], v[114:117]
	v_mfma_f32_16x16x32_bf16 v[94:97], v[14:17], v[200:203], v[94:97]
	v_mfma_f32_16x16x32_bf16 v[90:93], v[34:37], v[200:203], v[90:93]
	v_mfma_f32_16x16x32_bf16 v[212:215], v[14:17], v[204:207], v[58:61]
	v_mfma_f32_16x16x32_bf16 v[216:219], v[34:37], v[204:207], v[54:57]
	v_mfma_f32_16x16x32_bf16 v[220:223], v[14:17], v[208:211], v[26:29]
	v_mfma_f32_16x16x32_bf16 v[66:69], v[34:37], v[208:211], v[22:25]
	s_waitcnt lgkmcnt(0)
	v_mfma_f32_16x16x32_bf16 v[38:41], v[180:183], v[204:207], v[30:33]
	v_mfma_f32_16x16x32_bf16 v[62:65], v[50:53], v[176:179], v[102:105]
	v_mfma_f32_16x16x32_bf16 v[46:49], v[180:183], v[176:179], v[98:101]
	v_mfma_f32_16x16x32_bf16 v[58:61], v[50:53], v[200:203], v[74:77]
	v_mfma_f32_16x16x32_bf16 v[42:45], v[180:183], v[200:203], v[188:191]
	v_mfma_f32_16x16x32_bf16 v[54:57], v[50:53], v[204:207], v[196:199]
	v_mfma_f32_16x16x32_bf16 v[50:53], v[50:53], v[208:211], v[10:13]
	v_mfma_f32_16x16x32_bf16 v[34:37], v[180:183], v[208:211], v[6:9]
	s_nop 2
	v_mov_b32_e32 v8, v1
	s_waitcnt vmcnt(0)
	s_barrier
; __device__ __forceinline__ unsigned pack2(float a, float b) { unsigned r; asm("v_cvt_pk_bf16_f32 %0, %1, %2" : "=v"(r) : "v"(a), "v"(b)); return r; }
; template <bool SWAP, class Epi, bool THIN = false> ...
;     ...
;       bf16_t* Zw = (bf16_t*)smem + ((wr_e >> 1) * 2 + wc_e) * (128 * 132);
;       const int nt2w = nt * 2 + wc_e;
; #pragma unroll
;       for (int n = 0; n < 8; ++n) {
;         const int cl = n * 16 + fq_e * 4;
;         f32x4 b4 = {0.f, 0.f, 0.f, 0.f};
;         if (epi.pre_bias) b4 = *(const f32x4*)(epi.pre_bias + epi.norig(nt2w, cl));
; #pragma unroll
;         for (int m = 0; m < 4; ++m) {
;           const int rl = rw + m * 16 + fr_e;
;           const int pos = rig0 + rl;
;           const bool ok = pos >= 0 && pos < grows;
;           f32x4 vv = acc[m][n] + b4;
;           if (!ok) vv = (f32x4){0.f, 0.f, 0.f, 0.f};
;           uint2 u; u.x = pack2(vv[0], vv[1]); u.y = pack2(vv[2], vv[3]);
;           *(uint2*)(Zw + rl * 132 + cl) = u;
;         }
	v_mfma_f32_16x16x32_bf16 v[30:33], v[224:227], v[176:179], v[70:73]
	v_ashrrev_i32_e32 v98, 8, v8
	v_add_u32_e32 v6, s4, v98
	v_mul_hi_i32 v7, v6, s26
	v_lshrrev_b32_e32 v9, 31, v7
	v_ashrrev_i32_e32 v7, 3, v7
	v_add_u32_e32 v70, v7, v9
	v_and_b32_e32 v71, 15, v8
	v_mad_u64_u32 v[6:7], s[4:5], v70, s27, v[6:7]
	v_lshrrev_b32_e32 v74, 1, v8
	v_bfe_u32 v73, v8, 6, 1
	v_mul_lo_u32 v72, v6, s28
	v_and_or_b32 v71, v74, 64, v71
	v_add_u32_e32 v99, v72, v71
	v_lshl_or_b32 v73, v98, 1, v73
	v_mul_lo_u32 v73, v73, s29
	v_add_u32_e32 v100, -1, v99
	v_and_or_b32 v73, v74, 24, v73
	v_pk_add_f32 v[74:75], v[128:129], 0 op_sel_hi:[1,0]
	v_pk_add_f32 v[76:77], v[126:127], 0 op_sel_hi:[1,0]
	v_cmp_gt_u32_e32 vcc, s30, v100
	v_mfma_f32_16x16x32_bf16 v[22:25], v[224:227], v[204:207], v[18:21]
	v_mad_u32_u24 v71, v71, s31, v73
	v_add_u32_e32 v73, 15, v99
	v_cmp_gt_u32_e64 s[4:5], s30, v73
	v_mfma_f32_16x16x32_bf16 v[18:21], v[224:227], v[208:211], v[2:5]
	s_lshl_b32 s24, s6, 7
	v_cndmask_b32_e32 v75, 0, v75, vcc
	v_pk_add_f32 v[84:85], v[84:85], 0 op_sel_hi:[1,0]
	v_mfma_f32_16x16x32_bf16 v[2:5], v[228:231], v[208:211], v[86:89]
	v_add_f32_e64 v82, v82, 0
	v_add_f32_e64 v83, v83, 0
	v_pk_add_f32 v[66:67], v[66:67], 0 op_sel_hi:[1,0]
	v_pk_add_f32 v[62:63], v[62:63], 0 op_sel_hi:[1,0]
	v_cndmask_b32_e32 v86, 0, v74, vcc
	v_cndmask_b32_e32 v74, 0, v76, vcc
	v_cndmask_b32_e32 v76, 0, v77, vcc
	v_cvt_pk_bf16_f32 v74, v74, v76
	v_pk_add_f32 v[76:77], v[112:113], 0 op_sel_hi:[1,0]
	v_cvt_pk_bf16_f32 v75, v86, v75
	v_pk_add_f32 v[86:87], v[110:111], 0 op_sel_hi:[1,0]
	v_cndmask_b32_e64 v73, 0, v76, s[4:5]
	v_cndmask_b32_e64 v77, 0, v77, s[4:5]
	v_cvt_pk_bf16_f32 v77, v73, v77
	v_add_u32_e32 v73, 31, v99
	v_cmp_gt_u32_e64 s[6:7], s30, v73
	v_cndmask_b32_e64 v76, 0, v86, s[4:5]
	v_cndmask_b32_e64 v86, 0, v87, s[4:5]
	v_cndmask_b32_e64 v73, 0, v84, s[6:7]
	v_cndmask_b32_e64 v82, 0, v82, s[6:7]
	v_cndmask_b32_e64 v83, 0, v83, s[6:7]
	v_cndmask_b32_e64 v84, 0, v85, s[6:7]
	v_cvt_pk_bf16_f32 v82, v82, v83
	v_cvt_pk_bf16_f32 v83, v73, v84
	v_add_u32_e32 v73, 47, v99
	v_cvt_pk_bf16_f32 v76, v76, v86
	v_pk_add_f32 v[84:85], v[174:175], 0 op_sel_hi:[1,0]
	v_pk_add_f32 v[86:87], v[172:173], 0 op_sel_hi:[1,0]
	v_cmp_gt_u32_e64 s[8:9], s30, v73
	v_pk_add_f32 v[88:89], v[122:123], 0 op_sel_hi:[1,0]
	v_mfma_f32_16x16x32_bf16 v[26:29], v[224:227], v[200:203], v[192:195]
	v_cndmask_b32_e64 v73, 0, v84, s[8:9]
	v_cndmask_b32_e64 v84, 0, v86, s[8:9]
	v_cndmask_b32_e64 v86, 0, v87, s[8:9]
	v_cndmask_b32_e64 v85, 0, v85, s[8:9]
	v_cvt_pk_bf16_f32 v84, v84, v86
	v_pk_add_f32 v[86:87], v[124:125], 0 op_sel_hi:[1,0]
	v_cvt_pk_bf16_f32 v85, v73, v85
	v_mfma_f32_16x16x32_bf16 v[14:17], v[228:231], v[176:179], v[160:163]
	v_cndmask_b32_e32 v73, 0, v86, vcc
	v_cndmask_b32_e32 v87, 0, v87, vcc
	v_cndmask_b32_e32 v86, 0, v88, vcc
	v_cndmask_b32_e32 v88, 0, v89, vcc
	v_cvt_pk_bf16_f32 v86, v86, v88
	v_cvt_pk_bf16_f32 v87, v73, v87
	ds_write2_b64 v71, v[74:75], v[86:87] offset1:4
	v_pk_add_f32 v[74:75], v[108:109], 0 op_sel_hi:[1,0]
	v_pk_add_f32 v[86:87], v[106:107], 0 op_sel_hi:[1,0]
	v_cndmask_b32_e64 v73, 0, v74, s[4:5]
	v_cndmask_b32_e64 v75, 0, v75, s[4:5]
	v_cndmask_b32_e64 v74, 0, v86, s[4:5]
	v_cndmask_b32_e64 v86, 0, v87, s[4:5]
	v_cvt_pk_bf16_f32 v74, v74, v86
	v_cvt_pk_bf16_f32 v75, v73, v75
	v_add_u32_e32 v73, 0x1000, v71
	ds_write2_b64 v73, v[76:77], v[74:75] offset0:16 offset1:20
	v_pk_add_f32 v[74:75], v[80:81], 0 op_sel_hi:[1,0]
	v_pk_add_f32 v[76:77], v[78:79], 0 op_sel_hi:[1,0]
	v_cndmask_b32_e64 v78, 0, v74, s[6:7]
	v_cndmask_b32_e64 v75, 0, v75, s[6:7]
	v_cndmask_b32_e64 v74, 0, v76, s[6:7]
	v_cndmask_b32_e64 v76, 0, v77, s[6:7]
	v_cvt_pk_bf16_f32 v74, v74, v76
	v_cvt_pk_bf16_f32 v75, v78, v75
	v_add_u32_e32 v86, 0x2000, v71
	ds_write2_b64 v86, v[82:83], v[74:75] offset0:32 offset1:36
	v_pk_add_f32 v[74:75], v[186:187], 0 op_sel_hi:[1,0]
	v_pk_add_f32 v[76:77], v[184:185], 0 op_sel_hi:[1,0]
	v_cndmask_b32_e64 v78, 0, v74, s[8:9]
	v_cndmask_b32_e64 v75, 0, v75, s[8:9]
	v_cndmask_b32_e64 v74, 0, v76, s[8:9]
	v_cndmask_b32_e64 v76, 0, v77, s[8:9]
	v_cvt_pk_bf16_f32 v74, v74, v76
	v_cvt_pk_bf16_f32 v75, v78, v75
	v_add_u32_e32 v87, 0x3000, v71
	ds_write2_b64 v87, v[84:85], v[74:75] offset0:48 offset1:52
	v_pk_add_f32 v[74:75], v[120:121], 0 op_sel_hi:[1,0]
	v_pk_add_f32 v[76:77], v[118:119], 0 op_sel_hi:[1,0]
	v_cndmask_b32_e32 v78, 0, v74, vcc
	v_cndmask_b32_e32 v75, 0, v75, vcc
	v_cndmask_b32_e32 v74, 0, v76, vcc
	v_cndmask_b32_e32 v76, 0, v77, vcc
	v_cvt_pk_bf16_f32 v74, v74, v76
	v_cvt_pk_bf16_f32 v75, v78, v75
	v_pk_add_f32 v[76:77], v[96:97], 0 op_sel_hi:[1,0]
	v_pk_add_f32 v[78:79], v[94:95], 0 op_sel_hi:[1,0]
	v_cndmask_b32_e64 v80, 0, v76, s[4:5]
	v_cndmask_b32_e64 v77, 0, v77, s[4:5]
	v_cndmask_b32_e64 v76, 0, v78, s[4:5]
	v_cndmask_b32_e64 v78, 0, v79, s[4:5]
	v_cvt_pk_bf16_f32 v76, v76, v78
	v_cvt_pk_bf16_f32 v77, v80, v77
	v_pk_add_f32 v[78:79], v[214:215], 0 op_sel_hi:[1,0]
	v_pk_add_f32 v[80:81], v[212:213], 0 op_sel_hi:[1,0]
	v_cndmask_b32_e64 v82, 0, v78, s[6:7]
	v_cndmask_b32_e64 v79, 0, v79, s[6:7]
	v_cndmask_b32_e64 v78, 0, v80, s[6:7]
	v_cndmask_b32_e64 v80, 0, v81, s[6:7]
	v_cvt_pk_bf16_f32 v78, v78, v80
	v_cvt_pk_bf16_f32 v79, v82, v79
	v_pk_add_f32 v[80:81], v[222:223], 0 op_sel_hi:[1,0]
	v_pk_add_f32 v[82:83], v[220:221], 0 op_sel_hi:[1,0]
	v_cndmask_b32_e64 v84, 0, v80, s[8:9]
	v_cndmask_b32_e64 v81, 0, v81, s[8:9]
	v_cndmask_b32_e64 v80, 0, v82, s[8:9]
	v_cndmask_b32_e64 v82, 0, v83, s[8:9]
	v_cvt_pk_bf16_f32 v80, v80, v82
	v_cvt_pk_bf16_f32 v81, v84, v81
	v_pk_add_f32 v[82:83], v[116:117], 0 op_sel_hi:[1,0]
	v_pk_add_f32 v[84:85], v[114:115], 0 op_sel_hi:[1,0]
; __device__ __forceinline__ unsigned pack2(float a, float b) { unsigned r; asm("v_cvt_pk_bf16_f32 %0, %1, %2" : "=v"(r) : "v"(a), "v"(b)); return r; }
; template <bool SWAP, class Epi, bool THIN = false> ...
;     ...
;         f32x4 b4 = {0.f, 0.f, 0.f, 0.f};
;         if (epi.pre_bias) b4 = *(const f32x4*)(epi.pre_bias + epi.norig(nt2w, cl));
; #pragma unroll
;         for (int m = 0; m < 4; ++m) {
;           const int rl = rw + m * 16 + fr_e;
;           const int pos = rig0 + rl;
;           const bool ok = pos >= 0 && pos < grows;
;           f32x4 vv = acc[m][n] + b4;
;           if (!ok) vv = (f32x4){0.f, 0.f, 0.f, 0.f};
;           uint2 u; u.x = pack2(vv[0], vv[1]); u.y = pack2(vv[2], vv[3]);
;           *(uint2*)(Zw + rl * 132 + cl) = u;
;         }
	v_cndmask_b32_e32 v88, 0, v82, vcc
	v_cndmask_b32_e32 v83, 0, v83, vcc
	v_cndmask_b32_e32 v82, 0, v84, vcc
	v_mfma_f32_16x16x32_bf16 v[10:13], v[228:231], v[200:203], v[164:167]
	v_cndmask_b32_e32 v84, 0, v85, vcc
	v_cvt_pk_bf16_f32 v82, v82, v84
	v_cvt_pk_bf16_f32 v83, v88, v83
	v_mfma_f32_16x16x32_bf16 v[6:9], v[228:231], v[204:207], v[168:171]
	ds_write2_b64 v71, v[74:75], v[82:83] offset0:8 offset1:12
	v_pk_add_f32 v[74:75], v[92:93], 0 op_sel_hi:[1,0]
	v_pk_add_f32 v[82:83], v[90:91], 0 op_sel_hi:[1,0]
	v_cndmask_b32_e64 v84, 0, v74, s[4:5]
	v_cndmask_b32_e64 v75, 0, v75, s[4:5]
	v_cndmask_b32_e64 v74, 0, v82, s[4:5]
	v_cndmask_b32_e64 v82, 0, v83, s[4:5]
	v_cvt_pk_bf16_f32 v74, v74, v82
	v_cvt_pk_bf16_f32 v75, v84, v75
	v_pk_add_f32 v[28:29], v[28:29], 0 op_sel_hi:[1,0]
	v_pk_add_f32 v[26:27], v[26:27], 0 op_sel_hi:[1,0]
	ds_write2_b64 v73, v[76:77], v[74:75] offset0:24 offset1:28
	v_pk_add_f32 v[74:75], v[218:219], 0 op_sel_hi:[1,0]
	v_pk_add_f32 v[76:77], v[216:217], 0 op_sel_hi:[1,0]
	v_pk_add_f32 v[58:59], v[58:59], 0 op_sel_hi:[1,0]
	v_pk_add_f32 v[54:55], v[54:55], 0 op_sel_hi:[1,0]
	v_pk_add_f32 v[50:51], v[50:51], 0 op_sel_hi:[1,0]
	v_pk_add_f32 v[46:47], v[46:47], 0 op_sel_hi:[1,0]
	v_pk_add_f32 v[42:43], v[42:43], 0 op_sel_hi:[1,0]
	v_pk_add_f32 v[38:39], v[38:39], 0 op_sel_hi:[1,0]
	v_pk_add_f32 v[34:35], v[34:35], 0 op_sel_hi:[1,0]
	v_pk_add_f32 v[30:31], v[30:31], 0 op_sel_hi:[1,0]
	v_cndmask_b32_e64 v28, 0, v28, s[4:5]
	v_cndmask_b32_e64 v26, 0, v26, s[4:5]
	v_cndmask_b32_e64 v27, 0, v27, s[4:5]
	v_pk_add_f32 v[22:23], v[22:23], 0 op_sel_hi:[1,0]
	v_pk_add_f32 v[18:19], v[18:19], 0 op_sel_hi:[1,0]
	v_pk_add_f32 v[14:15], v[14:15], 0 op_sel_hi:[1,0]
	v_pk_add_f32 v[10:11], v[10:11], 0 op_sel_hi:[1,0]
	v_pk_add_f32 v[6:7], v[6:7], 0 op_sel_hi:[1,0]
	v_pk_add_f32 v[2:3], v[2:3], 0 op_sel_hi:[1,0]
	v_cndmask_b32_e64 v82, 0, v74, s[6:7]
	v_cndmask_b32_e64 v75, 0, v75, s[6:7]
	v_cndmask_b32_e64 v74, 0, v76, s[6:7]
	v_pk_add_f32 v[68:69], v[68:69], 0 op_sel_hi:[1,0]
	v_cndmask_b32_e64 v66, 0, v66, s[8:9]
	v_cndmask_b32_e64 v67, 0, v67, s[8:9]
	v_pk_add_f32 v[64:65], v[64:65], 0 op_sel_hi:[1,0]
	v_cndmask_b32_e32 v62, 0, v62, vcc
	v_cndmask_b32_e32 v63, 0, v63, vcc
	v_pk_add_f32 v[60:61], v[60:61], 0 op_sel_hi:[1,0]
	v_cndmask_b32_e64 v58, 0, v58, s[4:5]
	v_cndmask_b32_e64 v59, 0, v59, s[4:5]
	v_pk_add_f32 v[56:57], v[56:57], 0 op_sel_hi:[1,0]
	v_cndmask_b32_e64 v54, 0, v54, s[6:7]
	v_cndmask_b32_e64 v55, 0, v55, s[6:7]
	v_pk_add_f32 v[52:53], v[52:53], 0 op_sel_hi:[1,0]
	v_cndmask_b32_e64 v50, 0, v50, s[8:9]
	v_cndmask_b32_e64 v51, 0, v51, s[8:9]
	v_pk_add_f32 v[48:49], v[48:49], 0 op_sel_hi:[1,0]
	v_cndmask_b32_e32 v46, 0, v46, vcc
	v_cndmask_b32_e32 v47, 0, v47, vcc
	v_pk_add_f32 v[44:45], v[44:45], 0 op_sel_hi:[1,0]
	v_cndmask_b32_e64 v42, 0, v42, s[4:5]
	v_cndmask_b32_e64 v43, 0, v43, s[4:5]
	v_pk_add_f32 v[40:41], v[40:41], 0 op_sel_hi:[1,0]
	v_cndmask_b32_e64 v38, 0, v38, s[6:7]
	v_cndmask_b32_e64 v39, 0, v39, s[6:7]
	v_pk_add_f32 v[36:37], v[36:37], 0 op_sel_hi:[1,0]
	v_cndmask_b32_e64 v34, 0, v34, s[8:9]
	v_cndmask_b32_e64 v35, 0, v35, s[8:9]
	v_pk_add_f32 v[32:33], v[32:33], 0 op_sel_hi:[1,0]
	v_cndmask_b32_e32 v30, 0, v30, vcc
	v_cndmask_b32_e32 v31, 0, v31, vcc
	v_cndmask_b32_e64 v29, 0, v29, s[4:5]
	v_cvt_pk_bf16_f32 v26, v26, v27
	v_cvt_pk_bf16_f32 v27, v28, v29
	v_pk_add_f32 v[24:25], v[24:25], 0 op_sel_hi:[1,0]
	v_cndmask_b32_e64 v22, 0, v22, s[6:7]
	v_cndmask_b32_e64 v23, 0, v23, s[6:7]
	v_pk_add_f32 v[20:21], v[20:21], 0 op_sel_hi:[1,0]
	v_cndmask_b32_e64 v18, 0, v18, s[8:9]
	v_cndmask_b32_e64 v19, 0, v19, s[8:9]
	v_pk_add_f32 v[16:17], v[16:17], 0 op_sel_hi:[1,0]
	v_cndmask_b32_e32 v14, 0, v14, vcc
	v_cndmask_b32_e32 v15, 0, v15, vcc
	v_pk_add_f32 v[12:13], v[12:13], 0 op_sel_hi:[1,0]
	v_cndmask_b32_e64 v10, 0, v10, s[4:5]
	v_cndmask_b32_e64 v11, 0, v11, s[4:5]
	v_pk_add_f32 v[8:9], v[8:9], 0 op_sel_hi:[1,0]
	v_cndmask_b32_e64 v6, 0, v6, s[6:7]
	v_cndmask_b32_e64 v7, 0, v7, s[6:7]
	v_pk_add_f32 v[4:5], v[4:5], 0 op_sel_hi:[1,0]
	v_cndmask_b32_e64 v2, 0, v2, s[8:9]
	v_cndmask_b32_e64 v3, 0, v3, s[8:9]
	v_mov_b32_e32 v28, v142
	v_cndmask_b32_e64 v76, 0, v77, s[6:7]
	v_cvt_pk_bf16_f32 v74, v74, v76
	v_cvt_pk_bf16_f32 v75, v82, v75
	ds_write2_b64 v86, v[78:79], v[74:75] offset0:40 offset1:44
	v_cndmask_b32_e64 v68, 0, v68, s[8:9]
	v_cndmask_b32_e64 v69, 0, v69, s[8:9]
	v_cvt_pk_bf16_f32 v66, v66, v67
	v_cvt_pk_bf16_f32 v67, v68, v69
	ds_write2_b64 v87, v[80:81], v[66:67] offset0:56 offset1:60
	v_cndmask_b32_e32 v64, 0, v64, vcc
	v_cndmask_b32_e32 v65, 0, v65, vcc
	v_cvt_pk_bf16_f32 v62, v62, v63
	v_cvt_pk_bf16_f32 v63, v64, v65
	v_cndmask_b32_e64 v60, 0, v60, s[4:5]
	v_cndmask_b32_e64 v61, 0, v61, s[4:5]
	v_cvt_pk_bf16_f32 v58, v58, v59
	v_cvt_pk_bf16_f32 v59, v60, v61
	v_cndmask_b32_e64 v56, 0, v56, s[6:7]
	v_cndmask_b32_e64 v57, 0, v57, s[6:7]
	v_cvt_pk_bf16_f32 v54, v54, v55
	v_cvt_pk_bf16_f32 v55, v56, v57
	v_cndmask_b32_e64 v52, 0, v52, s[8:9]
	v_cndmask_b32_e64 v53, 0, v53, s[8:9]
	v_cvt_pk_bf16_f32 v50, v50, v51
	v_cvt_pk_bf16_f32 v51, v52, v53
	v_cndmask_b32_e32 v48, 0, v48, vcc
	v_cndmask_b32_e32 v49, 0, v49, vcc
	v_cvt_pk_bf16_f32 v46, v46, v47
	v_cvt_pk_bf16_f32 v47, v48, v49
	ds_write2_b64 v71, v[62:63], v[46:47] offset0:16 offset1:20
	v_cndmask_b32_e64 v44, 0, v44, s[4:5]
	v_cndmask_b32_e64 v45, 0, v45, s[4:5]
	v_cvt_pk_bf16_f32 v42, v42, v43
;   template <class F>
;   __device__ __forceinline__ void finish(const bf16_t* Z, int g, int rig0, int nt, F&& pre) const {
;     ...
;         const int f2 = (tid & 31) * 2, q8 = tid >> 5;
;         const int q0 = 1 + 16 * q8, q1 = (q0 + 16 < 127) ? q0 + 16 : 127;
;         const int na = norig(nt, f2), ng = norig(nt, 64 + f2);
;         const f32x2 a0 = *(const f32x2*)(cw + na), a1 = *(const f32x2*)(cw + NC + na), a2 = *(const f32x2*)(cw + 2 * NC + na), ab = *(const f32x2*)(cb + na);
;         const f32x2 g0 = *(const f32x2*)(cw + ng), g1 = *(const f32x2*)(cw + NC + ng), g2 = *(const f32x2*)(cw + 2 * NC + ng), gb = *(const f32x2*)(cb + ng);
;         pre();
;         f32x2 am = ldz(Z, q0 - 1, f2), ac = ldz(Z, q0, f2);
;         f32x2 gm = ldz(Z, q0 - 1, 64 + f2), gc = ldz(Z, q0, 64 + f2);
; template <bool SWAP, class Epi, bool THIN = false> ...
;     ...
;           *(uint2*)(Zw + rl * 132 + cl) = u;
;         }
;       }
;       __syncthreads();
;       {
;         auto no_pre = []() {};
;         const bf16_t* Zr = (const bf16_t*)smem + ((wr_e >> 1) * 2) * (128 * 132);
;         epi.finish(Zr, g, rig0, nt * 2, no_pre);
;         epi.finish(Zr + 128 * 132, g, rig0, nt * 2 + 1, no_pre);
	v_cvt_pk_bf16_f32 v43, v44, v45
	ds_write2_b64 v73, v[58:59], v[42:43] offset0:32 offset1:36
	v_cndmask_b32_e64 v40, 0, v40, s[6:7]
	v_cndmask_b32_e64 v41, 0, v41, s[6:7]
	v_cvt_pk_bf16_f32 v38, v38, v39
	v_cvt_pk_bf16_f32 v39, v40, v41
	ds_write2_b64 v86, v[54:55], v[38:39] offset0:48 offset1:52
	v_cndmask_b32_e64 v36, 0, v36, s[8:9]
	v_cndmask_b32_e64 v37, 0, v37, s[8:9]
	v_cvt_pk_bf16_f32 v34, v34, v35
	v_cvt_pk_bf16_f32 v35, v36, v37
	ds_write2_b64 v87, v[50:51], v[34:35] offset0:64 offset1:68
	v_cndmask_b32_e32 v32, 0, v32, vcc
	v_cndmask_b32_e32 v33, 0, v33, vcc
	v_cvt_pk_bf16_f32 v30, v30, v31
	v_cvt_pk_bf16_f32 v31, v32, v33
	v_cndmask_b32_e64 v24, 0, v24, s[6:7]
	v_cndmask_b32_e64 v25, 0, v25, s[6:7]
	v_cvt_pk_bf16_f32 v22, v22, v23
	v_cvt_pk_bf16_f32 v23, v24, v25
	v_cndmask_b32_e64 v20, 0, v20, s[8:9]
	v_cndmask_b32_e64 v21, 0, v21, s[8:9]
	v_cvt_pk_bf16_f32 v18, v18, v19
	v_cvt_pk_bf16_f32 v19, v20, v21
	v_cndmask_b32_e32 v16, 0, v16, vcc
	v_cndmask_b32_e32 v17, 0, v17, vcc
	v_cvt_pk_bf16_f32 v14, v14, v15
	v_cvt_pk_bf16_f32 v15, v16, v17
	ds_write2_b64 v71, v[30:31], v[14:15] offset0:24 offset1:28
	v_cndmask_b32_e64 v12, 0, v12, s[4:5]
	v_cndmask_b32_e64 v13, 0, v13, s[4:5]
	v_cvt_pk_bf16_f32 v10, v10, v11
	v_cvt_pk_bf16_f32 v11, v12, v13
	ds_write2_b64 v73, v[26:27], v[10:11] offset0:40 offset1:44
	v_cndmask_b32_e64 v8, 0, v8, s[6:7]
	v_cndmask_b32_e64 v9, 0, v9, s[6:7]
	v_cvt_pk_bf16_f32 v6, v6, v7
	v_cvt_pk_bf16_f32 v7, v8, v9
	ds_write2_b64 v86, v[22:23], v[6:7] offset0:56 offset1:60
	v_cndmask_b32_e64 v4, 0, v4, s[8:9]
	v_cndmask_b32_e64 v5, 0, v5, s[8:9]
	v_cvt_pk_bf16_f32 v2, v2, v3
	v_cvt_pk_bf16_f32 v3, v4, v5
	ds_write2_b64 v87, v[18:19], v[2:3] offset0:72 offset1:76
	s_waitcnt lgkmcnt(0)
	s_barrier
	v_mul_i32_i24_e32 v2, 0x10800, v98
	v_ashrrev_i32_e32 v29, 1, v28
	v_and_b32_e32 v38, -16, v29
	v_min_i32_e32 v3, 0x6e, v38
	v_or_b32_e32 v20, 1, v38
	v_add_u32_e32 v3, 17, v3
	v_cmp_lt_i32_e32 vcc, v20, v3
	v_ashrrev_i32_e32 v71, 31, v70
	s_and_saveexec_b64 s[4:5], vcc
	s_cbranch_execz .LBB0_3432
	v_lshlrev_b32_e32 v4, 1, v28
	v_and_b32_e32 v21, 62, v4
	v_or_b32_e32 v4, s24, v21
	s_add_i32 s6, s24, 0xb00
	v_ashrrev_i32_e32 v5, 31, v4
	v_or_b32_e32 v12, s6, v21
	v_lshlrev_b64 v[10:11], 2, v[4:5]
	v_lshl_add_u64 v[14:15], s[16:17], 0, v[10:11]
	v_lshl_add_u64 v[18:19], s[22:23], 0, v[10:11]
	v_ashrrev_i32_e32 v13, 31, v12
	v_lshl_add_u64 v[16:17], s[20:21], 0, v[10:11]
	global_load_dwordx2 v[4:5], v[14:15], off
	global_load_dwordx2 v[6:7], v[16:17], off
	global_load_dwordx2 v[8:9], v[18:19], off
	v_lshlrev_b64 v[18:19], 2, v[12:13]
	v_lshl_add_u64 v[10:11], s[18:19], 0, v[10:11]
	v_lshl_add_u64 v[22:23], s[16:17], 0, v[18:19]
	global_load_dwordx2 v[10:11], v[10:11], off
	v_lshl_add_u64 v[24:25], s[20:21], 0, v[18:19]
	v_lshl_add_u64 v[26:27], s[22:23], 0, v[18:19]
	global_load_dwordx2 v[12:13], v[22:23], off
	global_load_dwordx2 v[14:15], v[24:25], off
	global_load_dwordx2 v[16:17], v[26:27], off
	v_lshl_add_u64 v[18:19], s[18:19], 0, v[18:19]
	global_load_dwordx2 v[18:19], v[18:19], off
	v_mov_b32_e32 v117, 0
	v_lshlrev_b32_e32 v88, 1, v142
	v_and_b32_e32 v105, 62, v88
	v_add3_u32 v88, v105, s24, 64
	s_add_i32 s38, s24, 0xb40
	v_ashrrev_i32_e32 v89, 31, v88
	v_or_b32_e32 v96, s38, v105
	v_lshlrev_b64 v[94:95], 2, v[88:89]
	v_lshl_add_u64 v[98:99], s[16:17], 0, v[94:95]
	v_lshl_add_u64 v[102:103], s[22:23], 0, v[94:95]
	v_ashrrev_i32_e32 v97, 31, v96
	v_lshl_add_u64 v[100:101], s[20:21], 0, v[94:95]
	global_load_dwordx2 v[88:89], v[98:99], off
	global_load_dwordx2 v[90:91], v[100:101], off
	global_load_dwordx2 v[92:93], v[102:103], off
	v_lshlrev_b64 v[102:103], 2, v[96:97]
	v_lshl_add_u64 v[94:95], s[18:19], 0, v[94:95]
	v_lshl_add_u64 v[106:107], s[16:17], 0, v[102:103]
	global_load_dwordx2 v[94:95], v[94:95], off
	v_lshl_add_u64 v[108:109], s[20:21], 0, v[102:103]
	v_lshl_add_u64 v[110:111], s[22:23], 0, v[102:103]
	global_load_dwordx2 v[96:97], v[106:107], off
	global_load_dwordx2 v[98:99], v[108:109], off
	global_load_dwordx2 v[100:101], v[110:111], off
	v_lshl_add_u64 v[102:103], s[18:19], 0, v[102:103]
	global_load_dwordx2 v[102:103], v[102:103], off
	v_lshlrev_b32_e32 v136, 1, v21
	v_mul_lo_u32 v22, v38, s31
	v_mul_lo_u32 v20, v20, s31
	v_add3_u32 v22, v2, v22, v136
	v_add3_u32 v20, v2, v20, v136
	ds_read2_b32 v[22:23], v22 offset1:32
	ds_read2_b32 v[20:21], v20 offset1:32
	s_ashr_i32 s25, s24, 31
	s_lshl_b64 s[6:7], s[24:25], 1
	s_add_u32 s6, s12, s6
	s_addc_u32 s7, s13, s7
	v_lshrrev_b32_e32 v29, 4, v29
	v_and_b32_e32 v28, 31, v28
	s_waitcnt lgkmcnt(1)
	v_lshlrev_b32_e32 v32, 16, v23
	v_and_b32_e32 v33, 0xffff0000, v23
	v_lshlrev_b32_e32 v34, 16, v22
	v_and_b32_e32 v35, 0xffff0000, v22
	v_lshl_add_u64 v[22:23], s[6:7], 0, v[136:137]
	v_mad_u64_u32 v[30:31], s[6:7], v29, s33, v[2:3]
	v_lshlrev_b32_e32 v28, 2, v28
	s_waitcnt lgkmcnt(0)
	v_lshlrev_b32_e32 v24, 16, v21
	v_and_b32_e32 v25, 0xffff0000, v21
	v_lshlrev_b32_e32 v26, 16, v20
	v_and_b32_e32 v27, 0xffff0000, v20
	v_lshlrev_b64 v[20:21], 11, v[70:71]
	v_add3_u32 v39, v30, v28, s34
	s_mov_b32 s98, 0x1600
	s_mov_b32 s99, 0
	v_add_u32_e32 v48, v72, v38
	v_ashrrev_i32_e32 v49, 31, v48
	v_lshl_add_u64 v[48:49], v[20:21], 0, v[48:49]
	v_mad_u64_u32 v[50:51], s[38:39], v48, s35, v[22:23]
	v_mad_i32_i24 v51, v49, s35, v51
	s_mov_b64 s[6:7], 0
	s_waitcnt vmcnt(0)
	ds_read2_b32 v[44:45], v39 offset1:32
	s_branch .LBB0_3428

; template <bool SWAP, class Epi, bool THIN = false> ...
;     ...
;     for (int st = 0; st < ns; ++st) {
;       asm volatile("s_waitcnt vmcnt(0)" ::: "memory");
;       __builtin_amdgcn_s_barrier();
;       asm volatile("" ::: "memory");
;       if (st + 1 < ns) {
;         char* nb = smem + ((st + 1) & 1) * 65536;
;         const int ko = (st + 1) * 64;
; #pragma unroll
;         for (int i = 0; i < 4; ++i) { GLDS16(A + (size_t)(ap[i] + ko), nb + tid * 16 + i * 8192); GLDS16(Bt + (size_t)(bp[i] + ko), nb + 32768 + tid * 16 + i * 8192); }
;       }
;       const char* sa = smem + (st & 1) * 65536 + (wr * 64 + fr) * 128;
;       const char* sb = smem + (st & 1) * 65536 + 32768 + (wc * 128 + fr) * 128;
;       if constexpr (THIN) {
;         if (wc == 0) {
; #pragma unroll
;           for (int ks = 0; ks < 2; ++ks) {
;             bf16x8 af[4], bf[2];
; #pragma unroll
;             for (int m = 0; m < 4; ++m) af[m] = *(const bf16x8*)(sa + m * 2048 + (((ks * 4 + fq) ^ swz) << 4));
; #pragma unroll
;             for (int n = 0; n < 2; ++n) bf[n] = *(const bf16x8*)(sb + n * 2048 + (((ks * 4 + fq) ^ swz) << 4));
; #pragma unroll
;             for (int m = 0; m < 4; ++m)
; #pragma unroll
;               for (int n = 0; n < 2; ++n)
;                 acc[m][n] = SWAP ? __builtin_amdgcn_mfma_f32_16x16x32_bf16(bf[n], af[m], acc[m][n], 0, 0, 0)
;                                  : __builtin_amdgcn_mfma_f32_16x16x32_bf16(af[m], bf[n], acc[m][n], 0, 0, 0);
;           }
;         }
;       } else {
;       bf16x8 afA[4], afB[4], bfb[2][2];
; #pragma unroll
;       for (int m = 0; m < 4; ++m) afA[m] = *(const bf16x8*)(sa + m * 2048 + ((fq ^ swz) << 4));
; #pragma unroll
;       for (int n = 0; n < 2; ++n) bfb[0][n] = *(const bf16x8*)(sb + n * 2048 + ((fq ^ swz) << 4));
; #pragma unroll
;       for (int gq = 0; gq < 8; ++gq) {
;         const int ks = gq >> 2, nh = gq & 3;
;         if (gq < 7) {
;           const int ks2 = (gq + 1) >> 2, nh2 = (gq + 1) & 3;
; #pragma unroll
;           for (int n = 0; n < 2; ++n) bfb[(gq + 1) & 1][n] = *(const bf16x8*)(sb + (nh2 * 2 + n) * 2048 + (((ks2 * 4 + fq) ^ swz) << 4));
;         }
;         if (gq == 3) {
; #pragma unroll
;           for (int m = 0; m < 4; ++m) afB[m] = *(const bf16x8*)(sa + m * 2048 + (((4 + fq) ^ swz) << 4));
;         }
;         __builtin_amdgcn_sched_barrier(0);
; #pragma unroll
.LBB0_3516:
	s_add_i32 s9, s7, 0x10000
	s_and_b32 s8, s9, 0x10000
	v_add_u32_e32 v139, s8, v144
	s_nop 0
	v_readfirstlane_b32 s10, v139
	s_and_b32 s7, s7, 0x10000
	v_add_u32_e32 v130, s7, v145
	v_add_u32_e32 v139, v130, v147
	s_waitcnt vmcnt(0)
	s_barrier
	ds_read_b128 v[168:171], v139
	ds_read_b128 v[172:175], v139 offset:2048
	ds_read_b128 v[176:179], v139 offset:4096
	ds_read_b128 v[180:183], v139 offset:6144
	v_or_b32_e32 v139, s7, v146
	v_add_u32_e32 v141, v139, v147
	ds_read_b128 v[184:187], v141 offset:32768
	ds_read_b128 v[188:191], v141 offset:34816
	ds_read_b128 v[192:195], v141 offset:36864
	ds_read_b128 v[196:199], v141 offset:38912
	v_add_u32_e32 v130, v130, v148
	s_waitcnt lgkmcnt(3)
	v_mfma_f32_16x16x32_bf16 v[126:129], v[184:187], v[168:171], v[126:129]
	s_mov_b32 m0, s10
	v_mfma_f32_16x16x32_bf16 v[110:113], v[184:187], v[172:175], v[110:113]
	global_load_lds_dwordx4 v138, s[24:25]
	v_add_u32_e32 v138, 0x80, v138
	v_mfma_f32_16x16x32_bf16 v[82:85], v[184:187], v[176:179], v[82:85]
	v_mfma_f32_16x16x32_bf16 v[50:53], v[184:187], v[180:183], v[50:53]
	ds_read_b128 v[184:187], v141 offset:40960
	ds_read_b128 v[200:203], v141 offset:43008
	s_waitcnt lgkmcnt(4)
	v_mfma_f32_16x16x32_bf16 v[122:125], v[188:191], v[168:171], v[122:125]
	s_add_u32 m0, s10, 0x8000
	v_mfma_f32_16x16x32_bf16 v[106:109], v[188:191], v[172:175], v[106:109]
	global_load_lds_dwordx4 v137, s[20:21]
	v_add_u32_e32 v137, 0x80, v137
	v_mfma_f32_16x16x32_bf16 v[78:81], v[188:191], v[176:179], v[78:81]
	v_mfma_f32_16x16x32_bf16 v[38:41], v[188:191], v[180:183], v[38:41]
	s_waitcnt lgkmcnt(3)
	v_mfma_f32_16x16x32_bf16 v[118:121], v[192:195], v[168:171], v[118:121]
	s_add_u32 m0, s10, 0x2000
	v_mfma_f32_16x16x32_bf16 v[94:97], v[192:195], v[172:175], v[94:97]
	global_load_lds_dwordx4 v136, s[24:25]
	v_add_u32_e32 v136, 0x80, v136
	v_mfma_f32_16x16x32_bf16 v[58:61], v[192:195], v[176:179], v[58:61]
	v_mfma_f32_16x16x32_bf16 v[26:29], v[192:195], v[180:183], v[26:29]
	ds_read_b128 v[188:191], v141 offset:45056
	ds_read_b128 v[192:195], v141 offset:47104
	s_waitcnt lgkmcnt(4)
	v_mfma_f32_16x16x32_bf16 v[114:117], v[196:199], v[168:171], v[114:117]
	s_add_u32 m0, s10, 0xa000
	v_mfma_f32_16x16x32_bf16 v[86:89], v[196:199], v[172:175], v[86:89]
	global_load_lds_dwordx4 v135, s[20:21]
	v_add_u32_e32 v135, 0x80, v135
	v_mfma_f32_16x16x32_bf16 v[54:57], v[196:199], v[176:179], v[54:57]
	v_mfma_f32_16x16x32_bf16 v[22:25], v[196:199], v[180:183], v[22:25]
	v_add_u32_e32 v139, v139, v148
	s_waitcnt lgkmcnt(3)
	v_mfma_f32_16x16x32_bf16 v[102:105], v[184:187], v[168:171], v[102:105]
	ds_read_b128 v[196:199], v139 offset:32768
	ds_read_b128 v[204:207], v139 offset:34816
	s_add_u32 m0, s10, 0x4000
	v_mfma_f32_16x16x32_bf16 v[74:77], v[184:187], v[172:175], v[74:77]
	global_load_lds_dwordx4 v134, s[24:25]
	v_add_u32_e32 v134, 0x80, v134
	v_mfma_f32_16x16x32_bf16 v[46:49], v[184:187], v[176:179], v[46:49]
	v_mfma_f32_16x16x32_bf16 v[10:13], v[184:187], v[180:183], v[10:13]
	ds_read_b128 v[184:187], v130
	ds_read_b128 v[208:211], v130 offset:2048
	ds_read_b128 v[212:215], v130 offset:4096
	ds_read_b128 v[216:219], v130 offset:6144
	s_waitcnt lgkmcnt(8)
	v_mfma_f32_16x16x32_bf16 v[98:101], v[200:203], v[168:171], v[98:101]
	s_add_u32 m0, s10, 0xc000
	v_mfma_f32_16x16x32_bf16 v[66:69], v[200:203], v[172:175], v[66:69]
	global_load_lds_dwordx4 v133, s[20:21]
	v_add_u32_e32 v133, 0x80, v133
	v_mfma_f32_16x16x32_bf16 v[34:37], v[200:203], v[176:179], v[34:37]
	v_mfma_f32_16x16x32_bf16 v[6:9], v[200:203], v[180:183], v[6:9]
	s_waitcnt lgkmcnt(7)
	v_mfma_f32_16x16x32_bf16 v[70:73], v[188:191], v[168:171], v[70:73]
	s_add_u32 m0, s10, 0x6000
	s_waitcnt lgkmcnt(6)
	v_mfma_f32_16x16x32_bf16 v[62:65], v[192:195], v[168:171], v[62:65]
	global_load_lds_dwordx4 v132, s[24:25]
	v_add_u32_e32 v132, 0x80, v132
	v_mfma_f32_16x16x32_bf16 v[42:45], v[188:191], v[172:175], v[42:45]
	v_mfma_f32_16x16x32_bf16 v[30:33], v[192:195], v[172:175], v[30:33]
	ds_read_b128 v[168:171], v139 offset:36864
	ds_read_b128 v[172:175], v139 offset:38912
	v_mfma_f32_16x16x32_bf16 v[18:21], v[188:191], v[176:179], v[18:21]
	s_add_u32 m0, s10, 0xe000
	v_mfma_f32_16x16x32_bf16 v[14:17], v[192:195], v[176:179], v[14:17]
	global_load_lds_dwordx4 v140, s[20:21]
	v_add_u32_e32 v140, 0x80, v140
	v_mfma_f32_16x16x32_bf16 v[2:5], v[188:191], v[180:183], v[2:5]
	v_mfma_f32_16x16x32_bf16 v[90:93], v[192:195], v[180:183], v[90:93]
	ds_read_b128 v[176:179], v139 offset:40960
	ds_read_b128 v[180:183], v139 offset:43008
	s_waitcnt lgkmcnt(7)
	v_mfma_f32_16x16x32_bf16 v[126:129], v[196:199], v[184:187], v[126:129]
	v_mfma_f32_16x16x32_bf16 v[122:125], v[204:207], v[184:187], v[122:125]
	s_waitcnt lgkmcnt(6)
	v_mfma_f32_16x16x32_bf16 v[110:113], v[196:199], v[208:211], v[110:113]
	v_mfma_f32_16x16x32_bf16 v[106:109], v[204:207], v[208:211], v[106:109]
	s_waitcnt lgkmcnt(5)
	v_mfma_f32_16x16x32_bf16 v[82:85], v[196:199], v[212:215], v[82:85]
	v_mfma_f32_16x16x32_bf16 v[78:81], v[204:207], v[212:215], v[78:81]
	s_waitcnt lgkmcnt(4)
	v_mfma_f32_16x16x32_bf16 v[50:53], v[196:199], v[216:219], v[50:53]
	v_mfma_f32_16x16x32_bf16 v[38:41], v[204:207], v[216:219], v[38:41]
	s_waitcnt lgkmcnt(3)
	v_mfma_f32_16x16x32_bf16 v[118:121], v[168:171], v[184:187], v[118:121]
	v_mfma_f32_16x16x32_bf16 v[94:97], v[168:171], v[208:211], v[94:97]
	v_mfma_f32_16x16x32_bf16 v[58:61], v[168:171], v[212:215], v[58:61]
	v_mfma_f32_16x16x32_bf16 v[26:29], v[168:171], v[216:219], v[26:29]
	ds_read_b128 v[168:171], v139 offset:45056
	ds_read_b128 v[188:191], v139 offset:47104
	s_waitcnt lgkmcnt(4)
; template <bool SWAP, class Epi, bool THIN = false> ...
;     ...
;     for (int st = 0; st < ns; ++st) {
;       asm volatile("s_waitcnt vmcnt(0)" ::: "memory");
;       __builtin_amdgcn_s_barrier();
;       asm volatile("" ::: "memory");
;       if (st + 1 < ns) {
;         char* nb = smem + ((st + 1) & 1) * 65536;
;         const int ko = (st + 1) * 64;
; #pragma unroll
;         for (int i = 0; i < 4; ++i) { GLDS16(A + (size_t)(ap[i] + ko), nb + tid * 16 + i * 8192); GLDS16(Bt + (size_t)(bp[i] + ko), nb + 32768 + tid * 16 + i * 8192); }
;       }
;       const char* sa = smem + (st & 1) * 65536 + (wr * 64 + fr) * 128;
;       const char* sb = smem + (st & 1) * 65536 + 32768 + (wc * 128 + fr) * 128;
;       if constexpr (THIN) {
;         if (wc == 0) {
; #pragma unroll
;           for (int ks = 0; ks < 2; ++ks) {
;             bf16x8 af[4], bf[2];
; #pragma unroll
;             for (int m = 0; m < 4; ++m) af[m] = *(const bf16x8*)(sa + m * 2048 + (((ks * 4 + fq) ^ swz) << 4));
; #pragma unroll
;             for (int n = 0; n < 2; ++n) bf[n] = *(const bf16x8*)(sb + n * 2048 + (((ks * 4 + fq) ^ swz) << 4));
; #pragma unroll
;             for (int m = 0; m < 4; ++m)
; #pragma unroll
;               for (int n = 0; n < 2; ++n)
;                 acc[m][n] = SWAP ? __builtin_amdgcn_mfma_f32_16x16x32_bf16(bf[n], af[m], acc[m][n], 0, 0, 0)
;                                  : __builtin_amdgcn_mfma_f32_16x16x32_bf16(af[m], bf[n], acc[m][n], 0, 0, 0);
;           }
;         }
;       } else {
;       bf16x8 afA[4], afB[4], bfb[2][2];
; #pragma unroll
;       for (int m = 0; m < 4; ++m) afA[m] = *(const bf16x8*)(sa + m * 2048 + ((fq ^ swz) << 4));
; #pragma unroll
;       for (int n = 0; n < 2; ++n) bfb[0][n] = *(const bf16x8*)(sb + n * 2048 + ((fq ^ swz) << 4));
; #pragma unroll
;       for (int gq = 0; gq < 8; ++gq) {
;         const int ks = gq >> 2, nh = gq & 3;
;         if (gq < 7) {
;           const int ks2 = (gq + 1) >> 2, nh2 = (gq + 1) & 3;
; #pragma unroll
;           for (int n = 0; n < 2; ++n) bfb[(gq + 1) & 1][n] = *(const bf16x8*)(sb + (nh2 * 2 + n) * 2048 + (((ks2 * 4 + fq) ^ swz) << 4));
;         }
;         if (gq == 3) {
; #pragma unroll
;           for (int m = 0; m < 4; ++m) afB[m] = *(const bf16x8*)(sa + m * 2048 + (((4 + fq) ^ swz) << 4));
;         }
;         __builtin_amdgcn_sched_barrier(0);
; #pragma unroll
	v_mfma_f32_16x16x32_bf16 v[114:117], v[172:175], v[184:187], v[114:117]
	v_mfma_f32_16x16x32_bf16 v[86:89], v[172:175], v[208:211], v[86:89]
	v_mfma_f32_16x16x32_bf16 v[54:57], v[172:175], v[212:215], v[54:57]
	v_mfma_f32_16x16x32_bf16 v[22:25], v[172:175], v[216:219], v[22:25]
	s_waitcnt lgkmcnt(3)
	v_mfma_f32_16x16x32_bf16 v[102:105], v[176:179], v[184:187], v[102:105]
	s_waitcnt lgkmcnt(2)
	v_mfma_f32_16x16x32_bf16 v[98:101], v[180:183], v[184:187], v[98:101]
	v_mfma_f32_16x16x32_bf16 v[74:77], v[176:179], v[208:211], v[74:77]
	v_mfma_f32_16x16x32_bf16 v[66:69], v[180:183], v[208:211], v[66:69]
	v_mfma_f32_16x16x32_bf16 v[46:49], v[176:179], v[212:215], v[46:49]
	v_mfma_f32_16x16x32_bf16 v[34:37], v[180:183], v[212:215], v[34:37]
	v_mfma_f32_16x16x32_bf16 v[10:13], v[176:179], v[216:219], v[10:13]
	v_mfma_f32_16x16x32_bf16 v[6:9], v[180:183], v[216:219], v[6:9]
	s_waitcnt lgkmcnt(1)
	v_mfma_f32_16x16x32_bf16 v[70:73], v[168:171], v[184:187], v[70:73]
	s_add_i32 s6, s6, 64
	s_cmpk_eq_i32 s6, 0xac0
	s_mov_b32 s7, s9
	s_waitcnt lgkmcnt(0)
	v_mfma_f32_16x16x32_bf16 v[62:65], v[188:191], v[184:187], v[62:65]
	v_mfma_f32_16x16x32_bf16 v[42:45], v[168:171], v[208:211], v[42:45]
	v_mfma_f32_16x16x32_bf16 v[30:33], v[188:191], v[208:211], v[30:33]
	v_mfma_f32_16x16x32_bf16 v[18:21], v[168:171], v[212:215], v[18:21]
	v_mfma_f32_16x16x32_bf16 v[14:17], v[188:191], v[212:215], v[14:17]
	v_mfma_f32_16x16x32_bf16 v[2:5], v[168:171], v[216:219], v[2:5]
	v_mfma_f32_16x16x32_bf16 v[90:93], v[188:191], v[216:219], v[90:93]
	s_cbranch_scc0 .LBB0_3516
	v_add_u32_e32 v130, s8, v145
	s_waitcnt vmcnt(0)
	s_barrier
	v_add_u32_e32 v140, v130, v147
	ds_read_b128 v[132:135], v140
	ds_read_b128 v[136:139], v140 offset:2048
	ds_read_b128 v[168:171], v140 offset:4096
	ds_read_b128 v[172:175], v140 offset:6144
	v_add_u32_e32 v140, s8, v146
	v_add_u32_e32 v141, v140, v147
	ds_read_b128 v[176:179], v141 offset:32768
	ds_read_b128 v[180:183], v141 offset:34816
	ds_read_b128 v[184:187], v141 offset:36864
	ds_read_b128 v[188:191], v141 offset:38912
	v_add_u32_e32 v130, v130, v148
	s_waitcnt lgkmcnt(0)
	v_mfma_f32_16x16x32_bf16 v[126:129], v[176:179], v[132:135], v[126:129]
	v_mfma_f32_16x16x32_bf16 v[110:113], v[176:179], v[136:139], v[110:113]
	v_mfma_f32_16x16x32_bf16 v[82:85], v[176:179], v[168:171], v[82:85]
	v_mfma_f32_16x16x32_bf16 v[50:53], v[176:179], v[172:175], v[50:53]
	ds_read_b128 v[176:179], v141 offset:40960
	ds_read_b128 v[192:195], v141 offset:43008
	v_mfma_f32_16x16x32_bf16 v[122:125], v[180:183], v[132:135], v[122:125]
	v_mfma_f32_16x16x32_bf16 v[106:109], v[180:183], v[136:139], v[106:109]
	v_mfma_f32_16x16x32_bf16 v[78:81], v[180:183], v[168:171], v[78:81]
	v_mfma_f32_16x16x32_bf16 v[38:41], v[180:183], v[172:175], v[38:41]
	v_mfma_f32_16x16x32_bf16 v[118:121], v[184:187], v[132:135], v[118:121]
	v_mfma_f32_16x16x32_bf16 v[180:183], v[184:187], v[136:139], v[94:97]
	v_mfma_f32_16x16x32_bf16 v[200:203], v[184:187], v[168:171], v[58:61]
	v_mfma_f32_16x16x32_bf16 v[204:207], v[188:191], v[168:171], v[54:57]
	v_mfma_f32_16x16x32_bf16 v[184:187], v[184:187], v[172:175], v[26:29]
	s_nop 2
	ds_read_b128 v[26:29], v141 offset:45056
	ds_read_b128 v[54:57], v141 offset:47104
	v_mfma_f32_16x16x32_bf16 v[114:117], v[188:191], v[132:135], v[114:117]
	v_mfma_f32_16x16x32_bf16 v[196:199], v[188:191], v[136:139], v[86:89]
	v_mfma_f32_16x16x32_bf16 v[188:191], v[188:191], v[172:175], v[22:25]
	v_add_u32_e32 v140, v140, v148
	s_waitcnt lgkmcnt(0)
	v_mfma_f32_16x16x32_bf16 v[102:105], v[176:179], v[132:135], v[102:105]
	ds_read_b128 v[22:25], v140 offset:32768
	ds_read_b128 v[86:89], v140 offset:34816
	v_mfma_f32_16x16x32_bf16 v[74:77], v[176:179], v[136:139], v[74:77]
	v_mfma_f32_16x16x32_bf16 v[46:49], v[176:179], v[168:171], v[46:49]
	v_mfma_f32_16x16x32_bf16 v[10:13], v[176:179], v[172:175], v[10:13]
	ds_read_b128 v[176:179], v130
	ds_read_b128 v[208:211], v130 offset:2048
	ds_read_b128 v[212:215], v130 offset:4096
	ds_read_b128 v[216:219], v130 offset:6144
	v_mfma_f32_16x16x32_bf16 v[98:101], v[192:195], v[132:135], v[98:101]
	v_mfma_f32_16x16x32_bf16 v[66:69], v[192:195], v[136:139], v[66:69]
	v_mfma_f32_16x16x32_bf16 v[34:37], v[192:195], v[168:171], v[34:37]
	v_mfma_f32_16x16x32_bf16 v[6:9], v[192:195], v[172:175], v[6:9]
	v_mfma_f32_16x16x32_bf16 v[220:223], v[26:29], v[168:171], v[18:21]
	v_mfma_f32_16x16x32_bf16 v[168:171], v[54:57], v[168:171], v[14:17]
	s_nop 2
	ds_read_b128 v[14:17], v140 offset:36864
	ds_read_b128 v[18:21], v140 offset:38912
	v_mfma_f32_16x16x32_bf16 v[70:73], v[26:29], v[132:135], v[70:73]
	v_mfma_f32_16x16x32_bf16 v[132:135], v[54:57], v[132:135], v[62:65]
	v_mfma_f32_16x16x32_bf16 v[192:195], v[26:29], v[136:139], v[42:45]
	v_mfma_f32_16x16x32_bf16 v[136:139], v[54:57], v[136:139], v[30:33]
	v_mfma_f32_16x16x32_bf16 v[2:5], v[26:29], v[172:175], v[2:5]
	v_mfma_f32_16x16x32_bf16 v[172:175], v[54:57], v[172:175], v[90:93]
	ds_read_b128 v[224:227], v140 offset:40960
	ds_read_b128 v[228:231], v140 offset:43008
	s_waitcnt lgkmcnt(0)
	v_mfma_f32_16x16x32_bf16 v[126:129], v[22:25], v[176:179], v[126:129]
	v_mfma_f32_16x16x32_bf16 v[122:125], v[86:89], v[176:179], v[122:125]
	v_mfma_f32_16x16x32_bf16 v[94:97], v[22:25], v[208:211], v[110:113]
	v_mfma_f32_16x16x32_bf16 v[90:93], v[86:89], v[208:211], v[106:109]
	v_mfma_f32_16x16x32_bf16 v[62:65], v[22:25], v[212:215], v[82:85]
	v_mfma_f32_16x16x32_bf16 v[58:61], v[86:89], v[212:215], v[78:81]
	v_mfma_f32_16x16x32_bf16 v[30:33], v[22:25], v[216:219], v[50:53]
	v_mfma_f32_16x16x32_bf16 v[26:29], v[86:89], v[216:219], v[38:41]
	v_mfma_f32_16x16x32_bf16 v[86:89], v[14:17], v[208:211], v[180:183]
	v_mfma_f32_16x16x32_bf16 v[22:25], v[14:17], v[216:219], v[184:187]
	s_nop 1
	ds_read_b128 v[180:183], v140 offset:45056
	ds_read_b128 v[184:187], v140 offset:47104
	v_mfma_f32_16x16x32_bf16 v[118:121], v[14:17], v[176:179], v[118:121]
	v_mfma_f32_16x16x32_bf16 v[114:117], v[18:21], v[176:179], v[114:117]
	v_mfma_f32_16x16x32_bf16 v[82:85], v[18:21], v[208:211], v[196:199]
	v_mfma_f32_16x16x32_bf16 v[54:57], v[14:17], v[212:215], v[200:203]
	v_mfma_f32_16x16x32_bf16 v[50:53], v[18:21], v[212:215], v[204:207]
	v_mfma_f32_16x16x32_bf16 v[18:21], v[18:21], v[216:219], v[188:191]
	v_mfma_f32_16x16x32_bf16 v[110:113], v[224:227], v[176:179], v[102:105]
	v_mfma_f32_16x16x32_bf16 v[106:109], v[228:231], v[176:179], v[98:101]
	v_mfma_f32_16x16x32_bf16 v[78:81], v[224:227], v[208:211], v[74:77]
	v_mfma_f32_16x16x32_bf16 v[74:77], v[228:231], v[208:211], v[66:69]
	v_mfma_f32_16x16x32_bf16 v[46:49], v[224:227], v[212:215], v[46:49]
	v_mfma_f32_16x16x32_bf16 v[42:45], v[228:231], v[212:215], v[34:37]
	v_mfma_f32_16x16x32_bf16 v[14:17], v[224:227], v[216:219], v[10:13]
	v_mfma_f32_16x16x32_bf16 v[10:13], v[228:231], v[216:219], v[6:9]
	v_mov_b32_e32 v130, v1
	s_waitcnt vmcnt(0) lgkmcnt(0)
	s_barrier
; __device__ __forceinline__ int get_tid512() { int t = threadIdx.x; asm volatile("" : "+v"(t)); return t; }
; __device__ __forceinline__ unsigned pack2(float a, float b) { unsigned r; asm("v_cvt_pk_bf16_f32 %0, %1, %2" : "=v"(r) : "v"(a), "v"(b)); return r; }
; __device__ __forceinline__ float bf2f(bf16_t h) { return __uint_as_float(((unsigned)h) << 16); }
;   __device__ __forceinline__ void c4(int g, int rig, int col, f32x4 v) const {
;     const size_t o = ((size_t)g * 2048 + rig) * 1024 + col;
;     f32x4 bs;
;     if (BASE_F32) bs = __builtin_nontemporal_load((const f32x4*)((const float*)base + o));
;     else {
;       const uint2 u = *(const uint2*)((const bf16_t*)base + o);
;       bs[0] = bf2f((bf16_t)(u.x & 0xffff)); bs[1] = bf2f((bf16_t)(u.x >> 16)); bs[2] = bf2f((bf16_t)(u.y & 0xffff)); bs[3] = bf2f((bf16_t)(u.y >> 16));
;     }
;     const f32x4 gt = *(const f32x4*)(gate + (size_t)g * 6144 + col);
;     f32x4 bi = {0.f, 0.f, 0.f, 0.f};
;     if (bias) bi = *(const f32x4*)(bias + col);
;     f32x4 r;
; #pragma unroll
;     for (int j = 0; j < 4; ++j) r[j] = bs[j] + gt[j] * (v[j] + bi[j]);
;     uint2 w; w.x = pack2(r[0], r[1]); w.y = pack2(r[2], r[3]);
;     *(uint2*)(X16 + o) = w;
;   }
; template <bool SWAP, class Epi, bool THIN = false> ...
;     ...
;     const int te = get_tid512();
;     const int fr_e = te & 15, fq_e = (te & 63) >> 4, wr_e = te >> 7, wc_e = (te >> 6) & 1;
;     const int sub = 2 * mt + (wr_e >> 1);
;     const int g = sub / tpg, ti = sub - g * tpg;
;     const int rig0 = ti * step - halo;
;     const int rw = (wr_e & 1) * 64;
;     if constexpr (Epi::KIND == 0) {
; #pragma unroll
;       for (int m = 0; m < 4; ++m) {
;         const int rig = rig0 + rw + m * 16 + fr_e;
;         if constexpr (Epi::ROWSUM) {
;           float ss = 0.f;
; #pragma unroll
;           for (int n = 0; n < 8; ++n) {
;             const int col = nt * 256 + wc_e * 128 + n * 16 + fq_e * 4;
;             if (col < N) ss += epi.c4(g, rig, col, acc[m][n]);
;           }
;           ss += __shfl_xor(ss, 16); ss += __shfl_xor(ss, 32);
;           if (fq_e == 0) epi.rowsum(g, rig, nt * 2 + wc_e, ss);
;         } else {
; #pragma unroll
;           for (int n = 0; n < 8; ++n) {
;             const int col = nt * 256 + wc_e * 128 + n * 16 + fq_e * 4;
;             if (col < N) epi.c4(g, rig, col, acc[m][n]);
;           }
	v_mfma_f32_16x16x32_bf16 v[98:101], v[184:187], v[176:179], v[132:135]
	v_ashrrev_i32_e32 v7, 8, v130
	v_add_u32_e32 v7, s5, v7
	v_ashrrev_i32_e32 v8, 31, v7
	v_lshrrev_b32_e32 v8, 28, v8
	v_add_u32_e32 v8, v7, v8
	v_ashrrev_i32_e32 v134, 4, v8
	v_lshlrev_b32_e32 v8, 11, v134
	v_lshlrev_b32_e32 v7, 7, v7
	v_sub_u32_e32 v7, v7, v8
	v_lshrrev_b32_e32 v8, 1, v130
	v_and_b32_e32 v6, 15, v130
	v_and_b32_e32 v8, 64, v8
	v_mfma_f32_16x16x32_bf16 v[66:69], v[184:187], v[208:211], v[136:139]
	v_ashrrev_i32_e32 v135, 31, v134
	s_nop 1
	v_or3_b32 v136, v7, v8, v6
	v_lshlrev_b32_e32 v6, 1, v130
	v_and_b32_e32 v132, 0x80, v6
	v_mfma_f32_16x16x32_bf16 v[6:9], v[180:183], v[216:219], v[2:5]
	v_ashrrev_i32_e32 v137, 31, v136
	v_lshlrev_b64 v[138:139], 21, v[134:135]
	v_lshlrev_b64 v[140:141], 10, v[136:137]
	v_lshrrev_b32_e32 v2, 2, v130
	v_and_b32_e32 v2, 12, v2
	v_mfma_f32_16x16x32_bf16 v[102:105], v[180:183], v[176:179], v[70:73]
	v_or3_b32 v132, v2, v132, s4
	v_mad_i64_i32 v[134:135], s[4:5], v134, s31, 0
	v_mfma_f32_16x16x32_bf16 v[70:73], v[180:183], v[208:211], v[192:195]
	v_lshl_add_u64 v[140:141], v[140:141], 0, v[138:139]
	v_cmp_gt_i32_e32 vcc, s34, v132
	v_ashrrev_i32_e32 v133, 31, v132
	v_bfe_u32 v246, v130, 4, 1
	v_mul_u32_u24_e32 v246, 24, v246
	v_mov_b32_e32 v247, 0
	v_mfma_f32_16x16x32_bf16 v[38:41], v[180:183], v[212:215], v[220:223]
	v_lshl_add_u64 v[134:135], s[22:23], 0, v[134:135]
	v_lshl_add_u64 v[140:141], v[140:141], 1, s[18:19]
	v_mfma_f32_16x16x32_bf16 v[34:37], v[184:187], v[212:215], v[168:171]
	v_mfma_f32_16x16x32_bf16 v[2:5], v[184:187], v[216:219], v[172:175]
	v_lshl_add_u64 v[218:219], v[132:133], 2, v[134:135]
	global_load_dwordx4 v[198:201], v[218:219], off
	global_load_dwordx4 v[202:205], v[218:219], off offset:64
	global_load_dwordx4 v[206:209], v[218:219], off offset:128
	global_load_dwordx4 v[210:213], v[218:219], off offset:192
	global_load_dwordx4 v[214:217], v[218:219], off offset:256
	global_load_dwordx4 v[224:227], v[218:219], off offset:320
	global_load_dwordx4 v[228:231], v[218:219], off offset:384
	global_load_dwordx4 v[232:235], v[218:219], off offset:448
	s_nop 0
	v_lshl_add_u64 v[172:173], v[132:133], 1, v[140:141]
	v_lshl_add_u64 v[196:197], v[132:133], 1, v[140:141]
	global_load_dwordx2 v[176:177], v[196:197], off
	global_load_dwordx2 v[178:179], v[196:197], off offset:32
	global_load_dwordx2 v[180:181], v[196:197], off offset:64
	global_load_dwordx2 v[182:183], v[196:197], off offset:96
	global_load_dwordx2 v[184:185], v[196:197], off offset:128
	global_load_dwordx2 v[186:187], v[196:197], off offset:160
	global_load_dwordx2 v[188:189], v[196:197], off offset:192
	global_load_dwordx2 v[190:191], v[196:197], off offset:224
	v_add_f32_e32 v126, 0, v126
	v_add_f32_e32 v127, 0, v127
	v_add_f32_e32 v128, 0, v128
	v_add_f32_e32 v129, 0, v129
	s_waitcnt vmcnt(7)
	v_lshlrev_b32_e32 v130, 16, v176
	v_and_b32_e32 v137, 0xffff0000, v176
	v_lshlrev_b32_e32 v167, 16, v177
	v_and_b32_e32 v174, 0xffff0000, v177
	v_fmac_f32_e32 v130, v126, v198
	v_fmac_f32_e32 v137, v127, v199
	v_fmac_f32_e32 v167, v128, v200
	v_fmac_f32_e32 v174, v129, v201
	v_cvt_pk_bf16_f32 v126, v130, v137
	v_cvt_pk_bf16_f32 v127, v167, v174
	v_lshl_add_u64 v[168:169], v[132:133], 1, v[140:141]
	v_add_f32_e32 v122, 0, v122
	v_add_f32_e32 v123, 0, v123
	v_add_f32_e32 v124, 0, v124
	v_add_f32_e32 v125, 0, v125
	s_waitcnt vmcnt(6)
	v_lshlrev_b32_e32 v130, 16, v178
	v_and_b32_e32 v137, 0xffff0000, v178
	v_lshlrev_b32_e32 v167, 16, v179
	v_and_b32_e32 v170, 0xffff0000, v179
	v_fmac_f32_e32 v130, v122, v202
	v_fmac_f32_e32 v137, v123, v203
	v_fmac_f32_e32 v167, v124, v204
	v_fmac_f32_e32 v170, v125, v205
	v_cvt_pk_bf16_f32 v128, v130, v137
	v_cvt_pk_bf16_f32 v129, v167, v170
	s_nop 1
	v_permlane16_swap_b32 v126, v128
	v_permlane16_swap_b32 v127, v129
	v_lshl_add_u64 v[248:249], v[168:169], 0, v[246:247]
	s_nop 0
	global_store_dwordx4 v[248:249], v[126:129], off
	s_nop 1
	v_or_b32_e32 v122, 32, v132
	v_lshl_add_u64 v[126:127], v[132:133], 1, v[140:141]
	v_add_f32_e32 v118, 0, v118
	v_add_f32_e32 v119, 0, v119
	v_add_f32_e32 v120, 0, v120
	v_add_f32_e32 v121, 0, v121
	s_waitcnt vmcnt(6)
	v_lshlrev_b32_e32 v130, 16, v180
	v_and_b32_e32 v128, 0xffff0000, v180
	v_lshlrev_b32_e32 v137, 16, v181
	v_and_b32_e32 v129, 0xffff0000, v181
	v_fmac_f32_e32 v130, v118, v206
	v_fmac_f32_e32 v128, v119, v207
	v_fmac_f32_e32 v137, v120, v208
	v_fmac_f32_e32 v129, v121, v209
	v_cvt_pk_bf16_f32 v118, v130, v128
	v_cvt_pk_bf16_f32 v119, v137, v129
	v_lshl_add_u64 v[122:123], v[132:133], 1, v[140:141]
	v_add_f32_e32 v114, 0, v114
	v_add_f32_e32 v115, 0, v115
	v_add_f32_e32 v116, 0, v116
	v_add_f32_e32 v117, 0, v117
	s_waitcnt vmcnt(5)
	v_lshlrev_b32_e32 v126, 16, v182
	v_and_b32_e32 v124, 0xffff0000, v182
	v_lshlrev_b32_e32 v127, 16, v183
	v_and_b32_e32 v125, 0xffff0000, v183
	v_fmac_f32_e32 v126, v114, v210
	v_fmac_f32_e32 v124, v115, v211
	v_fmac_f32_e32 v127, v116, v212
	v_fmac_f32_e32 v125, v117, v213
	v_cvt_pk_bf16_f32 v120, v126, v124
	v_cvt_pk_bf16_f32 v121, v127, v125
	s_nop 1
	v_permlane16_swap_b32 v118, v120
	v_permlane16_swap_b32 v119, v121
	v_lshl_add_u64 v[248:249], v[122:123], 0, v[246:247]
	s_nop 0
	global_store_dwordx4 v[248:249], v[118:121], off offset:64
	s_nop 1
	v_or_b32_e32 v114, 64, v132
	v_lshl_add_u64 v[118:119], v[132:133], 1, v[140:141]
	v_add_f32_e32 v110, 0, v110
	v_add_f32_e32 v111, 0, v111
	v_add_f32_e32 v112, 0, v112
	v_add_f32_e32 v113, 0, v113
	s_waitcnt vmcnt(5)
; __device__ __forceinline__ unsigned pack2(float a, float b) { unsigned r; asm("v_cvt_pk_bf16_f32 %0, %1, %2" : "=v"(r) : "v"(a), "v"(b)); return r; }
; __device__ __forceinline__ float bf2f(bf16_t h) { return __uint_as_float(((unsigned)h) << 16); }
;   __device__ __forceinline__ void c4(int g, int rig, int col, f32x4 v) const {
;     const size_t o = ((size_t)g * 2048 + rig) * 1024 + col;
;     f32x4 bs;
;     if (BASE_F32) bs = __builtin_nontemporal_load((const f32x4*)((const float*)base + o));
;     else {
;       const uint2 u = *(const uint2*)((const bf16_t*)base + o);
;       bs[0] = bf2f((bf16_t)(u.x & 0xffff)); bs[1] = bf2f((bf16_t)(u.x >> 16)); bs[2] = bf2f((bf16_t)(u.y & 0xffff)); bs[3] = bf2f((bf16_t)(u.y >> 16));
;     }
;     const f32x4 gt = *(const f32x4*)(gate + (size_t)g * 6144 + col);
;     f32x4 bi = {0.f, 0.f, 0.f, 0.f};
;     if (bias) bi = *(const f32x4*)(bias + col);
;     f32x4 r;
; #pragma unroll
;     for (int j = 0; j < 4; ++j) r[j] = bs[j] + gt[j] * (v[j] + bi[j]);
;     uint2 w; w.x = pack2(r[0], r[1]); w.y = pack2(r[2], r[3]);
;     *(uint2*)(X16 + o) = w;
;   }
	v_lshlrev_b32_e32 v122, 16, v184
	v_and_b32_e32 v120, 0xffff0000, v184
	v_lshlrev_b32_e32 v123, 16, v185
	v_and_b32_e32 v121, 0xffff0000, v185
	v_fmac_f32_e32 v122, v110, v214
	v_fmac_f32_e32 v120, v111, v215
	v_fmac_f32_e32 v123, v112, v216
	v_fmac_f32_e32 v121, v113, v217
	v_cvt_pk_bf16_f32 v110, v122, v120
	v_cvt_pk_bf16_f32 v111, v123, v121
	v_lshl_add_u64 v[114:115], v[132:133], 1, v[140:141]
	v_add_f32_e32 v106, 0, v106
	v_add_f32_e32 v107, 0, v107
	v_add_f32_e32 v108, 0, v108
	v_add_f32_e32 v109, 0, v109
	s_waitcnt vmcnt(4)
	v_lshlrev_b32_e32 v118, 16, v186
	v_and_b32_e32 v116, 0xffff0000, v186
	v_lshlrev_b32_e32 v119, 16, v187
	v_and_b32_e32 v117, 0xffff0000, v187
	v_fmac_f32_e32 v118, v106, v224
	v_fmac_f32_e32 v116, v107, v225
	v_fmac_f32_e32 v119, v108, v226
	v_fmac_f32_e32 v117, v109, v227
	v_cvt_pk_bf16_f32 v112, v118, v116
	v_cvt_pk_bf16_f32 v113, v119, v117
	s_nop 1
	v_permlane16_swap_b32 v110, v112
	v_permlane16_swap_b32 v111, v113
	v_lshl_add_u64 v[248:249], v[114:115], 0, v[246:247]
	s_nop 0
	global_store_dwordx4 v[248:249], v[110:113], off offset:128
	s_nop 1
	v_or_b32_e32 v106, 0x60, v132
	v_lshl_add_u64 v[110:111], v[132:133], 1, v[140:141]
	v_add_f32_e32 v102, 0, v102
	v_add_f32_e32 v103, 0, v103
	v_add_f32_e32 v104, 0, v104
	v_add_f32_e32 v105, 0, v105
	s_waitcnt vmcnt(4)
	v_lshlrev_b32_e32 v114, 16, v188
	v_and_b32_e32 v112, 0xffff0000, v188
	v_lshlrev_b32_e32 v115, 16, v189
	v_and_b32_e32 v113, 0xffff0000, v189
	v_fmac_f32_e32 v114, v102, v228
	v_fmac_f32_e32 v112, v103, v229
	v_fmac_f32_e32 v115, v104, v230
	v_fmac_f32_e32 v113, v105, v231
	v_cvt_pk_bf16_f32 v102, v114, v112
	v_cvt_pk_bf16_f32 v103, v115, v113
	v_lshl_add_u64 v[106:107], v[132:133], 1, v[140:141]
	v_add_f32_e32 v98, 0, v98
	v_add_f32_e32 v99, 0, v99
	v_add_f32_e32 v100, 0, v100
	v_add_f32_e32 v101, 0, v101
	s_waitcnt vmcnt(3)
	v_lshlrev_b32_e32 v110, 16, v190
	v_and_b32_e32 v108, 0xffff0000, v190
	v_lshlrev_b32_e32 v111, 16, v191
	v_and_b32_e32 v109, 0xffff0000, v191
	v_fmac_f32_e32 v110, v98, v232
	v_fmac_f32_e32 v108, v99, v233
	v_fmac_f32_e32 v111, v100, v234
	v_fmac_f32_e32 v109, v101, v235
	v_cvt_pk_bf16_f32 v104, v110, v108
	v_cvt_pk_bf16_f32 v105, v111, v109
	s_nop 1
	v_permlane16_swap_b32 v102, v104
	v_permlane16_swap_b32 v103, v105
	v_lshl_add_u64 v[248:249], v[106:107], 0, v[246:247]
	s_nop 0
	global_store_dwordx4 v[248:249], v[102:105], off offset:192
	s_nop 1
	v_or_b32_e32 v98, 16, v136
	v_ashrrev_i32_e32 v99, 31, v98
	v_lshlrev_b64 v[98:99], 10, v[98:99]
	v_lshl_add_u64 v[98:99], v[98:99], 0, v[138:139]
	v_lshl_add_u64 v[98:99], v[98:99], 1, s[18:19]
	v_lshl_add_u64 v[104:105], v[132:133], 1, v[98:99]
	v_lshl_add_u64 v[196:197], v[132:133], 1, v[98:99]
	global_load_dwordx2 v[176:177], v[196:197], off
	global_load_dwordx2 v[178:179], v[196:197], off offset:32
	global_load_dwordx2 v[180:181], v[196:197], off offset:64
	global_load_dwordx2 v[182:183], v[196:197], off offset:96
	global_load_dwordx2 v[184:185], v[196:197], off offset:128
	global_load_dwordx2 v[186:187], v[196:197], off offset:160
	global_load_dwordx2 v[188:189], v[196:197], off offset:192
	global_load_dwordx2 v[190:191], v[196:197], off offset:224
	v_add_f32_e32 v94, 0, v94
	v_add_f32_e32 v95, 0, v95
	v_add_f32_e32 v96, 0, v96
	v_add_f32_e32 v97, 0, v97
	s_waitcnt vmcnt(7)
	v_lshlrev_b32_e32 v108, 16, v176
	v_and_b32_e32 v106, 0xffff0000, v176
	v_lshlrev_b32_e32 v109, 16, v177
	v_and_b32_e32 v107, 0xffff0000, v177
	v_fmac_f32_e32 v108, v94, v198
	v_fmac_f32_e32 v106, v95, v199
	v_fmac_f32_e32 v109, v96, v200
	v_fmac_f32_e32 v107, v97, v201
	v_cvt_pk_bf16_f32 v94, v108, v106
	v_cvt_pk_bf16_f32 v95, v109, v107
	v_lshl_add_u64 v[100:101], v[132:133], 1, v[98:99]
	v_add_f32_e32 v90, 0, v90
	v_add_f32_e32 v91, 0, v91
	v_add_f32_e32 v92, 0, v92
	v_add_f32_e32 v93, 0, v93
	s_waitcnt vmcnt(6)
	v_lshlrev_b32_e32 v104, 16, v178
	v_and_b32_e32 v102, 0xffff0000, v178
	v_lshlrev_b32_e32 v105, 16, v179
	v_and_b32_e32 v103, 0xffff0000, v179
	v_fmac_f32_e32 v104, v90, v202
	v_fmac_f32_e32 v102, v91, v203
	v_fmac_f32_e32 v105, v92, v204
	v_fmac_f32_e32 v103, v93, v205
	v_cvt_pk_bf16_f32 v96, v104, v102
	v_cvt_pk_bf16_f32 v97, v105, v103
	s_nop 1
	v_permlane16_swap_b32 v94, v96
	v_permlane16_swap_b32 v95, v97
	v_lshl_add_u64 v[248:249], v[100:101], 0, v[246:247]
	s_nop 0
	global_store_dwordx4 v[248:249], v[94:97], off
	s_nop 1
	v_lshl_add_u64 v[94:95], v[132:133], 1, v[98:99]
	v_add_f32_e32 v86, 0, v86
	v_add_f32_e32 v87, 0, v87
	v_add_f32_e32 v88, 0, v88
	v_add_f32_e32 v89, 0, v89
	s_waitcnt vmcnt(6)
	v_lshlrev_b32_e32 v100, 16, v180
	v_and_b32_e32 v96, 0xffff0000, v180
	v_lshlrev_b32_e32 v101, 16, v181
	v_and_b32_e32 v97, 0xffff0000, v181
	v_fmac_f32_e32 v100, v86, v206
	v_fmac_f32_e32 v96, v87, v207
	v_fmac_f32_e32 v101, v88, v208
	v_fmac_f32_e32 v97, v89, v209
	v_cvt_pk_bf16_f32 v86, v100, v96
	v_cvt_pk_bf16_f32 v87, v101, v97
	v_lshl_add_u64 v[90:91], v[132:133], 1, v[98:99]
	v_add_f32_e32 v82, 0, v82
	v_add_f32_e32 v83, 0, v83
	v_add_f32_e32 v84, 0, v84
	v_add_f32_e32 v85, 0, v85
	s_waitcnt vmcnt(5)
	v_lshlrev_b32_e32 v94, 16, v182
	v_and_b32_e32 v92, 0xffff0000, v182
	v_lshlrev_b32_e32 v95, 16, v183
	v_and_b32_e32 v93, 0xffff0000, v183
	v_fmac_f32_e32 v94, v82, v210
	v_fmac_f32_e32 v92, v83, v211
	v_fmac_f32_e32 v95, v84, v212
	v_fmac_f32_e32 v93, v85, v213
	v_cvt_pk_bf16_f32 v88, v94, v92
	v_cvt_pk_bf16_f32 v89, v95, v93
	s_nop 1
	v_permlane16_swap_b32 v86, v88
	v_permlane16_swap_b32 v87, v89
	v_lshl_add_u64 v[248:249], v[90:91], 0, v[246:247]
	s_nop 0
	global_store_dwordx4 v[248:249], v[86:89], off offset:64
	s_nop 1
	v_lshl_add_u64 v[86:87], v[132:133], 1, v[98:99]
	v_add_f32_e32 v78, 0, v78
	v_add_f32_e32 v79, 0, v79
	v_add_f32_e32 v80, 0, v80
	v_add_f32_e32 v81, 0, v81
	s_waitcnt vmcnt(5)
; __device__ __forceinline__ unsigned pack2(float a, float b) { unsigned r; asm("v_cvt_pk_bf16_f32 %0, %1, %2" : "=v"(r) : "v"(a), "v"(b)); return r; }
; __device__ __forceinline__ float bf2f(bf16_t h) { return __uint_as_float(((unsigned)h) << 16); }
;   __device__ __forceinline__ void c4(int g, int rig, int col, f32x4 v) const {
;     const size_t o = ((size_t)g * 2048 + rig) * 1024 + col;
;     f32x4 bs;
;     if (BASE_F32) bs = __builtin_nontemporal_load((const f32x4*)((const float*)base + o));
;     else {
;       const uint2 u = *(const uint2*)((const bf16_t*)base + o);
;       bs[0] = bf2f((bf16_t)(u.x & 0xffff)); bs[1] = bf2f((bf16_t)(u.x >> 16)); bs[2] = bf2f((bf16_t)(u.y & 0xffff)); bs[3] = bf2f((bf16_t)(u.y >> 16));
;     }
;     const f32x4 gt = *(const f32x4*)(gate + (size_t)g * 6144 + col);
;     f32x4 bi = {0.f, 0.f, 0.f, 0.f};
;     if (bias) bi = *(const f32x4*)(bias + col);
;     f32x4 r;
; #pragma unroll
;     for (int j = 0; j < 4; ++j) r[j] = bs[j] + gt[j] * (v[j] + bi[j]);
;     uint2 w; w.x = pack2(r[0], r[1]); w.y = pack2(r[2], r[3]);
;     *(uint2*)(X16 + o) = w;
;   }
; template <bool SWAP, class Epi, bool THIN = false> ...
;     ...
;         } else {
; #pragma unroll
;           for (int n = 0; n < 8; ++n) {
;             const int col = nt * 256 + wc_e * 128 + n * 16 + fq_e * 4;
;             if (col < N) epi.c4(g, rig, col, acc[m][n]);
;           }
	v_lshlrev_b32_e32 v90, 16, v184
	v_and_b32_e32 v88, 0xffff0000, v184
	v_lshlrev_b32_e32 v91, 16, v185
	v_and_b32_e32 v89, 0xffff0000, v185
	v_fmac_f32_e32 v90, v78, v214
	v_fmac_f32_e32 v88, v79, v215
	v_fmac_f32_e32 v91, v80, v216
	v_fmac_f32_e32 v89, v81, v217
	v_cvt_pk_bf16_f32 v78, v90, v88
	v_cvt_pk_bf16_f32 v79, v91, v89
	v_lshl_add_u64 v[82:83], v[132:133], 1, v[98:99]
	v_add_f32_e32 v74, 0, v74
	v_add_f32_e32 v75, 0, v75
	v_add_f32_e32 v76, 0, v76
	v_add_f32_e32 v77, 0, v77
	s_waitcnt vmcnt(4)
	v_lshlrev_b32_e32 v86, 16, v186
	v_and_b32_e32 v84, 0xffff0000, v186
	v_lshlrev_b32_e32 v87, 16, v187
	v_and_b32_e32 v85, 0xffff0000, v187
	v_fmac_f32_e32 v86, v74, v224
	v_fmac_f32_e32 v84, v75, v225
	v_fmac_f32_e32 v87, v76, v226
	v_fmac_f32_e32 v85, v77, v227
	v_cvt_pk_bf16_f32 v80, v86, v84
	v_cvt_pk_bf16_f32 v81, v87, v85
	s_nop 1
	v_permlane16_swap_b32 v78, v80
	v_permlane16_swap_b32 v79, v81
	v_lshl_add_u64 v[248:249], v[82:83], 0, v[246:247]
	s_nop 0
	global_store_dwordx4 v[248:249], v[78:81], off offset:128
	s_nop 1
	v_lshl_add_u64 v[78:79], v[132:133], 1, v[98:99]
	v_add_f32_e32 v70, 0, v70
	v_add_f32_e32 v71, 0, v71
	v_add_f32_e32 v72, 0, v72
	v_add_f32_e32 v73, 0, v73
	s_waitcnt vmcnt(4)
	v_lshlrev_b32_e32 v82, 16, v188
	v_and_b32_e32 v80, 0xffff0000, v188
	v_lshlrev_b32_e32 v83, 16, v189
	v_and_b32_e32 v81, 0xffff0000, v189
	v_fmac_f32_e32 v82, v70, v228
	v_fmac_f32_e32 v80, v71, v229
	v_fmac_f32_e32 v83, v72, v230
	v_fmac_f32_e32 v81, v73, v231
	v_cvt_pk_bf16_f32 v70, v82, v80
	v_cvt_pk_bf16_f32 v71, v83, v81
	v_lshl_add_u64 v[74:75], v[132:133], 1, v[98:99]
	v_add_f32_e32 v66, 0, v66
	v_add_f32_e32 v67, 0, v67
	v_add_f32_e32 v68, 0, v68
	v_add_f32_e32 v69, 0, v69
	s_waitcnt vmcnt(3)
	v_lshlrev_b32_e32 v78, 16, v190
	v_and_b32_e32 v76, 0xffff0000, v190
	v_lshlrev_b32_e32 v79, 16, v191
	v_and_b32_e32 v77, 0xffff0000, v191
	v_fmac_f32_e32 v78, v66, v232
	v_fmac_f32_e32 v76, v67, v233
	v_fmac_f32_e32 v79, v68, v234
	v_fmac_f32_e32 v77, v69, v235
	v_cvt_pk_bf16_f32 v72, v78, v76
	v_cvt_pk_bf16_f32 v73, v79, v77
	s_nop 1
	v_permlane16_swap_b32 v70, v72
	v_permlane16_swap_b32 v71, v73
	v_lshl_add_u64 v[248:249], v[74:75], 0, v[246:247]
	s_nop 0
	global_store_dwordx4 v[248:249], v[70:73], off offset:192
	s_nop 1
	v_or_b32_e32 v66, 32, v136
	v_ashrrev_i32_e32 v67, 31, v66
	v_lshlrev_b64 v[66:67], 10, v[66:67]
	v_lshl_add_u64 v[66:67], v[66:67], 0, v[138:139]
	v_lshl_add_u64 v[66:67], v[66:67], 1, s[18:19]
	v_lshl_add_u64 v[72:73], v[132:133], 1, v[66:67]
	v_lshl_add_u64 v[196:197], v[132:133], 1, v[66:67]
	global_load_dwordx2 v[176:177], v[196:197], off
	global_load_dwordx2 v[178:179], v[196:197], off offset:32
	global_load_dwordx2 v[180:181], v[196:197], off offset:64
	global_load_dwordx2 v[182:183], v[196:197], off offset:96
	global_load_dwordx2 v[184:185], v[196:197], off offset:128
	global_load_dwordx2 v[186:187], v[196:197], off offset:160
	global_load_dwordx2 v[188:189], v[196:197], off offset:192
	global_load_dwordx2 v[190:191], v[196:197], off offset:224
	v_add_f32_e32 v62, 0, v62
	v_add_f32_e32 v63, 0, v63
	v_add_f32_e32 v64, 0, v64
	v_add_f32_e32 v65, 0, v65
	s_waitcnt vmcnt(7)
	v_lshlrev_b32_e32 v76, 16, v176
	v_and_b32_e32 v74, 0xffff0000, v176
	v_lshlrev_b32_e32 v77, 16, v177
	v_and_b32_e32 v75, 0xffff0000, v177
	v_fmac_f32_e32 v76, v62, v198
	v_fmac_f32_e32 v74, v63, v199
	v_fmac_f32_e32 v77, v64, v200
	v_fmac_f32_e32 v75, v65, v201
	v_cvt_pk_bf16_f32 v62, v76, v74
	v_cvt_pk_bf16_f32 v63, v77, v75
	v_lshl_add_u64 v[68:69], v[132:133], 1, v[66:67]
	v_add_f32_e32 v58, 0, v58
	v_add_f32_e32 v59, 0, v59
	v_add_f32_e32 v60, 0, v60
	v_add_f32_e32 v61, 0, v61
	s_waitcnt vmcnt(6)
	v_lshlrev_b32_e32 v72, 16, v178
	v_and_b32_e32 v70, 0xffff0000, v178
	v_lshlrev_b32_e32 v73, 16, v179
	v_and_b32_e32 v71, 0xffff0000, v179
	v_fmac_f32_e32 v72, v58, v202
	v_fmac_f32_e32 v70, v59, v203
	v_fmac_f32_e32 v73, v60, v204
	v_fmac_f32_e32 v71, v61, v205
	v_cvt_pk_bf16_f32 v64, v72, v70
	v_cvt_pk_bf16_f32 v65, v73, v71
	s_nop 1
	v_permlane16_swap_b32 v62, v64
	v_permlane16_swap_b32 v63, v65
	v_lshl_add_u64 v[248:249], v[68:69], 0, v[246:247]
	s_nop 0
	global_store_dwordx4 v[248:249], v[62:65], off
	s_nop 1
	v_lshl_add_u64 v[62:63], v[132:133], 1, v[66:67]
	v_add_f32_e32 v54, 0, v54
	v_add_f32_e32 v55, 0, v55
	v_add_f32_e32 v56, 0, v56
	v_add_f32_e32 v57, 0, v57
	s_waitcnt vmcnt(6)
	v_lshlrev_b32_e32 v68, 16, v180
	v_and_b32_e32 v64, 0xffff0000, v180
	v_lshlrev_b32_e32 v69, 16, v181
	v_and_b32_e32 v65, 0xffff0000, v181
	v_fmac_f32_e32 v68, v54, v206
	v_fmac_f32_e32 v64, v55, v207
	v_fmac_f32_e32 v69, v56, v208
	v_fmac_f32_e32 v65, v57, v209
	v_cvt_pk_bf16_f32 v54, v68, v64
	v_cvt_pk_bf16_f32 v55, v69, v65
	v_lshl_add_u64 v[58:59], v[132:133], 1, v[66:67]
	v_add_f32_e32 v50, 0, v50
	v_add_f32_e32 v51, 0, v51
	v_add_f32_e32 v52, 0, v52
	v_add_f32_e32 v53, 0, v53
	s_waitcnt vmcnt(5)
	v_lshlrev_b32_e32 v62, 16, v182
	v_and_b32_e32 v60, 0xffff0000, v182
	v_lshlrev_b32_e32 v63, 16, v183
	v_and_b32_e32 v61, 0xffff0000, v183
	v_fmac_f32_e32 v62, v50, v210
	v_fmac_f32_e32 v60, v51, v211
	v_fmac_f32_e32 v63, v52, v212
	v_fmac_f32_e32 v61, v53, v213
	v_cvt_pk_bf16_f32 v56, v62, v60
	v_cvt_pk_bf16_f32 v57, v63, v61
	s_nop 1
	v_permlane16_swap_b32 v54, v56
	v_permlane16_swap_b32 v55, v57
	v_lshl_add_u64 v[248:249], v[58:59], 0, v[246:247]
	s_nop 0
	global_store_dwordx4 v[248:249], v[54:57], off offset:64
	s_nop 1
	v_lshl_add_u64 v[54:55], v[132:133], 1, v[66:67]
	v_add_f32_e32 v46, 0, v46
	v_add_f32_e32 v47, 0, v47
	v_add_f32_e32 v48, 0, v48
	v_add_f32_e32 v49, 0, v49
	s_waitcnt vmcnt(5)
; __device__ __forceinline__ unsigned pack2(float a, float b) { unsigned r; asm("v_cvt_pk_bf16_f32 %0, %1, %2" : "=v"(r) : "v"(a), "v"(b)); return r; }
; __device__ __forceinline__ float bf2f(bf16_t h) { return __uint_as_float(((unsigned)h) << 16); }
;   __device__ __forceinline__ void c4(int g, int rig, int col, f32x4 v) const {
;     const size_t o = ((size_t)g * 2048 + rig) * 1024 + col;
;     f32x4 bs;
;     if (BASE_F32) bs = __builtin_nontemporal_load((const f32x4*)((const float*)base + o));
;     else {
;       const uint2 u = *(const uint2*)((const bf16_t*)base + o);
;       bs[0] = bf2f((bf16_t)(u.x & 0xffff)); bs[1] = bf2f((bf16_t)(u.x >> 16)); bs[2] = bf2f((bf16_t)(u.y & 0xffff)); bs[3] = bf2f((bf16_t)(u.y >> 16));
;     }
;     const f32x4 gt = *(const f32x4*)(gate + (size_t)g * 6144 + col);
;     f32x4 bi = {0.f, 0.f, 0.f, 0.f};
;     if (bias) bi = *(const f32x4*)(bias + col);
;     f32x4 r;
; #pragma unroll
;     for (int j = 0; j < 4; ++j) r[j] = bs[j] + gt[j] * (v[j] + bi[j]);
;     uint2 w; w.x = pack2(r[0], r[1]); w.y = pack2(r[2], r[3]);
;     *(uint2*)(X16 + o) = w;
;   }
; template <bool SWAP, class Epi, bool THIN = false> ...
;     ...
;         } else {
; #pragma unroll
;           for (int n = 0; n < 8; ++n) {
;             const int col = nt * 256 + wc_e * 128 + n * 16 + fq_e * 4;
;             if (col < N) epi.c4(g, rig, col, acc[m][n]);
;           }
	v_lshlrev_b32_e32 v58, 16, v184
	v_and_b32_e32 v56, 0xffff0000, v184
	v_lshlrev_b32_e32 v59, 16, v185
	v_and_b32_e32 v57, 0xffff0000, v185
	v_fmac_f32_e32 v58, v46, v214
	v_fmac_f32_e32 v56, v47, v215
	v_fmac_f32_e32 v59, v48, v216
	v_fmac_f32_e32 v57, v49, v217
	v_cvt_pk_bf16_f32 v46, v58, v56
	v_cvt_pk_bf16_f32 v47, v59, v57
	v_lshl_add_u64 v[50:51], v[132:133], 1, v[66:67]
	v_add_f32_e32 v42, 0, v42
	v_add_f32_e32 v43, 0, v43
	v_add_f32_e32 v44, 0, v44
	v_add_f32_e32 v45, 0, v45
	s_waitcnt vmcnt(4)
	v_lshlrev_b32_e32 v54, 16, v186
	v_and_b32_e32 v52, 0xffff0000, v186
	v_lshlrev_b32_e32 v55, 16, v187
	v_and_b32_e32 v53, 0xffff0000, v187
	v_fmac_f32_e32 v54, v42, v224
	v_fmac_f32_e32 v52, v43, v225
	v_fmac_f32_e32 v55, v44, v226
	v_fmac_f32_e32 v53, v45, v227
	v_cvt_pk_bf16_f32 v48, v54, v52
	v_cvt_pk_bf16_f32 v49, v55, v53
	s_nop 1
	v_permlane16_swap_b32 v46, v48
	v_permlane16_swap_b32 v47, v49
	v_lshl_add_u64 v[248:249], v[50:51], 0, v[246:247]
	s_nop 0
	global_store_dwordx4 v[248:249], v[46:49], off offset:128
	s_nop 1
	v_lshl_add_u64 v[46:47], v[132:133], 1, v[66:67]
	v_add_f32_e32 v38, 0, v38
	v_add_f32_e32 v39, 0, v39
	v_add_f32_e32 v40, 0, v40
	v_add_f32_e32 v41, 0, v41
	s_waitcnt vmcnt(4)
	v_lshlrev_b32_e32 v50, 16, v188
	v_and_b32_e32 v48, 0xffff0000, v188
	v_lshlrev_b32_e32 v51, 16, v189
	v_and_b32_e32 v49, 0xffff0000, v189
	v_fmac_f32_e32 v50, v38, v228
	v_fmac_f32_e32 v48, v39, v229
	v_fmac_f32_e32 v51, v40, v230
	v_fmac_f32_e32 v49, v41, v231
	v_cvt_pk_bf16_f32 v38, v50, v48
	v_cvt_pk_bf16_f32 v39, v51, v49
	v_lshl_add_u64 v[42:43], v[132:133], 1, v[66:67]
	v_add_f32_e32 v34, 0, v34
	v_add_f32_e32 v35, 0, v35
	v_add_f32_e32 v36, 0, v36
	v_add_f32_e32 v37, 0, v37
	s_waitcnt vmcnt(3)
	v_lshlrev_b32_e32 v46, 16, v190
	v_and_b32_e32 v44, 0xffff0000, v190
	v_lshlrev_b32_e32 v47, 16, v191
	v_and_b32_e32 v45, 0xffff0000, v191
	v_fmac_f32_e32 v46, v34, v232
	v_fmac_f32_e32 v44, v35, v233
	v_fmac_f32_e32 v47, v36, v234
	v_fmac_f32_e32 v45, v37, v235
	v_cvt_pk_bf16_f32 v40, v46, v44
	v_cvt_pk_bf16_f32 v41, v47, v45
	s_nop 1
	v_permlane16_swap_b32 v38, v40
	v_permlane16_swap_b32 v39, v41
	v_lshl_add_u64 v[248:249], v[42:43], 0, v[246:247]
	s_nop 0
	global_store_dwordx4 v[248:249], v[38:41], off offset:192
	s_nop 1
	v_or_b32_e32 v34, 48, v136
	v_ashrrev_i32_e32 v35, 31, v34
	v_lshlrev_b64 v[34:35], 10, v[34:35]
	v_lshl_add_u64 v[34:35], v[34:35], 0, v[138:139]
	v_lshl_add_u64 v[34:35], v[34:35], 1, s[18:19]
	v_lshl_add_u64 v[40:41], v[132:133], 1, v[34:35]
	v_lshl_add_u64 v[196:197], v[132:133], 1, v[34:35]
	global_load_dwordx2 v[176:177], v[196:197], off
	global_load_dwordx2 v[178:179], v[196:197], off offset:32
	global_load_dwordx2 v[180:181], v[196:197], off offset:64
	global_load_dwordx2 v[182:183], v[196:197], off offset:96
	global_load_dwordx2 v[184:185], v[196:197], off offset:128
	global_load_dwordx2 v[186:187], v[196:197], off offset:160
	global_load_dwordx2 v[188:189], v[196:197], off offset:192
	global_load_dwordx2 v[190:191], v[196:197], off offset:224
	v_add_f32_e32 v30, 0, v30
	v_add_f32_e32 v31, 0, v31
	v_add_f32_e32 v32, 0, v32
	v_add_f32_e32 v33, 0, v33
	s_waitcnt vmcnt(7)
	v_lshlrev_b32_e32 v44, 16, v176
	v_and_b32_e32 v42, 0xffff0000, v176
	v_lshlrev_b32_e32 v45, 16, v177
	v_and_b32_e32 v43, 0xffff0000, v177
	v_fmac_f32_e32 v44, v30, v198
	v_fmac_f32_e32 v42, v31, v199
	v_fmac_f32_e32 v45, v32, v200
	v_fmac_f32_e32 v43, v33, v201
	v_cvt_pk_bf16_f32 v30, v44, v42
	v_cvt_pk_bf16_f32 v31, v45, v43
	v_lshl_add_u64 v[36:37], v[132:133], 1, v[34:35]
	v_add_f32_e32 v26, 0, v26
	v_add_f32_e32 v27, 0, v27
	v_add_f32_e32 v28, 0, v28
	v_add_f32_e32 v29, 0, v29
	s_waitcnt vmcnt(6)
; __device__ __forceinline__ unsigned pack2(float a, float b) { unsigned r; asm("v_cvt_pk_bf16_f32 %0, %1, %2" : "=v"(r) : "v"(a), "v"(b)); return r; }
; __device__ __forceinline__ float bf2f(bf16_t h) { return __uint_as_float(((unsigned)h) << 16); }
;   __device__ __forceinline__ void c4(int g, int rig, int col, f32x4 v) const {
;     const size_t o = ((size_t)g * 2048 + rig) * 1024 + col;
;     f32x4 bs;
;     if (BASE_F32) bs = __builtin_nontemporal_load((const f32x4*)((const float*)base + o));
;     else {
;       const uint2 u = *(const uint2*)((const bf16_t*)base + o);
;       bs[0] = bf2f((bf16_t)(u.x & 0xffff)); bs[1] = bf2f((bf16_t)(u.x >> 16)); bs[2] = bf2f((bf16_t)(u.y & 0xffff)); bs[3] = bf2f((bf16_t)(u.y >> 16));
;     }
;     const f32x4 gt = *(const f32x4*)(gate + (size_t)g * 6144 + col);
;     f32x4 bi = {0.f, 0.f, 0.f, 0.f};
;     if (bias) bi = *(const f32x4*)(bias + col);
;     f32x4 r;
; #pragma unroll
;     for (int j = 0; j < 4; ++j) r[j] = bs[j] + gt[j] * (v[j] + bi[j]);
;     uint2 w; w.x = pack2(r[0], r[1]); w.y = pack2(r[2], r[3]);
;     *(uint2*)(X16 + o) = w;
;   }
; template <bool SWAP, class Epi, bool THIN = false> ...
;     ...
;         } else {
; #pragma unroll
;           for (int n = 0; n < 8; ++n) {
;             const int col = nt * 256 + wc_e * 128 + n * 16 + fq_e * 4;
;             if (col < N) epi.c4(g, rig, col, acc[m][n]);
;           }
	v_lshlrev_b32_e32 v40, 16, v178
	v_and_b32_e32 v38, 0xffff0000, v178
	v_lshlrev_b32_e32 v41, 16, v179
	v_and_b32_e32 v39, 0xffff0000, v179
	v_fmac_f32_e32 v40, v26, v202
	v_fmac_f32_e32 v38, v27, v203
	v_fmac_f32_e32 v41, v28, v204
	v_fmac_f32_e32 v39, v29, v205
	v_cvt_pk_bf16_f32 v32, v40, v38
	v_cvt_pk_bf16_f32 v33, v41, v39
	s_nop 1
	v_permlane16_swap_b32 v30, v32
	v_permlane16_swap_b32 v31, v33
	v_lshl_add_u64 v[248:249], v[36:37], 0, v[246:247]
	s_nop 0
	global_store_dwordx4 v[248:249], v[30:33], off
	s_nop 1
	v_lshl_add_u64 v[30:31], v[132:133], 1, v[34:35]
	v_add_f32_e32 v22, 0, v22
	v_add_f32_e32 v23, 0, v23
	v_add_f32_e32 v24, 0, v24
	v_add_f32_e32 v25, 0, v25
	s_waitcnt vmcnt(6)
	v_lshlrev_b32_e32 v36, 16, v180
	v_and_b32_e32 v32, 0xffff0000, v180
	v_lshlrev_b32_e32 v37, 16, v181
	v_and_b32_e32 v33, 0xffff0000, v181
	v_fmac_f32_e32 v36, v22, v206
	v_fmac_f32_e32 v32, v23, v207
	v_fmac_f32_e32 v37, v24, v208
	v_fmac_f32_e32 v33, v25, v209
	v_cvt_pk_bf16_f32 v22, v36, v32
	v_cvt_pk_bf16_f32 v23, v37, v33
	v_lshl_add_u64 v[26:27], v[132:133], 1, v[34:35]
	v_add_f32_e32 v18, 0, v18
	v_add_f32_e32 v19, 0, v19
	v_add_f32_e32 v20, 0, v20
	v_add_f32_e32 v21, 0, v21
	s_waitcnt vmcnt(5)
	v_lshlrev_b32_e32 v30, 16, v182
	v_and_b32_e32 v28, 0xffff0000, v182
	v_lshlrev_b32_e32 v31, 16, v183
	v_and_b32_e32 v29, 0xffff0000, v183
	v_fmac_f32_e32 v30, v18, v210
	v_fmac_f32_e32 v28, v19, v211
	v_fmac_f32_e32 v31, v20, v212
	v_fmac_f32_e32 v29, v21, v213
	v_cvt_pk_bf16_f32 v24, v30, v28
	v_cvt_pk_bf16_f32 v25, v31, v29
	s_nop 1
	v_permlane16_swap_b32 v22, v24
	v_permlane16_swap_b32 v23, v25
	v_lshl_add_u64 v[248:249], v[26:27], 0, v[246:247]
	s_nop 0
	global_store_dwordx4 v[248:249], v[22:25], off offset:64
	s_nop 1
	v_lshl_add_u64 v[22:23], v[132:133], 1, v[34:35]
	v_add_f32_e32 v14, 0, v14
	v_add_f32_e32 v15, 0, v15
	v_add_f32_e32 v16, 0, v16
	v_add_f32_e32 v17, 0, v17
	s_waitcnt vmcnt(5)
	v_lshlrev_b32_e32 v26, 16, v184
	v_and_b32_e32 v24, 0xffff0000, v184
	v_lshlrev_b32_e32 v27, 16, v185
	v_and_b32_e32 v25, 0xffff0000, v185
	v_fmac_f32_e32 v26, v14, v214
	v_fmac_f32_e32 v24, v15, v215
	v_fmac_f32_e32 v27, v16, v216
	v_fmac_f32_e32 v25, v17, v217
	v_cvt_pk_bf16_f32 v14, v26, v24
	v_cvt_pk_bf16_f32 v15, v27, v25
	v_lshl_add_u64 v[18:19], v[132:133], 1, v[34:35]
	v_add_f32_e32 v10, 0, v10
	v_add_f32_e32 v11, 0, v11
	v_add_f32_e32 v12, 0, v12
	v_add_f32_e32 v13, 0, v13
	s_waitcnt vmcnt(4)
	v_lshlrev_b32_e32 v22, 16, v186
	v_and_b32_e32 v20, 0xffff0000, v186
	v_lshlrev_b32_e32 v23, 16, v187
	v_and_b32_e32 v21, 0xffff0000, v187
	v_fmac_f32_e32 v22, v10, v224
	v_fmac_f32_e32 v20, v11, v225
	v_fmac_f32_e32 v23, v12, v226
	v_fmac_f32_e32 v21, v13, v227
	v_cvt_pk_bf16_f32 v16, v22, v20
	v_cvt_pk_bf16_f32 v17, v23, v21
	s_nop 1
	v_permlane16_swap_b32 v14, v16
	v_permlane16_swap_b32 v15, v17
	v_lshl_add_u64 v[248:249], v[18:19], 0, v[246:247]
	s_nop 0
	global_store_dwordx4 v[248:249], v[14:17], off offset:128
	s_nop 1
	v_lshl_add_u64 v[14:15], v[132:133], 1, v[34:35]
	v_add_f32_e32 v6, 0, v6
	v_add_f32_e32 v7, 0, v7
	v_add_f32_e32 v8, 0, v8
	v_add_f32_e32 v9, 0, v9
	s_waitcnt vmcnt(4)
	v_lshlrev_b32_e32 v18, 16, v188
	v_and_b32_e32 v16, 0xffff0000, v188
	v_lshlrev_b32_e32 v19, 16, v189
	v_and_b32_e32 v17, 0xffff0000, v189
	v_fmac_f32_e32 v18, v6, v228
	v_fmac_f32_e32 v16, v7, v229
	v_fmac_f32_e32 v19, v8, v230
	v_fmac_f32_e32 v17, v9, v231
	v_cvt_pk_bf16_f32 v6, v18, v16
	v_cvt_pk_bf16_f32 v7, v19, v17
	v_lshl_add_u64 v[10:11], v[132:133], 1, v[34:35]
	v_add_f32_e32 v2, 0, v2
	v_add_f32_e32 v3, 0, v3
	v_add_f32_e32 v4, 0, v4
	v_add_f32_e32 v5, 0, v5
	s_waitcnt vmcnt(3)
	v_lshlrev_b32_e32 v14, 16, v190
	v_and_b32_e32 v12, 0xffff0000, v190
	v_lshlrev_b32_e32 v15, 16, v191
	v_and_b32_e32 v13, 0xffff0000, v191
	v_fmac_f32_e32 v14, v2, v232
	v_fmac_f32_e32 v12, v3, v233
	v_fmac_f32_e32 v15, v4, v234
	v_fmac_f32_e32 v13, v5, v235
	v_cvt_pk_bf16_f32 v8, v14, v12
	v_cvt_pk_bf16_f32 v9, v15, v13
	s_nop 1
	v_permlane16_swap_b32 v6, v8
	v_permlane16_swap_b32 v7, v9
	v_lshl_add_u64 v[248:249], v[10:11], 0, v[246:247]
	s_nop 0
	global_store_dwordx4 v[248:249], v[6:9], off offset:192
	s_nop 1
	s_branch .LBB0_3514
